# v032 + f32->bf16 pair packs via v_cvt_pk_bf16_f32 instead of the 6-op integer RNE sequence (P0/LN/post/prep) + grid barrier one release hop fewer
# speedup vs baseline: 1.0045x; 1.0005x over previous
; #define GAS __attribute__((address_space(1)))
; #define LAS __attribute__((address_space(3)))
; #define LDS_WAIT() asm volatile("s_waitcnt lgkmcnt(0)" ::: "memory")
; __device__ __forceinline__ unsigned pk2(float lo, float hi) { return f2bf(lo) | (f2bf(hi) << 16); }
; #define WSL(F) ws_opaque((F).ws)
; __device__ __forceinline__ const float* karg(int i) { kseg_t ka = (kseg_t)__builtin_amdgcn_kernarg_segment_ptr(); asm volatile("" : "+s"(ka)); return *(const float* const __attribute__((address_space(4)))*)(ka + 8 * i); }
; __device__ __forceinline__ void p0_transpose_item(const float* W, int K, int N, bf16* WT, int ldt, LAS float* scr, int item, int lane) {
;     const int nblk = N / 32, kb = item / nblk, nb = item % nblk, k0 = 64 * kb, n0 = 32 * nb;
;     float wv[32];
; #pragma unroll
;     for (int i = 0; i < 32; ++i) wv[i] = __builtin_nontemporal_load(W + (size_t)(k0 + 2 * i + (lane >> 5)) * N + n0 + (lane & 31));
; #pragma unroll
;     for (int i = 0; i < 32; ++i) scr[(2 * i + (lane >> 5)) * 33 + (lane & 31)] = wv[i];
;     LDS_WAIT(); asm volatile("" ::: "memory");
;     const int c = lane & 7;
; #pragma unroll
;     for (int j = 0; j < 4; ++j) { const int n = (lane >> 3) + 8 * j; const LAS float* s = scr + (8 * c) * 33 + n;
;         v4u o; o.x = pk2(s[0 * 33], s[1 * 33]); o.y = pk2(s[2 * 33], s[3 * 33]); o.z = pk2(s[4 * 33], s[5 * 33]); o.w = pk2(s[6 * 33], s[7 * 33]);
;         __builtin_nontemporal_store(o, (GAS v4u*)(WT + (size_t)(n0 + n) * ldt + k0 + 8 * c)); }
;     LDS_WAIT(); asm volatile("" ::: "memory");
; }
; __device__ __forceinline__ void p0_prologue(Frame& F) {
;     ...
;         { const int h = r / ((KVL / 64) * (HD / 32)), rr = r % ((KVL / 64) * (HD / 32));
;           p0_transpose_item(karg(9) + ((size_t)l * DSA_H + h) * KVL * HD, KVL, HD, (bf16*)(WSL(F) + WS_WUVB) + ((size_t)(l * 5 + (h >> 1)) * 256 + (h & 1) * 128) * 1024 + (h & 1) * 512, 1024, scr, rr, lane); }
.LBB0_14:
	s_mul_hi_i32 s18, s80, 0x15390949
	s_lshr_b32 s19, s18, 31
	s_ashr_i32 s18, s18, 13
	s_add_i32 s18, s18, s19
	s_mul_i32 s19, s18, 0xfffe7e00
	s_add_i32 s81, s80, s19
	s_cmpk_gt_i32 s81, 0x60bf
	s_mov_b64 s[20:21], -1
	s_cbranch_scc0 .LBB0_28
	s_cmpk_gt_u32 s81, 0x80bf
	s_cbranch_scc0 .LBB0_25
	s_cmp_gt_u32 s81, 0x100bf
	s_cbranch_scc0 .LBB0_22
	s_cmp_gt_u32 s81, 0x180bf
	s_cbranch_scc0 .LBB0_19
	s_mov_b64 s[20:21], s[0:1]
	s_add_i32 s19, s81, 0xfffe7f40
	s_load_dwordx2 s[20:21], s[20:21], 0x48
	s_mul_i32 s84, s18, 10
	s_lshr_b32 s83, s19, 5
	s_ashr_i32 s85, s84, 31
	s_add_u32 s84, s83, s84
	s_addc_u32 s85, 0, s85
	s_lshl_b64 s[84:85], s[84:85], 18
	s_waitcnt lgkmcnt(0)
	s_add_u32 s83, s20, s84
	s_addc_u32 s88, s21, s85
	s_mul_i32 s84, s18, 5
	s_lshr_b32 s85, s19, 6
	s_add_i32 s84, s85, s84
	s_mov_b64 s[20:21], s[96:97]
	s_ashr_i32 s85, s84, 31
	s_bfe_u32 s19, s19, 0x10005
	s_lshl_b64 s[84:85], s[84:85], 19
	s_add_u32 s20, s20, s84
	s_addc_u32 s21, s21, s85
	s_lshl_b32 s84, s19, 18
	s_add_u32 s20, s20, s84
	s_addc_u32 s21, s21, 0
	s_lshl_b32 s19, s19, 10
	s_add_u32 s84, s20, s19
	s_addc_u32 s85, s21, 0
	s_and_b32 s19, s3, 0x60
	s_and_b32 s89, s22, 0x1c0
	s_lshl_b32 s20, s19, 2
	v_add_u32_e32 v18, s89, v4
	s_add_u32 s20, s83, s20
	s_addc_u32 s21, s88, 0
	v_ashrrev_i32_e32 v19, 31, v18
	v_lshl_add_u64 v[20:21], s[20:21], 0, v[0:1]
	v_lshlrev_b64 v[18:19], 9, v[18:19]
	v_lshl_add_u64 v[18:19], v[20:21], 0, v[18:19]
	s_movk_i32 s20, 0x1000
	v_add_co_u32_e32 v20, vcc, s20, v18
	s_movk_i32 s20, 0x2000
	s_nop 0
	v_addc_co_u32_e32 v21, vcc, 0, v19, vcc
	v_add_co_u32_e32 v22, vcc, s20, v18
	s_movk_i32 s20, 0x3000
	s_nop 0
	v_addc_co_u32_e32 v23, vcc, 0, v19, vcc
	v_add_co_u32_e32 v24, vcc, s20, v18
	s_movk_i32 s20, 0x4000
	s_nop 0
	v_addc_co_u32_e32 v25, vcc, 0, v19, vcc
	v_add_co_u32_e32 v26, vcc, s20, v18
	s_movk_i32 s20, 0x5000
	s_nop 0
	v_addc_co_u32_e32 v27, vcc, 0, v19, vcc
	global_load_dword v3, v[18:19], off nt
	global_load_dword v28, v[18:19], off offset:1024 nt
	global_load_dword v29, v[18:19], off offset:2048 nt
	global_load_dword v30, v[18:19], off offset:3072 nt
	global_load_dword v31, v[20:21], off offset:1024 nt
	global_load_dword v32, v[20:21], off offset:2048 nt
	global_load_dword v33, v[20:21], off offset:3072 nt
	global_load_dword v34, v[24:25], off offset:1024 nt
	global_load_dword v35, v[24:25], off offset:2048 nt
	s_nop 0
	global_load_dword v24, v[24:25], off offset:3072 nt
	s_nop 0
	global_load_dword v25, v[22:23], off offset:-4096 nt
	global_load_dword v36, v[22:23], off nt
	global_load_dword v37, v[22:23], off offset:1024 nt
	global_load_dword v38, v[22:23], off offset:2048 nt
	global_load_dword v39, v[22:23], off offset:3072 nt
	global_load_dword v40, v[26:27], off offset:-4096 nt
	global_load_dword v41, v[26:27], off nt
	v_add_co_u32_e32 v20, vcc, s20, v18
	s_movk_i32 s20, 0x6000
	s_nop 0
	v_addc_co_u32_e32 v21, vcc, 0, v19, vcc
	v_add_co_u32_e32 v22, vcc, s20, v18
	s_movk_i32 s20, 0x7000
	s_nop 0
	v_addc_co_u32_e32 v23, vcc, 0, v19, vcc
	v_add_co_u32_e32 v18, vcc, s20, v18
	global_load_dword v42, v[26:27], off offset:1024 nt
	global_load_dword v43, v[26:27], off offset:2048 nt
	s_nop 0
	global_load_dword v26, v[26:27], off offset:3072 nt
	s_nop 0
	global_load_dword v27, v[22:23], off offset:-4096 nt
	global_load_dword v44, v[22:23], off nt
	global_load_dword v45, v[22:23], off offset:1024 nt
	global_load_dword v46, v[22:23], off offset:2048 nt
	s_nop 0
	global_load_dword v22, v[22:23], off offset:3072 nt
	v_addc_co_u32_e32 v19, vcc, 0, v19, vcc
	global_load_dword v23, v[20:21], off offset:1024 nt
	global_load_dword v47, v[20:21], off offset:2048 nt
	s_nop 0
	global_load_dword v20, v[20:21], off offset:3072 nt
	s_nop 0
	global_load_dword v21, v[18:19], off nt
	global_load_dword v48, v[18:19], off offset:1024 nt
	global_load_dword v49, v[18:19], off offset:2048 nt
	s_nop 0
	global_load_dword v18, v[18:19], off offset:3072 nt
	s_lshl_b32 s20, s89, 1
	s_add_u32 s20, s84, s20
	s_addc_u32 s21, s85, 0
	v_readlane_b32 s84, v253, 4
	s_waitcnt vmcnt(30)
	ds_write2_b32 v5, v3, v28 offset1:66
	s_waitcnt vmcnt(28)
	ds_write2_b32 v5, v29, v30 offset0:132 offset1:198
	s_waitcnt vmcnt(21)
	ds_write2_b32 v11, v25, v31 offset0:8 offset1:74
	ds_write2_b32 v11, v32, v33 offset0:140 offset1:206
	s_waitcnt vmcnt(19)
	ds_write2_b32 v12, v36, v37 offset0:16 offset1:82
	s_waitcnt vmcnt(17)
	ds_write2_b32 v12, v38, v39 offset0:148 offset1:214
	s_waitcnt vmcnt(16)
	ds_write2_b32 v13, v40, v34 offset0:24 offset1:90
	ds_write2_b32 v13, v35, v24 offset0:156 offset1:222
	s_waitcnt vmcnt(14)
	ds_write2_b32 v14, v41, v42 offset0:32 offset1:98
	s_waitcnt vmcnt(12)
	ds_write2_b32 v14, v43, v26 offset0:164 offset1:230
	s_waitcnt vmcnt(6)
	ds_write2_b32 v15, v27, v23 offset0:40 offset1:106
	s_waitcnt vmcnt(4)
	ds_write2_b32 v15, v47, v20 offset0:172 offset1:238
	ds_write2_b32 v16, v44, v45 offset0:48 offset1:114
	ds_write2_b32 v16, v46, v22 offset0:180 offset1:246
	s_waitcnt vmcnt(2)
	ds_write2_b32 v17, v21, v48 offset0:56 offset1:122
	s_waitcnt vmcnt(0)
	ds_write2_b32 v17, v49, v18 offset0:188 offset1:254
	s_waitcnt lgkmcnt(0)
	ds_read2_b32 v[22:23], v7 offset1:8
	ds_read2_b32 v[26:27], v7 offset0:33 offset1:41
	ds_read2_b32 v[28:29], v7 offset0:66 offset1:74
	v_mov_b32_e32 v3, v1
	ds_read2_b32 v[30:31], v7 offset0:99 offset1:107
	v_lshl_add_u64 v[18:19], s[20:21], 0, v[2:3]
	s_mov_b64 s[20:21], 0x30900000
	s_waitcnt lgkmcnt(3)
	v_lshl_add_u64 v[24:25], v[18:19], 0, s[20:21]
	s_waitcnt lgkmcnt(2)
	ds_read2_b32 v[32:33], v7 offset0:132 offset1:140
	ds_read2_b32 v[34:35], v7 offset0:165 offset1:173
	v_cvt_pk_bf16_f32 v18, v22, v26
	s_waitcnt lgkmcnt(3)
; #define GAS __attribute__((address_space(1)))
; #define LAS __attribute__((address_space(3)))
; #define LDS_WAIT() asm volatile("s_waitcnt lgkmcnt(0)" ::: "memory")
; __device__ __forceinline__ unsigned pk2(float lo, float hi) { return f2bf(lo) | (f2bf(hi) << 16); }
; __device__ __forceinline__ const float* karg(int i) { kseg_t ka = (kseg_t)__builtin_amdgcn_kernarg_segment_ptr(); asm volatile("" : "+s"(ka)); return *(const float* const __attribute__((address_space(4)))*)(ka + 8 * i); }
; __device__ __forceinline__ void p0_transpose_item(const float* W, int K, int N, bf16* WT, int ldt, LAS float* scr, int item, int lane) {
;     ...
;     const int c = lane & 7;
; #pragma unroll
;     for (int j = 0; j < 4; ++j) { const int n = (lane >> 3) + 8 * j; const LAS float* s = scr + (8 * c) * 33 + n;
;         v4u o; o.x = pk2(s[0 * 33], s[1 * 33]); o.y = pk2(s[2 * 33], s[3 * 33]); o.z = pk2(s[4 * 33], s[5 * 33]); o.w = pk2(s[6 * 33], s[7 * 33]);
;         __builtin_nontemporal_store(o, (GAS v4u*)(WT + (size_t)(n0 + n) * ldt + k0 + 8 * c)); }
;     LDS_WAIT(); asm volatile("" ::: "memory");
; }
; __device__ __forceinline__ void p0_prologue(Frame& F) {
;     ...
;         if (r < I_DN) { p0_transpose_item(karg(14) + (size_t)l * DFF * DM, DFF, DM, w_layer(F, l, 3), DFF, scr, r, lane); continue; } r -= I_DN;
	s_waitcnt lgkmcnt(2)
	ds_read2_b32 v[36:37], v7 offset0:198 offset1:206
	ds_read2_b32 v[38:39], v7 offset0:231 offset1:239
	v_cvt_pk_bf16_f32 v19, v28, v30
	s_waitcnt lgkmcnt(3)
	s_waitcnt lgkmcnt(2)
	v_cvt_pk_bf16_f32 v20, v32, v34
	s_waitcnt lgkmcnt(1)
	v_add_u32_e32 v40, s19, v6
	s_waitcnt lgkmcnt(0)
	v_ashrrev_i32_e32 v41, 31, v40
	v_lshlrev_b64 v[40:41], 11, v[40:41]
	v_cvt_pk_bf16_f32 v21, v36, v38
	v_lshl_add_u64 v[40:41], v[24:25], 0, v[40:41]
	global_store_dwordx4 v[40:41], v[18:21], off nt
	s_nop 1
	v_cvt_pk_bf16_f32 v18, v23, v27
	v_cvt_pk_bf16_f32 v19, v29, v31
	v_cvt_pk_bf16_f32 v20, v33, v35
	v_add_u32_e32 v22, s19, v8
	v_ashrrev_i32_e32 v23, 31, v22
	v_lshlrev_b64 v[22:23], 11, v[22:23]
	v_cvt_pk_bf16_f32 v21, v37, v39
	ds_read2_b32 v[26:27], v7 offset0:16 offset1:24
	v_lshl_add_u64 v[22:23], v[24:25], 0, v[22:23]
	global_store_dwordx4 v[22:23], v[18:21], off nt
	ds_read2_b32 v[22:23], v7 offset0:49 offset1:57
	ds_read2_b32 v[28:29], v7 offset0:82 offset1:90
	ds_read2_b32 v[30:31], v7 offset0:115 offset1:123
	s_waitcnt lgkmcnt(3)
	s_waitcnt lgkmcnt(2)
	ds_read2_b32 v[32:33], v7 offset0:148 offset1:156
	ds_read2_b32 v[34:35], v7 offset0:181 offset1:189
	v_cvt_pk_bf16_f32 v18, v26, v22
	s_waitcnt lgkmcnt(3)
	s_waitcnt lgkmcnt(2)
	ds_read2_b32 v[36:37], v7 offset0:214 offset1:222
	ds_read2_b32 v[38:39], v7 offset0:247 offset1:255
	v_cvt_pk_bf16_f32 v19, v28, v30
	s_waitcnt lgkmcnt(3)
	s_waitcnt lgkmcnt(2)
	v_cvt_pk_bf16_f32 v20, v32, v34
	s_waitcnt lgkmcnt(1)
	v_add_u32_e32 v40, s19, v9
	s_waitcnt lgkmcnt(0)
	v_ashrrev_i32_e32 v41, 31, v40
	v_lshlrev_b64 v[40:41], 11, v[40:41]
	v_cvt_pk_bf16_f32 v21, v36, v38
	v_lshl_add_u64 v[40:41], v[24:25], 0, v[40:41]
	global_store_dwordx4 v[40:41], v[18:21], off nt
	s_nop 1
	v_cvt_pk_bf16_f32 v18, v27, v23
	v_cvt_pk_bf16_f32 v19, v29, v31
	v_cvt_pk_bf16_f32 v20, v33, v35
	v_add_u32_e32 v22, s19, v10
	v_ashrrev_i32_e32 v23, 31, v22
	v_lshlrev_b64 v[22:23], 11, v[22:23]
	v_cvt_pk_bf16_f32 v21, v37, v39
	v_lshl_add_u64 v[22:23], v[24:25], 0, v[22:23]
	global_store_dwordx4 v[22:23], v[18:21], off nt
	s_waitcnt lgkmcnt(0)
	s_mov_b64 s[20:21], 0
.LBB0_19:
	s_andn2_b64 vcc, exec, s[20:21]
	s_cbranch_vccnz .LBB0_21
	s_mov_b64 s[20:21], s[0:1]
	s_load_dwordx2 s[20:21], s[20:21], 0x70
	s_ashr_i32 s19, s18, 31
	s_add_i32 s83, s81, 0xfffeff40
	s_lshl_b64 s[84:85], s[18:19], 28
	s_mul_i32 s19, s18, 0x18100000
	s_waitcnt lgkmcnt(0)
	s_add_u32 s84, s20, s84
	s_addc_u32 s85, s21, s85
	s_mov_b64 s[20:21], s[96:97]
	s_mul_hi_i32 s88, s18, 0x18100000
	s_add_u32 s20, s20, s19
	s_addc_u32 s21, s21, s88
	s_lshr_b32 s19, s83, 1
	s_and_b32 s83, s19, 0x7fc0
	s_add_i32 s19, s3, 0xffdfe800
	s_and_b32 s19, s19, 0xfe0
	s_lshl_b32 s88, s19, 2
	v_add_u32_e32 v18, s83, v4
	s_add_u32 s84, s84, s88
	s_addc_u32 s85, s85, 0
	v_ashrrev_i32_e32 v19, 31, v18
	v_lshl_add_u64 v[20:21], s[84:85], 0, v[0:1]
	v_lshlrev_b64 v[18:19], 14, v[18:19]
	v_lshl_add_u64 v[18:19], v[20:21], 0, v[18:19]
	v_add_co_u32_e32 v20, vcc, s26, v18
	s_lshl_b32 s83, s83, 1
	s_nop 0
	v_addc_co_u32_e32 v21, vcc, 0, v19, vcc
	v_add_co_u32_e32 v22, vcc, s27, v18
	s_add_u32 s20, s20, s83
	s_nop 0
	v_addc_co_u32_e32 v23, vcc, 0, v19, vcc
	v_add_co_u32_e32 v24, vcc, s28, v18
	s_addc_u32 s21, s21, 0
	s_nop 0
	v_addc_co_u32_e32 v25, vcc, 0, v19, vcc
	v_add_co_u32_e32 v26, vcc, s29, v18
	v_readlane_b32 s84, v253, 4
	s_nop 0
	v_addc_co_u32_e32 v27, vcc, 0, v19, vcc
	v_add_co_u32_e32 v28, vcc, s30, v18
	s_nop 1
	v_addc_co_u32_e32 v29, vcc, 0, v19, vcc
	v_add_co_u32_e32 v30, vcc, s31, v18
	s_nop 1
	v_addc_co_u32_e32 v31, vcc, 0, v19, vcc
	v_add_co_u32_e32 v32, vcc, s33, v18
	s_nop 1
	v_addc_co_u32_e32 v33, vcc, 0, v19, vcc
	global_load_dword v3, v[18:19], off nt
	global_load_dword v36, v[20:21], off nt
	global_load_dword v37, v[22:23], off nt
	global_load_dword v38, v[24:25], off nt
	global_load_dword v39, v[26:27], off nt
	global_load_dword v40, v[28:29], off nt
	global_load_dword v41, v[30:31], off nt
	global_load_dword v42, v[32:33], off nt
	v_add_co_u32_e32 v20, vcc, s34, v18
	s_nop 1
	v_addc_co_u32_e32 v21, vcc, 0, v19, vcc
	v_add_co_u32_e32 v22, vcc, s35, v18
	s_nop 1
	v_addc_co_u32_e32 v23, vcc, 0, v19, vcc
	v_add_co_u32_e32 v24, vcc, s36, v18
	s_nop 1
	v_addc_co_u32_e32 v25, vcc, 0, v19, vcc
	v_add_co_u32_e32 v26, vcc, s37, v18
	s_nop 1
	v_addc_co_u32_e32 v27, vcc, 0, v19, vcc
	v_add_co_u32_e32 v28, vcc, s38, v18
	s_nop 1
	v_addc_co_u32_e32 v29, vcc, 0, v19, vcc
	v_add_co_u32_e32 v30, vcc, s39, v18
	s_nop 1
	v_addc_co_u32_e32 v31, vcc, 0, v19, vcc
	v_add_co_u32_e32 v32, vcc, s40, v18
	s_nop 1
	v_addc_co_u32_e32 v33, vcc, 0, v19, vcc
	v_add_co_u32_e32 v34, vcc, s41, v18
	s_nop 1
	v_addc_co_u32_e32 v35, vcc, 0, v19, vcc
	global_load_dword v43, v[20:21], off nt
	global_load_dword v44, v[22:23], off nt
	global_load_dword v45, v[24:25], off nt
	global_load_dword v46, v[26:27], off nt
	global_load_dword v47, v[28:29], off nt
	global_load_dword v48, v[30:31], off nt
	global_load_dword v49, v[32:33], off nt
	global_load_dword v50, v[34:35], off nt
	v_add_co_u32_e32 v20, vcc, s42, v18
	s_nop 1
	v_addc_co_u32_e32 v21, vcc, 0, v19, vcc
	v_add_co_u32_e32 v22, vcc, s43, v18
	s_nop 1
	v_addc_co_u32_e32 v23, vcc, 0, v19, vcc
	v_add_co_u32_e32 v24, vcc, s44, v18
	s_nop 1
	v_addc_co_u32_e32 v25, vcc, 0, v19, vcc
	v_add_co_u32_e32 v26, vcc, s45, v18
	s_nop 1
	v_addc_co_u32_e32 v27, vcc, 0, v19, vcc
	v_add_co_u32_e32 v28, vcc, s46, v18
	s_nop 1
	v_addc_co_u32_e32 v29, vcc, 0, v19, vcc
; #define GAS __attribute__((address_space(1)))
; #define LAS __attribute__((address_space(3)))
; #define LDS_WAIT() asm volatile("s_waitcnt lgkmcnt(0)" ::: "memory")
; __device__ __forceinline__ unsigned pk2(float lo, float hi) { return f2bf(lo) | (f2bf(hi) << 16); }
; __device__ __forceinline__ const float* karg(int i) { kseg_t ka = (kseg_t)__builtin_amdgcn_kernarg_segment_ptr(); asm volatile("" : "+s"(ka)); return *(const float* const __attribute__((address_space(4)))*)(ka + 8 * i); }
; __device__ __forceinline__ void p0_transpose_item(const float* W, int K, int N, bf16* WT, int ldt, LAS float* scr, int item, int lane) {
;     const int nblk = N / 32, kb = item / nblk, nb = item % nblk, k0 = 64 * kb, n0 = 32 * nb;
;     float wv[32];
; #pragma unroll
;     for (int i = 0; i < 32; ++i) wv[i] = __builtin_nontemporal_load(W + (size_t)(k0 + 2 * i + (lane >> 5)) * N + n0 + (lane & 31));
; #pragma unroll
;     for (int i = 0; i < 32; ++i) scr[(2 * i + (lane >> 5)) * 33 + (lane & 31)] = wv[i];
;     LDS_WAIT(); asm volatile("" ::: "memory");
;     const int c = lane & 7;
; #pragma unroll
;     for (int j = 0; j < 4; ++j) { const int n = (lane >> 3) + 8 * j; const LAS float* s = scr + (8 * c) * 33 + n;
;         v4u o; o.x = pk2(s[0 * 33], s[1 * 33]); o.y = pk2(s[2 * 33], s[3 * 33]); o.z = pk2(s[4 * 33], s[5 * 33]); o.w = pk2(s[6 * 33], s[7 * 33]);
;         __builtin_nontemporal_store(o, (GAS v4u*)(WT + (size_t)(n0 + n) * ldt + k0 + 8 * c)); }
;     LDS_WAIT(); asm volatile("" ::: "memory");
; }
; __device__ __forceinline__ void p0_prologue(Frame& F) {
;     ...
;         if (r < I_DN) { p0_transpose_item(karg(14) + (size_t)l * DFF * DM, DFF, DM, w_layer(F, l, 3), DFF, scr, r, lane); continue; } r -= I_DN;
	v_add_co_u32_e32 v30, vcc, s47, v18
	s_nop 1
	v_addc_co_u32_e32 v31, vcc, 0, v19, vcc
	v_add_co_u32_e32 v32, vcc, s48, v18
	s_nop 1
	v_addc_co_u32_e32 v33, vcc, 0, v19, vcc
	v_add_co_u32_e32 v34, vcc, s49, v18
	s_nop 1
	v_addc_co_u32_e32 v35, vcc, 0, v19, vcc
	global_load_dword v51, v[20:21], off nt
	global_load_dword v52, v[22:23], off nt
	global_load_dword v53, v[24:25], off nt
	global_load_dword v54, v[26:27], off nt
	global_load_dword v55, v[28:29], off nt
	global_load_dword v56, v[30:31], off nt
	global_load_dword v57, v[32:33], off nt
	s_nop 0
	global_load_dword v34, v[34:35], off nt
	v_add_co_u32_e32 v20, vcc, s50, v18
	s_nop 1
	v_addc_co_u32_e32 v21, vcc, 0, v19, vcc
	v_add_co_u32_e32 v22, vcc, s51, v18
	s_nop 1
	v_addc_co_u32_e32 v23, vcc, 0, v19, vcc
	v_add_co_u32_e32 v24, vcc, s52, v18
	s_nop 1
	v_addc_co_u32_e32 v25, vcc, 0, v19, vcc
	v_add_co_u32_e32 v26, vcc, s53, v18
	s_nop 1
	v_addc_co_u32_e32 v27, vcc, 0, v19, vcc
	v_add_co_u32_e32 v28, vcc, s54, v18
	s_nop 1
	v_addc_co_u32_e32 v29, vcc, 0, v19, vcc
	v_add_co_u32_e32 v30, vcc, s55, v18
	s_nop 1
	v_addc_co_u32_e32 v31, vcc, 0, v19, vcc
	v_add_co_u32_e32 v32, vcc, s56, v18
	s_nop 1
	v_addc_co_u32_e32 v33, vcc, 0, v19, vcc
	v_add_co_u32_e32 v18, vcc, s57, v18
	s_nop 1
	v_addc_co_u32_e32 v19, vcc, 0, v19, vcc
	global_load_dword v20, v[20:21], off nt
	s_nop 0
	global_load_dword v21, v[22:23], off nt
	s_nop 0
	global_load_dword v22, v[24:25], off nt
	global_load_dword v23, v[26:27], off nt
	s_nop 0
	global_load_dword v24, v[28:29], off nt
	global_load_dword v25, v[30:31], off nt
	global_load_dword v26, v[32:33], off nt
	s_nop 0
	global_load_dword v18, v[18:19], off nt
	s_waitcnt vmcnt(30)
	ds_write2_b32 v5, v3, v36 offset1:66
	s_waitcnt vmcnt(28)
	ds_write2_b32 v5, v37, v38 offset0:132 offset1:198
	s_waitcnt vmcnt(26)
	ds_write2_b32 v11, v39, v40 offset0:8 offset1:74
	s_waitcnt vmcnt(24)
	ds_write2_b32 v11, v41, v42 offset0:140 offset1:206
	s_waitcnt vmcnt(22)
	ds_write2_b32 v12, v43, v44 offset0:16 offset1:82
	s_waitcnt vmcnt(20)
	ds_write2_b32 v12, v45, v46 offset0:148 offset1:214
	s_waitcnt vmcnt(18)
	ds_write2_b32 v13, v47, v48 offset0:24 offset1:90
	s_waitcnt vmcnt(16)
	ds_write2_b32 v13, v49, v50 offset0:156 offset1:222
	s_waitcnt vmcnt(14)
	ds_write2_b32 v14, v51, v52 offset0:32 offset1:98
	s_waitcnt vmcnt(12)
	ds_write2_b32 v14, v53, v54 offset0:164 offset1:230
	s_waitcnt vmcnt(10)
	ds_write2_b32 v15, v55, v56 offset0:40 offset1:106
	s_waitcnt vmcnt(8)
	ds_write2_b32 v15, v57, v34 offset0:172 offset1:238
	s_waitcnt vmcnt(6)
	ds_write2_b32 v16, v20, v21 offset0:48 offset1:114
	s_waitcnt vmcnt(4)
	ds_write2_b32 v16, v22, v23 offset0:180 offset1:246
	s_waitcnt vmcnt(2)
	ds_write2_b32 v17, v24, v25 offset0:56 offset1:122
	s_waitcnt vmcnt(0)
	ds_write2_b32 v17, v26, v18 offset0:188 offset1:254
	s_waitcnt lgkmcnt(0)
	ds_read2_b32 v[22:23], v7 offset1:8
	ds_read2_b32 v[26:27], v7 offset0:33 offset1:41
	ds_read2_b32 v[28:29], v7 offset0:66 offset1:74
	v_mov_b32_e32 v3, v1
	ds_read2_b32 v[30:31], v7 offset0:99 offset1:107
	v_lshl_add_u64 v[18:19], s[20:21], 0, v[2:3]
	s_waitcnt lgkmcnt(3)
	v_lshl_add_u64 v[24:25], v[18:19], 0, s[4:5]
	s_waitcnt lgkmcnt(2)
	ds_read2_b32 v[32:33], v7 offset0:132 offset1:140
	ds_read2_b32 v[34:35], v7 offset0:165 offset1:173
	v_cvt_pk_bf16_f32 v18, v22, v26
	s_waitcnt lgkmcnt(3)
	s_waitcnt lgkmcnt(2)
	ds_read2_b32 v[36:37], v7 offset0:198 offset1:206
	ds_read2_b32 v[38:39], v7 offset0:231 offset1:239
	v_cvt_pk_bf16_f32 v19, v28, v30
	s_waitcnt lgkmcnt(3)
	s_waitcnt lgkmcnt(2)
	v_cvt_pk_bf16_f32 v20, v32, v34
	s_waitcnt lgkmcnt(1)
	v_add_u32_e32 v40, s19, v6
	s_waitcnt lgkmcnt(0)
	v_ashrrev_i32_e32 v41, 31, v40
	v_lshlrev_b64 v[40:41], 15, v[40:41]
	v_cvt_pk_bf16_f32 v21, v36, v38
	v_lshl_add_u64 v[40:41], v[24:25], 0, v[40:41]
	global_store_dwordx4 v[40:41], v[18:21], off nt
	s_nop 1
	v_cvt_pk_bf16_f32 v18, v23, v27
	v_cvt_pk_bf16_f32 v19, v29, v31
	v_cvt_pk_bf16_f32 v20, v33, v35
	v_add_u32_e32 v22, s19, v8
	v_ashrrev_i32_e32 v23, 31, v22
	v_lshlrev_b64 v[22:23], 15, v[22:23]
	v_cvt_pk_bf16_f32 v21, v37, v39
	ds_read2_b32 v[26:27], v7 offset0:16 offset1:24
	v_lshl_add_u64 v[22:23], v[24:25], 0, v[22:23]
	global_store_dwordx4 v[22:23], v[18:21], off nt
	ds_read2_b32 v[22:23], v7 offset0:49 offset1:57
	ds_read2_b32 v[28:29], v7 offset0:82 offset1:90
	ds_read2_b32 v[30:31], v7 offset0:115 offset1:123
	s_waitcnt lgkmcnt(3)
	s_waitcnt lgkmcnt(2)
	ds_read2_b32 v[32:33], v7 offset0:148 offset1:156
	ds_read2_b32 v[34:35], v7 offset0:181 offset1:189
	v_cvt_pk_bf16_f32 v18, v26, v22
	s_waitcnt lgkmcnt(3)
	s_waitcnt lgkmcnt(2)
	ds_read2_b32 v[36:37], v7 offset0:214 offset1:222
	ds_read2_b32 v[38:39], v7 offset0:247 offset1:255
	v_cvt_pk_bf16_f32 v19, v28, v30
	s_waitcnt lgkmcnt(3)
	s_waitcnt lgkmcnt(2)
	v_cvt_pk_bf16_f32 v20, v32, v34
	s_waitcnt lgkmcnt(1)
	v_add_u32_e32 v40, s19, v9
	s_waitcnt lgkmcnt(0)
	v_ashrrev_i32_e32 v41, 31, v40
	v_lshlrev_b64 v[40:41], 15, v[40:41]
	v_cvt_pk_bf16_f32 v21, v36, v38
	v_lshl_add_u64 v[40:41], v[24:25], 0, v[40:41]
	global_store_dwordx4 v[40:41], v[18:21], off nt
	s_nop 1
	v_cvt_pk_bf16_f32 v18, v27, v23
	v_cvt_pk_bf16_f32 v19, v29, v31
	v_cvt_pk_bf16_f32 v20, v33, v35
	v_add_u32_e32 v22, s19, v10
	v_ashrrev_i32_e32 v23, 31, v22
	v_lshlrev_b64 v[22:23], 15, v[22:23]
	v_cvt_pk_bf16_f32 v21, v37, v39
	v_lshl_add_u64 v[22:23], v[24:25], 0, v[22:23]
	global_store_dwordx4 v[22:23], v[18:21], off nt
	s_waitcnt lgkmcnt(0)

; #define LAS __attribute__((address_space(3)))
; __device__ __forceinline__ const float* karg(int i) { kseg_t ka = (kseg_t)__builtin_amdgcn_kernarg_segment_ptr(); asm volatile("" : "+s"(ka)); return *(const float* const __attribute__((address_space(4)))*)(ka + 8 * i); }
; __device__ __forceinline__ void p0_transpose_item(const float* W, int K, int N, bf16* WT, int ldt, LAS float* scr, int item, int lane) {
;     const int nblk = N / 32, kb = item / nblk, nb = item % nblk, k0 = 64 * kb, n0 = 32 * nb;
;     float wv[32];
; #pragma unroll
;     for (int i = 0; i < 32; ++i) wv[i] = __builtin_nontemporal_load(W + (size_t)(k0 + 2 * i + (lane >> 5)) * N + n0 + (lane & 31));
; #pragma unroll
; __device__ __forceinline__ void p0_prologue(Frame& F) {
;     ...
;         if (r < I_UP) { p0_transpose_item(karg(13) + (size_t)l * DM * DFF, DM, DFF, w_layer(F, l, 2), DM, scr, r, lane); continue; } r -= I_UP;
.LBB0_22:
	s_andn2_b64 vcc, exec, s[20:21]
	s_cbranch_vccnz .LBB0_24
	s_mov_b64 s[20:21], s[0:1]
	s_load_dwordx2 s[20:21], s[20:21], 0x68
	s_ashr_i32 s19, s18, 31
	s_add_i32 s83, s81, 0xffff7f40
	s_lshl_b64 s[84:85], s[18:19], 28
	s_mul_i32 s19, s18, 0x18100000
	s_waitcnt lgkmcnt(0)
	s_add_u32 s84, s20, s84
	s_addc_u32 s85, s21, s85
	s_mov_b64 s[20:21], s[96:97]
	s_mul_hi_i32 s88, s18, 0x18100000
	s_add_u32 s20, s20, s19
	s_addc_u32 s21, s21, s88
	s_lshr_b32 s19, s83, 3
	s_and_b32 s83, s19, 0x1fc0
	s_add_i32 s19, s3, 0xffefe800
	s_and_b32 s19, s19, 0x3fe0
	s_lshl_b32 s88, s19, 2
	v_add_u32_e32 v18, s83, v4
	s_add_u32 s84, s84, s88
	s_addc_u32 s85, s85, 0
	v_ashrrev_i32_e32 v19, 31, v18
	v_lshl_add_u64 v[20:21], s[84:85], 0, v[0:1]
	v_lshlrev_b64 v[18:19], 16, v[18:19]
	v_lshl_add_u64 v[18:19], v[20:21], 0, v[18:19]
	v_add_co_u32_e32 v20, vcc, s29, v18
	s_mov_b32 s84, 0x100000
	s_nop 0
	v_addc_co_u32_e32 v21, vcc, 0, v19, vcc
	v_add_co_u32_e32 v22, vcc, s34, v18
	s_lshl_b32 s83, s83, 1
	s_nop 0
	v_addc_co_u32_e32 v23, vcc, 0, v19, vcc
	v_add_co_u32_e32 v24, vcc, s38, v18
	s_add_u32 s20, s20, s83
	s_nop 0
	v_addc_co_u32_e32 v25, vcc, 0, v19, vcc
	v_add_co_u32_e32 v26, vcc, s42, v18
	s_addc_u32 s21, s21, 0
	s_nop 0
	v_addc_co_u32_e32 v27, vcc, 0, v19, vcc
	v_add_co_u32_e32 v28, vcc, s46, v18
	s_nop 1
	v_addc_co_u32_e32 v29, vcc, 0, v19, vcc
	v_add_co_u32_e32 v30, vcc, s50, v18
	s_nop 1
	v_addc_co_u32_e32 v31, vcc, 0, v19, vcc
	v_add_co_u32_e32 v32, vcc, s54, v18
	s_nop 1
	v_addc_co_u32_e32 v33, vcc, 0, v19, vcc
	global_load_dword v3, v[18:19], off nt
	global_load_dword v36, v[20:21], off nt
	global_load_dword v37, v[22:23], off nt
	global_load_dword v38, v[24:25], off nt
	global_load_dword v39, v[26:27], off nt
	global_load_dword v40, v[28:29], off nt
	global_load_dword v41, v[30:31], off nt
	global_load_dword v42, v[32:33], off nt
	v_add_co_u32_e32 v20, vcc, s84, v18
	s_mov_b32 s84, 0x120000
	s_nop 0
	v_addc_co_u32_e32 v21, vcc, 0, v19, vcc
	v_add_co_u32_e32 v22, vcc, s84, v18
	s_mov_b32 s84, 0x140000
	s_nop 0
	v_addc_co_u32_e32 v23, vcc, 0, v19, vcc
	v_add_co_u32_e32 v24, vcc, s84, v18
	v_readlane_b32 s84, v253, 4
	s_nop 0
	v_addc_co_u32_e32 v25, vcc, 0, v19, vcc
	v_add_co_u32_e32 v26, vcc, s58, v18
	s_nop 1
	v_addc_co_u32_e32 v27, vcc, 0, v19, vcc
	v_add_co_u32_e32 v28, vcc, s59, v18
	s_nop 1
	v_addc_co_u32_e32 v29, vcc, 0, v19, vcc
	v_add_co_u32_e32 v30, vcc, s60, v18
	s_nop 1
	v_addc_co_u32_e32 v31, vcc, 0, v19, vcc
	v_add_co_u32_e32 v32, vcc, s61, v18
	s_nop 1
	v_addc_co_u32_e32 v33, vcc, 0, v19, vcc
	v_add_co_u32_e32 v34, vcc, s62, v18
	s_nop 1
	v_addc_co_u32_e32 v35, vcc, 0, v19, vcc
	global_load_dword v43, v[20:21], off nt
	global_load_dword v44, v[22:23], off nt
	global_load_dword v45, v[24:25], off nt
	global_load_dword v46, v[26:27], off nt
	global_load_dword v47, v[28:29], off nt
	global_load_dword v48, v[30:31], off nt
	global_load_dword v49, v[32:33], off nt
	global_load_dword v50, v[34:35], off nt
	v_add_co_u32_e32 v20, vcc, s63, v18
	s_nop 1
	v_addc_co_u32_e32 v21, vcc, 0, v19, vcc
	v_add_co_u32_e32 v22, vcc, s64, v18
	s_nop 1
	v_addc_co_u32_e32 v23, vcc, 0, v19, vcc
	v_add_co_u32_e32 v24, vcc, s65, v18
	s_nop 1
	v_addc_co_u32_e32 v25, vcc, 0, v19, vcc
	v_add_co_u32_e32 v26, vcc, s66, v18
	s_nop 1
	v_addc_co_u32_e32 v27, vcc, 0, v19, vcc
	v_add_co_u32_e32 v28, vcc, s67, v18
	s_nop 1
	v_addc_co_u32_e32 v29, vcc, 0, v19, vcc
	v_add_co_u32_e32 v30, vcc, s68, v18
	s_nop 1
	v_addc_co_u32_e32 v31, vcc, 0, v19, vcc
	v_add_co_u32_e32 v32, vcc, s69, v18
	s_nop 1
	v_addc_co_u32_e32 v33, vcc, 0, v19, vcc
	v_add_co_u32_e32 v34, vcc, s70, v18
	s_nop 1
	v_addc_co_u32_e32 v35, vcc, 0, v19, vcc
	global_load_dword v51, v[20:21], off nt
	global_load_dword v52, v[22:23], off nt
	global_load_dword v53, v[24:25], off nt
	global_load_dword v54, v[26:27], off nt
	global_load_dword v55, v[28:29], off nt
	global_load_dword v56, v[30:31], off nt
	global_load_dword v57, v[32:33], off nt
	s_nop 0
	global_load_dword v34, v[34:35], off nt
	v_add_co_u32_e32 v20, vcc, s71, v18
	s_nop 1
	v_addc_co_u32_e32 v21, vcc, 0, v19, vcc
	v_add_co_u32_e32 v22, vcc, s72, v18
	s_nop 1
	v_addc_co_u32_e32 v23, vcc, 0, v19, vcc
	v_add_co_u32_e32 v24, vcc, s73, v18
	s_nop 1
	v_addc_co_u32_e32 v25, vcc, 0, v19, vcc
	v_add_co_u32_e32 v26, vcc, s74, v18
	s_nop 1
	v_addc_co_u32_e32 v27, vcc, 0, v19, vcc
	v_add_co_u32_e32 v28, vcc, s75, v18
	s_nop 1
	v_addc_co_u32_e32 v29, vcc, 0, v19, vcc
	v_add_co_u32_e32 v30, vcc, s76, v18
	s_nop 1
	v_addc_co_u32_e32 v31, vcc, 0, v19, vcc
	v_add_co_u32_e32 v32, vcc, s77, v18
	s_nop 1
	v_addc_co_u32_e32 v33, vcc, 0, v19, vcc
	v_add_co_u32_e32 v18, vcc, s78, v18
	s_nop 1
	v_addc_co_u32_e32 v19, vcc, 0, v19, vcc
	global_load_dword v20, v[20:21], off nt
	s_nop 0
	global_load_dword v21, v[22:23], off nt
	s_nop 0
	global_load_dword v22, v[24:25], off nt
	global_load_dword v23, v[26:27], off nt
	s_nop 0
	global_load_dword v24, v[28:29], off nt
	global_load_dword v25, v[30:31], off nt
	global_load_dword v26, v[32:33], off nt
	s_nop 0
	global_load_dword v18, v[18:19], off nt
	s_waitcnt vmcnt(30)
; #define GAS __attribute__((address_space(1)))
; #define LAS __attribute__((address_space(3)))
; #define LDS_WAIT() asm volatile("s_waitcnt lgkmcnt(0)" ::: "memory")
; __device__ __forceinline__ unsigned pk2(float lo, float hi) { return f2bf(lo) | (f2bf(hi) << 16); }
; __device__ __forceinline__ const float* karg(int i) { kseg_t ka = (kseg_t)__builtin_amdgcn_kernarg_segment_ptr(); asm volatile("" : "+s"(ka)); return *(const float* const __attribute__((address_space(4)))*)(ka + 8 * i); }
; __device__ __forceinline__ void p0_transpose_item(const float* W, int K, int N, bf16* WT, int ldt, LAS float* scr, int item, int lane) {
;     ...
; #pragma unroll
;     for (int i = 0; i < 32; ++i) scr[(2 * i + (lane >> 5)) * 33 + (lane & 31)] = wv[i];
;     LDS_WAIT(); asm volatile("" ::: "memory");
;     const int c = lane & 7;
; #pragma unroll
;     for (int j = 0; j < 4; ++j) { const int n = (lane >> 3) + 8 * j; const LAS float* s = scr + (8 * c) * 33 + n;
;         v4u o; o.x = pk2(s[0 * 33], s[1 * 33]); o.y = pk2(s[2 * 33], s[3 * 33]); o.z = pk2(s[4 * 33], s[5 * 33]); o.w = pk2(s[6 * 33], s[7 * 33]);
;         __builtin_nontemporal_store(o, (GAS v4u*)(WT + (size_t)(n0 + n) * ldt + k0 + 8 * c)); }
;     LDS_WAIT(); asm volatile("" ::: "memory");
; }
; __device__ __forceinline__ void p0_prologue(Frame& F) {
;     ...
;         if (r < I_UP) { p0_transpose_item(karg(13) + (size_t)l * DM * DFF, DM, DFF, w_layer(F, l, 2), DM, scr, r, lane); continue; } r -= I_UP;
	ds_write2_b32 v5, v3, v36 offset1:66
	s_waitcnt vmcnt(28)
	ds_write2_b32 v5, v37, v38 offset0:132 offset1:198
	s_waitcnt vmcnt(26)
	ds_write2_b32 v11, v39, v40 offset0:8 offset1:74
	s_waitcnt vmcnt(24)
	ds_write2_b32 v11, v41, v42 offset0:140 offset1:206
	s_waitcnt vmcnt(22)
	ds_write2_b32 v12, v43, v44 offset0:16 offset1:82
	s_waitcnt vmcnt(20)
	ds_write2_b32 v12, v45, v46 offset0:148 offset1:214
	s_waitcnt vmcnt(18)
	ds_write2_b32 v13, v47, v48 offset0:24 offset1:90
	s_waitcnt vmcnt(16)
	ds_write2_b32 v13, v49, v50 offset0:156 offset1:222
	s_waitcnt vmcnt(14)
	ds_write2_b32 v14, v51, v52 offset0:32 offset1:98
	s_waitcnt vmcnt(12)
	ds_write2_b32 v14, v53, v54 offset0:164 offset1:230
	s_waitcnt vmcnt(10)
	ds_write2_b32 v15, v55, v56 offset0:40 offset1:106
	s_waitcnt vmcnt(8)
	ds_write2_b32 v15, v57, v34 offset0:172 offset1:238
	s_waitcnt vmcnt(6)
	ds_write2_b32 v16, v20, v21 offset0:48 offset1:114
	s_waitcnt vmcnt(4)
	ds_write2_b32 v16, v22, v23 offset0:180 offset1:246
	s_waitcnt vmcnt(2)
	ds_write2_b32 v17, v24, v25 offset0:56 offset1:122
	s_waitcnt vmcnt(0)
	ds_write2_b32 v17, v26, v18 offset0:188 offset1:254
	s_waitcnt lgkmcnt(0)
	ds_read2_b32 v[22:23], v7 offset1:8
	ds_read2_b32 v[26:27], v7 offset0:33 offset1:41
	ds_read2_b32 v[28:29], v7 offset0:66 offset1:74
	v_mov_b32_e32 v3, v1
	ds_read2_b32 v[30:31], v7 offset0:99 offset1:107
	v_lshl_add_u64 v[18:19], s[20:21], 0, v[2:3]
	s_waitcnt lgkmcnt(3)
	v_lshl_add_u64 v[24:25], v[18:19], 0, s[12:13]
	s_waitcnt lgkmcnt(2)
	ds_read2_b32 v[32:33], v7 offset0:132 offset1:140
	ds_read2_b32 v[34:35], v7 offset0:165 offset1:173
	v_cvt_pk_bf16_f32 v18, v22, v26
	s_waitcnt lgkmcnt(3)
	s_waitcnt lgkmcnt(2)
	ds_read2_b32 v[36:37], v7 offset0:198 offset1:206
	ds_read2_b32 v[38:39], v7 offset0:231 offset1:239
	v_cvt_pk_bf16_f32 v19, v28, v30
	s_waitcnt lgkmcnt(3)
	s_waitcnt lgkmcnt(2)
	v_cvt_pk_bf16_f32 v20, v32, v34
	s_waitcnt lgkmcnt(1)
	v_add_u32_e32 v40, s19, v6
	s_waitcnt lgkmcnt(0)
	v_ashrrev_i32_e32 v41, 31, v40
	v_lshlrev_b64 v[40:41], 13, v[40:41]
	v_cvt_pk_bf16_f32 v21, v36, v38
	v_lshl_add_u64 v[40:41], v[24:25], 0, v[40:41]
	global_store_dwordx4 v[40:41], v[18:21], off nt
	s_nop 1
	v_cvt_pk_bf16_f32 v18, v23, v27
	v_cvt_pk_bf16_f32 v19, v29, v31
	v_cvt_pk_bf16_f32 v20, v33, v35
	v_add_u32_e32 v22, s19, v8
	v_ashrrev_i32_e32 v23, 31, v22
	v_lshlrev_b64 v[22:23], 13, v[22:23]
	v_cvt_pk_bf16_f32 v21, v37, v39
	ds_read2_b32 v[26:27], v7 offset0:16 offset1:24
	v_lshl_add_u64 v[22:23], v[24:25], 0, v[22:23]
	global_store_dwordx4 v[22:23], v[18:21], off nt
	ds_read2_b32 v[22:23], v7 offset0:49 offset1:57
	ds_read2_b32 v[28:29], v7 offset0:82 offset1:90
	ds_read2_b32 v[30:31], v7 offset0:115 offset1:123
	s_waitcnt lgkmcnt(3)
	s_waitcnt lgkmcnt(2)
	ds_read2_b32 v[32:33], v7 offset0:148 offset1:156
	ds_read2_b32 v[34:35], v7 offset0:181 offset1:189
	v_cvt_pk_bf16_f32 v18, v26, v22
	s_waitcnt lgkmcnt(3)
	s_waitcnt lgkmcnt(2)
	ds_read2_b32 v[36:37], v7 offset0:214 offset1:222
	ds_read2_b32 v[38:39], v7 offset0:247 offset1:255
	v_cvt_pk_bf16_f32 v19, v28, v30
	s_waitcnt lgkmcnt(3)
	s_waitcnt lgkmcnt(2)
	v_cvt_pk_bf16_f32 v20, v32, v34
	s_waitcnt lgkmcnt(1)
	v_add_u32_e32 v40, s19, v9
	s_waitcnt lgkmcnt(0)
	v_ashrrev_i32_e32 v41, 31, v40
	v_lshlrev_b64 v[40:41], 13, v[40:41]
	v_cvt_pk_bf16_f32 v21, v36, v38
	v_lshl_add_u64 v[40:41], v[24:25], 0, v[40:41]
	global_store_dwordx4 v[40:41], v[18:21], off nt
	s_nop 1
	v_cvt_pk_bf16_f32 v18, v27, v23
	v_cvt_pk_bf16_f32 v19, v29, v31
	v_cvt_pk_bf16_f32 v20, v33, v35
	v_add_u32_e32 v22, s19, v10
	v_ashrrev_i32_e32 v23, 31, v22
	v_lshlrev_b64 v[22:23], 13, v[22:23]
	v_cvt_pk_bf16_f32 v21, v37, v39
	v_lshl_add_u64 v[22:23], v[24:25], 0, v[22:23]
	global_store_dwordx4 v[22:23], v[18:21], off nt
	s_waitcnt lgkmcnt(0)

; #define LAS __attribute__((address_space(3)))
; __device__ __forceinline__ const float* karg(int i) { kseg_t ka = (kseg_t)__builtin_amdgcn_kernarg_segment_ptr(); asm volatile("" : "+s"(ka)); return *(const float* const __attribute__((address_space(4)))*)(ka + 8 * i); }
; __device__ __forceinline__ void p0_transpose_item(const float* W, int K, int N, bf16* WT, int ldt, LAS float* scr, int item, int lane) {
;     const int nblk = N / 32, kb = item / nblk, nb = item % nblk, k0 = 64 * kb, n0 = 32 * nb;
;     float wv[32];
; #pragma unroll
;     for (int i = 0; i < 32; ++i) wv[i] = __builtin_nontemporal_load(W + (size_t)(k0 + 2 * i + (lane >> 5)) * N + n0 + (lane & 31));
; #pragma unroll
; __device__ __forceinline__ void p0_prologue(Frame& F) {
;     ...
;         if (r < I_O) { p0_transpose_item(karg(10) + (size_t)l * DM * DM, DM, DM, w_layer(F, l, 1), DM, scr, r, lane); continue; } r -= I_O;
.LBB0_25:
	s_andn2_b64 vcc, exec, s[20:21]
	s_cbranch_vccnz .LBB0_27
	s_mov_b64 s[20:21], s[0:1]
	s_load_dwordx2 s[20:21], s[20:21], 0x50
	s_ashr_i32 s19, s18, 31
	s_add_i32 s83, s81, 0xffff9f40
	s_lshl_b64 s[84:85], s[18:19], 26
	s_mul_i32 s19, s18, 0x18100000
	s_waitcnt lgkmcnt(0)
	s_add_u32 s84, s20, s84
	s_addc_u32 s85, s21, s85
	s_mov_b64 s[20:21], s[96:97]
	s_mul_hi_i32 s88, s18, 0x18100000
	s_add_u32 s20, s20, s19
	s_addc_u32 s21, s21, s88
	s_lshr_b32 s19, s83, 1
	s_and_b32 s83, s19, 0x7fc0
	s_add_i32 s19, s3, 0xfff3e800
	s_and_b32 s19, s19, 0xfe0
	s_lshl_b32 s88, s19, 2
	v_add_u32_e32 v18, s83, v4
	s_add_u32 s84, s84, s88
	s_addc_u32 s85, s85, 0
	v_ashrrev_i32_e32 v19, 31, v18
	v_lshl_add_u64 v[20:21], s[84:85], 0, v[0:1]
	v_lshlrev_b64 v[18:19], 14, v[18:19]
	v_lshl_add_u64 v[18:19], v[20:21], 0, v[18:19]
	v_add_co_u32_e32 v20, vcc, s26, v18
	s_lshl_b32 s83, s83, 1
	s_nop 0
	v_addc_co_u32_e32 v21, vcc, 0, v19, vcc
	v_add_co_u32_e32 v22, vcc, s27, v18
	s_add_u32 s20, s20, s83
	s_nop 0
	v_addc_co_u32_e32 v23, vcc, 0, v19, vcc
	v_add_co_u32_e32 v24, vcc, s28, v18
	s_addc_u32 s21, s21, 0
	s_nop 0
	v_addc_co_u32_e32 v25, vcc, 0, v19, vcc
	v_add_co_u32_e32 v26, vcc, s29, v18
	v_readlane_b32 s84, v253, 4
	s_nop 0
	v_addc_co_u32_e32 v27, vcc, 0, v19, vcc
	v_add_co_u32_e32 v28, vcc, s30, v18
	s_nop 1
	v_addc_co_u32_e32 v29, vcc, 0, v19, vcc
	v_add_co_u32_e32 v30, vcc, s31, v18
	s_nop 1
	v_addc_co_u32_e32 v31, vcc, 0, v19, vcc
	v_add_co_u32_e32 v32, vcc, s33, v18
	s_nop 1
	v_addc_co_u32_e32 v33, vcc, 0, v19, vcc
	global_load_dword v3, v[18:19], off nt
	global_load_dword v36, v[20:21], off nt
	global_load_dword v37, v[22:23], off nt
	global_load_dword v38, v[24:25], off nt
	global_load_dword v39, v[26:27], off nt
	global_load_dword v40, v[28:29], off nt
	global_load_dword v41, v[30:31], off nt
	global_load_dword v42, v[32:33], off nt
	v_add_co_u32_e32 v20, vcc, s34, v18
	s_nop 1
	v_addc_co_u32_e32 v21, vcc, 0, v19, vcc
	v_add_co_u32_e32 v22, vcc, s35, v18
	s_nop 1
	v_addc_co_u32_e32 v23, vcc, 0, v19, vcc
	v_add_co_u32_e32 v24, vcc, s36, v18
	s_nop 1
	v_addc_co_u32_e32 v25, vcc, 0, v19, vcc
	v_add_co_u32_e32 v26, vcc, s37, v18
	s_nop 1
	v_addc_co_u32_e32 v27, vcc, 0, v19, vcc
	v_add_co_u32_e32 v28, vcc, s38, v18
	s_nop 1
	v_addc_co_u32_e32 v29, vcc, 0, v19, vcc
	v_add_co_u32_e32 v30, vcc, s39, v18
	s_nop 1
	v_addc_co_u32_e32 v31, vcc, 0, v19, vcc
	v_add_co_u32_e32 v32, vcc, s40, v18
	s_nop 1
	v_addc_co_u32_e32 v33, vcc, 0, v19, vcc
	v_add_co_u32_e32 v34, vcc, s41, v18
	s_nop 1
	v_addc_co_u32_e32 v35, vcc, 0, v19, vcc
	global_load_dword v43, v[20:21], off nt
	global_load_dword v44, v[22:23], off nt
	global_load_dword v45, v[24:25], off nt
	global_load_dword v46, v[26:27], off nt
	global_load_dword v47, v[28:29], off nt
	global_load_dword v48, v[30:31], off nt
	global_load_dword v49, v[32:33], off nt
	global_load_dword v50, v[34:35], off nt
	v_add_co_u32_e32 v20, vcc, s42, v18
	s_nop 1
	v_addc_co_u32_e32 v21, vcc, 0, v19, vcc
	v_add_co_u32_e32 v22, vcc, s43, v18
	s_nop 1
	v_addc_co_u32_e32 v23, vcc, 0, v19, vcc
	v_add_co_u32_e32 v24, vcc, s44, v18
	s_nop 1
	v_addc_co_u32_e32 v25, vcc, 0, v19, vcc
	v_add_co_u32_e32 v26, vcc, s45, v18
	s_nop 1
	v_addc_co_u32_e32 v27, vcc, 0, v19, vcc
	v_add_co_u32_e32 v28, vcc, s46, v18
	s_nop 1
	v_addc_co_u32_e32 v29, vcc, 0, v19, vcc
	v_add_co_u32_e32 v30, vcc, s47, v18
	s_nop 1
	v_addc_co_u32_e32 v31, vcc, 0, v19, vcc
	v_add_co_u32_e32 v32, vcc, s48, v18
	s_nop 1
	v_addc_co_u32_e32 v33, vcc, 0, v19, vcc
	v_add_co_u32_e32 v34, vcc, s49, v18
	s_nop 1
	v_addc_co_u32_e32 v35, vcc, 0, v19, vcc
	global_load_dword v51, v[20:21], off nt
	global_load_dword v52, v[22:23], off nt
	global_load_dword v53, v[24:25], off nt
	global_load_dword v54, v[26:27], off nt
	global_load_dword v55, v[28:29], off nt
	global_load_dword v56, v[30:31], off nt
	global_load_dword v57, v[32:33], off nt
	s_nop 0
	global_load_dword v34, v[34:35], off nt
	v_add_co_u32_e32 v20, vcc, s50, v18
	s_nop 1
	v_addc_co_u32_e32 v21, vcc, 0, v19, vcc
	v_add_co_u32_e32 v22, vcc, s51, v18
	s_nop 1
	v_addc_co_u32_e32 v23, vcc, 0, v19, vcc
	v_add_co_u32_e32 v24, vcc, s52, v18
	s_nop 1
	v_addc_co_u32_e32 v25, vcc, 0, v19, vcc
	v_add_co_u32_e32 v26, vcc, s53, v18
	s_nop 1
	v_addc_co_u32_e32 v27, vcc, 0, v19, vcc
	v_add_co_u32_e32 v28, vcc, s54, v18
	s_nop 1
	v_addc_co_u32_e32 v29, vcc, 0, v19, vcc
	v_add_co_u32_e32 v30, vcc, s55, v18
	s_nop 1
	v_addc_co_u32_e32 v31, vcc, 0, v19, vcc
	v_add_co_u32_e32 v32, vcc, s56, v18
	s_nop 1
	v_addc_co_u32_e32 v33, vcc, 0, v19, vcc
	v_add_co_u32_e32 v18, vcc, s57, v18
	s_nop 1
	v_addc_co_u32_e32 v19, vcc, 0, v19, vcc
	global_load_dword v20, v[20:21], off nt
	s_nop 0
	global_load_dword v21, v[22:23], off nt
	s_nop 0
	global_load_dword v22, v[24:25], off nt
	global_load_dword v23, v[26:27], off nt
	s_nop 0
	global_load_dword v24, v[28:29], off nt
	global_load_dword v25, v[30:31], off nt
	global_load_dword v26, v[32:33], off nt
	s_nop 0
	global_load_dword v18, v[18:19], off nt
	s_waitcnt vmcnt(30)
; #define GAS __attribute__((address_space(1)))
; #define LAS __attribute__((address_space(3)))
; #define LDS_WAIT() asm volatile("s_waitcnt lgkmcnt(0)" ::: "memory")
; __device__ __forceinline__ unsigned pk2(float lo, float hi) { return f2bf(lo) | (f2bf(hi) << 16); }
; __device__ __forceinline__ const float* karg(int i) { kseg_t ka = (kseg_t)__builtin_amdgcn_kernarg_segment_ptr(); asm volatile("" : "+s"(ka)); return *(const float* const __attribute__((address_space(4)))*)(ka + 8 * i); }
; __device__ __forceinline__ void p0_transpose_item(const float* W, int K, int N, bf16* WT, int ldt, LAS float* scr, int item, int lane) {
;     ...
; #pragma unroll
;     for (int i = 0; i < 32; ++i) scr[(2 * i + (lane >> 5)) * 33 + (lane & 31)] = wv[i];
;     LDS_WAIT(); asm volatile("" ::: "memory");
;     const int c = lane & 7;
; #pragma unroll
;     for (int j = 0; j < 4; ++j) { const int n = (lane >> 3) + 8 * j; const LAS float* s = scr + (8 * c) * 33 + n;
;         v4u o; o.x = pk2(s[0 * 33], s[1 * 33]); o.y = pk2(s[2 * 33], s[3 * 33]); o.z = pk2(s[4 * 33], s[5 * 33]); o.w = pk2(s[6 * 33], s[7 * 33]);
;         __builtin_nontemporal_store(o, (GAS v4u*)(WT + (size_t)(n0 + n) * ldt + k0 + 8 * c)); }
;     LDS_WAIT(); asm volatile("" ::: "memory");
; }
; __device__ __forceinline__ void p0_prologue(Frame& F) {
;     ...
;         if (r < I_O) { p0_transpose_item(karg(10) + (size_t)l * DM * DM, DM, DM, w_layer(F, l, 1), DM, scr, r, lane); continue; } r -= I_O;
	ds_write2_b32 v5, v3, v36 offset1:66
	s_waitcnt vmcnt(28)
	ds_write2_b32 v5, v37, v38 offset0:132 offset1:198
	s_waitcnt vmcnt(26)
	ds_write2_b32 v11, v39, v40 offset0:8 offset1:74
	s_waitcnt vmcnt(24)
	ds_write2_b32 v11, v41, v42 offset0:140 offset1:206
	s_waitcnt vmcnt(22)
	ds_write2_b32 v12, v43, v44 offset0:16 offset1:82
	s_waitcnt vmcnt(20)
	ds_write2_b32 v12, v45, v46 offset0:148 offset1:214
	s_waitcnt vmcnt(18)
	ds_write2_b32 v13, v47, v48 offset0:24 offset1:90
	s_waitcnt vmcnt(16)
	ds_write2_b32 v13, v49, v50 offset0:156 offset1:222
	s_waitcnt vmcnt(14)
	ds_write2_b32 v14, v51, v52 offset0:32 offset1:98
	s_waitcnt vmcnt(12)
	ds_write2_b32 v14, v53, v54 offset0:164 offset1:230
	s_waitcnt vmcnt(10)
	ds_write2_b32 v15, v55, v56 offset0:40 offset1:106
	s_waitcnt vmcnt(8)
	ds_write2_b32 v15, v57, v34 offset0:172 offset1:238
	s_waitcnt vmcnt(6)
	ds_write2_b32 v16, v20, v21 offset0:48 offset1:114
	s_waitcnt vmcnt(4)
	ds_write2_b32 v16, v22, v23 offset0:180 offset1:246
	s_waitcnt vmcnt(2)
	ds_write2_b32 v17, v24, v25 offset0:56 offset1:122
	s_waitcnt vmcnt(0)
	ds_write2_b32 v17, v26, v18 offset0:188 offset1:254
	s_waitcnt lgkmcnt(0)
	ds_read2_b32 v[22:23], v7 offset1:8
	ds_read2_b32 v[26:27], v7 offset0:33 offset1:41
	ds_read2_b32 v[28:29], v7 offset0:66 offset1:74
	v_mov_b32_e32 v3, v1
	ds_read2_b32 v[30:31], v7 offset0:99 offset1:107
	v_lshl_add_u64 v[18:19], s[20:21], 0, v[2:3]
	s_waitcnt lgkmcnt(3)
	v_lshl_add_u64 v[24:25], v[18:19], 0, s[14:15]
	s_waitcnt lgkmcnt(2)
	ds_read2_b32 v[32:33], v7 offset0:132 offset1:140
	ds_read2_b32 v[34:35], v7 offset0:165 offset1:173
	v_cvt_pk_bf16_f32 v18, v22, v26
	s_waitcnt lgkmcnt(3)
	s_waitcnt lgkmcnt(2)
	ds_read2_b32 v[36:37], v7 offset0:198 offset1:206
	ds_read2_b32 v[38:39], v7 offset0:231 offset1:239
	v_cvt_pk_bf16_f32 v19, v28, v30
	s_waitcnt lgkmcnt(3)
	s_waitcnt lgkmcnt(2)
	v_cvt_pk_bf16_f32 v20, v32, v34
	s_waitcnt lgkmcnt(1)
	v_add_u32_e32 v40, s19, v6
	s_waitcnt lgkmcnt(0)
	v_ashrrev_i32_e32 v41, 31, v40
	v_lshlrev_b64 v[40:41], 13, v[40:41]
	v_cvt_pk_bf16_f32 v21, v36, v38
	v_lshl_add_u64 v[40:41], v[24:25], 0, v[40:41]
	global_store_dwordx4 v[40:41], v[18:21], off nt
	s_nop 1
	v_cvt_pk_bf16_f32 v18, v23, v27
	v_cvt_pk_bf16_f32 v19, v29, v31
	v_cvt_pk_bf16_f32 v20, v33, v35
	v_add_u32_e32 v22, s19, v8
	v_ashrrev_i32_e32 v23, 31, v22
	v_lshlrev_b64 v[22:23], 13, v[22:23]
	v_cvt_pk_bf16_f32 v21, v37, v39
	ds_read2_b32 v[26:27], v7 offset0:16 offset1:24
	v_lshl_add_u64 v[22:23], v[24:25], 0, v[22:23]
	global_store_dwordx4 v[22:23], v[18:21], off nt
	ds_read2_b32 v[22:23], v7 offset0:49 offset1:57
	ds_read2_b32 v[28:29], v7 offset0:82 offset1:90
	ds_read2_b32 v[30:31], v7 offset0:115 offset1:123
	s_waitcnt lgkmcnt(3)
	s_waitcnt lgkmcnt(2)
	ds_read2_b32 v[32:33], v7 offset0:148 offset1:156
	ds_read2_b32 v[34:35], v7 offset0:181 offset1:189
	v_cvt_pk_bf16_f32 v18, v26, v22
	s_waitcnt lgkmcnt(3)
	s_waitcnt lgkmcnt(2)
	ds_read2_b32 v[36:37], v7 offset0:214 offset1:222
	ds_read2_b32 v[38:39], v7 offset0:247 offset1:255
	v_cvt_pk_bf16_f32 v19, v28, v30
	s_waitcnt lgkmcnt(3)
	s_waitcnt lgkmcnt(2)
	v_cvt_pk_bf16_f32 v20, v32, v34
	s_waitcnt lgkmcnt(1)
	v_add_u32_e32 v40, s19, v9
	s_waitcnt lgkmcnt(0)
	v_ashrrev_i32_e32 v41, 31, v40
	v_lshlrev_b64 v[40:41], 13, v[40:41]
	v_cvt_pk_bf16_f32 v21, v36, v38
	v_lshl_add_u64 v[40:41], v[24:25], 0, v[40:41]
	global_store_dwordx4 v[40:41], v[18:21], off nt
	s_nop 1
	v_cvt_pk_bf16_f32 v18, v27, v23
	v_cvt_pk_bf16_f32 v19, v29, v31
	v_cvt_pk_bf16_f32 v20, v33, v35
	v_add_u32_e32 v22, s19, v10
	v_ashrrev_i32_e32 v23, 31, v22
	v_lshlrev_b64 v[22:23], 13, v[22:23]
	v_cvt_pk_bf16_f32 v21, v37, v39
	v_lshl_add_u64 v[22:23], v[24:25], 0, v[22:23]
	global_store_dwordx4 v[22:23], v[18:21], off nt
	s_waitcnt lgkmcnt(0)

; #define LAS __attribute__((address_space(3)))
; __device__ __forceinline__ const float* karg(int i) { kseg_t ka = (kseg_t)__builtin_amdgcn_kernarg_segment_ptr(); asm volatile("" : "+s"(ka)); return *(const float* const __attribute__((address_space(4)))*)(ka + 8 * i); }
; __device__ __forceinline__ void p0_transpose_item(const float* W, int K, int N, bf16* WT, int ldt, LAS float* scr, int item, int lane) {
;     const int nblk = N / 32, kb = item / nblk, nb = item % nblk, k0 = 64 * kb, n0 = 32 * nb;
;     float wv[32];
; #pragma unroll
;     for (int i = 0; i < 32; ++i) wv[i] = __builtin_nontemporal_load(W + (size_t)(k0 + 2 * i + (lane >> 5)) * N + n0 + (lane & 31));
; #pragma unroll
; __device__ __forceinline__ void p0_prologue(Frame& F) {
;     ...
;         if (r < I_IN) { p0_transpose_item(karg(4) + (size_t)l * DM * DIN, DM, DIN, w_layer(F, l, 0), DM, scr, r, lane); continue; } r -= I_IN;
.LBB0_28:
	s_andn2_b64 vcc, exec, s[20:21]
	s_cbranch_vccnz .LBB0_13
	s_mov_b64 s[20:21], s[0:1]
	s_load_dwordx2 s[20:21], s[20:21], 0x20
	s_mul_i32 s83, s18, 0xc180000
	s_mul_hi_i32 s19, s18, 0xc180000
	s_mul_hi_i32 s84, s18, 0x18100000
	s_mul_i32 s85, s18, 0x18100000
	s_waitcnt lgkmcnt(0)
	s_add_u32 s83, s20, s83
	s_addc_u32 s21, s21, s19
	s_mov_b64 s[18:19], s[96:97]
	s_add_u32 s88, s18, s85
	s_mul_hi_i32 s18, s81, 0x54abfd5b
	s_addc_u32 s89, s19, s84
	s_lshr_b32 s19, s18, 31
	s_ashr_i32 s18, s18, 7
	s_add_i32 s18, s18, s19
	s_mul_i32 s19, s18, 0x183
	s_sub_i32 s19, s81, s19
	s_lshl_b32 s20, s18, 6
	s_lshl_b32 s18, s19, 5
	s_ashr_i32 s19, s18, 31
	s_lshl_b64 s[84:85], s[18:19], 2
	s_add_u32 s84, s83, s84
	v_add_u32_e32 v3, s20, v4
	s_addc_u32 s85, s21, s85
	v_lshl_add_u64 v[18:19], s[84:85], 0, v[0:1]
	v_add_u32_e32 v22, 2, v3
	v_add_u32_e32 v24, 4, v3
	v_add_u32_e32 v26, 6, v3
	v_add_u32_e32 v28, 8, v3
	v_add_u32_e32 v30, 10, v3
	v_add_u32_e32 v32, 12, v3
	v_add_u32_e32 v34, 14, v3
	v_mad_i64_i32 v[20:21], s[84:85], v3, s79, v[18:19]
	v_mad_i64_i32 v[22:23], s[84:85], v22, s79, v[18:19]
	v_mad_i64_i32 v[24:25], s[84:85], v24, s79, v[18:19]
	v_mad_i64_i32 v[26:27], s[84:85], v26, s79, v[18:19]
	v_mad_i64_i32 v[28:29], s[84:85], v28, s79, v[18:19]
	v_mad_i64_i32 v[30:31], s[84:85], v30, s79, v[18:19]
	v_mad_i64_i32 v[32:33], s[84:85], v32, s79, v[18:19]
	v_mad_i64_i32 v[34:35], s[84:85], v34, s79, v[18:19]
	global_load_dword v36, v[20:21], off nt
	global_load_dword v37, v[22:23], off nt
	global_load_dword v38, v[24:25], off nt
	global_load_dword v39, v[26:27], off nt
	global_load_dword v40, v[28:29], off nt
	global_load_dword v41, v[30:31], off nt
	global_load_dword v42, v[32:33], off nt
	global_load_dword v43, v[34:35], off nt
	v_add_u32_e32 v20, 16, v3
	v_add_u32_e32 v22, 18, v3
	v_add_u32_e32 v24, 20, v3
	v_add_u32_e32 v26, 22, v3
	v_add_u32_e32 v28, 24, v3
	v_add_u32_e32 v30, 26, v3
	v_add_u32_e32 v32, 28, v3
	v_add_u32_e32 v34, 30, v3
	v_mad_i64_i32 v[20:21], s[84:85], v20, s79, v[18:19]
	v_mad_i64_i32 v[22:23], s[84:85], v22, s79, v[18:19]
	v_mad_i64_i32 v[24:25], s[84:85], v24, s79, v[18:19]
	v_mad_i64_i32 v[26:27], s[84:85], v26, s79, v[18:19]
	v_mad_i64_i32 v[28:29], s[84:85], v28, s79, v[18:19]
	v_mad_i64_i32 v[30:31], s[84:85], v30, s79, v[18:19]
	v_mad_i64_i32 v[32:33], s[84:85], v32, s79, v[18:19]
	v_mad_i64_i32 v[34:35], s[84:85], v34, s79, v[18:19]
	global_load_dword v44, v[20:21], off nt
	global_load_dword v45, v[22:23], off nt
	global_load_dword v46, v[24:25], off nt
	global_load_dword v47, v[26:27], off nt
	global_load_dword v48, v[28:29], off nt
	global_load_dword v49, v[30:31], off nt
	global_load_dword v50, v[32:33], off nt
	global_load_dword v51, v[34:35], off nt
	v_add_u32_e32 v20, 32, v3
	v_add_u32_e32 v22, 34, v3
	v_add_u32_e32 v24, 36, v3
	v_add_u32_e32 v26, 38, v3
	v_add_u32_e32 v28, 40, v3
	v_add_u32_e32 v30, 42, v3
	v_add_u32_e32 v32, 44, v3
	v_add_u32_e32 v34, 46, v3
	v_mad_i64_i32 v[20:21], s[84:85], v20, s79, v[18:19]
	v_mad_i64_i32 v[22:23], s[84:85], v22, s79, v[18:19]
	v_mad_i64_i32 v[24:25], s[84:85], v24, s79, v[18:19]
	v_mad_i64_i32 v[26:27], s[84:85], v26, s79, v[18:19]
	v_mad_i64_i32 v[28:29], s[84:85], v28, s79, v[18:19]
	v_mad_i64_i32 v[30:31], s[84:85], v30, s79, v[18:19]
	v_mad_i64_i32 v[32:33], s[84:85], v32, s79, v[18:19]
	v_mad_i64_i32 v[34:35], s[84:85], v34, s79, v[18:19]
	global_load_dword v52, v[20:21], off nt
	global_load_dword v53, v[22:23], off nt
	global_load_dword v54, v[24:25], off nt
	global_load_dword v55, v[26:27], off nt
	global_load_dword v56, v[28:29], off nt
	global_load_dword v57, v[30:31], off nt
	global_load_dword v58, v[32:33], off nt
	s_nop 0
	global_load_dword v34, v[34:35], off nt
	v_add_u32_e32 v20, 48, v3
	v_add_u32_e32 v22, 50, v3
	v_add_u32_e32 v24, 52, v3
	v_add_u32_e32 v26, 54, v3
	v_add_u32_e32 v28, 56, v3
	v_add_u32_e32 v30, 58, v3
	v_add_u32_e32 v32, 60, v3
	v_add_u32_e32 v3, 62, v3
	v_mad_i64_i32 v[20:21], s[84:85], v20, s79, v[18:19]
	v_mad_i64_i32 v[22:23], s[84:85], v22, s79, v[18:19]
	v_mad_i64_i32 v[24:25], s[84:85], v24, s79, v[18:19]
	v_mad_i64_i32 v[26:27], s[84:85], v26, s79, v[18:19]
	v_mad_i64_i32 v[28:29], s[84:85], v28, s79, v[18:19]
	v_mad_i64_i32 v[30:31], s[84:85], v30, s79, v[18:19]
	v_mad_i64_i32 v[32:33], s[84:85], v32, s79, v[18:19]
	v_mad_i64_i32 v[18:19], s[84:85], v3, s79, v[18:19]
	global_load_dword v3, v[20:21], off nt
	s_nop 0
	global_load_dword v20, v[22:23], off nt
	global_load_dword v21, v[24:25], off nt
	s_nop 0
	global_load_dword v22, v[26:27], off nt
	global_load_dword v23, v[28:29], off nt
	global_load_dword v24, v[30:31], off nt
	global_load_dword v25, v[32:33], off nt
	s_nop 0
	global_load_dword v18, v[18:19], off nt
	s_waitcnt vmcnt(30)
; #define GAS __attribute__((address_space(1)))
; #define LAS __attribute__((address_space(3)))
; #define LDS_WAIT() asm volatile("s_waitcnt lgkmcnt(0)" ::: "memory")
; __device__ __forceinline__ unsigned pk2(float lo, float hi) { return f2bf(lo) | (f2bf(hi) << 16); }
; __device__ __forceinline__ const float* karg(int i) { kseg_t ka = (kseg_t)__builtin_amdgcn_kernarg_segment_ptr(); asm volatile("" : "+s"(ka)); return *(const float* const __attribute__((address_space(4)))*)(ka + 8 * i); }
; __device__ __forceinline__ void p0_transpose_item(const float* W, int K, int N, bf16* WT, int ldt, LAS float* scr, int item, int lane) {
;     ...
; #pragma unroll
;     for (int i = 0; i < 32; ++i) scr[(2 * i + (lane >> 5)) * 33 + (lane & 31)] = wv[i];
;     LDS_WAIT(); asm volatile("" ::: "memory");
;     const int c = lane & 7;
; #pragma unroll
;     for (int j = 0; j < 4; ++j) { const int n = (lane >> 3) + 8 * j; const LAS float* s = scr + (8 * c) * 33 + n;
;         v4u o; o.x = pk2(s[0 * 33], s[1 * 33]); o.y = pk2(s[2 * 33], s[3 * 33]); o.z = pk2(s[4 * 33], s[5 * 33]); o.w = pk2(s[6 * 33], s[7 * 33]);
;         __builtin_nontemporal_store(o, (GAS v4u*)(WT + (size_t)(n0 + n) * ldt + k0 + 8 * c)); }
;     LDS_WAIT(); asm volatile("" ::: "memory");
; }
; __device__ __forceinline__ void p0_prologue(Frame& F) {
;     ...
;         if (r < I_IN) { p0_transpose_item(karg(4) + (size_t)l * DM * DIN, DM, DIN, w_layer(F, l, 0), DM, scr, r, lane); continue; } r -= I_IN;
	ds_write2_b32 v5, v36, v37 offset1:66
	s_waitcnt vmcnt(28)
	ds_write2_b32 v5, v38, v39 offset0:132 offset1:198
	s_waitcnt vmcnt(26)
	ds_write2_b32 v11, v40, v41 offset0:8 offset1:74
	s_waitcnt vmcnt(24)
	ds_write2_b32 v11, v42, v43 offset0:140 offset1:206
	s_waitcnt vmcnt(22)
	ds_write2_b32 v12, v44, v45 offset0:16 offset1:82
	s_waitcnt vmcnt(20)
	ds_write2_b32 v12, v46, v47 offset0:148 offset1:214
	s_waitcnt vmcnt(18)
	ds_write2_b32 v13, v48, v49 offset0:24 offset1:90
	s_waitcnt vmcnt(16)
	ds_write2_b32 v13, v50, v51 offset0:156 offset1:222
	s_waitcnt vmcnt(14)
	ds_write2_b32 v14, v52, v53 offset0:32 offset1:98
	s_waitcnt vmcnt(12)
	ds_write2_b32 v14, v54, v55 offset0:164 offset1:230
	s_waitcnt vmcnt(10)
	ds_write2_b32 v15, v56, v57 offset0:40 offset1:106
	s_waitcnt vmcnt(8)
	ds_write2_b32 v15, v58, v34 offset0:172 offset1:238
	s_waitcnt vmcnt(6)
	ds_write2_b32 v16, v3, v20 offset0:48 offset1:114
	s_waitcnt vmcnt(4)
	ds_write2_b32 v16, v21, v22 offset0:180 offset1:246
	s_waitcnt vmcnt(2)
	ds_write2_b32 v17, v23, v24 offset0:56 offset1:122
	s_waitcnt vmcnt(0)
	ds_write2_b32 v17, v25, v18 offset0:188 offset1:254
	s_waitcnt lgkmcnt(0)
	ds_read2_b32 v[22:23], v7 offset1:8
	s_ashr_i32 s21, s20, 31
	ds_read2_b32 v[26:27], v7 offset0:33 offset1:41
	s_lshl_b64 s[20:21], s[20:21], 1
	s_add_u32 s20, s88, s20
	ds_read2_b32 v[28:29], v7 offset0:66 offset1:74
	s_addc_u32 s21, s89, s21
	v_mov_b32_e32 v3, v1
	ds_read2_b32 v[30:31], v7 offset0:99 offset1:107
	v_lshl_add_u64 v[18:19], s[20:21], 0, v[2:3]
	s_waitcnt lgkmcnt(3)
	v_lshl_add_u64 v[24:25], v[18:19], 0, s[16:17]
	s_waitcnt lgkmcnt(2)
	ds_read2_b32 v[32:33], v7 offset0:132 offset1:140
	ds_read2_b32 v[34:35], v7 offset0:165 offset1:173
	v_cvt_pk_bf16_f32 v18, v22, v26
	s_waitcnt lgkmcnt(3)
	s_waitcnt lgkmcnt(2)
	ds_read2_b32 v[36:37], v7 offset0:198 offset1:206
	ds_read2_b32 v[38:39], v7 offset0:231 offset1:239
	v_cvt_pk_bf16_f32 v19, v28, v30
	s_waitcnt lgkmcnt(3)
	s_waitcnt lgkmcnt(2)
	v_cvt_pk_bf16_f32 v20, v32, v34
	s_waitcnt lgkmcnt(1)
	v_add_u32_e32 v40, s18, v6
	s_waitcnt lgkmcnt(0)
	v_ashrrev_i32_e32 v41, 31, v40
	v_lshlrev_b64 v[40:41], 13, v[40:41]
	v_cvt_pk_bf16_f32 v21, v36, v38
	v_lshl_add_u64 v[40:41], v[24:25], 0, v[40:41]
	global_store_dwordx4 v[40:41], v[18:21], off nt
	s_nop 1
	v_cvt_pk_bf16_f32 v18, v23, v27
	v_cvt_pk_bf16_f32 v19, v29, v31
	v_cvt_pk_bf16_f32 v20, v33, v35
	v_add_u32_e32 v22, s18, v8
	v_ashrrev_i32_e32 v23, 31, v22
	v_lshlrev_b64 v[22:23], 13, v[22:23]
	v_cvt_pk_bf16_f32 v21, v37, v39
	ds_read2_b32 v[26:27], v7 offset0:16 offset1:24
	v_lshl_add_u64 v[22:23], v[24:25], 0, v[22:23]
	global_store_dwordx4 v[22:23], v[18:21], off nt
	ds_read2_b32 v[22:23], v7 offset0:49 offset1:57
	ds_read2_b32 v[28:29], v7 offset0:82 offset1:90
	ds_read2_b32 v[30:31], v7 offset0:115 offset1:123
	s_waitcnt lgkmcnt(3)
	s_waitcnt lgkmcnt(2)
	ds_read2_b32 v[32:33], v7 offset0:148 offset1:156
	ds_read2_b32 v[34:35], v7 offset0:181 offset1:189
	v_cvt_pk_bf16_f32 v18, v26, v22
	s_waitcnt lgkmcnt(3)
	s_waitcnt lgkmcnt(2)
	ds_read2_b32 v[36:37], v7 offset0:214 offset1:222
	ds_read2_b32 v[38:39], v7 offset0:247 offset1:255
	v_cvt_pk_bf16_f32 v19, v28, v30
	s_waitcnt lgkmcnt(3)
	s_waitcnt lgkmcnt(2)
	v_cvt_pk_bf16_f32 v20, v32, v34
	s_waitcnt lgkmcnt(1)
	v_add_u32_e32 v40, s18, v9
	s_waitcnt lgkmcnt(0)
	v_ashrrev_i32_e32 v41, 31, v40
	v_lshlrev_b64 v[40:41], 13, v[40:41]
	v_cvt_pk_bf16_f32 v21, v36, v38
	v_lshl_add_u64 v[40:41], v[24:25], 0, v[40:41]
	global_store_dwordx4 v[40:41], v[18:21], off nt
	s_nop 1
	v_cvt_pk_bf16_f32 v18, v27, v23
	v_cvt_pk_bf16_f32 v19, v29, v31
	v_cvt_pk_bf16_f32 v20, v33, v35
	v_add_u32_e32 v22, s18, v10
	v_ashrrev_i32_e32 v23, 31, v22
	v_lshlrev_b64 v[22:23], 13, v[22:23]
	v_cvt_pk_bf16_f32 v21, v37, v39
	v_lshl_add_u64 v[22:23], v[24:25], 0, v[22:23]
	global_store_dwordx4 v[22:23], v[18:21], off nt
	s_waitcnt lgkmcnt(0)
	v_readlane_b32 s84, v253, 4
	s_branch .LBB0_13

; #define GAS __attribute__((address_space(1)))
; __device__ __forceinline__ unsigned pk2(float lo, float hi) { return f2bf(lo) | (f2bf(hi) << 16); }
; #define WSL(F) ws_opaque((F).ws)
; __device__ __forceinline__ const float* karg(int i) { kseg_t ka = (kseg_t)__builtin_amdgcn_kernarg_segment_ptr(); asm volatile("" : "+s"(ka)); return *(const float* const __attribute__((address_space(4)))*)(ka + 8 * i); }
; __device__ __forceinline__ void p0_prologue(Frame& F) {
;     ...
;     { const GAS f32x4* src = (const GAS f32x4*)karg(8); GAS v2u* dst = (GAS v2u*)(WSL(F) + WS_WUK); const int n4 = DEPTH * DSA_H * KVL * HD / 4;
;       for (int i = gw * 64 + lane; i < n4; i += NGW * 64) { const f32x4 v = src[i]; v2u o; o.x = pk2(v.x, v.y); o.y = pk2(v.z, v.w); dst[i] = o; } }
.LBB0_35:
	global_load_dwordx4 v[6:9], v[4:5], off
	v_add_u32_e32 v0, s4, v0
	v_cmp_lt_i32_e32 vcc, s11, v0
	v_lshl_add_u64 v[4:5], v[4:5], 0, s[16:17]
	s_or_b64 s[18:19], vcc, s[18:19]
	s_waitcnt vmcnt(0)
	v_bfe_u32 v1, v6, 16, 1
	v_bfe_u32 v10, v7, 16, 1
	v_add3_u32 v1, v6, v1, s3
	v_add3_u32 v6, v7, v10, s3
	v_lshrrev_b32_e32 v1, 16, v1
	v_and_or_b32 v6, v6, s5, v1
	v_cvt_pk_bf16_f32 v7, v8, v9
	global_store_dwordx2 v[2:3], v[6:7], off
	v_lshl_add_u64 v[2:3], v[2:3], 0, s[14:15]
	s_andn2_b64 exec, exec, s[18:19]
	s_cbranch_execnz .LBB0_35

; #define GAS __attribute__((address_space(1)))
; #define WSL(F) ws_opaque((F).ws)
; __device__ __forceinline__ const float* karg(int i) { kseg_t ka = (kseg_t)__builtin_amdgcn_kernarg_segment_ptr(); asm volatile("" : "+s"(ka)); return *(const float* const __attribute__((address_space(4)))*)(ka + 8 * i); }
; template <bool IN_BF16>
; __device__ __forceinline__ void ln_row(int lane, const void* zrow, const float* g, const float* b, float* hrow, bf16* xrow) {
;     ...
;     if (IN_BF16) { const GAS v2u* zr = (const GAS v2u*)zrow + lane;
; #pragma unroll
;         for (int j = 0; j < 16; ++j) { const v2u w = zr[64 * j]; v[j] = (f32x4){bflo(w.x), bfhi(w.x), bflo(w.y), bfhi(w.y)}; s += (v[j].x + v[j].y) + (v[j].z + v[j].w); } }
;     else { const GAS f32x4* zr = (const GAS f32x4*)zrow + lane;
; #pragma unroll
;         for (int j = 0; j < 16; ++j) { v[j] = zr[64 * j]; s += (v[j].x + v[j].y) + (v[j].z + v[j].w); } }
;     const float mean = wave_sum(s) * (1.f / DM); float s2 = 0.f;
; #pragma unroll
;     for (int j = 0; j < 16; ++j) { v[j] = v[j] - mean; s2 += (v[j].x * v[j].x + v[j].y * v[j].y) + (v[j].z * v[j].z + v[j].w * v[j].w); }
; __device__ __forceinline__ void p0_prologue(Frame& F) {
;     ...
;     for (int m = gw; m < M; m += NGW) ln_row<false>(lane, karg(0) + (size_t)m * DM, karg(1), karg(2), nullptr, (bf16*)(WSL(F) + WS_XN) + (size_t)m * DM);
.LBB0_38:
	s_mov_b64 s[4:5], s[0:1]
	s_load_dwordx2 s[20:21], s[4:5], 0x0
	s_mov_b64 s[16:17], s[0:1]
	s_mov_b64 s[34:35], s[0:1]
	s_mov_b64 s[18:19], s[96:97]
	s_waitcnt lgkmcnt(0)
	v_lshl_add_u64 v[52:53], s[20:21], 0, v[74:75]
	s_load_dwordx2 s[4:5], s[16:17], 0x8
	v_add_co_u32_e32 v54, vcc, s23, v52
	s_load_dwordx2 s[16:17], s[34:35], 0x10
	s_nop 0
	v_addc_co_u32_e32 v55, vcc, -1, v53, vcc
	global_load_dwordx4 v[16:19], v[52:53], off offset:-4096
	global_load_dwordx4 v[12:15], v[52:53], off offset:-3072
	global_load_dwordx4 v[8:11], v[52:53], off offset:-2048
	global_load_dwordx4 v[4:7], v[52:53], off offset:-1024
	v_add_co_u32_e32 v56, vcc, s24, v52
	global_load_dwordx4 v[0:3], v[52:53], off
	s_nop 0
	v_addc_co_u32_e32 v57, vcc, -1, v53, vcc
	v_add_co_u32_e32 v88, vcc, s11, v52
	s_waitcnt lgkmcnt(0)
	v_lshl_add_u64 v[78:79], s[4:5], 0, v[76:77]
	global_load_dwordx4 v[48:51], v[54:55], off offset:-4096
	global_load_dwordx4 v[44:47], v[54:55], off offset:-3072
	global_load_dwordx4 v[40:43], v[54:55], off offset:-2048
	global_load_dwordx4 v[36:39], v[54:55], off offset:-1024
	global_load_dwordx4 v[32:35], v[54:55], off
	global_load_dwordx4 v[28:31], v[56:57], off offset:-3072
	global_load_dwordx4 v[24:27], v[56:57], off offset:-2048
	global_load_dwordx4 v[20:23], v[56:57], off offset:-1024
	v_addc_co_u32_e32 v89, vcc, -1, v53, vcc
	v_lshl_add_u64 v[84:85], s[16:17], 0, v[76:77]
	global_load_dwordx4 v[52:55], v[78:79], off
	global_load_dwordx4 v[68:71], v[88:89], off offset:-3072
	global_load_dwordx4 v[64:67], v[88:89], off offset:-2048
	global_load_dwordx4 v[60:63], v[88:89], off offset:-1024
	global_load_dwordx4 v[56:59], v[84:85], off
	v_add_co_u32_e32 v86, vcc, s29, v78
	s_add_u32 s18, s18, s3
	s_nop 0
	v_addc_co_u32_e32 v87, vcc, 0, v79, vcc
	v_add_co_u32_e32 v90, vcc, s28, v78
	s_addc_u32 s19, s19, s22
	s_nop 0
	v_addc_co_u32_e32 v91, vcc, 0, v79, vcc
	v_add_co_u32_e32 v88, vcc, s29, v84
	v_lshl_add_u64 v[80:81], v[72:73], 3, s[18:19]
	s_nop 0
	v_addc_co_u32_e32 v89, vcc, 0, v85, vcc
	v_add_co_u32_e32 v92, vcc, s28, v84
	v_add_co_u32_e64 v82, s[4:5], s28, v80
	s_nop 0
	v_addc_co_u32_e32 v93, vcc, 0, v85, vcc
	v_addc_co_u32_e64 v83, s[4:5], 0, v81, s[4:5]
	s_add_i32 s10, s10, s92
	s_add_u32 s3, s3, s12
	s_addc_u32 s22, s22, s13
	v_lshl_add_u64 v[74:75], v[74:75], 0, s[14:15]
	s_cmpk_lt_i32 s10, 0x2000
	s_waitcnt vmcnt(17)
	v_add_f32_e32 v96, v16, v17
	v_add_f32_e32 v97, v18, v19
	s_waitcnt vmcnt(16)
	v_add_f32_e32 v98, v12, v13
	v_add_f32_e32 v99, v14, v15
	s_waitcnt vmcnt(15)
	v_add_f32_e32 v100, v8, v9
	v_add_f32_e32 v101, v10, v11
	s_waitcnt vmcnt(14)
	v_add_f32_e32 v102, v4, v5
	v_add_f32_e32 v103, v6, v7
	s_waitcnt vmcnt(13)
	v_add_f32_e32 v104, v0, v1
	v_add_f32_e32 v105, v2, v3
	s_waitcnt vmcnt(12)
	v_add_f32_e32 v106, v48, v49
	v_add_f32_e32 v107, v50, v51
	s_waitcnt vmcnt(11)
	v_add_f32_e32 v108, v44, v45
	v_add_f32_e32 v109, v46, v47
	v_add_f32_e32 v96, v96, v97
	s_waitcnt vmcnt(10)
	v_add_f32_e32 v97, v40, v41
	v_add_f32_e32 v98, v98, v99
	v_add_f32_e32 v99, v42, v43
	v_add_f32_e32 v100, v100, v101
	s_waitcnt vmcnt(9)
	v_add_f32_e32 v101, v36, v37
	v_add_f32_e32 v102, v102, v103
	v_add_f32_e32 v103, v38, v39
	s_waitcnt vmcnt(8)
	v_add_f32_e32 v110, v32, v33
	v_add_f32_e32 v111, v34, v35
	s_waitcnt vmcnt(7)
	v_add_f32_e32 v112, v28, v29
	v_add_f32_e32 v113, v30, v31
	v_add_f32_e32 v104, v104, v105
	v_add_f32_e32 v105, v106, v107
	v_add_f32_e32 v106, v108, v109
	v_add_f32_e32 v97, v97, v99
	v_add_f32_e32 v99, v101, v103
	v_add_f32_e32 v101, v110, v111
	s_waitcnt vmcnt(3)
	v_add_f32_e32 v109, v68, v69
	v_add_f32_e32 v110, v70, v71
	v_add_f32_e32 v114, v24, v25
	v_add_f32_e32 v115, v26, v27
	v_add_f32_e32 v103, v112, v113
	s_waitcnt vmcnt(2)
	v_add_f32_e32 v111, v64, v65
	v_add_f32_e32 v112, v66, v67
	v_add_f32_e32 v109, v109, v110
	v_add_f32_e32 v107, v114, v115
	s_waitcnt vmcnt(1)
	v_add_f32_e32 v113, v60, v61
	v_add_f32_e32 v114, v62, v63
	v_add_f32_e32 v110, v111, v112
	v_add_f32_e32 v109, 0, v109
	v_add_f32_e32 v111, v113, v114
	v_add_f32_e32 v109, v109, v110
	v_add_f32_e32 v109, v109, v111
	v_add_f32_e32 v105, v109, v105
	v_add_f32_e32 v105, v105, v106
	v_add_f32_e32 v97, v105, v97
	v_add_f32_e32 v97, v97, v99
	v_add_f32_e32 v97, v97, v101
	v_add_f32_e32 v116, v20, v21
	v_add_f32_e32 v117, v22, v23
	v_add_f32_e32 v97, v97, v103
	v_add_f32_e32 v108, v116, v117
	v_add_f32_e32 v97, v97, v107
	v_add_f32_e32 v97, v97, v108
	v_add_f32_e32 v96, v97, v96
	v_add_f32_e32 v96, v96, v98
	v_add_f32_e32 v96, v96, v100
	v_add_f32_e32 v96, v96, v102
	v_add_f32_e32 v96, v96, v104
	s_nop 1
	v_add_f32_dpp v96, v96, v96 quad_perm:[1,0,3,2] row_mask:0xf bank_mask:0xf bound_ctrl:1
	s_nop 1
	v_add_f32_dpp v96, v96, v96 quad_perm:[2,3,0,1] row_mask:0xf bank_mask:0xf bound_ctrl:1
	s_nop 1
	v_add_f32_dpp v96, v96, v96 row_half_mirror row_mask:0xf bank_mask:0xf bound_ctrl:1
	s_nop 1
	v_add_f32_dpp v96, v96, v96 row_mirror row_mask:0xf bank_mask:0xf bound_ctrl:1
	v_mov_b32_e32 v97, v96
	s_nop 1
	v_permlane16_swap_b32_e32 v96, v97
	v_add_f32_e32 v96, v96, v97
	v_mov_b32_e32 v97, v96
	s_nop 1
	v_permlane32_swap_b32_e32 v96, v97
	v_add_f32_e32 v98, v96, v97
	v_fmamk_f32 v71, v98, 0xb9800000, v71
	v_fmac_f32_e32 v69, 0xb9800000, v98
	v_fmamk_f32 v67, v98, 0xb9800000, v67
	v_fmac_f32_e32 v65, 0xb9800000, v98
	v_fmamk_f32 v70, v98, 0xb9800000, v70
	v_fmamk_f32 v68, v98, 0xb9800000, v68
	v_fmamk_f32 v66, v98, 0xb9800000, v66
	v_fmamk_f32 v64, v98, 0xb9800000, v64
	v_fmamk_f32 v62, v98, 0xb9800000, v62
	v_fmamk_f32 v63, v98, 0xb9800000, v63
	v_fmamk_f32 v60, v98, 0xb9800000, v60
	v_fmac_f32_e32 v61, 0xb9800000, v98
	v_fmamk_f32 v50, v98, 0xb9800000, v50
; #define GAS __attribute__((address_space(1)))
; template <bool IN_BF16>
; __device__ __forceinline__ void ln_row(int lane, const void* zrow, const float* g, const float* b, float* hrow, bf16* xrow) {
;     ...
;     for (int j = 0; j < 16; ++j) { v[j] = v[j] - mean; s2 += (v[j].x * v[j].x + v[j].y * v[j].y) + (v[j].z * v[j].z + v[j].w * v[j].w); }
;     const float rstd = 1.f / sqrtf(wave_sum(s2) * (1.f / DM) + LN_EPS);
;     const GAS f32x4* gr = (const GAS f32x4*)g + lane; const GAS f32x4* br = (const GAS f32x4*)b + lane;
; #pragma unroll
;     for (int j = 0; j < 16; ++j) { const f32x4 o = v[j] * rstd * gr[64 * j] + br[64 * j];
	v_fmamk_f32 v51, v98, 0xb9800000, v51
	v_fmamk_f32 v48, v98, 0xb9800000, v48
	v_fmac_f32_e32 v49, 0xb9800000, v98
	v_fmamk_f32 v46, v98, 0xb9800000, v46
	v_fmamk_f32 v47, v98, 0xb9800000, v47
	v_fmamk_f32 v44, v98, 0xb9800000, v44
	v_fmac_f32_e32 v45, 0xb9800000, v98
	v_fmamk_f32 v42, v98, 0xb9800000, v42
	v_fmamk_f32 v43, v98, 0xb9800000, v43
	v_fmamk_f32 v40, v98, 0xb9800000, v40
	v_fmac_f32_e32 v41, 0xb9800000, v98
	v_fmamk_f32 v38, v98, 0xb9800000, v38
	v_fmamk_f32 v39, v98, 0xb9800000, v39
	v_fmamk_f32 v36, v98, 0xb9800000, v36
	v_fmac_f32_e32 v37, 0xb9800000, v98
	v_fmamk_f32 v34, v98, 0xb9800000, v34
	v_fmamk_f32 v35, v98, 0xb9800000, v35
	v_fmamk_f32 v32, v98, 0xb9800000, v32
	v_fmac_f32_e32 v33, 0xb9800000, v98
	v_fmamk_f32 v96, v98, 0xb9800000, v30
	v_fmamk_f32 v97, v98, 0xb9800000, v31
	v_fmamk_f32 v28, v98, 0xb9800000, v28
	v_fmac_f32_e32 v29, 0xb9800000, v98
	v_fmamk_f32 v30, v98, 0xb9800000, v26
	v_fmamk_f32 v31, v98, 0xb9800000, v27
	v_fmamk_f32 v24, v98, 0xb9800000, v24
	v_fmac_f32_e32 v25, 0xb9800000, v98
	v_fmamk_f32 v26, v98, 0xb9800000, v22
	v_fmamk_f32 v27, v98, 0xb9800000, v23
	v_fmamk_f32 v20, v98, 0xb9800000, v20
	v_fmac_f32_e32 v21, 0xb9800000, v98
	v_fmamk_f32 v22, v98, 0xb9800000, v18
	v_fmamk_f32 v23, v98, 0xb9800000, v19
	v_fmamk_f32 v16, v98, 0xb9800000, v16
	v_fmac_f32_e32 v17, 0xb9800000, v98
	v_fmamk_f32 v14, v98, 0xb9800000, v14
	v_fmamk_f32 v15, v98, 0xb9800000, v15
	v_fmamk_f32 v12, v98, 0xb9800000, v12
	v_fmac_f32_e32 v13, 0xb9800000, v98
	v_fmamk_f32 v10, v98, 0xb9800000, v10
	v_fmamk_f32 v11, v98, 0xb9800000, v11
	v_fmamk_f32 v8, v98, 0xb9800000, v8
	v_fmac_f32_e32 v9, 0xb9800000, v98
	v_fmamk_f32 v6, v98, 0xb9800000, v6
	v_fmamk_f32 v7, v98, 0xb9800000, v7
	v_fmamk_f32 v4, v98, 0xb9800000, v4
	v_fmac_f32_e32 v5, 0xb9800000, v98
	v_fmamk_f32 v2, v98, 0xb9800000, v2
	v_fmamk_f32 v3, v98, 0xb9800000, v3
	v_fmamk_f32 v0, v98, 0xb9800000, v0
	v_fmac_f32_e32 v1, 0xb9800000, v98
	v_mul_f32_e32 v18, v69, v69
	v_mul_f32_e32 v19, v71, v71
	v_mul_f32_e32 v98, v65, v65
	v_mul_f32_e32 v99, v67, v67
	v_mul_f32_e32 v100, v61, v61
	v_mul_f32_e32 v101, v63, v63
	v_fmac_f32_e32 v18, v68, v68
	v_fmac_f32_e32 v19, v70, v70
	v_fmac_f32_e32 v98, v64, v64
	v_fmac_f32_e32 v99, v66, v66
	v_mul_f32_e32 v102, v49, v49
	v_mul_f32_e32 v103, v51, v51
	v_fmac_f32_e32 v100, v60, v60
	v_fmac_f32_e32 v101, v62, v62
	v_add_f32_e32 v18, v18, v19
	v_add_f32_e32 v19, v98, v99
	v_mul_f32_e32 v104, v45, v45
	v_mul_f32_e32 v105, v47, v47
	v_fmac_f32_e32 v102, v48, v48
	v_fmac_f32_e32 v103, v50, v50
	v_add_f32_e32 v98, v100, v101
	v_add_f32_e32 v18, v18, v19
	v_mul_f32_e32 v106, v41, v41
	v_mul_f32_e32 v107, v43, v43
	v_fmac_f32_e32 v104, v44, v44
	v_fmac_f32_e32 v105, v46, v46
	v_add_f32_e32 v99, v102, v103
	v_add_f32_e32 v18, v98, v18
	v_mul_f32_e32 v108, v37, v37
	v_mul_f32_e32 v109, v39, v39
	v_fmac_f32_e32 v106, v40, v40
	v_fmac_f32_e32 v107, v42, v42
	v_add_f32_e32 v100, v104, v105
	v_add_f32_e32 v18, v99, v18
	v_mul_f32_e32 v110, v33, v33
	v_mul_f32_e32 v111, v35, v35
	v_fmac_f32_e32 v108, v36, v36
	v_fmac_f32_e32 v109, v38, v38
	v_add_f32_e32 v101, v106, v107
	v_add_f32_e32 v18, v100, v18
	v_mul_f32_e32 v112, v29, v29
	v_mul_f32_e32 v113, v97, v97
	v_fmac_f32_e32 v110, v32, v32
	v_fmac_f32_e32 v111, v34, v34
	v_add_f32_e32 v102, v108, v109
	v_add_f32_e32 v18, v101, v18
	v_mul_f32_e32 v114, v25, v25
	v_mul_f32_e32 v115, v31, v31
	v_fmac_f32_e32 v112, v28, v28
	v_fmac_f32_e32 v113, v96, v96
	v_add_f32_e32 v103, v110, v111
	v_add_f32_e32 v18, v102, v18
	v_mul_f32_e32 v116, v21, v21
	v_mul_f32_e32 v117, v27, v27
	v_fmac_f32_e32 v114, v24, v24
	v_fmac_f32_e32 v115, v30, v30
	v_add_f32_e32 v104, v112, v113
	v_add_f32_e32 v18, v103, v18
	v_mul_f32_e32 v118, v17, v17
	v_mul_f32_e32 v119, v23, v23
	v_fmac_f32_e32 v116, v20, v20
	v_fmac_f32_e32 v117, v26, v26
	v_add_f32_e32 v105, v114, v115
	v_add_f32_e32 v18, v104, v18
	v_mul_f32_e32 v120, v13, v13
	v_mul_f32_e32 v121, v15, v15
	v_fmac_f32_e32 v118, v16, v16
	v_fmac_f32_e32 v119, v22, v22
	v_add_f32_e32 v106, v116, v117
	v_add_f32_e32 v18, v105, v18
	v_mul_f32_e32 v122, v9, v9
	v_mul_f32_e32 v123, v11, v11
	v_fmac_f32_e32 v120, v12, v12
	v_fmac_f32_e32 v121, v14, v14
	v_add_f32_e32 v107, v118, v119
	v_add_f32_e32 v18, v106, v18
	v_mul_f32_e32 v124, v5, v5
	v_mul_f32_e32 v125, v7, v7
	v_fmac_f32_e32 v122, v8, v8
	v_fmac_f32_e32 v123, v10, v10
	v_add_f32_e32 v108, v120, v121
	v_add_f32_e32 v18, v107, v18
	v_mul_f32_e32 v126, v1, v1
	v_mul_f32_e32 v127, v3, v3
	v_fmac_f32_e32 v124, v4, v4
	v_fmac_f32_e32 v125, v6, v6
	v_add_f32_e32 v109, v122, v123
	v_add_f32_e32 v18, v108, v18
	v_fmac_f32_e32 v126, v0, v0
	v_fmac_f32_e32 v127, v2, v2
	v_add_f32_e32 v110, v124, v125
	v_add_f32_e32 v18, v109, v18
	v_add_f32_e32 v111, v126, v127
	v_add_f32_e32 v18, v110, v18
	v_add_f32_e32 v18, v111, v18
	s_nop 1
	v_add_f32_dpp v18, v18, v18 quad_perm:[1,0,3,2] row_mask:0xf bank_mask:0xf bound_ctrl:1
	s_nop 1
	v_add_f32_dpp v18, v18, v18 quad_perm:[2,3,0,1] row_mask:0xf bank_mask:0xf bound_ctrl:1
	s_nop 1
	v_add_f32_dpp v18, v18, v18 row_half_mirror row_mask:0xf bank_mask:0xf bound_ctrl:1
	s_nop 1
	v_add_f32_dpp v18, v18, v18 row_mirror row_mask:0xf bank_mask:0xf bound_ctrl:1
	v_mov_b32_e32 v19, v18
	s_nop 1
	v_permlane16_swap_b32_e32 v18, v19
	v_add_f32_e32 v18, v18, v19
	v_mov_b32_e32 v19, v18
	s_nop 1
	v_permlane32_swap_b32_e32 v18, v19
	v_add_f32_e32 v18, v18, v19
	v_fmamk_f32 v18, v18, 0x39800000, v94
	v_mul_f32_e32 v19, 0x4f800000, v18
	v_cmp_gt_f32_e32 vcc, s25, v18
	s_nop 1
	v_cndmask_b32_e32 v18, v18, v19, vcc
	v_sqrt_f32_e32 v19, v18
	s_nop 0
	v_add_u32_e32 v98, -1, v19
	v_add_u32_e32 v99, 1, v19
	v_fma_f32 v100, -v98, v19, v18
	v_fma_f32 v101, -v99, v19, v18
	v_cmp_ge_f32_e64 s[4:5], 0, v100
	s_nop 1
	v_cndmask_b32_e64 v19, v19, v98, s[4:5]
	v_cmp_lt_f32_e64 s[4:5], 0, v101
	s_nop 1
	v_cndmask_b32_e64 v19, v19, v99, s[4:5]
	v_mul_f32_e32 v98, 0x37800000, v19
	v_cndmask_b32_e32 v19, v19, v98, vcc
	v_cmp_class_f32_e32 vcc, v18, v95
	s_nop 1
	v_cndmask_b32_e32 v18, v19, v18, vcc
	v_div_scale_f32 v19, s[4:5], v18, v18, 1.0
	v_rcp_f32_e32 v99, v19
	v_div_scale_f32 v98, vcc, 1.0, v18, 1.0
	v_fma_f32 v100, -v19, v99, 1.0
	v_fmac_f32_e32 v99, v100, v99
	v_mul_f32_e32 v100, v98, v99
	v_fma_f32 v101, -v19, v100, v98
	v_fmac_f32_e32 v100, v101, v99
	v_fma_f32 v19, -v19, v100, v98
	v_div_fmas_f32 v19, v19, v99, v100
	v_div_fixup_f32 v18, v19, v18, 1.0
	v_pk_mul_f32 v[68:69], v[68:69], v[18:19] op_sel_hi:[1,0]
	v_pk_mul_f32 v[70:71], v[70:71], v[18:19] op_sel_hi:[1,0]
	v_pk_mul_f32 v[102:103], v[32:33], v[18:19] op_sel_hi:[1,0]
	v_pk_mul_f32 v[104:105], v[34:35], v[18:19] op_sel_hi:[1,0]
	s_waitcnt vmcnt(0)
; #define GAS __attribute__((address_space(1)))
; __device__ __forceinline__ unsigned pk2(float lo, float hi) { return f2bf(lo) | (f2bf(hi) << 16); }
; template <bool IN_BF16>
; __device__ __forceinline__ void ln_row(int lane, const void* zrow, const float* g, const float* b, float* hrow, bf16* xrow) {
;     ...
;     for (int j = 0; j < 16; ++j) { const f32x4 o = v[j] * rstd * gr[64 * j] + br[64 * j];
;         if (hrow) ((GAS f32x4*)hrow + lane)[64 * j] = o;
;         if (xrow) ((GAS unsigned long long*)xrow + lane)[64 * j] = (unsigned long long)pk2(o.x, o.y) | ((unsigned long long)pk2(o.z, o.w) << 32); }
	v_pk_fma_f32 v[32:33], v[54:55], v[70:71], v[58:59]
	v_pk_fma_f32 v[34:35], v[52:53], v[68:69], v[56:57]
	v_pk_mul_f32 v[64:65], v[64:65], v[18:19] op_sel_hi:[1,0]
	v_pk_mul_f32 v[66:67], v[66:67], v[18:19] op_sel_hi:[1,0]
	v_pk_mul_f32 v[60:61], v[60:61], v[18:19] op_sel_hi:[1,0]
	v_pk_mul_f32 v[62:63], v[62:63], v[18:19] op_sel_hi:[1,0]
	v_pk_mul_f32 v[48:49], v[48:49], v[18:19] op_sel_hi:[1,0]
	v_pk_mul_f32 v[50:51], v[50:51], v[18:19] op_sel_hi:[1,0]
	v_pk_mul_f32 v[44:45], v[44:45], v[18:19] op_sel_hi:[1,0]
	v_pk_mul_f32 v[46:47], v[46:47], v[18:19] op_sel_hi:[1,0]
	v_pk_mul_f32 v[40:41], v[40:41], v[18:19] op_sel_hi:[1,0]
	v_pk_mul_f32 v[42:43], v[42:43], v[18:19] op_sel_hi:[1,0]
	v_pk_mul_f32 v[98:99], v[36:37], v[18:19] op_sel_hi:[1,0]
	v_pk_mul_f32 v[100:101], v[38:39], v[18:19] op_sel_hi:[1,0]
	v_pk_mul_f32 v[28:29], v[28:29], v[18:19] op_sel_hi:[1,0]
	v_pk_mul_f32 v[96:97], v[96:97], v[18:19] op_sel_hi:[1,0]
	v_bfe_u32 v19, v34, 16, 1
	v_bfe_u32 v37, v32, 16, 1
	v_bfe_u32 v36, v35, 16, 1
	v_bfe_u32 v38, v33, 16, 1
	v_add3_u32 v19, v34, v19, s26
	v_add3_u32 v32, v32, v37, s26
	v_add3_u32 v34, v35, v36, s26
	v_add3_u32 v33, v33, v38, s26
	v_lshrrev_b32_e32 v19, 16, v19
	v_lshrrev_b32_e32 v35, 16, v32
	v_and_or_b32 v32, v34, s27, v19
	v_and_or_b32 v33, v33, s27, v35
	global_store_dwordx2 v[80:81], v[32:33], off
	global_load_dwordx4 v[32:35], v[78:79], off offset:1024
	s_nop 0
	global_load_dwordx4 v[36:39], v[84:85], off offset:1024
	s_waitcnt vmcnt(0)
	v_pk_fma_f32 v[34:35], v[34:35], v[66:67], v[38:39]
	v_pk_fma_f32 v[32:33], v[32:33], v[64:65], v[36:37]
	v_bfe_u32 v19, v32, 16, 1
	v_bfe_u32 v36, v33, 16, 1
	v_add3_u32 v19, v32, v19, s26
	v_add3_u32 v32, v33, v36, s26
	v_lshrrev_b32_e32 v19, 16, v19
	v_and_or_b32 v32, v32, s27, v19
	v_cvt_pk_bf16_f32 v33, v34, v35
	global_store_dwordx2 v[80:81], v[32:33], off offset:512
	global_load_dwordx4 v[32:35], v[78:79], off offset:2048
	s_nop 0
	global_load_dwordx4 v[36:39], v[84:85], off offset:2048
	s_waitcnt vmcnt(0)
	v_pk_fma_f32 v[34:35], v[34:35], v[62:63], v[38:39]
	v_pk_fma_f32 v[32:33], v[32:33], v[60:61], v[36:37]
	v_bfe_u32 v19, v32, 16, 1
	v_bfe_u32 v36, v33, 16, 1
	v_add3_u32 v19, v32, v19, s26
	v_add3_u32 v32, v33, v36, s26
	v_lshrrev_b32_e32 v19, 16, v19
	v_and_or_b32 v32, v32, s27, v19
	v_cvt_pk_bf16_f32 v33, v34, v35
	global_store_dwordx2 v[80:81], v[32:33], off offset:1024
	global_load_dwordx4 v[32:35], v[78:79], off offset:3072
	s_nop 0
	global_load_dwordx4 v[36:39], v[84:85], off offset:3072
	s_waitcnt vmcnt(0)
	v_pk_fma_f32 v[34:35], v[50:51], v[34:35], v[38:39]
	v_pk_fma_f32 v[32:33], v[48:49], v[32:33], v[36:37]
	v_bfe_u32 v19, v32, 16, 1
	v_bfe_u32 v36, v33, 16, 1
	v_add3_u32 v19, v32, v19, s26
	v_add3_u32 v32, v33, v36, s26
	v_lshrrev_b32_e32 v19, 16, v19
	v_and_or_b32 v32, v32, s27, v19
	v_cvt_pk_bf16_f32 v33, v34, v35
	global_store_dwordx2 v[80:81], v[32:33], off offset:1536
	global_load_dwordx4 v[32:35], v[86:87], off offset:-4096
	s_nop 0
	global_load_dwordx4 v[36:39], v[88:89], off offset:-4096
	s_waitcnt vmcnt(0)
	v_pk_fma_f32 v[34:35], v[46:47], v[34:35], v[38:39]
	v_pk_fma_f32 v[32:33], v[44:45], v[32:33], v[36:37]
	v_bfe_u32 v19, v32, 16, 1
	v_bfe_u32 v36, v33, 16, 1
	v_add3_u32 v19, v32, v19, s26
	v_add3_u32 v32, v33, v36, s26
	v_lshrrev_b32_e32 v19, 16, v19
	v_and_or_b32 v32, v32, s27, v19
	v_cvt_pk_bf16_f32 v33, v34, v35
	global_store_dwordx2 v[80:81], v[32:33], off offset:2048
	global_load_dwordx4 v[32:35], v[90:91], off offset:1024
	s_nop 0
	global_load_dwordx4 v[36:39], v[92:93], off offset:1024
	s_waitcnt vmcnt(0)
	v_pk_fma_f32 v[34:35], v[42:43], v[34:35], v[38:39]
	v_pk_fma_f32 v[32:33], v[40:41], v[32:33], v[36:37]
	v_bfe_u32 v19, v32, 16, 1
	v_bfe_u32 v36, v33, 16, 1
	v_add3_u32 v19, v32, v19, s26
	v_add3_u32 v32, v33, v36, s26
	v_lshrrev_b32_e32 v19, 16, v19
	v_and_or_b32 v32, v32, s27, v19
	v_cvt_pk_bf16_f32 v33, v34, v35
	global_store_dwordx2 v[80:81], v[32:33], off offset:2560
	global_load_dwordx4 v[32:35], v[90:91], off offset:2048
	s_nop 0
	global_load_dwordx4 v[36:39], v[92:93], off offset:2048
	s_waitcnt vmcnt(0)
	v_pk_fma_f32 v[34:35], v[100:101], v[34:35], v[38:39]
	v_pk_fma_f32 v[32:33], v[98:99], v[32:33], v[36:37]
	v_bfe_u32 v19, v32, 16, 1
	v_bfe_u32 v36, v33, 16, 1
	v_add3_u32 v19, v32, v19, s26
	v_add3_u32 v32, v33, v36, s26
	v_lshrrev_b32_e32 v19, 16, v19
	v_and_or_b32 v32, v32, s27, v19
	v_cvt_pk_bf16_f32 v33, v34, v35
	global_store_dwordx2 v[80:81], v[32:33], off offset:3072
	global_load_dwordx4 v[32:35], v[90:91], off offset:3072
	s_nop 0
	global_load_dwordx4 v[36:39], v[92:93], off offset:3072
	s_waitcnt vmcnt(0)
; #define GAS __attribute__((address_space(1)))
; __device__ __forceinline__ unsigned pk2(float lo, float hi) { return f2bf(lo) | (f2bf(hi) << 16); }
; template <bool IN_BF16>
; __device__ __forceinline__ void ln_row(int lane, const void* zrow, const float* g, const float* b, float* hrow, bf16* xrow) {
;     ...
;     for (int j = 0; j < 16; ++j) { const f32x4 o = v[j] * rstd * gr[64 * j] + br[64 * j];
;         if (hrow) ((GAS f32x4*)hrow + lane)[64 * j] = o;
;         if (xrow) ((GAS unsigned long long*)xrow + lane)[64 * j] = (unsigned long long)pk2(o.x, o.y) | ((unsigned long long)pk2(o.z, o.w) << 32); }
	v_pk_fma_f32 v[34:35], v[104:105], v[34:35], v[38:39]
	v_pk_fma_f32 v[32:33], v[102:103], v[32:33], v[36:37]
	v_bfe_u32 v19, v32, 16, 1
	v_bfe_u32 v36, v33, 16, 1
	v_add3_u32 v19, v32, v19, s26
	v_add3_u32 v32, v33, v36, s26
	v_lshrrev_b32_e32 v19, 16, v19
	v_and_or_b32 v32, v32, s27, v19
	v_cvt_pk_bf16_f32 v33, v34, v35
	global_store_dwordx2 v[80:81], v[32:33], off offset:3584
	global_load_dwordx4 v[32:35], v[86:87], off
	s_nop 0
	global_load_dwordx4 v[36:39], v[88:89], off
	s_waitcnt vmcnt(0)
	v_pk_fma_f32 v[34:35], v[96:97], v[34:35], v[38:39]
	v_pk_fma_f32 v[28:29], v[28:29], v[32:33], v[36:37]
	v_bfe_u32 v19, v28, 16, 1
	v_bfe_u32 v32, v29, 16, 1
	v_add3_u32 v19, v28, v19, s26
	v_add3_u32 v28, v29, v32, s26
	v_lshrrev_b32_e32 v19, 16, v19
	v_and_or_b32 v28, v28, s27, v19
	v_cvt_pk_bf16_f32 v29, v34, v35
	global_store_dwordx2 v[82:83], v[28:29], off
	global_load_dwordx4 v[32:35], v[86:87], off offset:1024
	global_load_dwordx4 v[36:39], v[88:89], off offset:1024
	v_pk_mul_f32 v[24:25], v[24:25], v[18:19] op_sel_hi:[1,0]
	v_pk_mul_f32 v[28:29], v[30:31], v[18:19] op_sel_hi:[1,0]
	s_waitcnt vmcnt(0)
	v_pk_fma_f32 v[24:25], v[24:25], v[32:33], v[36:37]
	v_pk_fma_f32 v[28:29], v[28:29], v[34:35], v[38:39]
	v_bfe_u32 v19, v24, 16, 1
	v_bfe_u32 v30, v25, 16, 1
	v_add3_u32 v19, v24, v19, s26
	v_add3_u32 v24, v25, v30, s26
	v_lshrrev_b32_e32 v19, 16, v19
	v_and_or_b32 v24, v24, s27, v19
	v_cvt_pk_bf16_f32 v25, v28, v29
	global_store_dwordx2 v[82:83], v[24:25], off offset:512
	global_load_dwordx4 v[28:31], v[86:87], off offset:2048
	global_load_dwordx4 v[32:35], v[88:89], off offset:2048
	v_pk_mul_f32 v[20:21], v[20:21], v[18:19] op_sel_hi:[1,0]
	v_pk_mul_f32 v[24:25], v[26:27], v[18:19] op_sel_hi:[1,0]
	s_waitcnt vmcnt(0)
	v_pk_fma_f32 v[20:21], v[20:21], v[28:29], v[32:33]
	v_pk_fma_f32 v[24:25], v[24:25], v[30:31], v[34:35]
	v_bfe_u32 v19, v20, 16, 1
	v_bfe_u32 v26, v21, 16, 1
	v_add3_u32 v19, v20, v19, s26
	v_add3_u32 v20, v21, v26, s26
	v_lshrrev_b32_e32 v19, 16, v19
	v_and_or_b32 v20, v20, s27, v19
	v_cvt_pk_bf16_f32 v21, v24, v25
	global_store_dwordx2 v[82:83], v[20:21], off offset:1024
	global_load_dwordx4 v[24:27], v[86:87], off offset:3072
	global_load_dwordx4 v[28:31], v[88:89], off offset:3072
	v_pk_mul_f32 v[16:17], v[16:17], v[18:19] op_sel_hi:[1,0]
	v_pk_mul_f32 v[20:21], v[22:23], v[18:19] op_sel_hi:[1,0]
	v_add_co_u32_e32 v32, vcc, s30, v78
	s_waitcnt vmcnt(0)
	v_pk_fma_f32 v[20:21], v[20:21], v[26:27], v[30:31]
	v_pk_fma_f32 v[16:17], v[16:17], v[24:25], v[28:29]
	v_bfe_u32 v23, v20, 16, 1
	v_bfe_u32 v24, v21, 16, 1
	v_add3_u32 v19, v20, v23, s26
	v_add3_u32 v20, v21, v24, s26
	v_lshrrev_b32_e32 v19, 16, v19
	v_addc_co_u32_e32 v33, vcc, 0, v79, vcc
	v_cvt_pk_bf16_f32 v16, v16, v17
	v_and_or_b32 v17, v20, s27, v19
	v_add_co_u32_e32 v34, vcc, s30, v84
	global_store_dwordx2 v[82:83], v[16:17], off offset:1536
	s_nop 0
	v_addc_co_u32_e32 v35, vcc, 0, v85, vcc
	global_load_dwordx4 v[20:23], v[32:33], off
	global_load_dwordx4 v[24:27], v[34:35], off
	v_pk_mul_f32 v[12:13], v[12:13], v[18:19] op_sel_hi:[1,0]
	v_pk_mul_f32 v[14:15], v[14:15], v[18:19] op_sel_hi:[1,0]
	s_waitcnt vmcnt(0)
	v_pk_fma_f32 v[12:13], v[12:13], v[20:21], v[24:25]
	v_pk_fma_f32 v[14:15], v[14:15], v[22:23], v[26:27]
	v_bfe_u32 v19, v14, 16, 1
	v_bfe_u32 v20, v15, 16, 1
	v_add3_u32 v14, v14, v19, s26
	v_add3_u32 v15, v15, v20, s26
	v_lshrrev_b32_e32 v14, 16, v14
	v_cvt_pk_bf16_f32 v12, v12, v13
	v_and_or_b32 v13, v15, s27, v14
	global_store_dwordx2 v[82:83], v[12:13], off offset:2048
	global_load_dwordx4 v[12:15], v[32:33], off offset:1024
	s_nop 0
	global_load_dwordx4 v[20:23], v[34:35], off offset:1024
	v_pk_mul_f32 v[8:9], v[8:9], v[18:19] op_sel_hi:[1,0]
	v_pk_mul_f32 v[10:11], v[10:11], v[18:19] op_sel_hi:[1,0]
	v_pk_mul_f32 v[4:5], v[4:5], v[18:19] op_sel_hi:[1,0]
	v_pk_mul_f32 v[6:7], v[6:7], v[18:19] op_sel_hi:[1,0]
	v_pk_mul_f32 v[0:1], v[0:1], v[18:19] op_sel_hi:[1,0]
	v_pk_mul_f32 v[2:3], v[2:3], v[18:19] op_sel_hi:[1,0]
	s_waitcnt vmcnt(0)
	v_pk_fma_f32 v[10:11], v[10:11], v[14:15], v[22:23]
	v_pk_fma_f32 v[8:9], v[8:9], v[12:13], v[20:21]
	v_cvt_pk_bf16_f32 v8, v8, v9
	v_cvt_pk_bf16_f32 v9, v10, v11
	global_store_dwordx2 v[82:83], v[8:9], off offset:2560
	global_load_dwordx4 v[8:11], v[32:33], off offset:2048
	s_nop 0
	global_load_dwordx4 v[12:15], v[34:35], off offset:2048
	s_waitcnt vmcnt(0)
	v_pk_fma_f32 v[6:7], v[6:7], v[10:11], v[14:15]
	v_pk_fma_f32 v[4:5], v[4:5], v[8:9], v[12:13]
	v_cvt_pk_bf16_f32 v4, v4, v5
	v_cvt_pk_bf16_f32 v5, v6, v7
	global_store_dwordx2 v[82:83], v[4:5], off offset:3072
	global_load_dwordx4 v[4:7], v[32:33], off offset:3072
	s_nop 0
	global_load_dwordx4 v[8:11], v[34:35], off offset:3072
	s_waitcnt vmcnt(0)
	v_pk_fma_f32 v[2:3], v[2:3], v[6:7], v[10:11]
	v_pk_fma_f32 v[0:1], v[0:1], v[4:5], v[8:9]
	v_cvt_pk_bf16_f32 v0, v0, v1
	v_cvt_pk_bf16_f32 v1, v2, v3
	global_store_dwordx2 v[82:83], v[0:1], off offset:3584
	s_cbranch_scc1 .LBB0_38

; #define GAS __attribute__((address_space(1)))
; __device__ __forceinline__ unsigned f2bf(float f) { unsigned u = __builtin_bit_cast(unsigned, f); return (u + 0x7fffu + ((u >> 16) & 1u)) >> 16; }
; __device__ __forceinline__ unsigned pk2(float lo, float hi) { return f2bf(lo) | (f2bf(hi) << 16); }
; #define TAIL ((float*)(WSL(F) + WS_TAIL))
; __device__ __forceinline__ void prep_phase(Frame& F, int l) {
;     ...
;         const v4u cw = *(const GAS v4u*)(PROJ + (size_t)m * DINM + O_CKV + lane * 8);
;         float c[8] = {bflo(cw.x), bfhi(cw.x), bflo(cw.y), bfhi(cw.y), bflo(cw.z), bfhi(cw.z), bflo(cw.w), bfhi(cw.w)};
;         float ss = 0.f;
; #pragma unroll
;         for (int j = 0; j < 8; ++j) ss += c[j] * c[j];
;         const float r = 1.f / sqrtf(wave_sum(ss) * (1.f / KVL) + RMS_EPS);
;         v4u o; o.x = pk2(c[0] * r * g0.x, c[1] * r * g0.y); o.y = pk2(c[2] * r * g0.z, c[3] * r * g0.w); o.z = pk2(c[4] * r * g1.x, c[5] * r * g1.y); o.w = pk2(c[6] * r * g1.z, c[7] * r * g1.w);
;         *(GAS v4u*)(CKVN + (size_t)m * KVL + lane * 8) = o;
;         const float kv = TAIL[(size_t)m * NTAIL + lane];
;         const float mean = wave_sum(kv) * (1.f / 64.f); const float d = kv - mean;
;         const float var = wave_sum(d * d) * (1.f / 64.f);
;         KI[(size_t)m * 64 + lane] = (bf16)f2bf(d / sqrtf(var + LN_EPS));
;         if (lane < 32) WI[(size_t)m * 32 + lane] = TAIL[(size_t)m * NTAIL + 64 + lane] * (0.17677669529663687f * 0.125f);
.LBB0_185:
	global_load_dwordx4 v[22:25], v[20:21], off
	s_mov_b32 s19, 0xf800000
	s_waitcnt vmcnt(0)
	v_lshlrev_b32_e32 v27, 16, v23
	v_lshlrev_b32_e32 v26, 16, v22
	v_and_b32_e32 v23, 0xffff0000, v23
	v_and_b32_e32 v22, 0xffff0000, v22
	v_pk_mul_f32 v[28:29], v[26:27], v[26:27]
	v_pk_mul_f32 v[30:31], v[22:23], v[22:23]
	v_lshlrev_b32_e32 v33, 16, v25
	v_add_f32_e32 v0, v28, v30
	v_lshlrev_b32_e32 v32, 16, v24
	v_add_f32_e32 v0, v29, v0
	v_and_b32_e32 v25, 0xffff0000, v25
	v_and_b32_e32 v24, 0xffff0000, v24
	v_pk_mul_f32 v[34:35], v[32:33], v[32:33]
	v_add_f32_e32 v0, v31, v0
	v_pk_mul_f32 v[36:37], v[24:25], v[24:25]
	v_add_f32_e32 v0, v34, v0
	v_add_f32_e32 v0, v36, v0
	v_add_f32_e32 v0, v35, v0
	v_add_f32_e32 v0, v37, v0
	s_nop 1
	v_add_f32_dpp v0, v0, v0 quad_perm:[1,0,3,2] row_mask:0xf bank_mask:0xf bound_ctrl:1
	s_nop 1
	v_add_f32_dpp v0, v0, v0 quad_perm:[2,3,0,1] row_mask:0xf bank_mask:0xf bound_ctrl:1
	s_nop 1
	v_add_f32_dpp v0, v0, v0 row_half_mirror row_mask:0xf bank_mask:0xf bound_ctrl:1
	s_nop 1
	v_add_f32_dpp v0, v0, v0 row_mirror row_mask:0xf bank_mask:0xf bound_ctrl:1
	v_mov_b32_e32 v11, v0
	s_nop 1
	v_permlane16_swap_b32_e32 v0, v11
	v_add_f32_e32 v0, v0, v11
	v_mov_b32_e32 v11, v0
	s_nop 1
	v_permlane32_swap_b32_e32 v0, v11
	v_add_f32_e32 v0, v0, v11
	v_fmamk_f32 v0, v0, 0x3b000000, v233
	v_cmp_gt_f32_e32 vcc, s19, v0
	v_mul_f32_e32 v11, 0x4f800000, v0
	s_nop 0
	v_cndmask_b32_e32 v0, v0, v11, vcc
	v_sqrt_f32_e32 v11, v0
	s_nop 0
	v_add_u32_e32 v13, -1, v11
	v_fma_f32 v28, -v13, v11, v0
	v_cmp_ge_f32_e64 s[42:43], 0, v28
	v_add_u32_e32 v28, 1, v11
	s_nop 0
	v_cndmask_b32_e64 v13, v11, v13, s[42:43]
	v_fma_f32 v11, -v28, v11, v0
	v_cmp_lt_f32_e64 s[42:43], 0, v11
	s_nop 1
	v_cndmask_b32_e64 v11, v13, v28, s[42:43]
	v_mul_f32_e32 v13, 0x37800000, v11
	v_cndmask_b32_e32 v11, v11, v13, vcc
	v_cmp_class_f32_e32 vcc, v0, v238
	s_nop 1
	v_cndmask_b32_e32 v0, v11, v0, vcc
	v_div_scale_f32 v11, s[14:15], v0, v0, 1.0
	v_rcp_f32_e32 v13, v11
	s_mov_b32 s14, 0x48900000
	v_fma_f32 v28, -v11, v13, 1.0
	v_fmac_f32_e32 v13, v28, v13
	v_div_scale_f32 v28, vcc, 1.0, v0, 1.0
	v_mul_f32_e32 v29, v28, v13
	v_fma_f32 v30, -v11, v29, v28
	v_fmac_f32_e32 v29, v30, v13
	v_fma_f32 v11, -v11, v29, v28
	v_div_fmas_f32 v11, v11, v13, v29
	v_div_fixup_f32 v0, v11, v0, 1.0
	v_pk_mul_f32 v[22:23], v[0:1], v[22:23] op_sel_hi:[0,1]
	v_pk_mul_f32 v[24:25], v[0:1], v[24:25] op_sel_hi:[0,1]
	v_pk_mul_f32 v[26:27], v[0:1], v[26:27] op_sel_hi:[0,1]
	v_pk_mul_f32 v[22:23], v[14:15], v[22:23]
	v_pk_mul_f32 v[28:29], v[0:1], v[32:33] op_sel_hi:[0,1]
	v_pk_mul_f32 v[24:25], v[8:9], v[24:25]
	v_pk_mul_f32 v[26:27], v[6:7], v[26:27]
	v_pk_mul_f32 v[28:29], v[2:3], v[28:29]
	v_bfe_u32 v0, v25, 16, 1
	v_bfe_u32 v11, v24, 16, 1
	v_bfe_u32 v13, v23, 16, 1
	v_add3_u32 v13, v23, v13, s25
	v_add3_u32 v11, v24, v11, s25
	v_add3_u32 v0, v25, v0, s25
	v_bfe_u32 v24, v27, 16, 1
	v_bfe_u32 v25, v28, 16, 1
	v_bfe_u32 v30, v29, 16, 1
	v_add3_u32 v29, v29, v30, s25
	v_add3_u32 v25, v28, v25, s25
	v_add3_u32 v24, v27, v24, s25
	v_lshrrev_b32_e32 v23, 16, v24
	v_lshrrev_b32_e32 v24, 16, v25
	v_lshrrev_b32_e32 v25, 16, v29
	v_and_or_b32 v25, v0, s33, v25
	v_and_or_b32 v24, v11, s33, v24
	v_and_or_b32 v23, v13, s33, v23
	v_cvt_pk_bf16_f32 v22, v26, v22
	global_store_dwordx4 v[18:19], v[22:25], off
	s_nop 1
	v_lshl_add_u64 v[22:23], s[50:51], 0, v[4:5]
	v_add_co_u32_e32 v24, vcc, s14, v22
	s_nop 1
	v_addc_co_u32_e32 v25, vcc, 0, v23, vcc
	flat_load_dword v0, v[24:25]
	s_waitcnt vmcnt(0) lgkmcnt(0)
	s_nop 0
	v_add_f32_dpp v11, v0, v0 quad_perm:[1,0,3,2] row_mask:0xf bank_mask:0xf bound_ctrl:1
	s_nop 1
	v_add_f32_dpp v11, v11, v11 quad_perm:[2,3,0,1] row_mask:0xf bank_mask:0xf bound_ctrl:1
	s_nop 1
	v_add_f32_dpp v11, v11, v11 row_half_mirror row_mask:0xf bank_mask:0xf bound_ctrl:1
	s_nop 1
	v_add_f32_dpp v11, v11, v11 row_mirror row_mask:0xf bank_mask:0xf bound_ctrl:1
	v_mov_b32_e32 v13, v11
	s_nop 1
	v_permlane16_swap_b32_e32 v11, v13
	v_add_f32_e32 v11, v11, v13
	v_mov_b32_e32 v13, v11
	s_nop 1
	v_permlane32_swap_b32_e32 v11, v13
	v_add_f32_e32 v11, v11, v13
	v_fmac_f32_e32 v0, 0xbc800000, v11
	v_mul_f32_e32 v11, v0, v0
	s_nop 1
	v_mov_b32_dpp v11, v11 quad_perm:[1,0,3,2] row_mask:0xf bank_mask:0xf bound_ctrl:1
	v_fmac_f32_e32 v11, v0, v0
	s_nop 1
	v_add_f32_dpp v11, v11, v11 quad_perm:[2,3,0,1] row_mask:0xf bank_mask:0xf bound_ctrl:1
	s_nop 1
	v_add_f32_dpp v11, v11, v11 row_half_mirror row_mask:0xf bank_mask:0xf bound_ctrl:1
	s_nop 1
	v_add_f32_dpp v11, v11, v11 row_mirror row_mask:0xf bank_mask:0xf bound_ctrl:1
	v_mov_b32_e32 v13, v11
	s_nop 1
	v_permlane16_swap_b32_e32 v11, v13
	v_add_f32_e32 v11, v11, v13
	v_mov_b32_e32 v13, v11
	s_nop 1
	v_permlane32_swap_b32_e32 v11, v13
	v_add_f32_e32 v11, v11, v13
	v_fmamk_f32 v11, v11, 0x3c800000, v233
	v_cmp_gt_f32_e32 vcc, s19, v11
	v_mul_f32_e32 v13, 0x4f800000, v11
	s_nop 0
	v_cndmask_b32_e32 v11, v11, v13, vcc
	v_sqrt_f32_e32 v13, v11
	s_nop 0
	v_add_u32_e32 v24, -1, v13
	v_fma_f32 v25, -v24, v13, v11
	v_cmp_ge_f32_e64 s[42:43], 0, v25
	v_add_u32_e32 v25, 1, v13
	s_nop 0
	v_cndmask_b32_e64 v24, v13, v24, s[42:43]
	v_fma_f32 v13, -v25, v13, v11
	v_cmp_lt_f32_e64 s[42:43], 0, v13
	s_nop 1
	v_cndmask_b32_e64 v13, v24, v25, s[42:43]
	v_mul_f32_e32 v24, 0x37800000, v13
	v_cndmask_b32_e32 v13, v13, v24, vcc
	v_cmp_class_f32_e32 vcc, v11, v238
	s_nop 1
	v_cndmask_b32_e32 v11, v13, v11, vcc
	v_div_scale_f32 v13, s[14:15], v11, v11, v0
	v_rcp_f32_e32 v24, v13
	s_nop 0
	v_fma_f32 v25, -v13, v24, 1.0
	v_fmac_f32_e32 v24, v25, v24
	v_div_scale_f32 v25, vcc, v0, v11, v0
	v_mul_f32_e32 v26, v25, v24
	v_fma_f32 v27, -v13, v26, v25
	v_fmac_f32_e32 v26, v27, v24
	v_fma_f32 v13, -v13, v26, v25
	v_div_fmas_f32 v13, v13, v24, v26
	v_div_fixup_f32 v0, v13, v11, v0
	v_bfe_u32 v11, v0, 16, 1
	v_add3_u32 v0, v0, v11, s25
	flat_store_short_d16_hi v[16:17], v0
	s_and_saveexec_b64 s[14:15], s[40:41]
	s_cbranch_execz .LBB0_184
	v_add_co_u32_e32 v22, vcc, 0x48900000, v22
	s_nop 1
	v_addc_co_u32_e32 v23, vcc, 0, v23, vcc
	flat_load_dword v0, v[22:23] offset:256
	v_lshl_add_u64 v[22:23], s[48:49], 0, v[4:5]
	s_waitcnt vmcnt(0) lgkmcnt(0)
	v_mul_f32_e32 v0, 0x3cb504f3, v0
	flat_store_dword v[22:23], v0
	s_branch .LBB0_184

; #define GAS __attribute__((address_space(1)))
; #define LN_X8(W, x) const float x##0 = bflo(W.x), x##1 = bfhi(W.x), x##2 = bflo(W.y), x##3 = bfhi(W.y), x##4 = bflo(W.z), x##5 = bfhi(W.z), x##6 = bflo(W.w), x##7 = bfhi(W.w)
; template <int NR>
; __device__ __forceinline__ void ln_rows(int lane, const bf16* Z, size_t rstride, const float* g, const float* b, float* Fout, bf16* Xout) {
;     ...
; #pragma unroll
;     for (int r = 0; r < NR; ++r) { const GAS v4u* zr = (const GAS v4u*)(Z + r * rstride) + lane;
; #pragma unroll
;         for (int j = 0; j < 8; ++j) w[r][j] = zr[64 * j]; }
;     float mean[NR], rstd[NR];
;     ...
; #pragma unroll
;     for (int r = 0; r < NR; ++r) { float s = 0.f;
; #pragma unroll
;         for (int j = 0; j < 8; ++j) { LN_X8(w[r][j], x); s += ((x0 + x1) + (x2 + x3)) + ((x4 + x5) + (x6 + x7)); }
.LBB0_1012:
	s_add_u32 s26, s58, s56
	s_addc_u32 s27, s59, s57
	v_lshl_add_u64 v[2:3], s[26:27], 0, v[176:177]
	global_load_dwordx4 v[126:129], v[2:3], off
	global_load_dwordx4 v[98:101], v[2:3], off offset:1024
	global_load_dwordx4 v[82:85], v[2:3], off offset:2048
	global_load_dwordx4 v[66:69], v[2:3], off offset:3072
	s_movk_i32 s31, 0x1000
	v_add_co_u32_e32 v2, vcc, s31, v2
	s_add_u32 s26, s39, s56
	s_nop 0
	v_addc_co_u32_e32 v3, vcc, 0, v3, vcc
	global_load_dwordx4 v[50:53], v[2:3], off
	global_load_dwordx4 v[34:37], v[2:3], off offset:1024
	global_load_dwordx4 v[18:21], v[2:3], off offset:2048
	s_nop 0
	global_load_dwordx4 v[2:5], v[2:3], off offset:3072
	s_addc_u32 s27, s49, s57
	v_lshl_add_u64 v[6:7], s[26:27], 0, v[176:177]
	global_load_dwordx4 v[122:125], v[6:7], off
	global_load_dwordx4 v[102:105], v[6:7], off offset:1024
	global_load_dwordx4 v[86:89], v[6:7], off offset:2048
	global_load_dwordx4 v[70:73], v[6:7], off offset:3072
	v_add_co_u32_e32 v6, vcc, s31, v6
	s_add_u32 s26, s29, s56
	s_nop 0
	v_addc_co_u32_e32 v7, vcc, 0, v7, vcc
	global_load_dwordx4 v[54:57], v[6:7], off
	global_load_dwordx4 v[38:41], v[6:7], off offset:1024
	global_load_dwordx4 v[22:25], v[6:7], off offset:2048
	s_nop 0
	global_load_dwordx4 v[6:9], v[6:7], off offset:3072
	s_addc_u32 s27, s36, s57
	v_lshl_add_u64 v[10:11], s[26:27], 0, v[176:177]
	global_load_dwordx4 v[118:121], v[10:11], off
	global_load_dwordx4 v[106:109], v[10:11], off offset:1024
	global_load_dwordx4 v[90:93], v[10:11], off offset:2048
	global_load_dwordx4 v[74:77], v[10:11], off offset:3072
	v_add_co_u32_e32 v10, vcc, s31, v10
	s_add_u32 s26, s37, s56
	s_nop 0
	v_addc_co_u32_e32 v11, vcc, 0, v11, vcc
	global_load_dwordx4 v[58:61], v[10:11], off
	global_load_dwordx4 v[42:45], v[10:11], off offset:1024
	global_load_dwordx4 v[26:29], v[10:11], off offset:2048
	s_nop 0
	global_load_dwordx4 v[10:13], v[10:11], off offset:3072
	s_addc_u32 s27, s38, s57
	v_lshl_add_u64 v[14:15], s[26:27], 0, v[176:177]
	global_load_dwordx4 v[114:117], v[14:15], off
	global_load_dwordx4 v[110:113], v[14:15], off offset:1024
	global_load_dwordx4 v[94:97], v[14:15], off offset:2048
	global_load_dwordx4 v[78:81], v[14:15], off offset:3072
	v_add_co_u32_e32 v14, vcc, s31, v14
	s_waitcnt vmcnt(0)
	v_lshlrev_b32_e32 v0, 16, v126
	v_and_b32_e32 v130, 0xffff0000, v126
	v_lshlrev_b32_e32 v131, 16, v127
	v_and_b32_e32 v132, 0xffff0000, v127
	v_lshlrev_b32_e32 v133, 16, v128
	v_and_b32_e32 v134, 0xffff0000, v128
	v_lshlrev_b32_e32 v135, 16, v129
	v_and_b32_e32 v136, 0xffff0000, v129
	v_add_f32_e32 v0, v0, v130
	v_add_f32_e32 v130, v131, v132
	v_add_f32_e32 v0, v0, v130
	v_add_f32_e32 v130, v133, v134
	v_add_f32_e32 v131, v135, v136
	v_add_f32_e32 v130, v130, v131
	v_add_f32_e32 v0, v0, v130
	v_lshlrev_b32_e32 v130, 16, v98
	v_and_b32_e32 v131, 0xffff0000, v98
	v_lshlrev_b32_e32 v132, 16, v99
	v_and_b32_e32 v133, 0xffff0000, v99
	v_lshlrev_b32_e32 v134, 16, v100
	v_and_b32_e32 v135, 0xffff0000, v100
	v_lshlrev_b32_e32 v136, 16, v101
	v_and_b32_e32 v137, 0xffff0000, v101
	v_add_f32_e32 v130, v130, v131
	v_add_f32_e32 v131, v132, v133
	v_add_f32_e32 v130, v130, v131
	v_add_f32_e32 v131, v134, v135
	v_add_f32_e32 v132, v136, v137
	v_add_f32_e32 v131, v131, v132
	v_add_f32_e32 v0, 0, v0
	v_add_f32_e32 v130, v130, v131
	v_add_f32_e32 v0, v0, v130
	v_lshlrev_b32_e32 v130, 16, v82
	v_and_b32_e32 v131, 0xffff0000, v82
	v_lshlrev_b32_e32 v132, 16, v83
	v_and_b32_e32 v133, 0xffff0000, v83
	v_lshlrev_b32_e32 v134, 16, v84
	v_and_b32_e32 v135, 0xffff0000, v84
	v_lshlrev_b32_e32 v136, 16, v85
	v_and_b32_e32 v137, 0xffff0000, v85
	v_add_f32_e32 v130, v130, v131
	v_add_f32_e32 v131, v132, v133
	v_add_f32_e32 v130, v130, v131
	v_add_f32_e32 v131, v134, v135
	v_add_f32_e32 v132, v136, v137
	v_add_f32_e32 v131, v131, v132
	v_add_f32_e32 v130, v130, v131
	v_add_f32_e32 v0, v0, v130
	v_lshlrev_b32_e32 v130, 16, v66
	v_and_b32_e32 v131, 0xffff0000, v66
	v_lshlrev_b32_e32 v132, 16, v67
	v_and_b32_e32 v133, 0xffff0000, v67
	v_lshlrev_b32_e32 v134, 16, v68
	v_and_b32_e32 v135, 0xffff0000, v68
	v_lshlrev_b32_e32 v136, 16, v69
	v_and_b32_e32 v137, 0xffff0000, v69
	v_add_f32_e32 v130, v130, v131
	v_add_f32_e32 v131, v132, v133
	v_add_f32_e32 v130, v130, v131
	v_add_f32_e32 v131, v134, v135
	v_add_f32_e32 v132, v136, v137
	v_add_f32_e32 v131, v131, v132
	v_add_f32_e32 v130, v130, v131
	v_add_f32_e32 v0, v0, v130
	v_lshlrev_b32_e32 v130, 16, v50
	v_and_b32_e32 v131, 0xffff0000, v50
	v_lshlrev_b32_e32 v132, 16, v51
	v_and_b32_e32 v133, 0xffff0000, v51
	v_lshlrev_b32_e32 v134, 16, v52
	v_and_b32_e32 v135, 0xffff0000, v52
	v_lshlrev_b32_e32 v136, 16, v53
	v_and_b32_e32 v137, 0xffff0000, v53
	v_add_f32_e32 v130, v130, v131
	v_add_f32_e32 v131, v132, v133
	v_add_f32_e32 v130, v130, v131
	v_add_f32_e32 v131, v134, v135
	v_add_f32_e32 v132, v136, v137
	v_add_f32_e32 v131, v131, v132
	v_add_f32_e32 v130, v130, v131
	v_add_f32_e32 v0, v0, v130
	v_lshlrev_b32_e32 v130, 16, v34
	v_and_b32_e32 v131, 0xffff0000, v34
	v_lshlrev_b32_e32 v132, 16, v35
	v_and_b32_e32 v133, 0xffff0000, v35
	v_lshlrev_b32_e32 v134, 16, v36
	v_and_b32_e32 v135, 0xffff0000, v36
	v_lshlrev_b32_e32 v136, 16, v37
	v_and_b32_e32 v137, 0xffff0000, v37
	v_add_f32_e32 v130, v130, v131
	v_add_f32_e32 v131, v132, v133
	v_add_f32_e32 v130, v130, v131
	v_add_f32_e32 v131, v134, v135
	v_add_f32_e32 v132, v136, v137
	v_add_f32_e32 v131, v131, v132
	v_add_f32_e32 v130, v130, v131
	v_add_f32_e32 v0, v0, v130
	v_lshlrev_b32_e32 v130, 16, v18
	v_and_b32_e32 v131, 0xffff0000, v18
	v_lshlrev_b32_e32 v132, 16, v19
	v_and_b32_e32 v133, 0xffff0000, v19
	v_lshlrev_b32_e32 v134, 16, v20
; #define GAS __attribute__((address_space(1)))
; #define LN_X8(W, x) const float x##0 = bflo(W.x), x##1 = bfhi(W.x), x##2 = bflo(W.y), x##3 = bfhi(W.y), x##4 = bflo(W.z), x##5 = bfhi(W.z), x##6 = bflo(W.w), x##7 = bfhi(W.w)
; template <int NR>
; __device__ __forceinline__ void ln_rows(int lane, const bf16* Z, size_t rstride, const float* g, const float* b, float* Fout, bf16* Xout) {
;     ...
; #pragma unroll
;     for (int r = 0; r < NR; ++r) { const GAS v4u* zr = (const GAS v4u*)(Z + r * rstride) + lane;
; #pragma unroll
;         for (int j = 0; j < 8; ++j) w[r][j] = zr[64 * j]; }
;     float mean[NR], rstd[NR];
;     ...
; #pragma unroll
;     for (int r = 0; r < NR; ++r) { float s = 0.f;
; #pragma unroll
;         for (int j = 0; j < 8; ++j) { LN_X8(w[r][j], x); s += ((x0 + x1) + (x2 + x3)) + ((x4 + x5) + (x6 + x7)); }
	v_and_b32_e32 v135, 0xffff0000, v20
	v_lshlrev_b32_e32 v136, 16, v21
	v_and_b32_e32 v137, 0xffff0000, v21
	v_add_f32_e32 v130, v130, v131
	v_add_f32_e32 v131, v132, v133
	v_add_f32_e32 v130, v130, v131
	v_add_f32_e32 v131, v134, v135
	v_add_f32_e32 v132, v136, v137
	v_add_f32_e32 v131, v131, v132
	v_add_f32_e32 v130, v130, v131
	v_add_f32_e32 v0, v0, v130
	v_lshlrev_b32_e32 v130, 16, v2
	v_and_b32_e32 v131, 0xffff0000, v2
	v_lshlrev_b32_e32 v132, 16, v3
	v_and_b32_e32 v133, 0xffff0000, v3
	v_lshlrev_b32_e32 v134, 16, v4
	v_and_b32_e32 v135, 0xffff0000, v4
	v_lshlrev_b32_e32 v136, 16, v5
	v_and_b32_e32 v137, 0xffff0000, v5
	v_add_f32_e32 v130, v130, v131
	v_add_f32_e32 v131, v132, v133
	v_add_f32_e32 v130, v130, v131
	v_add_f32_e32 v131, v134, v135
	v_add_f32_e32 v132, v136, v137
	v_add_f32_e32 v131, v131, v132
	v_add_f32_e32 v130, v130, v131
	v_add_f32_e32 v0, v0, v130
	v_lshlrev_b32_e32 v130, 16, v122
	v_and_b32_e32 v131, 0xffff0000, v122
	v_lshlrev_b32_e32 v132, 16, v123
	v_and_b32_e32 v133, 0xffff0000, v123
	v_lshlrev_b32_e32 v134, 16, v124
	v_and_b32_e32 v135, 0xffff0000, v124
	v_lshlrev_b32_e32 v136, 16, v125
	v_and_b32_e32 v137, 0xffff0000, v125
	v_add_f32_e32 v130, v130, v131
	v_add_f32_e32 v131, v132, v133
	v_add_f32_e32 v130, v130, v131
	v_add_f32_e32 v131, v134, v135
	v_add_f32_e32 v132, v136, v137
	v_add_f32_e32 v131, v131, v132
	v_add_f32_e32 v130, v130, v131
	v_lshlrev_b32_e32 v131, 16, v102
	v_and_b32_e32 v132, 0xffff0000, v102
	v_lshlrev_b32_e32 v133, 16, v103
	v_and_b32_e32 v134, 0xffff0000, v103
	v_lshlrev_b32_e32 v135, 16, v104
	v_and_b32_e32 v136, 0xffff0000, v104
	v_lshlrev_b32_e32 v137, 16, v105
	v_and_b32_e32 v138, 0xffff0000, v105
	v_add_f32_e32 v131, v131, v132
	v_add_f32_e32 v132, v133, v134
	v_add_f32_e32 v131, v131, v132
	v_add_f32_e32 v132, v135, v136
	v_add_f32_e32 v133, v137, v138
	v_add_f32_e32 v132, v132, v133
	v_add_f32_e32 v130, 0, v130
	v_add_f32_e32 v131, v131, v132
	v_add_f32_e32 v130, v130, v131
	v_lshlrev_b32_e32 v131, 16, v86
	v_and_b32_e32 v132, 0xffff0000, v86
	v_lshlrev_b32_e32 v133, 16, v87
	v_and_b32_e32 v134, 0xffff0000, v87
	v_lshlrev_b32_e32 v135, 16, v88
	v_and_b32_e32 v136, 0xffff0000, v88
	v_lshlrev_b32_e32 v137, 16, v89
	v_and_b32_e32 v138, 0xffff0000, v89
	v_add_f32_e32 v131, v131, v132
	v_add_f32_e32 v132, v133, v134
	v_add_f32_e32 v131, v131, v132
	v_add_f32_e32 v132, v135, v136
	v_add_f32_e32 v133, v137, v138
	v_add_f32_e32 v132, v132, v133
	v_add_f32_e32 v131, v131, v132
	v_add_f32_e32 v130, v130, v131
	v_lshlrev_b32_e32 v131, 16, v70
	v_and_b32_e32 v132, 0xffff0000, v70
	v_lshlrev_b32_e32 v133, 16, v71
	v_and_b32_e32 v134, 0xffff0000, v71
	v_lshlrev_b32_e32 v135, 16, v72
	v_and_b32_e32 v136, 0xffff0000, v72
	v_lshlrev_b32_e32 v137, 16, v73
	v_and_b32_e32 v138, 0xffff0000, v73
	v_add_f32_e32 v131, v131, v132
	v_add_f32_e32 v132, v133, v134
	v_add_f32_e32 v131, v131, v132
	v_add_f32_e32 v132, v135, v136
	v_add_f32_e32 v133, v137, v138
	v_add_f32_e32 v132, v132, v133
	v_add_f32_e32 v131, v131, v132
	v_addc_co_u32_e32 v15, vcc, 0, v15, vcc
	v_add_f32_e32 v130, v130, v131
	v_lshlrev_b32_e32 v131, 16, v54
	v_and_b32_e32 v132, 0xffff0000, v54
	v_lshlrev_b32_e32 v133, 16, v55
	v_and_b32_e32 v134, 0xffff0000, v55
	global_load_dwordx4 v[62:65], v[14:15], off
	global_load_dwordx4 v[46:49], v[14:15], off offset:1024
	global_load_dwordx4 v[30:33], v[14:15], off offset:2048
	s_nop 0
	global_load_dwordx4 v[14:17], v[14:15], off offset:3072
	v_lshlrev_b32_e32 v135, 16, v56
	v_and_b32_e32 v136, 0xffff0000, v56
	v_lshlrev_b32_e32 v137, 16, v57
	v_and_b32_e32 v138, 0xffff0000, v57
	v_add_f32_e32 v131, v131, v132
	v_add_f32_e32 v132, v133, v134
	v_add_f32_e32 v131, v131, v132
	v_add_f32_e32 v132, v135, v136
	v_add_f32_e32 v133, v137, v138
	v_add_f32_e32 v132, v132, v133
	v_add_f32_e32 v131, v131, v132
	v_add_f32_e32 v130, v130, v131
	v_lshlrev_b32_e32 v131, 16, v38
	v_and_b32_e32 v132, 0xffff0000, v38
	v_lshlrev_b32_e32 v133, 16, v39
	v_and_b32_e32 v134, 0xffff0000, v39
	v_lshlrev_b32_e32 v135, 16, v40
	v_and_b32_e32 v136, 0xffff0000, v40
	v_lshlrev_b32_e32 v137, 16, v41
	v_and_b32_e32 v138, 0xffff0000, v41
	v_add_f32_e32 v131, v131, v132
	v_add_f32_e32 v132, v133, v134
	v_add_f32_e32 v131, v131, v132
	v_add_f32_e32 v132, v135, v136
	v_add_f32_e32 v133, v137, v138
	v_add_f32_e32 v132, v132, v133
	v_add_f32_e32 v131, v131, v132
	v_add_f32_e32 v130, v130, v131
	v_lshlrev_b32_e32 v131, 16, v22
	v_and_b32_e32 v132, 0xffff0000, v22
	v_lshlrev_b32_e32 v133, 16, v23
	v_and_b32_e32 v134, 0xffff0000, v23
	v_lshlrev_b32_e32 v135, 16, v24
	v_and_b32_e32 v136, 0xffff0000, v24
	v_lshlrev_b32_e32 v137, 16, v25
	v_and_b32_e32 v138, 0xffff0000, v25
	v_add_f32_e32 v131, v131, v132
	v_add_f32_e32 v132, v133, v134
	v_add_f32_e32 v131, v131, v132
	v_add_f32_e32 v132, v135, v136
	v_add_f32_e32 v133, v137, v138
	v_add_f32_e32 v132, v132, v133
	v_add_f32_e32 v131, v131, v132
	v_add_f32_e32 v130, v130, v131
	v_lshlrev_b32_e32 v131, 16, v6
	v_and_b32_e32 v132, 0xffff0000, v6
	v_lshlrev_b32_e32 v133, 16, v7
	v_and_b32_e32 v134, 0xffff0000, v7
	v_lshlrev_b32_e32 v135, 16, v8
	v_and_b32_e32 v136, 0xffff0000, v8
	v_lshlrev_b32_e32 v137, 16, v9
	v_and_b32_e32 v138, 0xffff0000, v9
	v_add_f32_e32 v131, v131, v132
	v_add_f32_e32 v132, v133, v134
	v_add_f32_e32 v131, v131, v132
	v_add_f32_e32 v132, v135, v136
	v_add_f32_e32 v133, v137, v138
	v_add_f32_e32 v132, v132, v133
	v_add_f32_e32 v131, v131, v132
	v_add_f32_e32 v130, v130, v131
	v_lshlrev_b32_e32 v131, 16, v118
	v_and_b32_e32 v132, 0xffff0000, v118
	v_lshlrev_b32_e32 v133, 16, v119
	v_and_b32_e32 v134, 0xffff0000, v119
	v_lshlrev_b32_e32 v135, 16, v120
	v_and_b32_e32 v136, 0xffff0000, v120
; #define LN_X8(W, x) const float x##0 = bflo(W.x), x##1 = bfhi(W.x), x##2 = bflo(W.y), x##3 = bfhi(W.y), x##4 = bflo(W.z), x##5 = bfhi(W.z), x##6 = bflo(W.w), x##7 = bfhi(W.w)
; #define LN_OPAQUE() do { _Pragma("unroll") for (int r = 0; r < NR; ++r) _Pragma("unroll") for (int j = 0; j < 8; ++j) asm volatile("" : "+v"(w[r][j].x), "+v"(w[r][j].y), "+v"(w[r][j].z), "+v"(w[r][j].w)); } while (0)
; template <int NR>
; __device__ __forceinline__ void ln_rows(int lane, const bf16* Z, size_t rstride, const float* g, const float* b, float* Fout, bf16* Xout) {
;     ...
;     for (int r = 0; r < NR; ++r) { float s = 0.f;
; #pragma unroll
;         for (int j = 0; j < 8; ++j) { LN_X8(w[r][j], x); s += ((x0 + x1) + (x2 + x3)) + ((x4 + x5) + (x6 + x7)); }
;         mean[r] = s; }
;     ...
;     LN_OPAQUE();
; #pragma unroll
;     for (int r = 0; r < NR; ++r) mean[r] = wave_sum(mean[r]) * (1.f / DM);
	v_lshlrev_b32_e32 v137, 16, v121
	v_and_b32_e32 v138, 0xffff0000, v121
	v_add_f32_e32 v131, v131, v132
	v_add_f32_e32 v132, v133, v134
	v_add_f32_e32 v131, v131, v132
	v_add_f32_e32 v132, v135, v136
	v_add_f32_e32 v133, v137, v138
	v_add_f32_e32 v132, v132, v133
	v_add_f32_e32 v131, v131, v132
	v_lshlrev_b32_e32 v132, 16, v106
	v_and_b32_e32 v133, 0xffff0000, v106
	v_lshlrev_b32_e32 v134, 16, v107
	v_and_b32_e32 v135, 0xffff0000, v107
	v_lshlrev_b32_e32 v136, 16, v108
	v_and_b32_e32 v137, 0xffff0000, v108
	v_lshlrev_b32_e32 v138, 16, v109
	v_and_b32_e32 v139, 0xffff0000, v109
	v_add_f32_e32 v132, v132, v133
	v_add_f32_e32 v133, v134, v135
	v_add_f32_e32 v132, v132, v133
	v_add_f32_e32 v133, v136, v137
	v_add_f32_e32 v134, v138, v139
	v_add_f32_e32 v133, v133, v134
	v_add_f32_e32 v131, 0, v131
	v_add_f32_e32 v132, v132, v133
	v_add_f32_e32 v131, v131, v132
	v_lshlrev_b32_e32 v132, 16, v90
	v_and_b32_e32 v133, 0xffff0000, v90
	v_lshlrev_b32_e32 v134, 16, v91
	v_and_b32_e32 v135, 0xffff0000, v91
	v_lshlrev_b32_e32 v136, 16, v92
	v_and_b32_e32 v137, 0xffff0000, v92
	v_lshlrev_b32_e32 v138, 16, v93
	v_and_b32_e32 v139, 0xffff0000, v93
	v_add_f32_e32 v132, v132, v133
	v_add_f32_e32 v133, v134, v135
	v_add_f32_e32 v132, v132, v133
	v_add_f32_e32 v133, v136, v137
	v_add_f32_e32 v134, v138, v139
	v_add_f32_e32 v133, v133, v134
	v_add_f32_e32 v132, v132, v133
	v_add_f32_e32 v131, v131, v132
	v_lshlrev_b32_e32 v132, 16, v74
	v_and_b32_e32 v133, 0xffff0000, v74
	v_lshlrev_b32_e32 v134, 16, v75
	v_and_b32_e32 v135, 0xffff0000, v75
	v_lshlrev_b32_e32 v136, 16, v76
	v_and_b32_e32 v137, 0xffff0000, v76
	v_lshlrev_b32_e32 v138, 16, v77
	v_and_b32_e32 v139, 0xffff0000, v77
	v_add_f32_e32 v132, v132, v133
	v_add_f32_e32 v133, v134, v135
	v_add_f32_e32 v132, v132, v133
	v_add_f32_e32 v133, v136, v137
	v_add_f32_e32 v134, v138, v139
	v_add_f32_e32 v133, v133, v134
	v_add_f32_e32 v132, v132, v133
	v_add_f32_e32 v131, v131, v132
	v_lshlrev_b32_e32 v132, 16, v58
	v_and_b32_e32 v133, 0xffff0000, v58
	v_lshlrev_b32_e32 v134, 16, v59
	v_and_b32_e32 v135, 0xffff0000, v59
	v_lshlrev_b32_e32 v136, 16, v60
	v_and_b32_e32 v137, 0xffff0000, v60
	v_lshlrev_b32_e32 v138, 16, v61
	v_and_b32_e32 v139, 0xffff0000, v61
	v_add_f32_e32 v132, v132, v133
	v_add_f32_e32 v133, v134, v135
	v_add_f32_e32 v132, v132, v133
	v_add_f32_e32 v133, v136, v137
	v_add_f32_e32 v134, v138, v139
	v_add_f32_e32 v133, v133, v134
	v_add_f32_e32 v132, v132, v133
	v_add_f32_e32 v131, v131, v132
	v_lshlrev_b32_e32 v132, 16, v42
	v_and_b32_e32 v133, 0xffff0000, v42
	v_lshlrev_b32_e32 v134, 16, v43
	v_and_b32_e32 v135, 0xffff0000, v43
	v_lshlrev_b32_e32 v136, 16, v44
	v_and_b32_e32 v137, 0xffff0000, v44
	v_lshlrev_b32_e32 v138, 16, v45
	v_and_b32_e32 v139, 0xffff0000, v45
	v_add_f32_e32 v132, v132, v133
	v_add_f32_e32 v133, v134, v135
	v_add_f32_e32 v132, v132, v133
	v_add_f32_e32 v133, v136, v137
	v_add_f32_e32 v134, v138, v139
	v_add_f32_e32 v133, v133, v134
	v_add_f32_e32 v132, v132, v133
	v_add_f32_e32 v131, v131, v132
	v_lshlrev_b32_e32 v132, 16, v26
	v_and_b32_e32 v133, 0xffff0000, v26
	v_lshlrev_b32_e32 v134, 16, v27
	v_and_b32_e32 v135, 0xffff0000, v27
	v_lshlrev_b32_e32 v136, 16, v28
	v_and_b32_e32 v137, 0xffff0000, v28
	v_lshlrev_b32_e32 v138, 16, v29
	v_and_b32_e32 v139, 0xffff0000, v29
	v_add_f32_e32 v132, v132, v133
	v_add_f32_e32 v133, v134, v135
	v_add_f32_e32 v132, v132, v133
	v_add_f32_e32 v133, v136, v137
	v_add_f32_e32 v134, v138, v139
	v_add_f32_e32 v133, v133, v134
	v_add_f32_e32 v132, v132, v133
	v_add_f32_e32 v131, v131, v132
	v_lshlrev_b32_e32 v132, 16, v10
	v_and_b32_e32 v133, 0xffff0000, v10
	v_lshlrev_b32_e32 v134, 16, v11
	v_and_b32_e32 v135, 0xffff0000, v11
	v_lshlrev_b32_e32 v136, 16, v12
	v_and_b32_e32 v137, 0xffff0000, v12
	v_lshlrev_b32_e32 v138, 16, v13
	v_and_b32_e32 v139, 0xffff0000, v13
	v_add_f32_e32 v132, v132, v133
	v_add_f32_e32 v133, v134, v135
	v_add_f32_e32 v132, v132, v133
	v_add_f32_e32 v133, v136, v137
	v_add_f32_e32 v134, v138, v139
	v_add_f32_e32 v133, v133, v134
	v_add_f32_e32 v132, v132, v133
	v_add_f32_e32 v131, v131, v132
	v_lshlrev_b32_e32 v132, 16, v114
	v_and_b32_e32 v133, 0xffff0000, v114
	v_lshlrev_b32_e32 v134, 16, v115
	v_and_b32_e32 v135, 0xffff0000, v115
	v_lshlrev_b32_e32 v136, 16, v116
	v_and_b32_e32 v137, 0xffff0000, v116
	v_lshlrev_b32_e32 v138, 16, v117
	v_and_b32_e32 v139, 0xffff0000, v117
	v_add_f32_e32 v132, v132, v133
	v_add_f32_e32 v133, v134, v135
	v_add_f32_e32 v132, v132, v133
	v_add_f32_e32 v133, v136, v137
	v_add_f32_e32 v134, v138, v139
	v_add_f32_e32 v133, v133, v134
	v_add_f32_e32 v132, v132, v133
	v_lshlrev_b32_e32 v133, 16, v110
	v_and_b32_e32 v134, 0xffff0000, v110
	v_lshlrev_b32_e32 v135, 16, v111
	v_and_b32_e32 v136, 0xffff0000, v111
	v_lshlrev_b32_e32 v137, 16, v112
	v_and_b32_e32 v138, 0xffff0000, v112
	v_lshlrev_b32_e32 v139, 16, v113
	v_and_b32_e32 v140, 0xffff0000, v113
	v_add_f32_e32 v133, v133, v134
	v_add_f32_e32 v134, v135, v136
	v_add_f32_e32 v133, v133, v134
	v_add_f32_e32 v134, v137, v138
	v_add_f32_e32 v135, v139, v140
	v_add_f32_e32 v134, v134, v135
	v_add_f32_e32 v132, 0, v132
	v_add_f32_e32 v133, v133, v134
	v_add_f32_e32 v132, v132, v133
	v_lshlrev_b32_e32 v133, 16, v94
	v_and_b32_e32 v134, 0xffff0000, v94
	v_lshlrev_b32_e32 v135, 16, v95
	v_and_b32_e32 v136, 0xffff0000, v95
	v_lshlrev_b32_e32 v137, 16, v96
	v_and_b32_e32 v138, 0xffff0000, v96
	v_lshlrev_b32_e32 v139, 16, v97
	v_and_b32_e32 v140, 0xffff0000, v97
	v_add_f32_e32 v133, v133, v134
	v_add_f32_e32 v134, v135, v136
	v_add_f32_e32 v133, v133, v134
	v_add_f32_e32 v134, v137, v138
	v_add_f32_e32 v135, v139, v140
	v_add_f32_e32 v134, v134, v135
	v_add_f32_e32 v133, v133, v134
	v_add_f32_dpp v0, v0, v0 quad_perm:[1,0,3,2] row_mask:0xf bank_mask:0xf bound_ctrl:1
	v_add_f32_e32 v132, v132, v133
	v_lshlrev_b32_e32 v133, 16, v78
	v_and_b32_e32 v134, 0xffff0000, v78
	v_lshlrev_b32_e32 v135, 16, v79
	v_and_b32_e32 v136, 0xffff0000, v79
	v_add_f32_dpp v0, v0, v0 quad_perm:[2,3,0,1] row_mask:0xf bank_mask:0xf bound_ctrl:1
	v_lshlrev_b32_e32 v137, 16, v80
	v_and_b32_e32 v138, 0xffff0000, v80
	v_lshlrev_b32_e32 v139, 16, v81
	v_and_b32_e32 v140, 0xffff0000, v81
	v_add_f32_e32 v133, v133, v134
	v_add_f32_e32 v134, v135, v136
	v_add_f32_dpp v0, v0, v0 row_half_mirror row_mask:0xf bank_mask:0xf bound_ctrl:1
	v_add_f32_e32 v133, v133, v134
	v_add_f32_e32 v134, v137, v138
	v_add_f32_e32 v135, v139, v140
	v_add_f32_dpp v0, v0, v0 row_mirror row_mask:0xf bank_mask:0xf bound_ctrl:1
	v_add_f32_e32 v134, v134, v135
	v_mov_b32_e32 v189, v100
	v_mov_b32_e32 v100, v35
	v_mov_b32_e32 v35, v2
	v_mov_b32_e32 v2, v0
	v_add_f32_e32 v133, v133, v134
	s_nop 0
	v_permlane16_swap_b32_e32 v0, v2
	v_add_f32_e32 v132, v132, v133
	s_waitcnt vmcnt(3)
; #define LN_X8(W, x) const float x##0 = bflo(W.x), x##1 = bfhi(W.x), x##2 = bflo(W.y), x##3 = bfhi(W.y), x##4 = bflo(W.z), x##5 = bfhi(W.z), x##6 = bflo(W.w), x##7 = bfhi(W.w)
; template <int NR>
; __device__ __forceinline__ void ln_rows(int lane, const bf16* Z, size_t rstride, const float* g, const float* b, float* Fout, bf16* Xout) {
;     ...
;     for (int r = 0; r < NR; ++r) mean[r] = wave_sum(mean[r]) * (1.f / DM);
; #pragma unroll
;     for (int r = 0; r < NR; ++r) { float q = 0.f; const float mu = mean[r];
; #pragma unroll
;         for (int j = 0; j < 8; ++j) { LN_X8(w[r][j], x); const float d0 = x0 - mu, d1 = x1 - mu, d2 = x2 - mu, d3 = x3 - mu, d4 = x4 - mu, d5 = x5 - mu, d6 = x6 - mu, d7 = x7 - mu;
	v_lshlrev_b32_e32 v133, 16, v62
	v_and_b32_e32 v134, 0xffff0000, v62
	v_lshlrev_b32_e32 v135, 16, v63
	v_and_b32_e32 v136, 0xffff0000, v63
	v_add_f32_e32 v0, v0, v2
	v_lshlrev_b32_e32 v137, 16, v64
	v_and_b32_e32 v138, 0xffff0000, v64
	v_lshlrev_b32_e32 v139, 16, v65
	v_and_b32_e32 v140, 0xffff0000, v65
	v_add_f32_e32 v133, v133, v134
	v_add_f32_e32 v134, v135, v136
	v_mov_b32_e32 v2, v0
	v_add_f32_e32 v133, v133, v134
	v_add_f32_e32 v134, v137, v138
	v_add_f32_e32 v135, v139, v140
	v_permlane32_swap_b32_e32 v0, v2
	v_add_f32_e32 v134, v134, v135
	v_add_f32_e32 v0, v0, v2
	v_add_f32_dpp v2, v130, v130 quad_perm:[1,0,3,2] row_mask:0xf bank_mask:0xf bound_ctrl:1
	v_add_f32_e32 v133, v133, v134
	v_add_f32_e32 v132, v132, v133
	v_add_f32_dpp v2, v2, v2 quad_perm:[2,3,0,1] row_mask:0xf bank_mask:0xf bound_ctrl:1
	s_waitcnt vmcnt(2)
	v_lshlrev_b32_e32 v133, 16, v46
	v_and_b32_e32 v134, 0xffff0000, v46
	v_lshlrev_b32_e32 v135, 16, v47
	v_and_b32_e32 v136, 0xffff0000, v47
	v_add_f32_dpp v2, v2, v2 row_half_mirror row_mask:0xf bank_mask:0xf bound_ctrl:1
	v_lshlrev_b32_e32 v137, 16, v48
	v_and_b32_e32 v138, 0xffff0000, v48
	v_lshlrev_b32_e32 v139, 16, v49
	v_and_b32_e32 v140, 0xffff0000, v49
	v_add_f32_e32 v133, v133, v134
	v_add_f32_e32 v134, v135, v136
	v_add_f32_dpp v2, v2, v2 row_mirror row_mask:0xf bank_mask:0xf bound_ctrl:1
	v_add_f32_e32 v133, v133, v134
	v_add_f32_e32 v134, v137, v138
	v_add_f32_e32 v135, v139, v140
	v_mov_b32_e32 v192, v129
	v_mov_b32_e32 v129, v37
	v_mov_b32_e32 v37, v4
	v_mov_b32_e32 v4, v2
	v_add_f32_e32 v134, v134, v135
	s_nop 0
	v_permlane16_swap_b32_e32 v2, v4
	v_add_f32_e32 v133, v133, v134
	v_add_f32_e32 v2, v2, v4
	v_add_f32_e32 v132, v132, v133
	s_waitcnt vmcnt(1)
	v_lshlrev_b32_e32 v133, 16, v30
	v_and_b32_e32 v134, 0xffff0000, v30
	v_lshlrev_b32_e32 v135, 16, v31
	v_and_b32_e32 v136, 0xffff0000, v31
	v_mov_b32_e32 v4, v2
	v_lshlrev_b32_e32 v137, 16, v32
	v_and_b32_e32 v138, 0xffff0000, v32
	v_lshlrev_b32_e32 v139, 16, v33
	v_and_b32_e32 v140, 0xffff0000, v33
	v_add_f32_e32 v133, v133, v134
	v_add_f32_e32 v134, v135, v136
	v_permlane32_swap_b32_e32 v2, v4
	v_add_f32_e32 v133, v133, v134
	v_add_f32_e32 v134, v137, v138
	v_add_f32_e32 v135, v139, v140
	v_add_f32_e32 v2, v2, v4
	v_add_f32_dpp v4, v131, v131 quad_perm:[1,0,3,2] row_mask:0xf bank_mask:0xf bound_ctrl:1
	v_add_f32_e32 v134, v134, v135
	v_add_f32_e32 v133, v133, v134
	v_add_f32_dpp v4, v4, v4 quad_perm:[2,3,0,1] row_mask:0xf bank_mask:0xf bound_ctrl:1
	v_add_f32_e32 v132, v132, v133
	s_waitcnt vmcnt(0)
	v_lshlrev_b32_e32 v133, 16, v14
	v_add_f32_dpp v4, v4, v4 row_half_mirror row_mask:0xf bank_mask:0xf bound_ctrl:1
	v_and_b32_e32 v134, 0xffff0000, v14
	v_lshlrev_b32_e32 v135, 16, v15
	v_and_b32_e32 v136, 0xffff0000, v15
	v_add_f32_dpp v4, v4, v4 row_mirror row_mask:0xf bank_mask:0xf bound_ctrl:1
	v_lshlrev_b32_e32 v137, 16, v16
	v_and_b32_e32 v138, 0xffff0000, v16
	v_lshlrev_b32_e32 v139, 16, v17
	v_and_b32_e32 v140, 0xffff0000, v17
	v_add_f32_e32 v133, v133, v134
	v_add_f32_e32 v134, v135, v136
	v_mov_b32_e32 v188, v98
	v_mov_b32_e32 v98, v20
	v_mov_b32_e32 v20, v6
	v_mov_b32_e32 v6, v4
	v_add_f32_e32 v133, v133, v134
	v_add_f32_e32 v134, v137, v138
	v_add_f32_e32 v135, v139, v140
	v_permlane16_swap_b32_e32 v4, v6
	v_add_f32_e32 v134, v134, v135
	v_add_f32_e32 v4, v4, v6
	v_add_f32_e32 v133, v133, v134
	v_mov_b32_e32 v6, v4
	v_add_f32_e32 v132, v132, v133
	s_nop 0
	v_permlane32_swap_b32_e32 v4, v6
	v_add_f32_e32 v4, v4, v6
	s_nop 0
	v_add_f32_dpp v6, v132, v132 quad_perm:[1,0,3,2] row_mask:0xf bank_mask:0xf bound_ctrl:1
	v_mov_b32_e32 v182, v88
	v_mov_b32_e32 v88, v41
	v_add_f32_dpp v6, v6, v6 quad_perm:[2,3,0,1] row_mask:0xf bank_mask:0xf bound_ctrl:1
	v_mov_b32_e32 v41, v22
	v_mov_b32_e32 v22, v8
	v_add_f32_dpp v6, v6, v6 row_half_mirror row_mask:0xf bank_mask:0xf bound_ctrl:1
	v_mov_b32_e32 v8, v14
	v_mov_b32_e32 v184, v84
	v_add_f32_dpp v6, v6, v6 row_mirror row_mask:0xf bank_mask:0xf bound_ctrl:1
	v_mov_b32_e32 v14, v6
	s_nop 1
	v_permlane16_swap_b32_e32 v6, v14
	v_add_f32_e32 v6, v6, v14
	v_mov_b32_e32 v14, v6
	v_mov_b32_e32 v84, v18
	v_mov_b32_e32 v18, v10
	v_mov_b32_e32 v10, v16
	v_permlane32_swap_b32_e32 v6, v14
	v_and_b32_e32 v16, 0xffff0000, v126
	v_mov_b32_e32 v181, v87
	v_mov_b32_e32 v87, v39
	v_mov_b32_e32 v39, v26
	v_mov_b32_e32 v26, v32
	v_add_f32_e32 v6, v6, v14
	v_lshlrev_b32_e32 v14, 16, v126
	v_and_b32_e32 v32, 0xffff0000, v127
	v_fmac_f32_e32 v16, 0xb9800000, v0
	v_mov_b32_e32 v183, v83
	v_mov_b32_e32 v83, v24
	v_mov_b32_e32 v24, v30
	v_lshlrev_b32_e32 v30, 16, v127
	v_fmac_f32_e32 v14, 0xb9800000, v0
	v_fmac_f32_e32 v32, 0xb9800000, v0
	v_mul_f32_e32 v16, v16, v16
	v_mov_b32_e32 v179, v66
	v_mov_b32_e32 v187, v104
	v_mov_b32_e32 v104, v70
	v_mov_b32_e32 v70, v74
	v_mov_b32_e32 v74, v60
	v_mov_b32_e32 v60, v45
	v_mov_b32_e32 v66, v78
	v_mov_b32_e32 v45, v49
	v_and_b32_e32 v49, 0xffff0000, v128
	v_and_b32_e32 v78, 0xffff0000, v192
	v_fmac_f32_e32 v30, 0xb9800000, v0
	v_fmac_f32_e32 v16, v14, v14
	v_mul_f32_e32 v14, v32, v32
	v_mov_b32_e32 v178, v52
	v_mov_b32_e32 v186, v102
	v_mov_b32_e32 v52, v54
	v_mov_b32_e32 v102, v56
	v_mov_b32_e32 v54, v58
	v_mov_b32_e32 v58, v43
	v_mov_b32_e32 v56, v62
	v_mov_b32_e32 v62, v64
	v_mov_b32_e32 v43, v47
	v_lshlrev_b32_e32 v47, 16, v128
	v_lshlrev_b32_e32 v64, 16, v192
	v_fmac_f32_e32 v49, 0xb9800000, v0
	v_fmac_f32_e32 v78, 0xb9800000, v0
	v_fmac_f32_e32 v14, v30, v30
	v_fmac_f32_e32 v47, 0xb9800000, v0
	v_fmac_f32_e32 v64, 0xb9800000, v0
	v_add_f32_e32 v14, v16, v14
	v_mul_f32_e32 v16, v49, v49
	v_mul_f32_e32 v30, v78, v78
	v_fmac_f32_e32 v16, v47, v47
	v_fmac_f32_e32 v30, v64, v64
; #define LN_X8(W, x) const float x##0 = bflo(W.x), x##1 = bfhi(W.x), x##2 = bflo(W.y), x##3 = bfhi(W.y), x##4 = bflo(W.z), x##5 = bfhi(W.z), x##6 = bflo(W.w), x##7 = bfhi(W.w)
; template <int NR>
; __device__ __forceinline__ void ln_rows(int lane, const bf16* Z, size_t rstride, const float* g, const float* b, float* Fout, bf16* Xout) {
;     ...
;     for (int r = 0; r < NR; ++r) { float q = 0.f; const float mu = mean[r];
; #pragma unroll
;         for (int j = 0; j < 8; ++j) { LN_X8(w[r][j], x); const float d0 = x0 - mu, d1 = x1 - mu, d2 = x2 - mu, d3 = x3 - mu, d4 = x4 - mu, d5 = x5 - mu, d6 = x6 - mu, d7 = x7 - mu;
;             q += ((d0 * d0 + d1 * d1) + (d2 * d2 + d3 * d3)) + ((d4 * d4 + d5 * d5) + (d6 * d6 + d7 * d7)); }
;         rstd[r] = q; }
	v_add_f32_e32 v16, v16, v30
	v_and_b32_e32 v30, 0xffff0000, v188
	v_add_f32_e32 v14, v14, v16
	v_lshlrev_b32_e32 v16, 16, v188
	v_and_b32_e32 v47, 0xffff0000, v99
	v_fmac_f32_e32 v30, 0xb9800000, v0
	v_lshlrev_b32_e32 v32, 16, v99
	v_fmac_f32_e32 v16, 0xb9800000, v0
	v_fmac_f32_e32 v47, 0xb9800000, v0
	v_mul_f32_e32 v30, v30, v30
	v_mov_b32_e32 v180, v69
	v_mov_b32_e32 v69, v81
	v_and_b32_e32 v64, 0xffff0000, v189
	v_and_b32_e32 v81, 0xffff0000, v101
	v_fmac_f32_e32 v32, 0xb9800000, v0
	v_fmac_f32_e32 v30, v16, v16
	v_mul_f32_e32 v16, v47, v47
	v_lshlrev_b32_e32 v49, 16, v189
	v_lshlrev_b32_e32 v78, 16, v101
	v_fmac_f32_e32 v64, 0xb9800000, v0
	v_fmac_f32_e32 v81, 0xb9800000, v0
	v_fmac_f32_e32 v16, v32, v32
	v_fmac_f32_e32 v49, 0xb9800000, v0
	v_fmac_f32_e32 v78, 0xb9800000, v0
	v_add_f32_e32 v16, v30, v16
	v_mul_f32_e32 v30, v64, v64
	v_mul_f32_e32 v32, v81, v81
	v_fmac_f32_e32 v30, v49, v49
	v_fmac_f32_e32 v32, v78, v78
	v_add_f32_e32 v30, v30, v32
	v_add_f32_e32 v16, v16, v30
	v_and_b32_e32 v30, 0xffff0000, v82
	v_add_f32_e32 v14, v14, v16
	v_lshlrev_b32_e32 v16, 16, v82
	v_and_b32_e32 v47, 0xffff0000, v183
	v_fmac_f32_e32 v30, 0xb9800000, v0
	v_lshlrev_b32_e32 v32, 16, v183
	v_fmac_f32_e32 v16, 0xb9800000, v0
	v_fmac_f32_e32 v47, 0xb9800000, v0
	v_mul_f32_e32 v30, v30, v30
	v_and_b32_e32 v64, 0xffff0000, v184
	v_and_b32_e32 v81, 0xffff0000, v85
	v_fmac_f32_e32 v32, 0xb9800000, v0
	v_fmac_f32_e32 v30, v16, v16
	v_mul_f32_e32 v16, v47, v47
	v_lshlrev_b32_e32 v49, 16, v184
	v_lshlrev_b32_e32 v78, 16, v85
	v_fmac_f32_e32 v64, 0xb9800000, v0
	v_fmac_f32_e32 v81, 0xb9800000, v0
	v_fmac_f32_e32 v16, v32, v32
	v_fmac_f32_e32 v49, 0xb9800000, v0
	v_fmac_f32_e32 v78, 0xb9800000, v0
	v_add_f32_e32 v16, v30, v16
	v_mul_f32_e32 v30, v64, v64
	v_mul_f32_e32 v32, v81, v81
	v_fmac_f32_e32 v30, v49, v49
	v_fmac_f32_e32 v32, v78, v78
	v_add_f32_e32 v30, v30, v32
	v_add_f32_e32 v16, v16, v30
	v_and_b32_e32 v30, 0xffff0000, v179
	v_add_f32_e32 v14, v16, v14
	v_lshlrev_b32_e32 v16, 16, v179
	v_and_b32_e32 v47, 0xffff0000, v67
	v_fmac_f32_e32 v30, 0xb9800000, v0
	v_lshlrev_b32_e32 v32, 16, v67
	v_fmac_f32_e32 v16, 0xb9800000, v0
	v_fmac_f32_e32 v47, 0xb9800000, v0
	v_mul_f32_e32 v30, v30, v30
	v_and_b32_e32 v64, 0xffff0000, v68
	v_and_b32_e32 v81, 0xffff0000, v180
	v_fmac_f32_e32 v32, 0xb9800000, v0
	v_fmac_f32_e32 v30, v16, v16
	v_mul_f32_e32 v16, v47, v47
	v_lshlrev_b32_e32 v49, 16, v68
	v_lshlrev_b32_e32 v78, 16, v180
	v_fmac_f32_e32 v64, 0xb9800000, v0
	v_fmac_f32_e32 v81, 0xb9800000, v0
	v_fmac_f32_e32 v16, v32, v32
	v_fmac_f32_e32 v49, 0xb9800000, v0
	v_fmac_f32_e32 v78, 0xb9800000, v0
	v_add_f32_e32 v16, v30, v16
	v_mul_f32_e32 v30, v64, v64
	v_mul_f32_e32 v32, v81, v81
	v_fmac_f32_e32 v30, v49, v49
	v_fmac_f32_e32 v32, v78, v78
	v_add_f32_e32 v30, v30, v32
	v_add_f32_e32 v16, v16, v30
	v_and_b32_e32 v30, 0xffff0000, v50
	v_add_f32_e32 v14, v16, v14
	v_lshlrev_b32_e32 v16, 16, v50
	v_and_b32_e32 v47, 0xffff0000, v51
	v_fmac_f32_e32 v30, 0xb9800000, v0
	v_lshlrev_b32_e32 v32, 16, v51
	v_fmac_f32_e32 v16, 0xb9800000, v0
	v_fmac_f32_e32 v47, 0xb9800000, v0
	v_mul_f32_e32 v30, v30, v30
	v_and_b32_e32 v64, 0xffff0000, v178
	v_and_b32_e32 v81, 0xffff0000, v53
	v_fmac_f32_e32 v32, 0xb9800000, v0
	v_fmac_f32_e32 v30, v16, v16
	v_mul_f32_e32 v16, v47, v47
	v_lshlrev_b32_e32 v49, 16, v178
	v_lshlrev_b32_e32 v78, 16, v53
	v_fmac_f32_e32 v64, 0xb9800000, v0
	v_fmac_f32_e32 v81, 0xb9800000, v0
	v_fmac_f32_e32 v16, v32, v32
	v_fmac_f32_e32 v49, 0xb9800000, v0
	v_fmac_f32_e32 v78, 0xb9800000, v0
	v_add_f32_e32 v16, v30, v16
	v_mul_f32_e32 v30, v64, v64
	v_mul_f32_e32 v32, v81, v81
	v_fmac_f32_e32 v30, v49, v49
	v_fmac_f32_e32 v32, v78, v78
	v_add_f32_e32 v30, v30, v32
	v_add_f32_e32 v16, v16, v30
	v_and_b32_e32 v30, 0xffff0000, v34
	v_add_f32_e32 v14, v16, v14
	v_lshlrev_b32_e32 v16, 16, v34
	v_and_b32_e32 v47, 0xffff0000, v100
	v_fmac_f32_e32 v30, 0xb9800000, v0
	v_lshlrev_b32_e32 v32, 16, v100
	v_fmac_f32_e32 v16, 0xb9800000, v0
	v_fmac_f32_e32 v47, 0xb9800000, v0
	v_mul_f32_e32 v30, v30, v30
	v_and_b32_e32 v64, 0xffff0000, v36
	v_and_b32_e32 v81, 0xffff0000, v129
	v_fmac_f32_e32 v32, 0xb9800000, v0
	v_fmac_f32_e32 v30, v16, v16
	v_mul_f32_e32 v16, v47, v47
	v_lshlrev_b32_e32 v49, 16, v36
	v_lshlrev_b32_e32 v78, 16, v129
	v_fmac_f32_e32 v64, 0xb9800000, v0
	v_fmac_f32_e32 v81, 0xb9800000, v0
	v_fmac_f32_e32 v16, v32, v32
	v_fmac_f32_e32 v49, 0xb9800000, v0
	v_fmac_f32_e32 v78, 0xb9800000, v0
	v_add_f32_e32 v16, v30, v16
	v_mul_f32_e32 v30, v64, v64
	v_mul_f32_e32 v32, v81, v81
	v_fmac_f32_e32 v30, v49, v49
	v_fmac_f32_e32 v32, v78, v78
	v_add_f32_e32 v30, v30, v32
	v_add_f32_e32 v16, v16, v30
	v_and_b32_e32 v30, 0xffff0000, v84
	v_add_f32_e32 v14, v16, v14
	v_lshlrev_b32_e32 v16, 16, v84
	v_and_b32_e32 v47, 0xffff0000, v19
	v_fmac_f32_e32 v30, 0xb9800000, v0
	v_lshlrev_b32_e32 v32, 16, v19
	v_fmac_f32_e32 v16, 0xb9800000, v0
	v_fmac_f32_e32 v47, 0xb9800000, v0
	v_mul_f32_e32 v30, v30, v30
	v_and_b32_e32 v64, 0xffff0000, v98
	v_and_b32_e32 v81, 0xffff0000, v21
	v_fmac_f32_e32 v32, 0xb9800000, v0
	v_fmac_f32_e32 v30, v16, v16
	v_mul_f32_e32 v16, v47, v47
	v_lshlrev_b32_e32 v49, 16, v98
	v_lshlrev_b32_e32 v78, 16, v21
	v_fmac_f32_e32 v64, 0xb9800000, v0
	v_fmac_f32_e32 v81, 0xb9800000, v0
	v_fmac_f32_e32 v16, v32, v32
	v_fmac_f32_e32 v49, 0xb9800000, v0
	v_fmac_f32_e32 v78, 0xb9800000, v0
	v_add_f32_e32 v16, v30, v16
	v_mul_f32_e32 v30, v64, v64
	v_mul_f32_e32 v32, v81, v81
	v_fmac_f32_e32 v30, v49, v49
	v_fmac_f32_e32 v32, v78, v78
	v_add_f32_e32 v30, v30, v32
	v_add_f32_e32 v16, v16, v30
	v_and_b32_e32 v30, 0xffff0000, v35
	v_add_f32_e32 v14, v16, v14
; #define LN_X8(W, x) const float x##0 = bflo(W.x), x##1 = bfhi(W.x), x##2 = bflo(W.y), x##3 = bfhi(W.y), x##4 = bflo(W.z), x##5 = bfhi(W.z), x##6 = bflo(W.w), x##7 = bfhi(W.w)
; template <int NR>
; __device__ __forceinline__ void ln_rows(int lane, const bf16* Z, size_t rstride, const float* g, const float* b, float* Fout, bf16* Xout) {
;     ...
;     for (int r = 0; r < NR; ++r) { float q = 0.f; const float mu = mean[r];
; #pragma unroll
;         for (int j = 0; j < 8; ++j) { LN_X8(w[r][j], x); const float d0 = x0 - mu, d1 = x1 - mu, d2 = x2 - mu, d3 = x3 - mu, d4 = x4 - mu, d5 = x5 - mu, d6 = x6 - mu, d7 = x7 - mu;
;             q += ((d0 * d0 + d1 * d1) + (d2 * d2 + d3 * d3)) + ((d4 * d4 + d5 * d5) + (d6 * d6 + d7 * d7)); }
;         rstd[r] = q; }
	v_lshlrev_b32_e32 v16, 16, v35
	v_and_b32_e32 v47, 0xffff0000, v3
	v_fmac_f32_e32 v30, 0xb9800000, v0
	v_lshlrev_b32_e32 v32, 16, v3
	v_fmac_f32_e32 v16, 0xb9800000, v0
	v_fmac_f32_e32 v47, 0xb9800000, v0
	v_mul_f32_e32 v30, v30, v30
	v_and_b32_e32 v64, 0xffff0000, v37
	v_and_b32_e32 v81, 0xffff0000, v5
	v_fmac_f32_e32 v32, 0xb9800000, v0
	v_fmac_f32_e32 v30, v16, v16
	v_mul_f32_e32 v16, v47, v47
	v_lshlrev_b32_e32 v49, 16, v37
	v_lshlrev_b32_e32 v78, 16, v5
	v_fmac_f32_e32 v64, 0xb9800000, v0
	v_fmac_f32_e32 v81, 0xb9800000, v0
	v_fmac_f32_e32 v16, v32, v32
	v_fmac_f32_e32 v49, 0xb9800000, v0
	v_fmac_f32_e32 v78, 0xb9800000, v0
	v_add_f32_e32 v16, v30, v16
	v_mul_f32_e32 v30, v64, v64
	v_mul_f32_e32 v32, v81, v81
	v_fmac_f32_e32 v30, v49, v49
	v_fmac_f32_e32 v32, v78, v78
	v_mov_b32_e32 v191, v125
	v_add_f32_e32 v30, v30, v32
	v_add_f32_e32 v16, v16, v30
	v_and_b32_e32 v30, 0xffff0000, v122
	v_add_f32_e32 v14, v16, v14
	v_lshlrev_b32_e32 v16, 16, v122
	v_and_b32_e32 v47, 0xffff0000, v123
	v_fmac_f32_e32 v30, 0xb9800000, v2
	v_lshlrev_b32_e32 v32, 16, v123
	v_fmac_f32_e32 v16, 0xb9800000, v2
	v_fmac_f32_e32 v47, 0xb9800000, v2
	v_mul_f32_e32 v30, v30, v30
	v_and_b32_e32 v64, 0xffff0000, v124
	v_and_b32_e32 v81, 0xffff0000, v191
	v_fmac_f32_e32 v32, 0xb9800000, v2
	v_fmac_f32_e32 v30, v16, v16
	v_mul_f32_e32 v16, v47, v47
	v_lshlrev_b32_e32 v49, 16, v124
	v_lshlrev_b32_e32 v78, 16, v191
	v_fmac_f32_e32 v64, 0xb9800000, v2
	v_fmac_f32_e32 v81, 0xb9800000, v2
	v_fmac_f32_e32 v16, v32, v32
	v_fmac_f32_e32 v49, 0xb9800000, v2
	v_fmac_f32_e32 v78, 0xb9800000, v2
	v_add_f32_e32 v16, v30, v16
	v_mul_f32_e32 v30, v64, v64
	v_mul_f32_e32 v32, v81, v81
	v_fmac_f32_e32 v30, v49, v49
	v_fmac_f32_e32 v32, v78, v78
	v_add_f32_e32 v30, v30, v32
	v_and_b32_e32 v32, 0xffff0000, v186
	v_add_f32_e32 v16, v16, v30
	v_lshlrev_b32_e32 v30, 16, v186
	v_and_b32_e32 v49, 0xffff0000, v103
	v_fmac_f32_e32 v32, 0xb9800000, v2
	v_lshlrev_b32_e32 v47, 16, v103
	v_fmac_f32_e32 v30, 0xb9800000, v2
	v_fmac_f32_e32 v49, 0xb9800000, v2
	v_mul_f32_e32 v32, v32, v32
	v_mov_b32_e32 v125, v73
	v_mov_b32_e32 v73, v77
	v_mov_b32_e32 v77, v95
	v_and_b32_e32 v78, 0xffff0000, v187
	v_and_b32_e32 v95, 0xffff0000, v105
	v_fmac_f32_e32 v47, 0xb9800000, v2
	v_fmac_f32_e32 v32, v30, v30
	v_mul_f32_e32 v30, v49, v49
	v_lshlrev_b32_e32 v64, 16, v187
	v_lshlrev_b32_e32 v81, 16, v105
	v_fmac_f32_e32 v78, 0xb9800000, v2
	v_fmac_f32_e32 v95, 0xb9800000, v2
	v_fmac_f32_e32 v30, v47, v47
	v_fmac_f32_e32 v64, 0xb9800000, v2
	v_fmac_f32_e32 v81, 0xb9800000, v2
	v_add_f32_e32 v30, v32, v30
	v_mul_f32_e32 v32, v78, v78
	v_mul_f32_e32 v47, v95, v95
	v_fmac_f32_e32 v32, v64, v64
	v_fmac_f32_e32 v47, v81, v81
	v_add_f32_e32 v32, v32, v47
	v_add_f32_e32 v30, v30, v32
	v_and_b32_e32 v32, 0xffff0000, v86
	v_add_f32_e32 v16, v16, v30
	v_lshlrev_b32_e32 v30, 16, v86
	v_and_b32_e32 v49, 0xffff0000, v181
	v_fmac_f32_e32 v32, 0xb9800000, v2
	v_lshlrev_b32_e32 v47, 16, v181
	v_fmac_f32_e32 v30, 0xb9800000, v2
	v_fmac_f32_e32 v49, 0xb9800000, v2
	v_mul_f32_e32 v32, v32, v32
	v_and_b32_e32 v78, 0xffff0000, v182
	v_and_b32_e32 v95, 0xffff0000, v89
	v_fmac_f32_e32 v47, 0xb9800000, v2
	v_fmac_f32_e32 v32, v30, v30
	v_mul_f32_e32 v30, v49, v49
	v_lshlrev_b32_e32 v64, 16, v182
	v_lshlrev_b32_e32 v81, 16, v89
	v_fmac_f32_e32 v78, 0xb9800000, v2
	v_fmac_f32_e32 v95, 0xb9800000, v2
	v_fmac_f32_e32 v30, v47, v47
	v_fmac_f32_e32 v64, 0xb9800000, v2
	v_fmac_f32_e32 v81, 0xb9800000, v2
	v_add_f32_e32 v30, v32, v30
	v_mul_f32_e32 v32, v78, v78
	v_mul_f32_e32 v47, v95, v95
	v_fmac_f32_e32 v32, v64, v64
	v_fmac_f32_e32 v47, v81, v81
	v_add_f32_e32 v32, v32, v47
	v_add_f32_e32 v30, v30, v32
	v_and_b32_e32 v32, 0xffff0000, v104
	v_add_f32_e32 v16, v30, v16
	v_lshlrev_b32_e32 v30, 16, v104
	v_and_b32_e32 v49, 0xffff0000, v71
	v_fmac_f32_e32 v32, 0xb9800000, v2
	v_lshlrev_b32_e32 v47, 16, v71
	v_fmac_f32_e32 v30, 0xb9800000, v2
	v_fmac_f32_e32 v49, 0xb9800000, v2
	v_mul_f32_e32 v32, v32, v32
	v_and_b32_e32 v78, 0xffff0000, v72
	v_and_b32_e32 v95, 0xffff0000, v125
	v_fmac_f32_e32 v47, 0xb9800000, v2
	v_fmac_f32_e32 v32, v30, v30
	v_mul_f32_e32 v30, v49, v49
	v_lshlrev_b32_e32 v64, 16, v72
	v_lshlrev_b32_e32 v81, 16, v125
	v_fmac_f32_e32 v78, 0xb9800000, v2
	v_fmac_f32_e32 v95, 0xb9800000, v2
	v_fmac_f32_e32 v30, v47, v47
	v_fmac_f32_e32 v64, 0xb9800000, v2
	v_fmac_f32_e32 v81, 0xb9800000, v2
	v_add_f32_e32 v30, v32, v30
	v_mul_f32_e32 v32, v78, v78
	v_mul_f32_e32 v47, v95, v95
	v_fmac_f32_e32 v32, v64, v64
	v_fmac_f32_e32 v47, v81, v81
	v_add_f32_e32 v32, v32, v47
	v_add_f32_e32 v30, v30, v32
	v_and_b32_e32 v32, 0xffff0000, v52
	v_add_f32_e32 v16, v30, v16
	v_lshlrev_b32_e32 v30, 16, v52
	v_and_b32_e32 v49, 0xffff0000, v55
	v_fmac_f32_e32 v32, 0xb9800000, v2
	v_lshlrev_b32_e32 v47, 16, v55
	v_fmac_f32_e32 v30, 0xb9800000, v2
	v_fmac_f32_e32 v49, 0xb9800000, v2
	v_mul_f32_e32 v32, v32, v32
	v_and_b32_e32 v78, 0xffff0000, v102
	v_and_b32_e32 v95, 0xffff0000, v57
	v_fmac_f32_e32 v47, 0xb9800000, v2
	v_fmac_f32_e32 v32, v30, v30
	v_mul_f32_e32 v30, v49, v49
	v_lshlrev_b32_e32 v64, 16, v102
	v_lshlrev_b32_e32 v81, 16, v57
	v_fmac_f32_e32 v78, 0xb9800000, v2
	v_fmac_f32_e32 v95, 0xb9800000, v2
	v_fmac_f32_e32 v30, v47, v47
	v_fmac_f32_e32 v64, 0xb9800000, v2
	v_fmac_f32_e32 v81, 0xb9800000, v2
	v_add_f32_e32 v30, v32, v30
	v_mul_f32_e32 v32, v78, v78
	v_mul_f32_e32 v47, v95, v95
	v_fmac_f32_e32 v32, v64, v64
	v_fmac_f32_e32 v47, v81, v81
	v_add_f32_e32 v32, v32, v47
	v_add_f32_e32 v30, v30, v32
	v_and_b32_e32 v32, 0xffff0000, v38
	v_add_f32_e32 v16, v30, v16
	v_lshlrev_b32_e32 v30, 16, v38
	v_and_b32_e32 v49, 0xffff0000, v87
; #define LN_X8(W, x) const float x##0 = bflo(W.x), x##1 = bfhi(W.x), x##2 = bflo(W.y), x##3 = bfhi(W.y), x##4 = bflo(W.z), x##5 = bfhi(W.z), x##6 = bflo(W.w), x##7 = bfhi(W.w)
; template <int NR>
; __device__ __forceinline__ void ln_rows(int lane, const bf16* Z, size_t rstride, const float* g, const float* b, float* Fout, bf16* Xout) {
;     ...
;     for (int r = 0; r < NR; ++r) { float q = 0.f; const float mu = mean[r];
; #pragma unroll
;         for (int j = 0; j < 8; ++j) { LN_X8(w[r][j], x); const float d0 = x0 - mu, d1 = x1 - mu, d2 = x2 - mu, d3 = x3 - mu, d4 = x4 - mu, d5 = x5 - mu, d6 = x6 - mu, d7 = x7 - mu;
;             q += ((d0 * d0 + d1 * d1) + (d2 * d2 + d3 * d3)) + ((d4 * d4 + d5 * d5) + (d6 * d6 + d7 * d7)); }
;         rstd[r] = q; }
	v_fmac_f32_e32 v32, 0xb9800000, v2
	v_lshlrev_b32_e32 v47, 16, v87
	v_fmac_f32_e32 v30, 0xb9800000, v2
	v_fmac_f32_e32 v49, 0xb9800000, v2
	v_mul_f32_e32 v32, v32, v32
	v_and_b32_e32 v78, 0xffff0000, v40
	v_and_b32_e32 v95, 0xffff0000, v88
	v_fmac_f32_e32 v47, 0xb9800000, v2
	v_fmac_f32_e32 v32, v30, v30
	v_mul_f32_e32 v30, v49, v49
	v_lshlrev_b32_e32 v64, 16, v40
	v_lshlrev_b32_e32 v81, 16, v88
	v_fmac_f32_e32 v78, 0xb9800000, v2
	v_fmac_f32_e32 v95, 0xb9800000, v2
	v_fmac_f32_e32 v30, v47, v47
	v_fmac_f32_e32 v64, 0xb9800000, v2
	v_fmac_f32_e32 v81, 0xb9800000, v2
	v_add_f32_e32 v30, v32, v30
	v_mul_f32_e32 v32, v78, v78
	v_mul_f32_e32 v47, v95, v95
	v_fmac_f32_e32 v32, v64, v64
	v_fmac_f32_e32 v47, v81, v81
	v_add_f32_e32 v32, v32, v47
	v_add_f32_e32 v30, v30, v32
	v_and_b32_e32 v32, 0xffff0000, v41
	v_add_f32_e32 v16, v30, v16
	v_lshlrev_b32_e32 v30, 16, v41
	v_and_b32_e32 v49, 0xffff0000, v23
	v_fmac_f32_e32 v32, 0xb9800000, v2
	v_lshlrev_b32_e32 v47, 16, v23
	v_fmac_f32_e32 v30, 0xb9800000, v2
	v_fmac_f32_e32 v49, 0xb9800000, v2
	v_mul_f32_e32 v32, v32, v32
	v_and_b32_e32 v78, 0xffff0000, v83
	v_and_b32_e32 v95, 0xffff0000, v25
	v_fmac_f32_e32 v47, 0xb9800000, v2
	v_fmac_f32_e32 v32, v30, v30
	v_mul_f32_e32 v30, v49, v49
	v_lshlrev_b32_e32 v64, 16, v83
	v_lshlrev_b32_e32 v81, 16, v25
	v_fmac_f32_e32 v78, 0xb9800000, v2
	v_fmac_f32_e32 v95, 0xb9800000, v2
	v_fmac_f32_e32 v30, v47, v47
	v_fmac_f32_e32 v64, 0xb9800000, v2
	v_fmac_f32_e32 v81, 0xb9800000, v2
	v_add_f32_e32 v30, v32, v30
	v_mul_f32_e32 v32, v78, v78
	v_mul_f32_e32 v47, v95, v95
	v_fmac_f32_e32 v32, v64, v64
	v_fmac_f32_e32 v47, v81, v81
	v_add_f32_e32 v32, v32, v47
	v_add_f32_e32 v30, v30, v32
	v_and_b32_e32 v32, 0xffff0000, v20
	v_add_f32_e32 v16, v30, v16
	v_lshlrev_b32_e32 v30, 16, v20
	v_and_b32_e32 v49, 0xffff0000, v7
	v_fmac_f32_e32 v32, 0xb9800000, v2
	v_lshlrev_b32_e32 v47, 16, v7
	v_fmac_f32_e32 v30, 0xb9800000, v2
	v_fmac_f32_e32 v49, 0xb9800000, v2
	v_mul_f32_e32 v32, v32, v32
	v_and_b32_e32 v78, 0xffff0000, v22
	v_and_b32_e32 v95, 0xffff0000, v9
	v_fmac_f32_e32 v47, 0xb9800000, v2
	v_fmac_f32_e32 v32, v30, v30
	v_mul_f32_e32 v30, v49, v49
	v_lshlrev_b32_e32 v64, 16, v22
	v_lshlrev_b32_e32 v81, 16, v9
	v_fmac_f32_e32 v78, 0xb9800000, v2
	v_fmac_f32_e32 v95, 0xb9800000, v2
	v_fmac_f32_e32 v30, v47, v47
	v_fmac_f32_e32 v64, 0xb9800000, v2
	v_fmac_f32_e32 v81, 0xb9800000, v2
	v_add_f32_e32 v30, v32, v30
	v_mul_f32_e32 v32, v78, v78
	v_mul_f32_e32 v47, v95, v95
	v_fmac_f32_e32 v32, v64, v64
	v_fmac_f32_e32 v47, v81, v81
	v_mov_b32_e32 v190, v121
	v_add_f32_e32 v32, v32, v47
	v_add_f32_e32 v30, v30, v32
	v_and_b32_e32 v32, 0xffff0000, v118
	v_add_f32_e32 v16, v30, v16
	v_lshlrev_b32_e32 v30, 16, v118
	v_and_b32_e32 v49, 0xffff0000, v119
	v_fmac_f32_e32 v32, 0xb9800000, v4
	v_lshlrev_b32_e32 v47, 16, v119
	v_fmac_f32_e32 v30, 0xb9800000, v4
	v_fmac_f32_e32 v49, 0xb9800000, v4
	v_mul_f32_e32 v32, v32, v32
	v_and_b32_e32 v78, 0xffff0000, v120
	v_and_b32_e32 v95, 0xffff0000, v190
	v_fmac_f32_e32 v47, 0xb9800000, v4
	v_fmac_f32_e32 v32, v30, v30
	v_mul_f32_e32 v30, v49, v49
	v_lshlrev_b32_e32 v64, 16, v120
	v_lshlrev_b32_e32 v81, 16, v190
	v_fmac_f32_e32 v78, 0xb9800000, v4
	v_fmac_f32_e32 v95, 0xb9800000, v4
	v_fmac_f32_e32 v30, v47, v47
	v_fmac_f32_e32 v64, 0xb9800000, v4
	v_fmac_f32_e32 v81, 0xb9800000, v4
	v_add_f32_e32 v30, v32, v30
	v_mul_f32_e32 v32, v78, v78
	v_mul_f32_e32 v47, v95, v95
	v_mov_b32_e32 v121, v106
	v_mov_b32_e32 v185, v108
	v_fmac_f32_e32 v32, v64, v64
	v_fmac_f32_e32 v47, v81, v81
	v_add_f32_e32 v32, v32, v47
	v_and_b32_e32 v47, 0xffff0000, v121
	v_add_f32_e32 v30, v30, v32
	v_lshlrev_b32_e32 v32, 16, v121
	v_and_b32_e32 v64, 0xffff0000, v107
	v_fmac_f32_e32 v47, 0xb9800000, v4
	v_lshlrev_b32_e32 v49, 16, v107
	v_fmac_f32_e32 v32, 0xb9800000, v4
	v_fmac_f32_e32 v64, 0xb9800000, v4
	v_mul_f32_e32 v47, v47, v47
	v_mov_b32_e32 v106, v92
	v_mov_b32_e32 v92, v91
	v_mov_b32_e32 v91, v96
	v_and_b32_e32 v81, 0xffff0000, v185
	v_and_b32_e32 v96, 0xffff0000, v109
	v_fmac_f32_e32 v49, 0xb9800000, v4
	v_fmac_f32_e32 v47, v32, v32
	v_mul_f32_e32 v32, v64, v64
	v_lshlrev_b32_e32 v78, 16, v185
	v_lshlrev_b32_e32 v95, 16, v109
	v_fmac_f32_e32 v81, 0xb9800000, v4
	v_fmac_f32_e32 v96, 0xb9800000, v4
	v_fmac_f32_e32 v32, v49, v49
	v_fmac_f32_e32 v78, 0xb9800000, v4
	v_fmac_f32_e32 v95, 0xb9800000, v4
	v_add_f32_e32 v32, v47, v32
	v_mul_f32_e32 v47, v81, v81
	v_mul_f32_e32 v49, v96, v96
	v_fmac_f32_e32 v47, v78, v78
	v_fmac_f32_e32 v49, v95, v95
	v_add_f32_e32 v47, v47, v49
	v_add_f32_e32 v32, v32, v47
	v_and_b32_e32 v47, 0xffff0000, v90
	v_add_f32_e32 v30, v30, v32
	v_lshlrev_b32_e32 v32, 16, v90
	v_and_b32_e32 v64, 0xffff0000, v92
	v_fmac_f32_e32 v47, 0xb9800000, v4
	v_lshlrev_b32_e32 v49, 16, v92
	v_fmac_f32_e32 v32, 0xb9800000, v4
	v_fmac_f32_e32 v64, 0xb9800000, v4
	v_mul_f32_e32 v47, v47, v47
	v_and_b32_e32 v81, 0xffff0000, v106
	v_and_b32_e32 v96, 0xffff0000, v93
	v_fmac_f32_e32 v49, 0xb9800000, v4
	v_fmac_f32_e32 v47, v32, v32
	v_mul_f32_e32 v32, v64, v64
	v_lshlrev_b32_e32 v78, 16, v106
	v_lshlrev_b32_e32 v95, 16, v93
	v_fmac_f32_e32 v81, 0xb9800000, v4
	v_fmac_f32_e32 v96, 0xb9800000, v4
	v_fmac_f32_e32 v32, v49, v49
	v_fmac_f32_e32 v78, 0xb9800000, v4
	v_fmac_f32_e32 v95, 0xb9800000, v4
	v_add_f32_e32 v32, v47, v32
	v_mul_f32_e32 v47, v81, v81
	v_mul_f32_e32 v49, v96, v96
	v_fmac_f32_e32 v47, v78, v78
	v_fmac_f32_e32 v49, v95, v95
	v_add_f32_e32 v47, v47, v49
	v_add_f32_e32 v32, v32, v47
	v_and_b32_e32 v47, 0xffff0000, v70
	v_add_f32_e32 v30, v32, v30
	v_lshlrev_b32_e32 v32, 16, v70
	v_and_b32_e32 v64, 0xffff0000, v75
	v_fmac_f32_e32 v47, 0xb9800000, v4
; #define LN_X8(W, x) const float x##0 = bflo(W.x), x##1 = bfhi(W.x), x##2 = bflo(W.y), x##3 = bfhi(W.y), x##4 = bflo(W.z), x##5 = bfhi(W.z), x##6 = bflo(W.w), x##7 = bfhi(W.w)
; template <int NR>
; __device__ __forceinline__ void ln_rows(int lane, const bf16* Z, size_t rstride, const float* g, const float* b, float* Fout, bf16* Xout) {
;     ...
;     for (int r = 0; r < NR; ++r) { float q = 0.f; const float mu = mean[r];
; #pragma unroll
;         for (int j = 0; j < 8; ++j) { LN_X8(w[r][j], x); const float d0 = x0 - mu, d1 = x1 - mu, d2 = x2 - mu, d3 = x3 - mu, d4 = x4 - mu, d5 = x5 - mu, d6 = x6 - mu, d7 = x7 - mu;
;             q += ((d0 * d0 + d1 * d1) + (d2 * d2 + d3 * d3)) + ((d4 * d4 + d5 * d5) + (d6 * d6 + d7 * d7)); }
;         rstd[r] = q; }
	v_lshlrev_b32_e32 v49, 16, v75
	v_fmac_f32_e32 v32, 0xb9800000, v4
	v_fmac_f32_e32 v64, 0xb9800000, v4
	v_mul_f32_e32 v47, v47, v47
	v_and_b32_e32 v81, 0xffff0000, v76
	v_and_b32_e32 v96, 0xffff0000, v73
	v_fmac_f32_e32 v49, 0xb9800000, v4
	v_fmac_f32_e32 v47, v32, v32
	v_mul_f32_e32 v32, v64, v64
	v_lshlrev_b32_e32 v78, 16, v76
	v_lshlrev_b32_e32 v95, 16, v73
	v_fmac_f32_e32 v81, 0xb9800000, v4
	v_fmac_f32_e32 v96, 0xb9800000, v4
	v_fmac_f32_e32 v32, v49, v49
	v_fmac_f32_e32 v78, 0xb9800000, v4
	v_fmac_f32_e32 v95, 0xb9800000, v4
	v_add_f32_e32 v32, v47, v32
	v_mul_f32_e32 v47, v81, v81
	v_mul_f32_e32 v49, v96, v96
	v_fmac_f32_e32 v47, v78, v78
	v_fmac_f32_e32 v49, v95, v95
	v_add_f32_e32 v47, v47, v49
	v_add_f32_e32 v32, v32, v47
	v_and_b32_e32 v47, 0xffff0000, v54
	v_add_f32_e32 v30, v32, v30
	v_lshlrev_b32_e32 v32, 16, v54
	v_and_b32_e32 v64, 0xffff0000, v59
	v_fmac_f32_e32 v47, 0xb9800000, v4
	v_lshlrev_b32_e32 v49, 16, v59
	v_fmac_f32_e32 v32, 0xb9800000, v4
	v_fmac_f32_e32 v64, 0xb9800000, v4
	v_mul_f32_e32 v47, v47, v47
	v_and_b32_e32 v81, 0xffff0000, v74
	v_and_b32_e32 v96, 0xffff0000, v61
	v_fmac_f32_e32 v49, 0xb9800000, v4
	v_fmac_f32_e32 v47, v32, v32
	v_mul_f32_e32 v32, v64, v64
	v_lshlrev_b32_e32 v78, 16, v74
	v_lshlrev_b32_e32 v95, 16, v61
	v_fmac_f32_e32 v81, 0xb9800000, v4
	v_fmac_f32_e32 v96, 0xb9800000, v4
	v_fmac_f32_e32 v32, v49, v49
	v_fmac_f32_e32 v78, 0xb9800000, v4
	v_fmac_f32_e32 v95, 0xb9800000, v4
	v_add_f32_e32 v32, v47, v32
	v_mul_f32_e32 v47, v81, v81
	v_mul_f32_e32 v49, v96, v96
	v_fmac_f32_e32 v47, v78, v78
	v_fmac_f32_e32 v49, v95, v95
	v_add_f32_e32 v47, v47, v49
	v_add_f32_e32 v32, v32, v47
	v_and_b32_e32 v47, 0xffff0000, v42
	v_add_f32_e32 v30, v32, v30
	v_lshlrev_b32_e32 v32, 16, v42
	v_and_b32_e32 v64, 0xffff0000, v58
	v_fmac_f32_e32 v47, 0xb9800000, v4
	v_lshlrev_b32_e32 v49, 16, v58
	v_fmac_f32_e32 v32, 0xb9800000, v4
	v_fmac_f32_e32 v64, 0xb9800000, v4
	v_mul_f32_e32 v47, v47, v47
	v_and_b32_e32 v81, 0xffff0000, v44
	v_and_b32_e32 v96, 0xffff0000, v60
	v_fmac_f32_e32 v49, 0xb9800000, v4
	v_fmac_f32_e32 v47, v32, v32
	v_mul_f32_e32 v32, v64, v64
	v_lshlrev_b32_e32 v78, 16, v44
	v_lshlrev_b32_e32 v95, 16, v60
	v_fmac_f32_e32 v81, 0xb9800000, v4
	v_fmac_f32_e32 v96, 0xb9800000, v4
	v_fmac_f32_e32 v32, v49, v49
	v_fmac_f32_e32 v78, 0xb9800000, v4
	v_fmac_f32_e32 v95, 0xb9800000, v4
	v_add_f32_e32 v32, v47, v32
	v_mul_f32_e32 v47, v81, v81
	v_mul_f32_e32 v49, v96, v96
	v_fmac_f32_e32 v47, v78, v78
	v_fmac_f32_e32 v49, v95, v95
	v_add_f32_e32 v47, v47, v49
	v_add_f32_e32 v32, v32, v47
	v_and_b32_e32 v47, 0xffff0000, v39
	v_add_f32_e32 v30, v32, v30
	v_lshlrev_b32_e32 v32, 16, v39
	v_and_b32_e32 v64, 0xffff0000, v27
	v_fmac_f32_e32 v47, 0xb9800000, v4
	v_lshlrev_b32_e32 v49, 16, v27
	v_fmac_f32_e32 v32, 0xb9800000, v4
	v_fmac_f32_e32 v64, 0xb9800000, v4
	v_mul_f32_e32 v47, v47, v47
	v_and_b32_e32 v81, 0xffff0000, v28
	v_and_b32_e32 v96, 0xffff0000, v29
	v_fmac_f32_e32 v49, 0xb9800000, v4
	v_fmac_f32_e32 v47, v32, v32
	v_mul_f32_e32 v32, v64, v64
	v_lshlrev_b32_e32 v78, 16, v28
	v_lshlrev_b32_e32 v95, 16, v29
	v_fmac_f32_e32 v81, 0xb9800000, v4
	v_fmac_f32_e32 v96, 0xb9800000, v4
	v_fmac_f32_e32 v32, v49, v49
	v_fmac_f32_e32 v78, 0xb9800000, v4
	v_fmac_f32_e32 v95, 0xb9800000, v4
	v_add_f32_e32 v32, v47, v32
	v_mul_f32_e32 v47, v81, v81
	v_mul_f32_e32 v49, v96, v96
	v_fmac_f32_e32 v47, v78, v78
	v_fmac_f32_e32 v49, v95, v95
	v_add_f32_e32 v47, v47, v49
	v_add_f32_e32 v32, v32, v47
	v_and_b32_e32 v47, 0xffff0000, v18
	v_add_f32_e32 v30, v32, v30
	v_lshlrev_b32_e32 v32, 16, v18
	v_and_b32_e32 v64, 0xffff0000, v11
	v_fmac_f32_e32 v47, 0xb9800000, v4
	v_lshlrev_b32_e32 v49, 16, v11
	v_fmac_f32_e32 v32, 0xb9800000, v4
	v_fmac_f32_e32 v64, 0xb9800000, v4
	v_mul_f32_e32 v47, v47, v47
	v_and_b32_e32 v81, 0xffff0000, v12
	v_and_b32_e32 v96, 0xffff0000, v13
	v_fmac_f32_e32 v49, 0xb9800000, v4
	v_fmac_f32_e32 v47, v32, v32
	v_mul_f32_e32 v32, v64, v64
	v_lshlrev_b32_e32 v78, 16, v12
	v_lshlrev_b32_e32 v95, 16, v13
	v_fmac_f32_e32 v81, 0xb9800000, v4
	v_fmac_f32_e32 v96, 0xb9800000, v4
	v_fmac_f32_e32 v32, v49, v49
	v_fmac_f32_e32 v78, 0xb9800000, v4
	v_fmac_f32_e32 v95, 0xb9800000, v4
	v_add_f32_e32 v32, v47, v32
	v_mul_f32_e32 v47, v81, v81
	v_mul_f32_e32 v49, v96, v96
	v_fmac_f32_e32 v47, v78, v78
	v_fmac_f32_e32 v49, v95, v95
	v_add_f32_e32 v47, v47, v49
	v_add_f32_e32 v32, v32, v47
	v_and_b32_e32 v47, 0xffff0000, v114
	v_add_f32_e32 v30, v32, v30
	v_lshlrev_b32_e32 v32, 16, v114
	v_and_b32_e32 v64, 0xffff0000, v115
	v_fmac_f32_e32 v47, 0xb9800000, v6
	v_lshlrev_b32_e32 v49, 16, v115
	v_fmac_f32_e32 v32, 0xb9800000, v6
	v_fmac_f32_e32 v64, 0xb9800000, v6
	v_mul_f32_e32 v47, v47, v47
	v_and_b32_e32 v81, 0xffff0000, v116
	v_and_b32_e32 v96, 0xffff0000, v117
	v_fmac_f32_e32 v49, 0xb9800000, v6
	v_fmac_f32_e32 v47, v32, v32
	v_mul_f32_e32 v32, v64, v64
	v_lshlrev_b32_e32 v78, 16, v116
	v_lshlrev_b32_e32 v95, 16, v117
	v_fmac_f32_e32 v81, 0xb9800000, v6
	v_fmac_f32_e32 v96, 0xb9800000, v6
	v_fmac_f32_e32 v32, v49, v49
	v_fmac_f32_e32 v78, 0xb9800000, v6
	v_fmac_f32_e32 v95, 0xb9800000, v6
	v_add_f32_e32 v32, v47, v32
	v_mul_f32_e32 v47, v81, v81
	v_mul_f32_e32 v49, v96, v96
	v_mov_b32_e32 v108, v110
	v_mov_b32_e32 v110, v112
	v_fmac_f32_e32 v47, v78, v78
	v_fmac_f32_e32 v49, v95, v95
	v_add_f32_e32 v47, v47, v49
	v_and_b32_e32 v49, 0xffff0000, v108
	v_add_f32_e32 v32, v32, v47
	v_lshlrev_b32_e32 v47, 16, v108
	v_and_b32_e32 v78, 0xffff0000, v111
	v_fmac_f32_e32 v49, 0xb9800000, v6
	v_lshlrev_b32_e32 v64, 16, v111
	v_fmac_f32_e32 v47, 0xb9800000, v6
	v_fmac_f32_e32 v78, 0xb9800000, v6
	v_mul_f32_e32 v49, v49, v49
; #define LN_X8(W, x) const float x##0 = bflo(W.x), x##1 = bfhi(W.x), x##2 = bflo(W.y), x##3 = bfhi(W.y), x##4 = bflo(W.z), x##5 = bfhi(W.z), x##6 = bflo(W.w), x##7 = bfhi(W.w)
; template <int NR>
; __device__ __forceinline__ void ln_rows(int lane, const bf16* Z, size_t rstride, const float* g, const float* b, float* Fout, bf16* Xout) {
;     ...
;     for (int r = 0; r < NR; ++r) { float q = 0.f; const float mu = mean[r];
; #pragma unroll
;         for (int j = 0; j < 8; ++j) { LN_X8(w[r][j], x); const float d0 = x0 - mu, d1 = x1 - mu, d2 = x2 - mu, d3 = x3 - mu, d4 = x4 - mu, d5 = x5 - mu, d6 = x6 - mu, d7 = x7 - mu;
;             q += ((d0 * d0 + d1 * d1) + (d2 * d2 + d3 * d3)) + ((d4 * d4 + d5 * d5) + (d6 * d6 + d7 * d7)); }
;         rstd[r] = q; }
	v_and_b32_e32 v95, 0xffff0000, v110
	v_and_b32_e32 v112, 0xffff0000, v113
	v_fmac_f32_e32 v64, 0xb9800000, v6
	v_fmac_f32_e32 v49, v47, v47
	v_mul_f32_e32 v47, v78, v78
	v_lshlrev_b32_e32 v81, 16, v110
	v_lshlrev_b32_e32 v96, 16, v113
	v_fmac_f32_e32 v95, 0xb9800000, v6
	v_fmac_f32_e32 v112, 0xb9800000, v6
	v_fmac_f32_e32 v47, v64, v64
	v_fmac_f32_e32 v81, 0xb9800000, v6
	v_fmac_f32_e32 v96, 0xb9800000, v6
	v_add_f32_e32 v47, v49, v47
	v_mul_f32_e32 v49, v95, v95
	v_mul_f32_e32 v64, v112, v112
	v_fmac_f32_e32 v49, v81, v81
	v_fmac_f32_e32 v64, v96, v96
	v_add_f32_e32 v49, v49, v64
	v_add_f32_e32 v47, v47, v49
	v_and_b32_e32 v49, 0xffff0000, v94
	v_add_f32_e32 v32, v32, v47
	v_lshlrev_b32_e32 v47, 16, v94
	v_and_b32_e32 v78, 0xffff0000, v77
	v_fmac_f32_e32 v49, 0xb9800000, v6
	v_lshlrev_b32_e32 v64, 16, v77
	v_fmac_f32_e32 v47, 0xb9800000, v6
	v_fmac_f32_e32 v78, 0xb9800000, v6
	v_mul_f32_e32 v49, v49, v49
	v_and_b32_e32 v95, 0xffff0000, v91
	v_and_b32_e32 v112, 0xffff0000, v97
	v_fmac_f32_e32 v64, 0xb9800000, v6
	v_fmac_f32_e32 v49, v47, v47
	v_mul_f32_e32 v47, v78, v78
	v_lshlrev_b32_e32 v81, 16, v91
	v_lshlrev_b32_e32 v96, 16, v97
	v_fmac_f32_e32 v95, 0xb9800000, v6
	v_fmac_f32_e32 v112, 0xb9800000, v6
	v_fmac_f32_e32 v47, v64, v64
	v_fmac_f32_e32 v81, 0xb9800000, v6
	v_fmac_f32_e32 v96, 0xb9800000, v6
	v_add_f32_e32 v47, v49, v47
	v_mul_f32_e32 v49, v95, v95
	v_mul_f32_e32 v64, v112, v112
	v_fmac_f32_e32 v49, v81, v81
	v_fmac_f32_e32 v64, v96, v96
	v_add_f32_e32 v49, v49, v64
	v_add_f32_e32 v47, v47, v49
	v_and_b32_e32 v49, 0xffff0000, v66
	v_add_f32_e32 v32, v47, v32
	v_lshlrev_b32_e32 v47, 16, v66
	v_and_b32_e32 v78, 0xffff0000, v79
	v_fmac_f32_e32 v49, 0xb9800000, v6
	v_lshlrev_b32_e32 v64, 16, v79
	v_fmac_f32_e32 v47, 0xb9800000, v6
	v_fmac_f32_e32 v78, 0xb9800000, v6
	v_mul_f32_e32 v49, v49, v49
	v_and_b32_e32 v95, 0xffff0000, v80
	v_and_b32_e32 v112, 0xffff0000, v69
	v_fmac_f32_e32 v64, 0xb9800000, v6
	v_fmac_f32_e32 v49, v47, v47
	v_mul_f32_e32 v47, v78, v78
	v_lshlrev_b32_e32 v81, 16, v80
	v_lshlrev_b32_e32 v96, 16, v69
	v_fmac_f32_e32 v95, 0xb9800000, v6
	v_fmac_f32_e32 v112, 0xb9800000, v6
	v_fmac_f32_e32 v47, v64, v64
	v_fmac_f32_e32 v81, 0xb9800000, v6
	v_fmac_f32_e32 v96, 0xb9800000, v6
	v_add_f32_e32 v47, v49, v47
	v_mul_f32_e32 v49, v95, v95
	v_mul_f32_e32 v64, v112, v112
	v_fmac_f32_e32 v49, v81, v81
	v_fmac_f32_e32 v64, v96, v96
	v_add_f32_e32 v49, v49, v64
	v_add_f32_e32 v47, v47, v49
	v_and_b32_e32 v49, 0xffff0000, v56
	v_add_f32_e32 v32, v47, v32
	v_lshlrev_b32_e32 v47, 16, v56
	v_and_b32_e32 v78, 0xffff0000, v63
	v_fmac_f32_e32 v49, 0xb9800000, v6
	v_lshlrev_b32_e32 v64, 16, v63
	v_fmac_f32_e32 v47, 0xb9800000, v6
	v_fmac_f32_e32 v78, 0xb9800000, v6
	v_mul_f32_e32 v49, v49, v49
	v_and_b32_e32 v95, 0xffff0000, v62
	v_and_b32_e32 v112, 0xffff0000, v65
	v_fmac_f32_e32 v64, 0xb9800000, v6
	v_fmac_f32_e32 v49, v47, v47
	v_mul_f32_e32 v47, v78, v78
	v_lshlrev_b32_e32 v81, 16, v62
	v_lshlrev_b32_e32 v96, 16, v65
	v_fmac_f32_e32 v95, 0xb9800000, v6
	v_fmac_f32_e32 v112, 0xb9800000, v6
	v_fmac_f32_e32 v47, v64, v64
	v_fmac_f32_e32 v81, 0xb9800000, v6
	v_fmac_f32_e32 v96, 0xb9800000, v6
	v_add_f32_e32 v47, v49, v47
	v_mul_f32_e32 v49, v95, v95
	v_mul_f32_e32 v64, v112, v112
	v_fmac_f32_e32 v49, v81, v81
	v_fmac_f32_e32 v64, v96, v96
	v_add_f32_e32 v49, v49, v64
	v_add_f32_e32 v47, v47, v49
	v_and_b32_e32 v49, 0xffff0000, v46
	v_add_f32_e32 v32, v47, v32
	v_lshlrev_b32_e32 v47, 16, v46
	v_and_b32_e32 v78, 0xffff0000, v43
	v_fmac_f32_e32 v49, 0xb9800000, v6
	v_lshlrev_b32_e32 v64, 16, v43
	v_fmac_f32_e32 v47, 0xb9800000, v6
	v_fmac_f32_e32 v78, 0xb9800000, v6
	v_mul_f32_e32 v49, v49, v49
	v_and_b32_e32 v95, 0xffff0000, v48
	v_and_b32_e32 v112, 0xffff0000, v45
	v_fmac_f32_e32 v64, 0xb9800000, v6
	v_fmac_f32_e32 v49, v47, v47
	v_mul_f32_e32 v47, v78, v78
	v_lshlrev_b32_e32 v81, 16, v48
	v_lshlrev_b32_e32 v96, 16, v45
	v_fmac_f32_e32 v95, 0xb9800000, v6
	v_fmac_f32_e32 v112, 0xb9800000, v6
	v_fmac_f32_e32 v47, v64, v64
	v_fmac_f32_e32 v81, 0xb9800000, v6
	v_fmac_f32_e32 v96, 0xb9800000, v6
	v_add_f32_e32 v47, v49, v47
	v_mul_f32_e32 v49, v95, v95
	v_mul_f32_e32 v64, v112, v112
	v_fmac_f32_e32 v49, v81, v81
	v_fmac_f32_e32 v64, v96, v96
	v_add_f32_e32 v49, v49, v64
	v_add_f32_e32 v47, v47, v49
	v_and_b32_e32 v49, 0xffff0000, v24
	v_add_f32_e32 v32, v47, v32
	v_lshlrev_b32_e32 v47, 16, v24
	v_and_b32_e32 v78, 0xffff0000, v31
	v_fmac_f32_e32 v49, 0xb9800000, v6
	v_lshlrev_b32_e32 v64, 16, v31
	v_fmac_f32_e32 v47, 0xb9800000, v6
	v_fmac_f32_e32 v78, 0xb9800000, v6
	v_mul_f32_e32 v49, v49, v49
	v_and_b32_e32 v95, 0xffff0000, v26
	v_and_b32_e32 v112, 0xffff0000, v33
	v_fmac_f32_e32 v64, 0xb9800000, v6
	v_fmac_f32_e32 v49, v47, v47
	v_mul_f32_e32 v47, v78, v78
	v_lshlrev_b32_e32 v81, 16, v26
	v_lshlrev_b32_e32 v96, 16, v33
	v_fmac_f32_e32 v95, 0xb9800000, v6
	v_fmac_f32_e32 v112, 0xb9800000, v6
	v_fmac_f32_e32 v47, v64, v64
	v_fmac_f32_e32 v81, 0xb9800000, v6
	v_fmac_f32_e32 v96, 0xb9800000, v6
	v_add_f32_e32 v47, v49, v47
	v_mul_f32_e32 v49, v95, v95
	v_mul_f32_e32 v64, v112, v112
	v_fmac_f32_e32 v49, v81, v81
	v_fmac_f32_e32 v64, v96, v96
	v_add_f32_e32 v49, v49, v64
	v_add_f32_e32 v47, v47, v49
	v_and_b32_e32 v49, 0xffff0000, v8
	v_add_f32_e32 v32, v47, v32
	v_lshlrev_b32_e32 v47, 16, v8
	v_and_b32_e32 v78, 0xffff0000, v15
	v_fmac_f32_e32 v49, 0xb9800000, v6
	v_lshlrev_b32_e32 v64, 16, v15
	v_fmac_f32_e32 v47, 0xb9800000, v6
	v_fmac_f32_e32 v78, 0xb9800000, v6
	v_mul_f32_e32 v49, v49, v49
	v_and_b32_e32 v95, 0xffff0000, v10
	v_and_b32_e32 v112, 0xffff0000, v17
	v_fmac_f32_e32 v64, 0xb9800000, v6
	v_fmac_f32_e32 v49, v47, v47
; #define GAS __attribute__((address_space(1)))
; #define LN_X8(W, x) const float x##0 = bflo(W.x), x##1 = bfhi(W.x), x##2 = bflo(W.y), x##3 = bfhi(W.y), x##4 = bflo(W.z), x##5 = bfhi(W.z), x##6 = bflo(W.w), x##7 = bfhi(W.w)
; #define LN_OPAQUE() do { _Pragma("unroll") for (int r = 0; r < NR; ++r) _Pragma("unroll") for (int j = 0; j < 8; ++j) asm volatile("" : "+v"(w[r][j].x), "+v"(w[r][j].y), "+v"(w[r][j].z), "+v"(w[r][j].w)); } while (0)
; template <int NR>
; __device__ __forceinline__ void ln_rows(int lane, const bf16* Z, size_t rstride, const float* g, const float* b, float* Fout, bf16* Xout) {
;     ...
;     LN_OPAQUE();
; #pragma unroll
;     for (int r = 0; r < NR; ++r) rstd[r] = 1.f / sqrtf(wave_sum(rstd[r]) * (1.f / DM) + LN_EPS);
;     const GAS f32x4* gr = (const GAS f32x4*)g + 2 * lane; const GAS f32x4* br = (const GAS f32x4*)b + 2 * lane;
; #pragma unroll
;     for (int j = 0; j < 8; ++j) { const f32x4 g0 = gr[128 * j], g1 = gr[128 * j + 1], b0 = br[128 * j], b1 = br[128 * j + 1];
; #pragma unroll
;         for (int r = 0; r < NR; ++r) { const float mu = mean[r], rs = rstd[r]; LN_X8(w[r][j], x);
;             const f32x4 o0 = (f32x4){(x0 - mu) * rs, (x1 - mu) * rs, (x2 - mu) * rs, (x3 - mu) * rs} * g0 + b0, o1 = (f32x4){(x4 - mu) * rs, (x5 - mu) * rs, (x6 - mu) * rs, (x7 - mu) * rs} * g1 + b1;
	v_mul_f32_e32 v47, v78, v78
	v_lshlrev_b32_e32 v81, 16, v10
	v_lshlrev_b32_e32 v96, 16, v17
	v_fmac_f32_e32 v95, 0xb9800000, v6
	v_fmac_f32_e32 v112, 0xb9800000, v6
	v_fmac_f32_e32 v47, v64, v64
	v_fmac_f32_e32 v81, 0xb9800000, v6
	v_fmac_f32_e32 v96, 0xb9800000, v6
	v_add_f32_e32 v47, v49, v47
	v_mul_f32_e32 v49, v95, v95
	v_mul_f32_e32 v64, v112, v112
	v_add_f32_dpp v14, v14, v14 quad_perm:[1,0,3,2] row_mask:0xf bank_mask:0xf bound_ctrl:1
	v_fmac_f32_e32 v49, v81, v81
	v_fmac_f32_e32 v64, v96, v96
	v_add_f32_dpp v14, v14, v14 quad_perm:[2,3,0,1] row_mask:0xf bank_mask:0xf bound_ctrl:1
	v_add_f32_e32 v49, v49, v64
	v_add_f32_e32 v47, v47, v49
	v_add_f32_dpp v14, v14, v14 row_half_mirror row_mask:0xf bank_mask:0xf bound_ctrl:1
	v_add_f32_e32 v32, v47, v32
	s_andn2_b64 vcc, exec, s[54:55]
	v_add_f32_dpp v14, v14, v14 row_mirror row_mask:0xf bank_mask:0xf bound_ctrl:1
	v_mov_b32_e32 v47, v14
	s_nop 1
	v_permlane16_swap_b32_e32 v14, v47
	v_add_f32_e32 v47, v14, v47
	s_nop 0
	v_add_f32_dpp v14, v16, v16 quad_perm:[1,0,3,2] row_mask:0xf bank_mask:0xf bound_ctrl:1
	v_mov_b32_e32 v49, v47
	s_nop 1
	v_permlane32_swap_b32_e32 v47, v49
	v_add_f32_dpp v14, v14, v14 quad_perm:[2,3,0,1] row_mask:0xf bank_mask:0xf bound_ctrl:1
	s_nop 1
	v_add_f32_dpp v14, v14, v14 row_half_mirror row_mask:0xf bank_mask:0xf bound_ctrl:1
	s_nop 1
	v_add_f32_dpp v14, v14, v14 row_mirror row_mask:0xf bank_mask:0xf bound_ctrl:1
	v_mov_b32_e32 v16, v14
	s_nop 1
	v_permlane16_swap_b32_e32 v14, v16
	v_add_f32_e32 v64, v14, v16
	s_nop 0
	v_add_f32_dpp v14, v30, v30 quad_perm:[1,0,3,2] row_mask:0xf bank_mask:0xf bound_ctrl:1
	v_mov_b32_e32 v78, v64
	s_nop 1
	v_permlane32_swap_b32_e32 v64, v78
	v_add_f32_dpp v14, v14, v14 quad_perm:[2,3,0,1] row_mask:0xf bank_mask:0xf bound_ctrl:1
	s_nop 1
	v_add_f32_dpp v14, v14, v14 row_half_mirror row_mask:0xf bank_mask:0xf bound_ctrl:1
	s_nop 1
	v_add_f32_dpp v14, v14, v14 row_mirror row_mask:0xf bank_mask:0xf bound_ctrl:1
	v_mov_b32_e32 v16, v14
	s_nop 1
	v_permlane16_swap_b32_e32 v14, v16
	v_add_f32_e32 v81, v14, v16
	s_nop 0
	v_add_f32_dpp v14, v32, v32 quad_perm:[1,0,3,2] row_mask:0xf bank_mask:0xf bound_ctrl:1
	v_mov_b32_e32 v95, v81
	s_nop 1
	v_permlane32_swap_b32_e32 v81, v95
	v_add_f32_dpp v14, v14, v14 quad_perm:[2,3,0,1] row_mask:0xf bank_mask:0xf bound_ctrl:1
	s_nop 1
	v_add_f32_dpp v14, v14, v14 row_half_mirror row_mask:0xf bank_mask:0xf bound_ctrl:1
	s_nop 1
	v_add_f32_dpp v14, v14, v14 row_mirror row_mask:0xf bank_mask:0xf bound_ctrl:1
	v_mov_b32_e32 v16, v14
	s_nop 1
	v_permlane16_swap_b32_e32 v14, v16
	v_add_f32_e32 v96, v14, v16
	v_mov_b32_e32 v112, v96
	s_nop 1
	v_permlane32_swap_b32_e32 v96, v112
	s_cbranch_vccnz .LBB0_1011
	v_mul_f32_e32 v32, 0x39800000, v0
	v_add_f32_e32 v0, v96, v112
	v_fmamk_f32 v0, v0, 0x39800000, v233
	s_mov_b32 s24, 0xf800000
	v_mul_f32_e32 v30, 0x39800000, v2
	v_cmp_gt_f32_e32 vcc, s24, v0
	v_mul_f32_e32 v2, 0x4f800000, v0
	v_mul_f32_e32 v16, 0x39800000, v4
	v_cndmask_b32_e32 v0, v0, v2, vcc
	v_sqrt_f32_e32 v2, v0
	v_mul_f32_e32 v14, 0x39800000, v6
	global_load_dwordx4 v[130:133], v[150:151], off
	global_load_dwordx4 v[138:141], v[150:151], off offset:16
	global_load_dwordx4 v[134:137], v[148:149], off
	global_load_dwordx4 v[142:145], v[148:149], off offset:16
	v_add_u32_e32 v4, -1, v2
	v_fma_f32 v6, -v4, v2, v0
	v_cmp_ge_f32_e64 s[42:43], 0, v6
	v_add_u32_e32 v6, 1, v2
	s_nop 0
	v_cndmask_b32_e64 v4, v2, v4, s[42:43]
	v_fma_f32 v2, -v6, v2, v0
	v_cmp_lt_f32_e64 s[42:43], 0, v2
	s_nop 1
	v_cndmask_b32_e64 v2, v4, v6, s[42:43]
	v_mul_f32_e32 v4, 0x37800000, v2
	v_cndmask_b32_e32 v2, v2, v4, vcc
	v_cmp_class_f32_e32 vcc, v0, v238
	s_nop 1
	v_cndmask_b32_e32 v0, v2, v0, vcc
	v_div_scale_f32 v2, s[26:27], v0, v0, 1.0
	v_rcp_f32_e32 v4, v2
	s_nop 0
	v_fma_f32 v6, -v2, v4, 1.0
	v_fmac_f32_e32 v4, v6, v4
	v_div_scale_f32 v6, vcc, 1.0, v0, 1.0
	v_mul_f32_e32 v96, v6, v4
	v_fma_f32 v112, -v2, v96, v6
	v_fmac_f32_e32 v96, v112, v4
	v_fma_f32 v2, -v2, v96, v6
	v_div_fmas_f32 v2, v2, v4, v96
	v_div_fixup_f32 v0, v2, v0, 1.0
	v_add_f32_e32 v2, v81, v95
	v_fmamk_f32 v2, v2, 0x39800000, v233
	v_cmp_gt_f32_e32 vcc, s24, v2
	v_mul_f32_e32 v4, 0x4f800000, v2
	s_nop 0
	v_cndmask_b32_e32 v2, v2, v4, vcc
	v_sqrt_f32_e32 v4, v2
	s_nop 0
	v_add_u32_e32 v6, -1, v4
	v_fma_f32 v81, -v6, v4, v2
	v_cmp_ge_f32_e64 s[42:43], 0, v81
	v_add_u32_e32 v81, 1, v4
	s_nop 0
	v_cndmask_b32_e64 v6, v4, v6, s[42:43]
	v_fma_f32 v4, -v81, v4, v2
	v_cmp_lt_f32_e64 s[42:43], 0, v4
	s_nop 1
	v_cndmask_b32_e64 v4, v6, v81, s[42:43]
	v_mul_f32_e32 v6, 0x37800000, v4
	v_cndmask_b32_e32 v4, v4, v6, vcc
	v_cmp_class_f32_e32 vcc, v2, v238
	s_nop 1
	v_cndmask_b32_e32 v2, v4, v2, vcc
	v_div_scale_f32 v4, s[26:27], v2, v2, 1.0
	v_rcp_f32_e32 v6, v4
	s_nop 0
	v_fma_f32 v81, -v4, v6, 1.0
	v_fmac_f32_e32 v6, v81, v6
	v_div_scale_f32 v81, vcc, 1.0, v2, 1.0
	v_mul_f32_e32 v95, v81, v6
	v_fma_f32 v96, -v4, v95, v81
	v_fmac_f32_e32 v95, v96, v6
	v_fma_f32 v4, -v4, v95, v81
	v_div_fmas_f32 v4, v4, v6, v95
	v_div_fixup_f32 v2, v4, v2, 1.0
	v_add_f32_e32 v4, v64, v78
	v_fmamk_f32 v4, v4, 0x39800000, v233
	v_cmp_gt_f32_e32 vcc, s24, v4
	v_mul_f32_e32 v6, 0x4f800000, v4
	s_nop 0
	v_cndmask_b32_e32 v4, v4, v6, vcc
	v_sqrt_f32_e32 v6, v4
	s_nop 0
	v_add_u32_e32 v64, -1, v6
	v_fma_f32 v78, -v64, v6, v4
	v_cmp_ge_f32_e64 s[42:43], 0, v78
	v_add_u32_e32 v78, 1, v6
	s_nop 0
	v_cndmask_b32_e64 v64, v6, v64, s[42:43]
	v_fma_f32 v6, -v78, v6, v4
	v_cmp_lt_f32_e64 s[42:43], 0, v6
	s_nop 1
	v_cndmask_b32_e64 v6, v64, v78, s[42:43]
	v_mul_f32_e32 v64, 0x37800000, v6
	v_cndmask_b32_e32 v6, v6, v64, vcc
	v_cmp_class_f32_e32 vcc, v4, v238
	s_nop 1
	v_cndmask_b32_e32 v4, v6, v4, vcc
; #define GAS __attribute__((address_space(1)))
; __device__ __forceinline__ unsigned pk2(float lo, float hi) { return f2bf(lo) | (f2bf(hi) << 16); }
; #define LN_X8(W, x) const float x##0 = bflo(W.x), x##1 = bfhi(W.x), x##2 = bflo(W.y), x##3 = bfhi(W.y), x##4 = bflo(W.z), x##5 = bfhi(W.z), x##6 = bflo(W.w), x##7 = bfhi(W.w)
; template <int NR>
; __device__ __forceinline__ void ln_rows(int lane, const bf16* Z, size_t rstride, const float* g, const float* b, float* Fout, bf16* Xout) {
;     ...
;     for (int j = 0; j < 8; ++j) { const f32x4 g0 = gr[128 * j], g1 = gr[128 * j + 1], b0 = br[128 * j], b1 = br[128 * j + 1];
; #pragma unroll
;         for (int r = 0; r < NR; ++r) { const float mu = mean[r], rs = rstd[r]; LN_X8(w[r][j], x);
;             const f32x4 o0 = (f32x4){(x0 - mu) * rs, (x1 - mu) * rs, (x2 - mu) * rs, (x3 - mu) * rs} * g0 + b0, o1 = (f32x4){(x4 - mu) * rs, (x5 - mu) * rs, (x6 - mu) * rs, (x7 - mu) * rs} * g1 + b1;
;             if (Fout) { GAS f32x4* fo = (GAS f32x4*)(Fout + r * rstride) + 2 * lane + 128 * j; fo[0] = o0; fo[1] = o1; }
;             if (Xout) { v4u ow; ow.x = pk2(o0.x, o0.y); ow.y = pk2(o0.z, o0.w); ow.z = pk2(o1.x, o1.y); ow.w = pk2(o1.z, o1.w); ((GAS v4u*)(Xout + r * rstride) + lane)[64 * j] = ow; } } }
	v_div_scale_f32 v6, s[26:27], v4, v4, 1.0
	v_rcp_f32_e32 v64, v6
	s_nop 0
	v_fma_f32 v78, -v6, v64, 1.0
	v_fmac_f32_e32 v64, v78, v64
	v_div_scale_f32 v78, vcc, 1.0, v4, 1.0
	v_mul_f32_e32 v81, v78, v64
	v_fma_f32 v95, -v6, v81, v78
	v_fmac_f32_e32 v81, v95, v64
	v_fma_f32 v6, -v6, v81, v78
	v_div_fmas_f32 v6, v6, v64, v81
	v_div_fixup_f32 v4, v6, v4, 1.0
	v_add_f32_e32 v6, v47, v49
	v_fmamk_f32 v6, v6, 0x39800000, v233
	v_cmp_gt_f32_e32 vcc, s24, v6
	v_mul_f32_e32 v47, 0x4f800000, v6
	s_nop 0
	v_cndmask_b32_e32 v6, v6, v47, vcc
	v_sqrt_f32_e32 v47, v6
	s_nop 0
	v_add_u32_e32 v49, -1, v47
	v_fma_f32 v64, -v49, v47, v6
	v_cmp_ge_f32_e64 s[42:43], 0, v64
	v_add_u32_e32 v64, 1, v47
	s_nop 0
	v_cndmask_b32_e64 v49, v47, v49, s[42:43]
	v_fma_f32 v47, -v64, v47, v6
	v_cmp_lt_f32_e64 s[42:43], 0, v47
	s_nop 1
	v_cndmask_b32_e64 v47, v49, v64, s[42:43]
	v_mul_f32_e32 v49, 0x37800000, v47
	v_cndmask_b32_e32 v47, v47, v49, vcc
	v_cmp_class_f32_e32 vcc, v6, v238
	s_nop 1
	v_cndmask_b32_e32 v6, v47, v6, vcc
	v_div_scale_f32 v47, s[26:27], v6, v6, 1.0
	v_rcp_f32_e32 v49, v47
	s_add_u32 s26, s60, s56
	s_addc_u32 s27, s61, s57
	v_fma_f32 v64, -v47, v49, 1.0
	v_fmac_f32_e32 v49, v64, v49
	v_div_scale_f32 v64, vcc, 1.0, v6, 1.0
	v_mul_f32_e32 v78, v64, v49
	v_fma_f32 v81, -v47, v78, v64
	v_fmac_f32_e32 v78, v81, v49
	v_fma_f32 v47, -v47, v78, v64
	v_div_fmas_f32 v47, v47, v49, v78
	v_lshlrev_b32_e32 v64, 16, v192
	v_and_b32_e32 v78, 0xffff0000, v192
	v_div_fixup_f32 v6, v47, v6, 1.0
	v_lshlrev_b32_e32 v47, 16, v128
	v_and_b32_e32 v49, 0xffff0000, v128
	v_sub_f32_e32 v193, v78, v32
	v_sub_f32_e32 v192, v64, v32
	v_sub_f32_e32 v195, v49, v32
	v_sub_f32_e32 v194, v47, v32
	v_pk_mul_f32 v[192:193], v[192:193], v[6:7] op_sel_hi:[1,0]
	v_lshlrev_b32_e32 v47, 16, v126
	v_and_b32_e32 v49, 0xffff0000, v126
	s_waitcnt vmcnt(0)
	v_pk_fma_f32 v[196:197], v[192:193], v[144:145], v[140:141]
	v_sub_f32_e32 v193, v49, v32
	v_sub_f32_e32 v192, v47, v32
	v_pk_mul_f32 v[192:193], v[192:193], v[6:7] op_sel_hi:[1,0]
	v_lshlrev_b32_e32 v64, 16, v127
	v_and_b32_e32 v78, 0xffff0000, v127
	v_pk_fma_f32 v[192:193], v[192:193], v[134:135], v[130:131]
	v_sub_f32_e32 v127, v78, v32
	v_sub_f32_e32 v126, v64, v32
	v_pk_mul_f32 v[126:127], v[126:127], v[6:7] op_sel_hi:[1,0]
	v_pk_fma_f32 v[126:127], v[126:127], v[136:137], v[132:133]
	v_cvt_pk_bf16_f32 v192, v192, v193
	v_pk_mul_f32 v[194:195], v[194:195], v[6:7] op_sel_hi:[1,0]
	v_pk_fma_f32 v[194:195], v[194:195], v[142:143], v[138:139]
	v_cvt_pk_bf16_f32 v193, v126, v127
	v_cvt_pk_bf16_f32 v194, v194, v195
	v_cvt_pk_bf16_f32 v195, v196, v197
	v_lshl_add_u64 v[126:127], s[26:27], 0, v[176:177]
	v_lshlrev_b32_e32 v64, 16, v191
	v_and_b32_e32 v78, 0xffff0000, v191
	global_store_dwordx4 v[126:127], v[192:195], off
	v_lshlrev_b32_e32 v47, 16, v124
	v_and_b32_e32 v49, 0xffff0000, v124
	v_sub_f32_e32 v193, v78, v30
	v_sub_f32_e32 v192, v64, v30
	v_sub_f32_e32 v195, v49, v30
	v_sub_f32_e32 v194, v47, v30
	v_pk_mul_f32 v[192:193], v[192:193], v[4:5] op_sel_hi:[1,0]
	v_lshlrev_b32_e32 v47, 16, v122
	v_and_b32_e32 v49, 0xffff0000, v122
	v_pk_fma_f32 v[196:197], v[192:193], v[144:145], v[140:141]
	v_sub_f32_e32 v193, v49, v30
	v_sub_f32_e32 v192, v47, v30
	v_pk_mul_f32 v[192:193], v[192:193], v[4:5] op_sel_hi:[1,0]
	v_lshlrev_b32_e32 v64, 16, v123
	v_and_b32_e32 v78, 0xffff0000, v123
	v_pk_fma_f32 v[192:193], v[192:193], v[134:135], v[130:131]
	v_sub_f32_e32 v123, v78, v30
	v_sub_f32_e32 v122, v64, v30
	v_pk_mul_f32 v[122:123], v[122:123], v[4:5] op_sel_hi:[1,0]
	v_pk_fma_f32 v[122:123], v[122:123], v[136:137], v[132:133]
	v_cvt_pk_bf16_f32 v192, v192, v193
	v_pk_mul_f32 v[194:195], v[194:195], v[4:5] op_sel_hi:[1,0]
	v_pk_fma_f32 v[194:195], v[194:195], v[142:143], v[138:139]
	v_cvt_pk_bf16_f32 v193, v122, v123
	v_cvt_pk_bf16_f32 v194, v194, v195
	s_add_u32 s26, s20, s56
	s_addc_u32 s27, s28, s57
	v_lshlrev_b32_e32 v64, 16, v190
	v_and_b32_e32 v78, 0xffff0000, v190
	v_cvt_pk_bf16_f32 v195, v196, v197
	v_lshl_add_u64 v[122:123], s[26:27], 0, v[176:177]
	v_lshlrev_b32_e32 v47, 16, v120
	v_and_b32_e32 v49, 0xffff0000, v120
	v_sub_f32_e32 v191, v78, v16
	v_sub_f32_e32 v190, v64, v16
	global_store_dwordx4 v[122:123], v[192:195], off
	v_pk_mul_f32 v[190:191], v[190:191], v[2:3] op_sel_hi:[1,0]
	v_lshlrev_b32_e32 v64, 16, v119
	v_sub_f32_e32 v193, v49, v16
	v_sub_f32_e32 v192, v47, v16
	v_lshlrev_b32_e32 v47, 16, v118
	v_and_b32_e32 v49, 0xffff0000, v118
	v_pk_fma_f32 v[194:195], v[144:145], v[190:191], v[140:141]
	v_sub_f32_e32 v191, v49, v16
	v_sub_f32_e32 v190, v47, v16
	v_pk_mul_f32 v[190:191], v[190:191], v[2:3] op_sel_hi:[1,0]
	v_and_b32_e32 v78, 0xffff0000, v119
	v_pk_fma_f32 v[190:191], v[134:135], v[190:191], v[130:131]
	v_sub_f32_e32 v119, v78, v16
	v_sub_f32_e32 v118, v64, v16
	v_pk_mul_f32 v[118:119], v[118:119], v[2:3] op_sel_hi:[1,0]
	v_pk_fma_f32 v[118:119], v[136:137], v[118:119], v[132:133]
	v_cvt_pk_bf16_f32 v190, v190, v191
	v_pk_mul_f32 v[192:193], v[192:193], v[2:3] op_sel_hi:[1,0]
	v_pk_fma_f32 v[192:193], v[142:143], v[192:193], v[138:139]
	v_cvt_pk_bf16_f32 v191, v118, v119
	v_cvt_pk_bf16_f32 v192, v192, v193
	s_add_u32 s26, s14, s56
	s_addc_u32 s27, s15, s57
	v_lshlrev_b32_e32 v64, 16, v117
	v_and_b32_e32 v78, 0xffff0000, v117
	v_cvt_pk_bf16_f32 v193, v194, v195
	v_lshl_add_u64 v[118:119], s[26:27], 0, v[176:177]
	v_lshlrev_b32_e32 v47, 16, v116
	v_and_b32_e32 v49, 0xffff0000, v116
	v_sub_f32_e32 v117, v78, v14
	v_sub_f32_e32 v116, v64, v14
	global_store_dwordx4 v[118:119], v[190:193], off
	v_pk_mul_f32 v[116:117], v[116:117], v[0:1] op_sel_hi:[1,0]
	v_lshlrev_b32_e32 v64, 16, v115
	v_sub_f32_e32 v191, v49, v14
; #define GAS __attribute__((address_space(1)))
; __device__ __forceinline__ unsigned pk2(float lo, float hi) { return f2bf(lo) | (f2bf(hi) << 16); }
; #define LN_X8(W, x) const float x##0 = bflo(W.x), x##1 = bfhi(W.x), x##2 = bflo(W.y), x##3 = bfhi(W.y), x##4 = bflo(W.z), x##5 = bfhi(W.z), x##6 = bflo(W.w), x##7 = bfhi(W.w)
; template <int NR>
; __device__ __forceinline__ void ln_rows(int lane, const bf16* Z, size_t rstride, const float* g, const float* b, float* Fout, bf16* Xout) {
;     ...
;     for (int j = 0; j < 8; ++j) { const f32x4 g0 = gr[128 * j], g1 = gr[128 * j + 1], b0 = br[128 * j], b1 = br[128 * j + 1];
; #pragma unroll
;         for (int r = 0; r < NR; ++r) { const float mu = mean[r], rs = rstd[r]; LN_X8(w[r][j], x);
;             const f32x4 o0 = (f32x4){(x0 - mu) * rs, (x1 - mu) * rs, (x2 - mu) * rs, (x3 - mu) * rs} * g0 + b0, o1 = (f32x4){(x4 - mu) * rs, (x5 - mu) * rs, (x6 - mu) * rs, (x7 - mu) * rs} * g1 + b1;
;             if (Fout) { GAS f32x4* fo = (GAS f32x4*)(Fout + r * rstride) + 2 * lane + 128 * j; fo[0] = o0; fo[1] = o1; }
;             if (Xout) { v4u ow; ow.x = pk2(o0.x, o0.y); ow.y = pk2(o0.z, o0.w); ow.z = pk2(o1.x, o1.y); ow.w = pk2(o1.z, o1.w); ((GAS v4u*)(Xout + r * rstride) + lane)[64 * j] = ow; } } }
	v_sub_f32_e32 v190, v47, v14
	v_lshlrev_b32_e32 v47, 16, v114
	v_and_b32_e32 v49, 0xffff0000, v114
	v_pk_fma_f32 v[116:117], v[144:145], v[116:117], v[140:141]
	v_sub_f32_e32 v141, v49, v14
	v_sub_f32_e32 v140, v47, v14
	v_pk_mul_f32 v[140:141], v[140:141], v[0:1] op_sel_hi:[1,0]
	v_and_b32_e32 v78, 0xffff0000, v115
	v_pk_fma_f32 v[130:131], v[134:135], v[140:141], v[130:131]
	v_sub_f32_e32 v115, v78, v14
	v_sub_f32_e32 v114, v64, v14
	v_pk_mul_f32 v[114:115], v[114:115], v[0:1] op_sel_hi:[1,0]
	v_pk_fma_f32 v[114:115], v[136:137], v[114:115], v[132:133]
	v_cvt_pk_bf16_f32 v130, v130, v131
	v_pk_mul_f32 v[190:191], v[190:191], v[0:1] op_sel_hi:[1,0]
	v_pk_fma_f32 v[138:139], v[142:143], v[190:191], v[138:139]
	v_cvt_pk_bf16_f32 v131, v114, v115
	v_cvt_pk_bf16_f32 v132, v138, v139
	s_add_u32 s26, s18, s56
	s_addc_u32 s27, s19, s57
	v_cvt_pk_bf16_f32 v133, v116, v117
	v_lshl_add_u64 v[114:115], s[26:27], 0, v[176:177]
	global_store_dwordx4 v[114:115], v[130:133], off
	global_load_dwordx4 v[130:133], v[148:149], off offset:2048
	s_nop 0
	global_load_dwordx4 v[134:137], v[148:149], off offset:2064
	global_load_dwordx4 v[138:141], v[150:151], off offset:2048
	global_load_dwordx4 v[142:145], v[150:151], off offset:2064
	v_lshlrev_b32_e32 v47, 16, v189
	v_and_b32_e32 v49, 0xffff0000, v189
	v_lshlrev_b32_e32 v64, 16, v101
	v_and_b32_e32 v78, 0xffff0000, v101
	v_sub_f32_e32 v117, v78, v32
	v_sub_f32_e32 v116, v64, v32
	v_sub_f32_e32 v191, v49, v32
	v_sub_f32_e32 v190, v47, v32
	v_lshlrev_b32_e32 v47, 16, v188
	v_and_b32_e32 v49, 0xffff0000, v188
	v_lshlrev_b32_e32 v64, 16, v99
	v_and_b32_e32 v78, 0xffff0000, v99
	v_sub_f32_e32 v189, v78, v32
	v_sub_f32_e32 v188, v64, v32
	v_sub_f32_e32 v193, v49, v32
	v_sub_f32_e32 v192, v47, v32
	v_pk_mul_f32 v[192:193], v[192:193], v[6:7] op_sel_hi:[1,0]
	v_pk_mul_f32 v[188:189], v[188:189], v[6:7] op_sel_hi:[1,0]
	v_pk_mul_f32 v[190:191], v[190:191], v[6:7] op_sel_hi:[1,0]
	v_pk_mul_f32 v[116:117], v[116:117], v[6:7] op_sel_hi:[1,0]
	v_lshlrev_b32_e32 v64, 16, v105
	v_and_b32_e32 v78, 0xffff0000, v105
	s_waitcnt vmcnt(1)
	v_pk_fma_f32 v[194:195], v[188:189], v[132:133], v[140:141]
	v_pk_fma_f32 v[188:189], v[192:193], v[130:131], v[138:139]
	s_waitcnt vmcnt(0)
	v_pk_fma_f32 v[190:191], v[190:191], v[134:135], v[142:143]
	v_cvt_pk_bf16_f32 v188, v188, v189
	v_cvt_pk_bf16_f32 v189, v194, v195
	v_pk_fma_f32 v[116:117], v[116:117], v[136:137], v[144:145]
	v_cvt_pk_bf16_f32 v190, v190, v191
	v_cvt_pk_bf16_f32 v191, v116, v117
	v_lshlrev_b32_e32 v47, 16, v187
	v_and_b32_e32 v49, 0xffff0000, v187
	global_store_dwordx4 v[126:127], v[188:191], off offset:1024
	v_sub_f32_e32 v117, v78, v30
	v_sub_f32_e32 v116, v64, v30
	v_sub_f32_e32 v189, v49, v30
	v_sub_f32_e32 v188, v47, v30
	v_lshlrev_b32_e32 v47, 16, v186
	v_and_b32_e32 v49, 0xffff0000, v186
	v_lshlrev_b32_e32 v64, 16, v103
	v_and_b32_e32 v78, 0xffff0000, v103
	v_sub_f32_e32 v187, v78, v30
	v_sub_f32_e32 v186, v64, v30
	v_sub_f32_e32 v191, v49, v30
	v_sub_f32_e32 v190, v47, v30
	v_pk_mul_f32 v[190:191], v[190:191], v[4:5] op_sel_hi:[1,0]
	v_pk_mul_f32 v[186:187], v[186:187], v[4:5] op_sel_hi:[1,0]
	v_pk_mul_f32 v[188:189], v[188:189], v[4:5] op_sel_hi:[1,0]
	v_pk_fma_f32 v[192:193], v[186:187], v[132:133], v[140:141]
	v_pk_fma_f32 v[186:187], v[190:191], v[130:131], v[138:139]
	v_pk_fma_f32 v[188:189], v[188:189], v[134:135], v[142:143]
	v_cvt_pk_bf16_f32 v186, v186, v187
	v_cvt_pk_bf16_f32 v187, v192, v193
	v_pk_mul_f32 v[116:117], v[116:117], v[4:5] op_sel_hi:[1,0]
	v_pk_fma_f32 v[116:117], v[116:117], v[136:137], v[144:145]
	v_cvt_pk_bf16_f32 v188, v188, v189
	v_cvt_pk_bf16_f32 v189, v116, v117
	v_lshlrev_b32_e32 v47, 16, v185
	v_and_b32_e32 v49, 0xffff0000, v185
	global_store_dwordx4 v[122:123], v[186:189], off offset:1024
	v_lshlrev_b32_e32 v64, 16, v109
	v_and_b32_e32 v78, 0xffff0000, v109
	v_sub_f32_e32 v187, v49, v16
	v_sub_f32_e32 v186, v47, v16
	v_pk_mul_f32 v[186:187], v[186:187], v[2:3] op_sel_hi:[1,0]
	v_lshlrev_b32_e32 v47, 16, v121
	v_and_b32_e32 v49, 0xffff0000, v121
	v_pk_fma_f32 v[188:189], v[186:187], v[134:135], v[142:143]
	v_sub_f32_e32 v187, v49, v16
	v_sub_f32_e32 v186, v47, v16
	v_pk_mul_f32 v[186:187], v[186:187], v[2:3] op_sel_hi:[1,0]
	v_sub_f32_e32 v117, v78, v16
	v_sub_f32_e32 v116, v64, v16
	v_lshlrev_b32_e32 v64, 16, v107
	v_and_b32_e32 v78, 0xffff0000, v107
	v_pk_fma_f32 v[186:187], v[186:187], v[130:131], v[138:139]
	v_sub_f32_e32 v121, v78, v16
	v_sub_f32_e32 v120, v64, v16
	v_pk_mul_f32 v[120:121], v[120:121], v[2:3] op_sel_hi:[1,0]
	v_pk_fma_f32 v[120:121], v[120:121], v[132:133], v[140:141]
	v_cvt_pk_bf16_f32 v186, v186, v187
	v_cvt_pk_bf16_f32 v187, v120, v121
	v_pk_mul_f32 v[116:117], v[116:117], v[2:3] op_sel_hi:[1,0]
	v_pk_fma_f32 v[116:117], v[116:117], v[136:137], v[144:145]
	v_cvt_pk_bf16_f32 v188, v188, v189
	v_cvt_pk_bf16_f32 v189, v116, v117
	v_lshlrev_b32_e32 v47, 16, v110
	v_and_b32_e32 v49, 0xffff0000, v110
	v_lshlrev_b32_e32 v64, 16, v113
	v_and_b32_e32 v78, 0xffff0000, v113
	v_sub_f32_e32 v113, v78, v14
	v_sub_f32_e32 v112, v64, v14
	v_sub_f32_e32 v117, v49, v14
	v_sub_f32_e32 v116, v47, v14
	v_lshlrev_b32_e32 v47, 16, v108
	v_and_b32_e32 v49, 0xffff0000, v108
	v_lshlrev_b32_e32 v64, 16, v111
	v_and_b32_e32 v78, 0xffff0000, v111
	v_sub_f32_e32 v109, v78, v14
	v_sub_f32_e32 v108, v64, v14
	v_sub_f32_e32 v111, v49, v14
	v_sub_f32_e32 v110, v47, v14
	v_pk_mul_f32 v[110:111], v[110:111], v[0:1] op_sel_hi:[1,0]
	v_pk_mul_f32 v[108:109], v[108:109], v[0:1] op_sel_hi:[1,0]
	v_pk_mul_f32 v[116:117], v[116:117], v[0:1] op_sel_hi:[1,0]
	v_pk_fma_f32 v[120:121], v[108:109], v[132:133], v[140:141]
; #define GAS __attribute__((address_space(1)))
; __device__ __forceinline__ unsigned pk2(float lo, float hi) { return f2bf(lo) | (f2bf(hi) << 16); }
; #define LN_X8(W, x) const float x##0 = bflo(W.x), x##1 = bfhi(W.x), x##2 = bflo(W.y), x##3 = bfhi(W.y), x##4 = bflo(W.z), x##5 = bfhi(W.z), x##6 = bflo(W.w), x##7 = bfhi(W.w)
; template <int NR>
; __device__ __forceinline__ void ln_rows(int lane, const bf16* Z, size_t rstride, const float* g, const float* b, float* Fout, bf16* Xout) {
;     ...
;     for (int j = 0; j < 8; ++j) { const f32x4 g0 = gr[128 * j], g1 = gr[128 * j + 1], b0 = br[128 * j], b1 = br[128 * j + 1];
; #pragma unroll
;         for (int r = 0; r < NR; ++r) { const float mu = mean[r], rs = rstd[r]; LN_X8(w[r][j], x);
;             const f32x4 o0 = (f32x4){(x0 - mu) * rs, (x1 - mu) * rs, (x2 - mu) * rs, (x3 - mu) * rs} * g0 + b0, o1 = (f32x4){(x4 - mu) * rs, (x5 - mu) * rs, (x6 - mu) * rs, (x7 - mu) * rs} * g1 + b1;
;             if (Fout) { GAS f32x4* fo = (GAS f32x4*)(Fout + r * rstride) + 2 * lane + 128 * j; fo[0] = o0; fo[1] = o1; }
;             if (Xout) { v4u ow; ow.x = pk2(o0.x, o0.y); ow.y = pk2(o0.z, o0.w); ow.z = pk2(o1.x, o1.y); ow.w = pk2(o1.z, o1.w); ((GAS v4u*)(Xout + r * rstride) + lane)[64 * j] = ow; } } }
	v_pk_fma_f32 v[108:109], v[110:111], v[130:131], v[138:139]
	v_pk_fma_f32 v[116:117], v[116:117], v[134:135], v[142:143]
	v_cvt_pk_bf16_f32 v108, v108, v109
	v_cvt_pk_bf16_f32 v109, v120, v121
	v_pk_mul_f32 v[112:113], v[112:113], v[0:1] op_sel_hi:[1,0]
	v_pk_fma_f32 v[112:113], v[112:113], v[136:137], v[144:145]
	v_cvt_pk_bf16_f32 v110, v116, v117
	v_cvt_pk_bf16_f32 v111, v112, v113
	global_store_dwordx4 v[118:119], v[186:189], off offset:1024
	global_store_dwordx4 v[114:115], v[108:111], off offset:1024
	global_load_dwordx4 v[108:111], v[152:153], off
	s_nop 0
	global_load_dwordx4 v[130:133], v[152:153], off offset:16
	global_load_dwordx4 v[134:137], v[154:155], off
	global_load_dwordx4 v[138:141], v[154:155], off offset:16
	v_lshlrev_b32_e32 v47, 16, v184
	v_and_b32_e32 v49, 0xffff0000, v184
	v_sub_f32_e32 v117, v49, v32
	v_sub_f32_e32 v116, v47, v32
	v_lshlrev_b32_e32 v47, 16, v82
	v_and_b32_e32 v49, 0xffff0000, v82
	v_sub_f32_e32 v143, v49, v32
	v_sub_f32_e32 v142, v47, v32
	v_lshlrev_b32_e32 v64, 16, v85
	v_and_b32_e32 v78, 0xffff0000, v85
	v_pk_mul_f32 v[142:143], v[142:143], v[6:7] op_sel_hi:[1,0]
	v_sub_f32_e32 v113, v78, v32
	v_sub_f32_e32 v112, v64, v32
	v_lshlrev_b32_e32 v64, 16, v183
	v_and_b32_e32 v78, 0xffff0000, v183
	v_sub_f32_e32 v121, v78, v32
	v_sub_f32_e32 v120, v64, v32
	v_pk_mul_f32 v[120:121], v[120:121], v[6:7] op_sel_hi:[1,0]
	v_pk_mul_f32 v[116:117], v[116:117], v[6:7] op_sel_hi:[1,0]
	v_pk_mul_f32 v[112:113], v[112:113], v[6:7] op_sel_hi:[1,0]
	v_lshlrev_b32_e32 v64, 16, v89
	v_and_b32_e32 v78, 0xffff0000, v89
	s_waitcnt vmcnt(1)
	v_pk_fma_f32 v[142:143], v[142:143], v[108:109], v[134:135]
	s_nop 0
	v_pk_fma_f32 v[120:121], v[120:121], v[110:111], v[136:137]
	v_cvt_pk_bf16_f32 v142, v142, v143
	s_waitcnt vmcnt(0)
	v_pk_fma_f32 v[116:117], v[116:117], v[130:131], v[138:139]
	v_cvt_pk_bf16_f32 v143, v120, v121
	v_pk_fma_f32 v[112:113], v[112:113], v[132:133], v[140:141]
	v_cvt_pk_bf16_f32 v144, v116, v117
	v_cvt_pk_bf16_f32 v145, v112, v113
	v_lshlrev_b32_e32 v47, 16, v182
	v_and_b32_e32 v49, 0xffff0000, v182
	v_sub_f32_e32 v117, v49, v30
	v_sub_f32_e32 v116, v47, v30
	v_lshlrev_b32_e32 v47, 16, v86
	v_and_b32_e32 v49, 0xffff0000, v86
	global_store_dwordx4 v[126:127], v[142:145], off offset:2048
	v_sub_f32_e32 v113, v78, v30
	v_sub_f32_e32 v112, v64, v30
	v_sub_f32_e32 v143, v49, v30
	v_sub_f32_e32 v142, v47, v30
	v_pk_mul_f32 v[142:143], v[142:143], v[4:5] op_sel_hi:[1,0]
	v_lshlrev_b32_e32 v64, 16, v181
	v_and_b32_e32 v78, 0xffff0000, v181
	v_pk_fma_f32 v[142:143], v[142:143], v[108:109], v[134:135]
	v_sub_f32_e32 v121, v78, v30
	v_sub_f32_e32 v120, v64, v30
	v_pk_mul_f32 v[120:121], v[120:121], v[4:5] op_sel_hi:[1,0]
	v_pk_fma_f32 v[120:121], v[120:121], v[110:111], v[136:137]
	v_cvt_pk_bf16_f32 v142, v142, v143
	v_pk_mul_f32 v[116:117], v[116:117], v[4:5] op_sel_hi:[1,0]
	v_pk_fma_f32 v[116:117], v[116:117], v[130:131], v[138:139]
	v_cvt_pk_bf16_f32 v143, v120, v121
	v_pk_mul_f32 v[112:113], v[112:113], v[4:5] op_sel_hi:[1,0]
	v_pk_fma_f32 v[112:113], v[112:113], v[132:133], v[140:141]
	v_cvt_pk_bf16_f32 v144, v116, v117
	v_cvt_pk_bf16_f32 v145, v112, v113
	v_lshlrev_b32_e32 v47, 16, v106
	v_and_b32_e32 v49, 0xffff0000, v106
	v_sub_f32_e32 v113, v49, v16
	v_sub_f32_e32 v112, v47, v16
	v_lshlrev_b32_e32 v47, 16, v90
	v_and_b32_e32 v49, 0xffff0000, v90
	v_sub_f32_e32 v117, v49, v16
	v_sub_f32_e32 v116, v47, v16
	v_lshlrev_b32_e32 v64, 16, v93
	v_and_b32_e32 v78, 0xffff0000, v93
	v_pk_mul_f32 v[116:117], v[116:117], v[2:3] op_sel_hi:[1,0]
	v_sub_f32_e32 v107, v78, v16
	v_sub_f32_e32 v106, v64, v16
	v_lshlrev_b32_e32 v64, 16, v92
	v_and_b32_e32 v78, 0xffff0000, v92
	v_pk_fma_f32 v[116:117], v[116:117], v[108:109], v[134:135]
	v_sub_f32_e32 v93, v78, v16
	v_sub_f32_e32 v92, v64, v16
	v_pk_mul_f32 v[92:93], v[92:93], v[2:3] op_sel_hi:[1,0]
	v_pk_fma_f32 v[92:93], v[92:93], v[110:111], v[136:137]
	global_store_dwordx4 v[122:123], v[142:145], off offset:2048
	v_pk_mul_f32 v[112:113], v[112:113], v[2:3] op_sel_hi:[1,0]
	v_pk_mul_f32 v[106:107], v[106:107], v[2:3] op_sel_hi:[1,0]
	v_cvt_pk_bf16_f32 v142, v116, v117
	v_pk_fma_f32 v[112:113], v[112:113], v[130:131], v[138:139]
	v_cvt_pk_bf16_f32 v143, v92, v93
	v_pk_fma_f32 v[106:107], v[106:107], v[132:133], v[140:141]
	v_cvt_pk_bf16_f32 v144, v112, v113
	v_lshlrev_b32_e32 v64, 16, v97
	v_and_b32_e32 v78, 0xffff0000, v97
	v_cvt_pk_bf16_f32 v145, v106, v107
	v_lshlrev_b32_e32 v47, 16, v91
	v_and_b32_e32 v49, 0xffff0000, v91
	v_sub_f32_e32 v91, v78, v14
	v_sub_f32_e32 v90, v64, v14
	v_sub_f32_e32 v93, v49, v14
	v_sub_f32_e32 v92, v47, v14
	v_pk_mul_f32 v[90:91], v[90:91], v[0:1] op_sel_hi:[1,0]
	v_lshlrev_b32_e32 v47, 16, v94
	v_and_b32_e32 v49, 0xffff0000, v94
	v_lshlrev_b32_e32 v64, 16, v77
	v_and_b32_e32 v77, 0xffff0000, v77
	v_pk_fma_f32 v[96:97], v[90:91], v[132:133], v[140:141]
	v_sub_f32_e32 v91, v77, v14
	v_sub_f32_e32 v90, v64, v14
	v_sub_f32_e32 v95, v49, v14
	v_sub_f32_e32 v94, v47, v14
	v_pk_mul_f32 v[94:95], v[94:95], v[0:1] op_sel_hi:[1,0]
	v_pk_mul_f32 v[90:91], v[90:91], v[0:1] op_sel_hi:[1,0]
	v_pk_mul_f32 v[92:93], v[92:93], v[0:1] op_sel_hi:[1,0]
	v_pk_fma_f32 v[106:107], v[90:91], v[110:111], v[136:137]
	v_pk_fma_f32 v[90:91], v[94:95], v[108:109], v[134:135]
	v_pk_fma_f32 v[92:93], v[92:93], v[130:131], v[138:139]
	v_cvt_pk_bf16_f32 v90, v90, v91
	v_cvt_pk_bf16_f32 v91, v106, v107
	v_cvt_pk_bf16_f32 v92, v92, v93
	v_cvt_pk_bf16_f32 v93, v96, v97
	global_store_dwordx4 v[118:119], v[142:145], off offset:2048
	global_store_dwordx4 v[114:115], v[90:93], off offset:2048
	global_load_dwordx4 v[90:93], v[156:157], off
	s_nop 0
	global_load_dwordx4 v[94:97], v[156:157], off offset:16
	global_load_dwordx4 v[106:109], v[158:159], off
	global_load_dwordx4 v[110:113], v[158:159], off offset:16
	v_lshlrev_b32_e32 v47, 16, v68
	v_and_b32_e32 v49, 0xffff0000, v68
	v_lshlrev_b32_e32 v64, 16, v180
	v_sub_f32_e32 v116, v64, v32
	v_sub_f32_e32 v121, v49, v32
	v_sub_f32_e32 v120, v47, v32
	v_lshlrev_b32_e32 v47, 16, v179
	v_and_b32_e32 v49, 0xffff0000, v179
	v_lshlrev_b32_e32 v64, 16, v67
	v_and_b32_e32 v67, 0xffff0000, v67
	v_sub_f32_e32 v131, v67, v32
	v_sub_f32_e32 v130, v64, v32
	v_sub_f32_e32 v133, v49, v32
	v_sub_f32_e32 v132, v47, v32
	v_pk_mul_f32 v[132:133], v[132:133], v[6:7] op_sel_hi:[1,0]
	v_pk_mul_f32 v[130:131], v[130:131], v[6:7] op_sel_hi:[1,0]
	v_pk_mul_f32 v[120:121], v[120:121], v[6:7] op_sel_hi:[1,0]
	v_and_b32_e32 v68, 0xffff0000, v180
	v_sub_f32_e32 v117, v68, v32
	v_pk_mul_f32 v[116:117], v[116:117], v[6:7] op_sel_hi:[1,0]
	v_lshlrev_b32_e32 v64, 16, v125
	v_and_b32_e32 v67, 0xffff0000, v125
	s_waitcnt vmcnt(1)
; #define GAS __attribute__((address_space(1)))
; __device__ __forceinline__ unsigned pk2(float lo, float hi) { return f2bf(lo) | (f2bf(hi) << 16); }
; #define LN_X8(W, x) const float x##0 = bflo(W.x), x##1 = bfhi(W.x), x##2 = bflo(W.y), x##3 = bfhi(W.y), x##4 = bflo(W.z), x##5 = bfhi(W.z), x##6 = bflo(W.w), x##7 = bfhi(W.w)
; template <int NR>
; __device__ __forceinline__ void ln_rows(int lane, const bf16* Z, size_t rstride, const float* g, const float* b, float* Fout, bf16* Xout) {
;     ...
;     for (int j = 0; j < 8; ++j) { const f32x4 g0 = gr[128 * j], g1 = gr[128 * j + 1], b0 = br[128 * j], b1 = br[128 * j + 1];
; #pragma unroll
;         for (int r = 0; r < NR; ++r) { const float mu = mean[r], rs = rstd[r]; LN_X8(w[r][j], x);
;             const f32x4 o0 = (f32x4){(x0 - mu) * rs, (x1 - mu) * rs, (x2 - mu) * rs, (x3 - mu) * rs} * g0 + b0, o1 = (f32x4){(x4 - mu) * rs, (x5 - mu) * rs, (x6 - mu) * rs, (x7 - mu) * rs} * g1 + b1;
;             if (Fout) { GAS f32x4* fo = (GAS f32x4*)(Fout + r * rstride) + 2 * lane + 128 * j; fo[0] = o0; fo[1] = o1; }
;             if (Xout) { v4u ow; ow.x = pk2(o0.x, o0.y); ow.y = pk2(o0.z, o0.w); ow.z = pk2(o1.x, o1.y); ow.w = pk2(o1.z, o1.w); ((GAS v4u*)(Xout + r * rstride) + lane)[64 * j] = ow; } } }
	v_pk_fma_f32 v[134:135], v[130:131], v[92:93], v[108:109]
	v_pk_fma_f32 v[130:131], v[132:133], v[90:91], v[106:107]
	s_waitcnt vmcnt(0)
	v_pk_fma_f32 v[120:121], v[120:121], v[94:95], v[110:111]
	v_cvt_pk_bf16_f32 v130, v130, v131
	v_cvt_pk_bf16_f32 v131, v134, v135
	v_pk_fma_f32 v[116:117], v[116:117], v[96:97], v[112:113]
	v_cvt_pk_bf16_f32 v132, v120, v121
	v_cvt_pk_bf16_f32 v133, v116, v117
	v_lshlrev_b32_e32 v47, 16, v72
	v_and_b32_e32 v49, 0xffff0000, v72
	v_sub_f32_e32 v121, v49, v30
	v_sub_f32_e32 v120, v47, v30
	v_lshlrev_b32_e32 v47, 16, v104
	v_and_b32_e32 v49, 0xffff0000, v104
	v_sub_f32_e32 v125, v49, v30
	v_sub_f32_e32 v124, v47, v30
	v_pk_mul_f32 v[124:125], v[124:125], v[4:5] op_sel_hi:[1,0]
	v_sub_f32_e32 v117, v67, v30
	v_sub_f32_e32 v116, v64, v30
	v_lshlrev_b32_e32 v64, 16, v71
	v_and_b32_e32 v67, 0xffff0000, v71
	v_pk_fma_f32 v[124:125], v[124:125], v[90:91], v[106:107]
	v_sub_f32_e32 v105, v67, v30
	v_sub_f32_e32 v104, v64, v30
	v_pk_mul_f32 v[104:105], v[104:105], v[4:5] op_sel_hi:[1,0]
	v_pk_fma_f32 v[104:105], v[104:105], v[92:93], v[108:109]
	global_store_dwordx4 v[126:127], v[130:133], off offset:3072
	v_pk_mul_f32 v[120:121], v[120:121], v[4:5] op_sel_hi:[1,0]
	v_pk_mul_f32 v[116:117], v[116:117], v[4:5] op_sel_hi:[1,0]
	v_cvt_pk_bf16_f32 v130, v124, v125
	v_pk_fma_f32 v[120:121], v[120:121], v[94:95], v[110:111]
	v_cvt_pk_bf16_f32 v131, v104, v105
	v_pk_fma_f32 v[116:117], v[116:117], v[96:97], v[112:113]
	v_cvt_pk_bf16_f32 v132, v120, v121
	v_cvt_pk_bf16_f32 v133, v116, v117
	v_lshlrev_b32_e32 v47, 16, v76
	v_and_b32_e32 v49, 0xffff0000, v76
	v_lshlrev_b32_e32 v64, 16, v73
	v_and_b32_e32 v67, 0xffff0000, v73
	v_sub_f32_e32 v73, v67, v16
	v_sub_f32_e32 v72, v64, v16
	v_sub_f32_e32 v77, v49, v16
	v_sub_f32_e32 v76, v47, v16
	v_pk_mul_f32 v[76:77], v[76:77], v[2:3] op_sel_hi:[1,0]
	v_pk_mul_f32 v[72:73], v[72:73], v[2:3] op_sel_hi:[1,0]
	v_lshlrev_b32_e32 v47, 16, v70
	v_and_b32_e32 v49, 0xffff0000, v70
	v_lshlrev_b32_e32 v64, 16, v75
	v_and_b32_e32 v67, 0xffff0000, v75
	v_pk_fma_f32 v[104:105], v[72:73], v[96:97], v[112:113]
	v_pk_fma_f32 v[72:73], v[76:77], v[94:95], v[110:111]
	v_sub_f32_e32 v71, v67, v16
	v_sub_f32_e32 v70, v64, v16
	v_sub_f32_e32 v77, v49, v16
	v_sub_f32_e32 v76, v47, v16
	v_pk_mul_f32 v[76:77], v[76:77], v[2:3] op_sel_hi:[1,0]
	v_pk_mul_f32 v[70:71], v[70:71], v[2:3] op_sel_hi:[1,0]
	v_lshlrev_b32_e32 v64, 16, v69
	v_pk_fma_f32 v[116:117], v[70:71], v[92:93], v[108:109]
	v_pk_fma_f32 v[70:71], v[76:77], v[90:91], v[106:107]
	v_and_b32_e32 v67, 0xffff0000, v69
	v_cvt_pk_bf16_f32 v70, v70, v71
	v_cvt_pk_bf16_f32 v71, v116, v117
	v_cvt_pk_bf16_f32 v72, v72, v73
	v_cvt_pk_bf16_f32 v73, v104, v105
	v_lshlrev_b32_e32 v47, 16, v80
	v_and_b32_e32 v49, 0xffff0000, v80
	global_store_dwordx4 v[122:123], v[130:133], off offset:3072
	global_store_dwordx4 v[118:119], v[70:73], off offset:3072
	v_sub_f32_e32 v69, v67, v14
	v_sub_f32_e32 v68, v64, v14
	v_sub_f32_e32 v71, v49, v14
	v_sub_f32_e32 v70, v47, v14
	v_pk_mul_f32 v[70:71], v[70:71], v[0:1] op_sel_hi:[1,0]
	v_pk_mul_f32 v[68:69], v[68:69], v[0:1] op_sel_hi:[1,0]
	v_lshlrev_b32_e32 v47, 16, v66
	v_and_b32_e32 v49, 0xffff0000, v66
	v_lshlrev_b32_e32 v64, 16, v79
	v_and_b32_e32 v66, 0xffff0000, v79
	v_pk_fma_f32 v[72:73], v[68:69], v[96:97], v[112:113]
	v_pk_fma_f32 v[68:69], v[70:71], v[94:95], v[110:111]
	v_sub_f32_e32 v67, v66, v14
	v_sub_f32_e32 v66, v64, v14
	v_sub_f32_e32 v71, v49, v14
	v_sub_f32_e32 v70, v47, v14
	v_pk_mul_f32 v[70:71], v[70:71], v[0:1] op_sel_hi:[1,0]
	v_pk_mul_f32 v[66:67], v[66:67], v[0:1] op_sel_hi:[1,0]
	v_lshlrev_b32_e32 v64, 16, v53
	v_pk_fma_f32 v[76:77], v[66:67], v[92:93], v[108:109]
	v_pk_fma_f32 v[66:67], v[70:71], v[90:91], v[106:107]
	v_and_b32_e32 v53, 0xffff0000, v53
	v_cvt_pk_bf16_f32 v66, v66, v67
	v_cvt_pk_bf16_f32 v67, v76, v77
	v_cvt_pk_bf16_f32 v68, v68, v69
	v_cvt_pk_bf16_f32 v69, v72, v73
	global_store_dwordx4 v[114:115], v[66:69], off offset:3072
	global_load_dwordx4 v[66:69], v[162:163], off
	s_nop 0
	global_load_dwordx4 v[76:79], v[162:163], off offset:16
	global_load_dwordx4 v[70:73], v[160:161], off
	global_load_dwordx4 v[90:93], v[160:161], off offset:16
	v_lshlrev_b32_e32 v47, 16, v178
	v_and_b32_e32 v49, 0xffff0000, v178
	v_sub_f32_e32 v95, v49, v32
	v_sub_f32_e32 v94, v47, v32
	v_pk_mul_f32 v[94:95], v[94:95], v[6:7] op_sel_hi:[1,0]
	v_lshlrev_b32_e32 v47, 16, v50
	v_and_b32_e32 v49, 0xffff0000, v50
	v_lshlrev_b32_e32 v50, 16, v51
	v_and_b32_e32 v51, 0xffff0000, v51
	v_sub_f32_e32 v51, v51, v32
	v_sub_f32_e32 v50, v50, v32
	v_pk_mul_f32 v[50:51], v[50:51], v[6:7] op_sel_hi:[1,0]
	v_sub_f32_e32 v81, v53, v32
	v_sub_f32_e32 v80, v64, v32
	v_pk_mul_f32 v[80:81], v[80:81], v[6:7] op_sel_hi:[1,0]
	v_lshlrev_b32_e32 v53, 16, v57
	v_and_b32_e32 v57, 0xffff0000, v57
	s_waitcnt vmcnt(1)
	v_pk_fma_f32 v[50:51], v[50:51], v[72:73], v[68:69]
	s_waitcnt vmcnt(0)
; #define GAS __attribute__((address_space(1)))
; __device__ __forceinline__ unsigned pk2(float lo, float hi) { return f2bf(lo) | (f2bf(hi) << 16); }
; #define LN_X8(W, x) const float x##0 = bflo(W.x), x##1 = bfhi(W.x), x##2 = bflo(W.y), x##3 = bfhi(W.y), x##4 = bflo(W.z), x##5 = bfhi(W.z), x##6 = bflo(W.w), x##7 = bfhi(W.w)
; template <int NR>
; __device__ __forceinline__ void ln_rows(int lane, const bf16* Z, size_t rstride, const float* g, const float* b, float* Fout, bf16* Xout) {
;     ...
;     for (int j = 0; j < 8; ++j) { const f32x4 g0 = gr[128 * j], g1 = gr[128 * j + 1], b0 = br[128 * j], b1 = br[128 * j + 1];
; #pragma unroll
;         for (int r = 0; r < NR; ++r) { const float mu = mean[r], rs = rstd[r]; LN_X8(w[r][j], x);
;             const f32x4 o0 = (f32x4){(x0 - mu) * rs, (x1 - mu) * rs, (x2 - mu) * rs, (x3 - mu) * rs} * g0 + b0, o1 = (f32x4){(x4 - mu) * rs, (x5 - mu) * rs, (x6 - mu) * rs, (x7 - mu) * rs} * g1 + b1;
;             if (Fout) { GAS f32x4* fo = (GAS f32x4*)(Fout + r * rstride) + 2 * lane + 128 * j; fo[0] = o0; fo[1] = o1; }
;             if (Xout) { v4u ow; ow.x = pk2(o0.x, o0.y); ow.y = pk2(o0.z, o0.w); ow.z = pk2(o1.x, o1.y); ow.w = pk2(o1.z, o1.w); ((GAS v4u*)(Xout + r * rstride) + lane)[64 * j] = ow; } } }
	v_pk_fma_f32 v[96:97], v[94:95], v[90:91], v[76:77]
	v_sub_f32_e32 v95, v49, v32
	v_sub_f32_e32 v94, v47, v32
	v_pk_mul_f32 v[94:95], v[94:95], v[6:7] op_sel_hi:[1,0]
	v_pk_fma_f32 v[80:81], v[80:81], v[92:93], v[78:79]
	v_pk_fma_f32 v[94:95], v[94:95], v[70:71], v[66:67]
	s_nop 0
	v_cvt_pk_bf16_f32 v94, v94, v95
	v_cvt_pk_bf16_f32 v95, v50, v51
	v_cvt_pk_bf16_f32 v96, v96, v97
	v_add_co_u32_e32 v50, vcc, s31, v126
	v_cvt_pk_bf16_f32 v97, v80, v81
	s_nop 0
	v_addc_co_u32_e32 v51, vcc, 0, v127, vcc
	v_lshlrev_b32_e32 v47, 16, v102
	v_and_b32_e32 v49, 0xffff0000, v102
	global_store_dwordx4 v[50:51], v[94:97], off
	v_sub_f32_e32 v80, v53, v30
	v_and_b32_e32 v53, 0xffff0000, v55
	v_sub_f32_e32 v95, v49, v30
	v_sub_f32_e32 v94, v47, v30
	v_pk_mul_f32 v[94:95], v[94:95], v[4:5] op_sel_hi:[1,0]
	v_lshlrev_b32_e32 v47, 16, v52
	v_and_b32_e32 v49, 0xffff0000, v52
	v_pk_fma_f32 v[96:97], v[94:95], v[90:91], v[76:77]
	v_sub_f32_e32 v95, v49, v30
	v_sub_f32_e32 v94, v47, v30
	v_pk_mul_f32 v[94:95], v[94:95], v[4:5] op_sel_hi:[1,0]
	v_lshlrev_b32_e32 v52, 16, v55
	v_pk_fma_f32 v[94:95], v[94:95], v[70:71], v[66:67]
	v_sub_f32_e32 v53, v53, v30
	v_sub_f32_e32 v52, v52, v30
	v_pk_mul_f32 v[52:53], v[52:53], v[4:5] op_sel_hi:[1,0]
	v_pk_fma_f32 v[52:53], v[52:53], v[72:73], v[68:69]
	v_cvt_pk_bf16_f32 v94, v94, v95
	v_sub_f32_e32 v81, v57, v30
	v_cvt_pk_bf16_f32 v95, v52, v53
	v_pk_mul_f32 v[80:81], v[80:81], v[4:5] op_sel_hi:[1,0]
	v_pk_fma_f32 v[80:81], v[80:81], v[92:93], v[78:79]
	v_cvt_pk_bf16_f32 v96, v96, v97
	v_cvt_pk_bf16_f32 v97, v80, v81
	v_add_co_u32_e32 v52, vcc, s31, v122
	v_lshlrev_b32_e32 v47, 16, v74
	v_and_b32_e32 v49, 0xffff0000, v74
	v_addc_co_u32_e32 v53, vcc, 0, v123, vcc
	v_sub_f32_e32 v81, v49, v16
	v_sub_f32_e32 v80, v47, v16
	v_lshlrev_b32_e32 v47, 16, v54
	v_and_b32_e32 v49, 0xffff0000, v54
	global_store_dwordx4 v[52:53], v[94:97], off
	v_lshlrev_b32_e32 v55, 16, v61
	v_sub_f32_e32 v74, v55, v16
	v_sub_f32_e32 v95, v49, v16
	v_sub_f32_e32 v94, v47, v16
	v_pk_mul_f32 v[94:95], v[94:95], v[2:3] op_sel_hi:[1,0]
	v_lshlrev_b32_e32 v54, 16, v59
	v_and_b32_e32 v55, 0xffff0000, v59
	v_pk_fma_f32 v[94:95], v[94:95], v[70:71], v[66:67]
	v_sub_f32_e32 v55, v55, v16
	v_sub_f32_e32 v54, v54, v16
	v_pk_mul_f32 v[54:55], v[54:55], v[2:3] op_sel_hi:[1,0]
	v_pk_fma_f32 v[54:55], v[54:55], v[72:73], v[68:69]
	v_cvt_pk_bf16_f32 v94, v94, v95
	v_pk_mul_f32 v[80:81], v[80:81], v[2:3] op_sel_hi:[1,0]
	v_and_b32_e32 v57, 0xffff0000, v61
	v_pk_fma_f32 v[80:81], v[80:81], v[90:91], v[76:77]
	v_sub_f32_e32 v75, v57, v16
	v_cvt_pk_bf16_f32 v95, v54, v55
	v_pk_mul_f32 v[74:75], v[74:75], v[2:3] op_sel_hi:[1,0]
	v_pk_fma_f32 v[74:75], v[74:75], v[92:93], v[78:79]
	v_cvt_pk_bf16_f32 v96, v80, v81
	v_cvt_pk_bf16_f32 v97, v74, v75
	v_lshlrev_b32_e32 v47, 16, v62
	v_and_b32_e32 v49, 0xffff0000, v62
	v_lshlrev_b32_e32 v57, 16, v65
	v_sub_f32_e32 v75, v49, v14
	v_sub_f32_e32 v74, v47, v14
	v_lshlrev_b32_e32 v47, 16, v56
	v_and_b32_e32 v49, 0xffff0000, v56
	v_sub_f32_e32 v64, v57, v14
	v_lshlrev_b32_e32 v56, 16, v63
	v_and_b32_e32 v57, 0xffff0000, v63
	v_sub_f32_e32 v63, v49, v14
	v_sub_f32_e32 v62, v47, v14
	v_pk_mul_f32 v[62:63], v[62:63], v[0:1] op_sel_hi:[1,0]
	v_sub_f32_e32 v57, v57, v14
	v_pk_fma_f32 v[62:63], v[62:63], v[70:71], v[66:67]
	v_sub_f32_e32 v56, v56, v14
	v_pk_mul_f32 v[56:57], v[56:57], v[0:1] op_sel_hi:[1,0]
	v_and_b32_e32 v59, 0xffff0000, v65
	v_pk_fma_f32 v[56:57], v[56:57], v[72:73], v[68:69]
	v_sub_f32_e32 v65, v59, v14
	v_cvt_pk_bf16_f32 v62, v62, v63
	v_pk_mul_f32 v[74:75], v[74:75], v[0:1] op_sel_hi:[1,0]
	v_pk_mul_f32 v[64:65], v[64:65], v[0:1] op_sel_hi:[1,0]
	v_pk_fma_f32 v[78:79], v[64:65], v[92:93], v[78:79]
	v_pk_fma_f32 v[64:65], v[74:75], v[90:91], v[76:77]
	v_cvt_pk_bf16_f32 v63, v56, v57
	v_add_co_u32_e32 v54, vcc, s31, v118
	v_cvt_pk_bf16_f32 v64, v64, v65
	s_nop 0
	v_addc_co_u32_e32 v55, vcc, 0, v119, vcc
	v_add_co_u32_e32 v56, vcc, s31, v114
	v_cvt_pk_bf16_f32 v65, v78, v79
	s_nop 0
	v_addc_co_u32_e32 v57, vcc, 0, v115, vcc
	global_store_dwordx4 v[54:55], v[94:97], off
	global_store_dwordx4 v[56:57], v[62:65], off
	global_load_dwordx4 v[62:65], v[164:165], off
	s_nop 0
	global_load_dwordx4 v[66:69], v[164:165], off offset:16
	global_load_dwordx4 v[70:73], v[166:167], off
	global_load_dwordx4 v[74:77], v[166:167], off offset:16
	v_lshlrev_b32_e32 v49, 16, v129
	v_and_b32_e32 v59, 0xffff0000, v129
	v_lshlrev_b32_e32 v47, 16, v36
	v_and_b32_e32 v36, 0xffff0000, v36
	v_sub_f32_e32 v79, v59, v32
	v_sub_f32_e32 v78, v49, v32
	v_sub_f32_e32 v81, v36, v32
	v_sub_f32_e32 v80, v47, v32
	v_pk_mul_f32 v[78:79], v[78:79], v[6:7] op_sel_hi:[1,0]
	v_lshlrev_b32_e32 v36, 16, v34
	v_and_b32_e32 v34, 0xffff0000, v34
	v_lshlrev_b32_e32 v47, 16, v100
	v_and_b32_e32 v49, 0xffff0000, v100
	v_sub_f32_e32 v93, v34, v32
	v_sub_f32_e32 v92, v36, v32
	v_pk_mul_f32 v[92:93], v[92:93], v[6:7] op_sel_hi:[1,0]
	v_pk_mul_f32 v[80:81], v[80:81], v[6:7] op_sel_hi:[1,0]
	s_waitcnt vmcnt(0)
; #define GAS __attribute__((address_space(1)))
; __device__ __forceinline__ unsigned pk2(float lo, float hi) { return f2bf(lo) | (f2bf(hi) << 16); }
; #define LN_X8(W, x) const float x##0 = bflo(W.x), x##1 = bfhi(W.x), x##2 = bflo(W.y), x##3 = bfhi(W.y), x##4 = bflo(W.z), x##5 = bfhi(W.z), x##6 = bflo(W.w), x##7 = bfhi(W.w)
; template <int NR>
; __device__ __forceinline__ void ln_rows(int lane, const bf16* Z, size_t rstride, const float* g, const float* b, float* Fout, bf16* Xout) {
;     ...
;     for (int j = 0; j < 8; ++j) { const f32x4 g0 = gr[128 * j], g1 = gr[128 * j + 1], b0 = br[128 * j], b1 = br[128 * j + 1];
; #pragma unroll
;         for (int r = 0; r < NR; ++r) { const float mu = mean[r], rs = rstd[r]; LN_X8(w[r][j], x);
;             const f32x4 o0 = (f32x4){(x0 - mu) * rs, (x1 - mu) * rs, (x2 - mu) * rs, (x3 - mu) * rs} * g0 + b0, o1 = (f32x4){(x4 - mu) * rs, (x5 - mu) * rs, (x6 - mu) * rs, (x7 - mu) * rs} * g1 + b1;
;             if (Fout) { GAS f32x4* fo = (GAS f32x4*)(Fout + r * rstride) + 2 * lane + 128 * j; fo[0] = o0; fo[1] = o1; }
;             if (Xout) { v4u ow; ow.x = pk2(o0.x, o0.y); ow.y = pk2(o0.z, o0.w); ow.z = pk2(o1.x, o1.y); ow.w = pk2(o1.z, o1.w); ((GAS v4u*)(Xout + r * rstride) + lane)[64 * j] = ow; } } }
	v_pk_fma_f32 v[90:91], v[78:79], v[68:69], v[76:77]
	v_sub_f32_e32 v79, v49, v32
	v_sub_f32_e32 v78, v47, v32
	v_pk_mul_f32 v[78:79], v[78:79], v[6:7] op_sel_hi:[1,0]
	v_pk_fma_f32 v[80:81], v[80:81], v[66:67], v[74:75]
	v_pk_fma_f32 v[94:95], v[78:79], v[64:65], v[72:73]
	v_pk_fma_f32 v[78:79], v[92:93], v[62:63], v[70:71]
	v_and_b32_e32 v47, 0xffff0000, v88
	v_cvt_pk_bf16_f32 v78, v78, v79
	v_cvt_pk_bf16_f32 v79, v94, v95
	v_cvt_pk_bf16_f32 v80, v80, v81
	v_cvt_pk_bf16_f32 v81, v90, v91
	v_lshlrev_b32_e32 v34, 16, v40
	v_and_b32_e32 v36, 0xffff0000, v40
	v_lshlrev_b32_e32 v40, 16, v88
	global_store_dwordx4 v[50:51], v[78:81], off offset:1024
	s_nop 1
	v_sub_f32_e32 v79, v47, v30
	v_sub_f32_e32 v78, v40, v30
	v_sub_f32_e32 v81, v36, v30
	v_sub_f32_e32 v80, v34, v30
	v_pk_mul_f32 v[78:79], v[78:79], v[4:5] op_sel_hi:[1,0]
	v_lshlrev_b32_e32 v34, 16, v38
	v_and_b32_e32 v36, 0xffff0000, v38
	v_lshlrev_b32_e32 v38, 16, v87
	v_and_b32_e32 v40, 0xffff0000, v87
	v_pk_fma_f32 v[88:89], v[78:79], v[68:69], v[76:77]
	v_sub_f32_e32 v79, v40, v30
	v_sub_f32_e32 v78, v38, v30
	v_sub_f32_e32 v87, v36, v30
	v_sub_f32_e32 v86, v34, v30
	v_pk_mul_f32 v[86:87], v[86:87], v[4:5] op_sel_hi:[1,0]
	v_pk_mul_f32 v[78:79], v[78:79], v[4:5] op_sel_hi:[1,0]
	v_pk_mul_f32 v[80:81], v[80:81], v[4:5] op_sel_hi:[1,0]
	v_pk_fma_f32 v[90:91], v[78:79], v[64:65], v[72:73]
	v_pk_fma_f32 v[78:79], v[86:87], v[62:63], v[70:71]
	v_pk_fma_f32 v[80:81], v[80:81], v[66:67], v[74:75]
	v_cvt_pk_bf16_f32 v78, v78, v79
	v_cvt_pk_bf16_f32 v79, v90, v91
	v_cvt_pk_bf16_f32 v80, v80, v81
	v_cvt_pk_bf16_f32 v81, v88, v89
	v_lshlrev_b32_e32 v34, 16, v44
	v_and_b32_e32 v36, 0xffff0000, v44
	v_lshlrev_b32_e32 v38, 16, v60
	v_and_b32_e32 v40, 0xffff0000, v60
	global_store_dwordx4 v[52:53], v[78:81], off offset:1024
	v_sub_f32_e32 v61, v40, v16
	v_sub_f32_e32 v60, v38, v16
	v_sub_f32_e32 v79, v36, v16
	v_sub_f32_e32 v78, v34, v16
	v_pk_mul_f32 v[78:79], v[78:79], v[2:3] op_sel_hi:[1,0]
	v_pk_mul_f32 v[60:61], v[60:61], v[2:3] op_sel_hi:[1,0]
	v_lshlrev_b32_e32 v34, 16, v42
	v_and_b32_e32 v36, 0xffff0000, v42
	v_lshlrev_b32_e32 v38, 16, v58
	v_and_b32_e32 v40, 0xffff0000, v58
	v_pk_fma_f32 v[80:81], v[60:61], v[68:69], v[76:77]
	v_pk_fma_f32 v[60:61], v[78:79], v[66:67], v[74:75]
	v_sub_f32_e32 v59, v40, v16
	v_sub_f32_e32 v58, v38, v16
	v_sub_f32_e32 v79, v36, v16
	v_sub_f32_e32 v78, v34, v16
	v_pk_mul_f32 v[78:79], v[78:79], v[2:3] op_sel_hi:[1,0]
	v_pk_mul_f32 v[58:59], v[58:59], v[2:3] op_sel_hi:[1,0]
	v_lshlrev_b32_e32 v38, 16, v45
	v_pk_fma_f32 v[86:87], v[58:59], v[64:65], v[72:73]
	v_pk_fma_f32 v[58:59], v[78:79], v[62:63], v[70:71]
	v_and_b32_e32 v40, 0xffff0000, v45
	v_cvt_pk_bf16_f32 v58, v58, v59
	v_cvt_pk_bf16_f32 v59, v86, v87
	v_cvt_pk_bf16_f32 v60, v60, v61
	v_cvt_pk_bf16_f32 v61, v80, v81
	v_lshlrev_b32_e32 v34, 16, v48
	v_and_b32_e32 v36, 0xffff0000, v48
	v_sub_f32_e32 v45, v40, v14
	v_sub_f32_e32 v44, v38, v14
	v_sub_f32_e32 v49, v36, v14
	v_sub_f32_e32 v48, v34, v14
	v_lshlrev_b32_e32 v34, 16, v46
	v_and_b32_e32 v36, 0xffff0000, v46
	v_lshlrev_b32_e32 v38, 16, v43
	v_and_b32_e32 v40, 0xffff0000, v43
	v_sub_f32_e32 v43, v40, v14
	v_sub_f32_e32 v42, v38, v14
	v_sub_f32_e32 v47, v36, v14
	v_sub_f32_e32 v46, v34, v14
	v_pk_mul_f32 v[48:49], v[48:49], v[0:1] op_sel_hi:[1,0]
	v_pk_mul_f32 v[44:45], v[44:45], v[0:1] op_sel_hi:[1,0]
	v_pk_mul_f32 v[46:47], v[46:47], v[0:1] op_sel_hi:[1,0]
	v_pk_mul_f32 v[42:43], v[42:43], v[0:1] op_sel_hi:[1,0]
	global_store_dwordx4 v[54:55], v[58:61], off offset:1024
	v_lshlrev_b32_e32 v38, 16, v21
	v_and_b32_e32 v21, 0xffff0000, v21
	v_pk_fma_f32 v[58:59], v[44:45], v[68:69], v[76:77]
	v_pk_fma_f32 v[44:45], v[48:49], v[66:67], v[74:75]
	v_pk_fma_f32 v[48:49], v[42:43], v[64:65], v[72:73]
	v_pk_fma_f32 v[42:43], v[46:47], v[62:63], v[70:71]
	v_sub_f32_e32 v67, v21, v32
	v_cvt_pk_bf16_f32 v42, v42, v43
	v_cvt_pk_bf16_f32 v43, v48, v49
	v_cvt_pk_bf16_f32 v44, v44, v45
	v_cvt_pk_bf16_f32 v45, v58, v59
	global_store_dwordx4 v[56:57], v[42:45], off offset:1024
	global_load_dwordx4 v[42:45], v[168:169], off
	s_nop 0
	global_load_dwordx4 v[46:49], v[168:169], off offset:16
	global_load_dwordx4 v[58:61], v[170:171], off
	global_load_dwordx4 v[62:65], v[170:171], off offset:16
	v_lshlrev_b32_e32 v34, 16, v98
	v_and_b32_e32 v36, 0xffff0000, v98
	v_sub_f32_e32 v66, v38, v32
	v_sub_f32_e32 v69, v36, v32
	v_sub_f32_e32 v68, v34, v32
	v_pk_mul_f32 v[66:67], v[66:67], v[6:7] op_sel_hi:[1,0]
	v_lshlrev_b32_e32 v21, 16, v84
	v_and_b32_e32 v34, 0xffff0000, v84
	v_lshlrev_b32_e32 v36, 16, v19
	v_and_b32_e32 v19, 0xffff0000, v19
	v_sub_f32_e32 v73, v34, v32
	v_sub_f32_e32 v72, v21, v32
	v_pk_mul_f32 v[72:73], v[72:73], v[6:7] op_sel_hi:[1,0]
	v_pk_mul_f32 v[68:69], v[68:69], v[6:7] op_sel_hi:[1,0]
	v_lshlrev_b32_e32 v34, 16, v25
	v_and_b32_e32 v25, 0xffff0000, v25
	s_waitcnt vmcnt(0)
; #define GAS __attribute__((address_space(1)))
; __device__ __forceinline__ unsigned pk2(float lo, float hi) { return f2bf(lo) | (f2bf(hi) << 16); }
; #define LN_X8(W, x) const float x##0 = bflo(W.x), x##1 = bfhi(W.x), x##2 = bflo(W.y), x##3 = bfhi(W.y), x##4 = bflo(W.z), x##5 = bfhi(W.z), x##6 = bflo(W.w), x##7 = bfhi(W.w)
; template <int NR>
; __device__ __forceinline__ void ln_rows(int lane, const bf16* Z, size_t rstride, const float* g, const float* b, float* Fout, bf16* Xout) {
;     ...
;     for (int j = 0; j < 8; ++j) { const f32x4 g0 = gr[128 * j], g1 = gr[128 * j + 1], b0 = br[128 * j], b1 = br[128 * j + 1];
; #pragma unroll
;         for (int r = 0; r < NR; ++r) { const float mu = mean[r], rs = rstd[r]; LN_X8(w[r][j], x);
;             const f32x4 o0 = (f32x4){(x0 - mu) * rs, (x1 - mu) * rs, (x2 - mu) * rs, (x3 - mu) * rs} * g0 + b0, o1 = (f32x4){(x4 - mu) * rs, (x5 - mu) * rs, (x6 - mu) * rs, (x7 - mu) * rs} * g1 + b1;
;             if (Fout) { GAS f32x4* fo = (GAS f32x4*)(Fout + r * rstride) + 2 * lane + 128 * j; fo[0] = o0; fo[1] = o1; }
;             if (Xout) { v4u ow; ow.x = pk2(o0.x, o0.y); ow.y = pk2(o0.z, o0.w); ow.z = pk2(o1.x, o1.y); ow.w = pk2(o1.z, o1.w); ((GAS v4u*)(Xout + r * rstride) + lane)[64 * j] = ow; } } }
	v_pk_fma_f32 v[70:71], v[66:67], v[48:49], v[64:65]
	v_sub_f32_e32 v67, v19, v32
	v_sub_f32_e32 v66, v36, v32
	v_pk_mul_f32 v[66:67], v[66:67], v[6:7] op_sel_hi:[1,0]
	v_pk_fma_f32 v[68:69], v[68:69], v[46:47], v[62:63]
	v_pk_fma_f32 v[74:75], v[66:67], v[44:45], v[60:61]
	v_pk_fma_f32 v[66:67], v[72:73], v[42:43], v[58:59]
	s_nop 0
	v_cvt_pk_bf16_f32 v66, v66, v67
	v_cvt_pk_bf16_f32 v67, v74, v75
	v_cvt_pk_bf16_f32 v68, v68, v69
	v_cvt_pk_bf16_f32 v69, v70, v71
	global_store_dwordx4 v[50:51], v[66:69], off offset:2048
	v_lshlrev_b32_e32 v19, 16, v83
	v_and_b32_e32 v21, 0xffff0000, v83
	v_sub_f32_e32 v67, v25, v30
	v_sub_f32_e32 v66, v34, v30
	v_sub_f32_e32 v69, v21, v30
	v_sub_f32_e32 v68, v19, v30
	v_pk_mul_f32 v[66:67], v[66:67], v[4:5] op_sel_hi:[1,0]
	v_lshlrev_b32_e32 v19, 16, v41
	v_and_b32_e32 v21, 0xffff0000, v41
	v_pk_fma_f32 v[70:71], v[66:67], v[48:49], v[64:65]
	v_sub_f32_e32 v67, v21, v30
	v_sub_f32_e32 v66, v19, v30
	v_pk_mul_f32 v[66:67], v[66:67], v[4:5] op_sel_hi:[1,0]
	v_lshlrev_b32_e32 v25, 16, v23
	v_and_b32_e32 v23, 0xffff0000, v23
	v_pk_fma_f32 v[66:67], v[66:67], v[42:43], v[58:59]
	v_sub_f32_e32 v41, v23, v30
	v_sub_f32_e32 v40, v25, v30
	v_pk_mul_f32 v[40:41], v[40:41], v[4:5] op_sel_hi:[1,0]
	v_pk_fma_f32 v[40:41], v[40:41], v[44:45], v[60:61]
	v_cvt_pk_bf16_f32 v66, v66, v67
	v_pk_mul_f32 v[68:69], v[68:69], v[4:5] op_sel_hi:[1,0]
	v_pk_fma_f32 v[68:69], v[68:69], v[46:47], v[62:63]
	v_cvt_pk_bf16_f32 v67, v40, v41
	v_cvt_pk_bf16_f32 v68, v68, v69
	v_cvt_pk_bf16_f32 v69, v70, v71
	v_lshlrev_b32_e32 v19, 16, v28
	v_and_b32_e32 v21, 0xffff0000, v28
	v_lshlrev_b32_e32 v23, 16, v29
	v_and_b32_e32 v25, 0xffff0000, v29
	v_sub_f32_e32 v29, v25, v16
	v_sub_f32_e32 v28, v23, v16
	v_sub_f32_e32 v41, v21, v16
	v_sub_f32_e32 v40, v19, v16
	v_lshlrev_b32_e32 v19, 16, v39
	v_and_b32_e32 v21, 0xffff0000, v39
	v_lshlrev_b32_e32 v23, 16, v27
	v_and_b32_e32 v25, 0xffff0000, v27
	global_store_dwordx4 v[52:53], v[66:69], off offset:2048
	v_sub_f32_e32 v39, v25, v16
	v_sub_f32_e32 v38, v23, v16
	v_sub_f32_e32 v67, v21, v16
	v_sub_f32_e32 v66, v19, v16
	v_pk_mul_f32 v[66:67], v[66:67], v[2:3] op_sel_hi:[1,0]
	v_pk_mul_f32 v[38:39], v[38:39], v[2:3] op_sel_hi:[1,0]
	v_pk_mul_f32 v[40:41], v[40:41], v[2:3] op_sel_hi:[1,0]
	v_pk_fma_f32 v[68:69], v[38:39], v[44:45], v[60:61]
	v_pk_fma_f32 v[38:39], v[66:67], v[42:43], v[58:59]
	v_pk_fma_f32 v[40:41], v[40:41], v[46:47], v[62:63]
	v_cvt_pk_bf16_f32 v38, v38, v39
	v_cvt_pk_bf16_f32 v39, v68, v69
	v_pk_mul_f32 v[28:29], v[28:29], v[2:3] op_sel_hi:[1,0]
	v_pk_fma_f32 v[28:29], v[28:29], v[48:49], v[64:65]
	v_cvt_pk_bf16_f32 v40, v40, v41
	v_cvt_pk_bf16_f32 v41, v28, v29
	v_lshlrev_b32_e32 v19, 16, v26
	v_and_b32_e32 v21, 0xffff0000, v26
	v_lshlrev_b32_e32 v23, 16, v33
	v_and_b32_e32 v25, 0xffff0000, v33
	v_sub_f32_e32 v27, v25, v14
	v_sub_f32_e32 v26, v23, v14
	v_sub_f32_e32 v29, v21, v14
	v_sub_f32_e32 v28, v19, v14
	v_pk_mul_f32 v[28:29], v[28:29], v[0:1] op_sel_hi:[1,0]
	v_pk_mul_f32 v[26:27], v[26:27], v[0:1] op_sel_hi:[1,0]
	v_lshlrev_b32_e32 v19, 16, v24
	v_and_b32_e32 v21, 0xffff0000, v24
	v_lshlrev_b32_e32 v23, 16, v31
	v_and_b32_e32 v24, 0xffff0000, v31
	global_store_dwordx4 v[54:55], v[38:41], off offset:2048
	v_sub_f32_e32 v25, v24, v14
	v_sub_f32_e32 v24, v23, v14
	v_pk_fma_f32 v[38:39], v[26:27], v[48:49], v[64:65]
	v_pk_fma_f32 v[26:27], v[28:29], v[46:47], v[62:63]
	v_sub_f32_e32 v29, v21, v14
	v_sub_f32_e32 v28, v19, v14
	v_pk_mul_f32 v[28:29], v[28:29], v[0:1] op_sel_hi:[1,0]
	v_pk_mul_f32 v[24:25], v[24:25], v[0:1] op_sel_hi:[1,0]
	v_lshlrev_b32_e32 v23, 16, v5
	v_pk_fma_f32 v[40:41], v[24:25], v[44:45], v[60:61]
	v_pk_fma_f32 v[24:25], v[28:29], v[42:43], v[58:59]
	v_and_b32_e32 v5, 0xffff0000, v5
	v_cvt_pk_bf16_f32 v24, v24, v25
	v_cvt_pk_bf16_f32 v25, v40, v41
	v_cvt_pk_bf16_f32 v26, v26, v27
	v_cvt_pk_bf16_f32 v27, v38, v39
	global_store_dwordx4 v[56:57], v[24:27], off offset:2048
	global_load_dwordx4 v[24:27], v[172:173], off
	s_nop 0
	global_load_dwordx4 v[38:41], v[172:173], off offset:16
	global_load_dwordx4 v[42:45], v[174:175], off
	global_load_dwordx4 v[46:49], v[174:175], off offset:16
	v_lshlrev_b32_e32 v19, 16, v37
	v_and_b32_e32 v21, 0xffff0000, v37
	v_sub_f32_e32 v29, v5, v32
	v_sub_f32_e32 v37, v21, v32
	v_sub_f32_e32 v36, v19, v32
	v_lshlrev_b32_e32 v5, 16, v35
	v_and_b32_e32 v19, 0xffff0000, v35
	v_lshlrev_b32_e32 v21, 16, v3
	v_and_b32_e32 v3, 0xffff0000, v3
	v_sub_f32_e32 v28, v23, v32
	v_sub_f32_e32 v35, v3, v32
	v_sub_f32_e32 v34, v21, v32
	v_sub_f32_e32 v33, v19, v32
	v_sub_f32_e32 v32, v5, v32
	v_pk_mul_f32 v[32:33], v[32:33], v[6:7] op_sel_hi:[1,0]
	v_pk_mul_f32 v[34:35], v[34:35], v[6:7] op_sel_hi:[1,0]
	v_pk_mul_f32 v[36:37], v[36:37], v[6:7] op_sel_hi:[1,0]
	v_pk_mul_f32 v[28:29], v[28:29], v[6:7] op_sel_hi:[1,0]
	v_lshlrev_b32_e32 v6, 16, v9
	v_and_b32_e32 v9, 0xffff0000, v9
	v_sub_f32_e32 v23, v9, v30
	v_and_b32_e32 v9, 0xffff0000, v18
	v_sub_f32_e32 v19, v9, v16
	s_waitcnt vmcnt(1)
; #define GAS __attribute__((address_space(1)))
; __device__ __forceinline__ unsigned pk2(float lo, float hi) { return f2bf(lo) | (f2bf(hi) << 16); }
; #define LN_X8(W, x) const float x##0 = bflo(W.x), x##1 = bfhi(W.x), x##2 = bflo(W.y), x##3 = bfhi(W.y), x##4 = bflo(W.z), x##5 = bfhi(W.z), x##6 = bflo(W.w), x##7 = bfhi(W.w)
; template <int NR>
; __device__ __forceinline__ void ln_rows(int lane, const bf16* Z, size_t rstride, const float* g, const float* b, float* Fout, bf16* Xout) {
;     ...
;     for (int j = 0; j < 8; ++j) { const f32x4 g0 = gr[128 * j], g1 = gr[128 * j + 1], b0 = br[128 * j], b1 = br[128 * j + 1];
; #pragma unroll
;         for (int r = 0; r < NR; ++r) { const float mu = mean[r], rs = rstd[r]; LN_X8(w[r][j], x);
;             const f32x4 o0 = (f32x4){(x0 - mu) * rs, (x1 - mu) * rs, (x2 - mu) * rs, (x3 - mu) * rs} * g0 + b0, o1 = (f32x4){(x4 - mu) * rs, (x5 - mu) * rs, (x6 - mu) * rs, (x7 - mu) * rs} * g1 + b1;
;             if (Fout) { GAS f32x4* fo = (GAS f32x4*)(Fout + r * rstride) + 2 * lane + 128 * j; fo[0] = o0; fo[1] = o1; }
;             if (Xout) { v4u ow; ow.x = pk2(o0.x, o0.y); ow.y = pk2(o0.z, o0.w); ow.z = pk2(o1.x, o1.y); ow.w = pk2(o1.z, o1.w); ((GAS v4u*)(Xout + r * rstride) + lane)[64 * j] = ow; } } }
	v_pk_fma_f32 v[32:33], v[32:33], v[24:25], v[42:43]
	s_nop 0
	v_pk_fma_f32 v[34:35], v[34:35], v[26:27], v[44:45]
	v_cvt_pk_bf16_f32 v32, v32, v33
	s_waitcnt vmcnt(0)
	v_pk_fma_f32 v[36:37], v[36:37], v[38:39], v[46:47]
	v_cvt_pk_bf16_f32 v33, v34, v35
	v_pk_fma_f32 v[28:29], v[28:29], v[40:41], v[48:49]
	v_cvt_pk_bf16_f32 v34, v36, v37
	v_cvt_pk_bf16_f32 v35, v28, v29
	v_lshlrev_b32_e32 v3, 16, v22
	v_and_b32_e32 v5, 0xffff0000, v22
	v_sub_f32_e32 v22, v6, v30
	v_sub_f32_e32 v29, v5, v30
	v_sub_f32_e32 v28, v3, v30
	v_pk_mul_f32 v[28:29], v[28:29], v[4:5] op_sel_hi:[1,0]
	v_pk_mul_f32 v[22:23], v[22:23], v[4:5] op_sel_hi:[1,0]
	v_lshlrev_b32_e32 v3, 16, v20
	v_and_b32_e32 v5, 0xffff0000, v20
	v_lshlrev_b32_e32 v6, 16, v7
	v_and_b32_e32 v7, 0xffff0000, v7
	v_sub_f32_e32 v7, v7, v30
	v_sub_f32_e32 v6, v6, v30
	v_sub_f32_e32 v21, v5, v30
	v_sub_f32_e32 v20, v3, v30
	v_pk_mul_f32 v[20:21], v[20:21], v[4:5] op_sel_hi:[1,0]
	v_pk_mul_f32 v[4:5], v[6:7], v[4:5] op_sel_hi:[1,0]
	v_pk_fma_f32 v[28:29], v[28:29], v[38:39], v[46:47]
	v_pk_fma_f32 v[6:7], v[4:5], v[26:27], v[44:45]
	v_pk_fma_f32 v[4:5], v[20:21], v[24:25], v[42:43]
	v_pk_fma_f32 v[22:23], v[22:23], v[40:41], v[48:49]
	v_cvt_pk_bf16_f32 v4, v4, v5
	v_cvt_pk_bf16_f32 v5, v6, v7
	v_cvt_pk_bf16_f32 v6, v28, v29
	v_cvt_pk_bf16_f32 v7, v22, v23
	global_store_dwordx4 v[50:51], v[32:35], off offset:3072
	global_store_dwordx4 v[52:53], v[4:7], off offset:3072
	v_lshlrev_b32_e32 v3, 16, v12
	s_nop 0
	v_and_b32_e32 v6, 0xffff0000, v12
	v_lshlrev_b32_e32 v4, 16, v13
	v_and_b32_e32 v5, 0xffff0000, v13
	v_sub_f32_e32 v5, v5, v16
	v_sub_f32_e32 v4, v4, v16
	v_sub_f32_e32 v7, v6, v16
	v_sub_f32_e32 v6, v3, v16
	v_pk_mul_f32 v[6:7], v[6:7], v[2:3] op_sel_hi:[1,0]
	v_pk_mul_f32 v[4:5], v[4:5], v[2:3] op_sel_hi:[1,0]
	v_lshlrev_b32_e32 v3, 16, v18
	v_pk_fma_f32 v[12:13], v[4:5], v[40:41], v[48:49]
	v_pk_fma_f32 v[4:5], v[6:7], v[38:39], v[46:47]
	v_lshlrev_b32_e32 v6, 16, v11
	v_and_b32_e32 v7, 0xffff0000, v11
	v_sub_f32_e32 v7, v7, v16
	v_sub_f32_e32 v6, v6, v16
	v_sub_f32_e32 v18, v3, v16
	v_pk_mul_f32 v[18:19], v[18:19], v[2:3] op_sel_hi:[1,0]
	v_pk_mul_f32 v[2:3], v[6:7], v[2:3] op_sel_hi:[1,0]
	s_nop 0
	v_pk_fma_f32 v[6:7], v[2:3], v[26:27], v[44:45]
	v_pk_fma_f32 v[2:3], v[18:19], v[24:25], v[42:43]
	s_nop 0
	v_cvt_pk_bf16_f32 v2, v2, v3
	v_cvt_pk_bf16_f32 v3, v6, v7
	v_cvt_pk_bf16_f32 v4, v4, v5
	v_bfe_u32 v5, v12, 16, 1
	v_add3_u32 v5, v12, v5, s25
	v_bfe_u32 v6, v13, 16, 1
	v_lshrrev_b32_e32 v5, 16, v5
	v_add3_u32 v6, v13, v6, s25
	v_and_or_b32 v5, v6, s33, v5
	global_store_dwordx4 v[54:55], v[2:5], off offset:3072
	s_nop 1
	v_lshlrev_b32_e32 v2, 16, v17
	v_and_b32_e32 v3, 0xffff0000, v17
	v_sub_f32_e32 v3, v3, v14
	v_sub_f32_e32 v2, v2, v14
	v_pk_mul_f32 v[2:3], v[2:3], v[0:1] op_sel_hi:[1,0]
	v_lshlrev_b32_e32 v4, 16, v10
	v_and_b32_e32 v5, 0xffff0000, v10
	v_pk_fma_f32 v[6:7], v[2:3], v[40:41], v[48:49]
	v_lshlrev_b32_e32 v10, 16, v8
	v_and_b32_e32 v8, 0xffff0000, v8
	v_lshlrev_b32_e32 v2, 16, v15
	v_and_b32_e32 v3, 0xffff0000, v15
	v_sub_f32_e32 v3, v3, v14
	v_sub_f32_e32 v2, v2, v14
	v_sub_f32_e32 v9, v8, v14
	v_sub_f32_e32 v8, v10, v14
	v_pk_mul_f32 v[8:9], v[8:9], v[0:1] op_sel_hi:[1,0]
	v_pk_mul_f32 v[2:3], v[2:3], v[0:1] op_sel_hi:[1,0]
	v_sub_f32_e32 v5, v5, v14
	v_sub_f32_e32 v4, v4, v14
	v_pk_fma_f32 v[10:11], v[2:3], v[26:27], v[44:45]
	v_pk_fma_f32 v[2:3], v[8:9], v[24:25], v[42:43]
	v_pk_mul_f32 v[4:5], v[4:5], v[0:1] op_sel_hi:[1,0]
	v_cvt_pk_bf16_f32 v2, v2, v3
	v_pk_fma_f32 v[4:5], v[4:5], v[38:39], v[46:47]
	v_cvt_pk_bf16_f32 v3, v10, v11
	v_cvt_pk_bf16_f32 v4, v4, v5
	v_cvt_pk_bf16_f32 v5, v6, v7
	global_store_dwordx4 v[56:57], v[2:5], off offset:3072
	s_branch .LBB0_1011

; #define GAS __attribute__((address_space(1)))
; template <bool IN_BF16>
; __device__ __forceinline__ void ln_row(int lane, const void* zrow, const float* g, const float* b, float* hrow, bf16* xrow) {
;     ...
;     if (IN_BF16) { const GAS v2u* zr = (const GAS v2u*)zrow + lane;
; #pragma unroll
;         for (int j = 0; j < 16; ++j) { const v2u w = zr[64 * j]; v[j] = (f32x4){bflo(w.x), bfhi(w.x), bflo(w.y), bfhi(w.y)}; s += (v[j].x + v[j].y) + (v[j].z + v[j].w); } }
;     else { const GAS f32x4* zr = (const GAS f32x4*)zrow + lane;
; #pragma unroll
;         for (int j = 0; j < 16; ++j) { v[j] = zr[64 * j]; s += (v[j].x + v[j].y) + (v[j].z + v[j].w); } }
;     const float mean = wave_sum(s) * (1.f / DM); float s2 = 0.f;
.LBB0_1017:
	s_add_u32 s14, s34, s50
	s_addc_u32 s15, s35, s51
	v_lshl_add_u64 v[54:55], v[146:147], 3, s[14:15]
	global_load_dwordx2 v[56:57], v[54:55], off
	global_load_dwordx2 v[58:59], v[54:55], off offset:512
	global_load_dwordx2 v[60:61], v[54:55], off offset:1024
	global_load_dwordx2 v[62:63], v[54:55], off offset:1536
	global_load_dwordx2 v[64:65], v[54:55], off offset:2048
	global_load_dwordx2 v[66:67], v[54:55], off offset:2560
	global_load_dwordx2 v[68:69], v[54:55], off offset:3072
	global_load_dwordx2 v[70:71], v[54:55], off offset:3584
	v_add_co_u32_e32 v54, vcc, s20, v54
	s_waitcnt vmcnt(7)
	v_lshlrev_b32_e32 v118, 16, v56
	v_addc_co_u32_e32 v55, vcc, 0, v55, vcc
	global_load_dwordx2 v[72:73], v[54:55], off
	global_load_dwordx2 v[74:75], v[54:55], off offset:512
	global_load_dwordx2 v[76:77], v[54:55], off offset:1024
	global_load_dwordx2 v[98:99], v[54:55], off offset:1536
	global_load_dwordx2 v[120:121], v[54:55], off offset:2048
	global_load_dwordx2 v[122:123], v[54:55], off offset:2560
	global_load_dwordx2 v[124:125], v[54:55], off offset:3072
	global_load_dwordx2 v[126:127], v[54:55], off offset:3584
	v_and_b32_e32 v119, 0xffff0000, v56
	v_lshlrev_b32_e32 v116, 16, v57
	v_and_b32_e32 v117, 0xffff0000, v57
	s_waitcnt vmcnt(14)
	v_lshlrev_b32_e32 v112, 16, v58
	v_and_b32_e32 v113, 0xffff0000, v58
	v_lshlrev_b32_e32 v114, 16, v59
	v_and_b32_e32 v115, 0xffff0000, v59
	v_add_f32_e32 v0, v118, v119
	v_add_f32_e32 v54, v116, v117
	s_waitcnt vmcnt(13)
	v_lshlrev_b32_e32 v108, 16, v60
	v_and_b32_e32 v109, 0xffff0000, v60
	v_lshlrev_b32_e32 v110, 16, v61
	v_and_b32_e32 v111, 0xffff0000, v61
	v_add_f32_e32 v55, v112, v113
	v_add_f32_e32 v56, v114, v115
	v_add_f32_e32 v0, v0, v54
	s_waitcnt vmcnt(12)
	v_lshlrev_b32_e32 v104, 16, v62
	v_and_b32_e32 v105, 0xffff0000, v62
	v_lshlrev_b32_e32 v106, 16, v63
	v_and_b32_e32 v107, 0xffff0000, v63
	v_add_f32_e32 v57, v108, v109
	v_add_f32_e32 v58, v110, v111
	v_add_f32_e32 v54, v55, v56
	v_add_f32_e32 v0, 0, v0
	s_waitcnt vmcnt(11)
	v_lshlrev_b32_e32 v100, 16, v64
	v_and_b32_e32 v101, 0xffff0000, v64
	v_lshlrev_b32_e32 v102, 16, v65
	v_and_b32_e32 v103, 0xffff0000, v65
	v_add_f32_e32 v59, v104, v105
	v_add_f32_e32 v60, v106, v107
	v_add_f32_e32 v55, v57, v58
	v_add_f32_e32 v0, v0, v54
	s_waitcnt vmcnt(10)
	v_lshlrev_b32_e32 v94, 16, v66
	v_and_b32_e32 v95, 0xffff0000, v66
	v_lshlrev_b32_e32 v96, 16, v67
	v_and_b32_e32 v97, 0xffff0000, v67
	v_add_f32_e32 v61, v100, v101
	v_add_f32_e32 v62, v102, v103
	v_add_f32_e32 v56, v59, v60
	v_add_f32_e32 v0, v0, v55
	s_waitcnt vmcnt(9)
	v_lshlrev_b32_e32 v90, 16, v68
	v_and_b32_e32 v91, 0xffff0000, v68
	v_lshlrev_b32_e32 v92, 16, v69
	v_and_b32_e32 v93, 0xffff0000, v69
	v_add_f32_e32 v63, v94, v95
	v_add_f32_e32 v64, v96, v97
	v_add_f32_e32 v57, v61, v62
	v_add_f32_e32 v0, v0, v56
	s_waitcnt vmcnt(8)
	v_lshlrev_b32_e32 v86, 16, v70
	v_and_b32_e32 v87, 0xffff0000, v70
	v_lshlrev_b32_e32 v88, 16, v71
	v_and_b32_e32 v89, 0xffff0000, v71
	v_add_f32_e32 v65, v90, v91
	v_add_f32_e32 v66, v92, v93
	v_add_f32_e32 v58, v63, v64
	v_add_f32_e32 v0, v0, v57
	v_add_f32_e32 v67, v86, v87
	v_add_f32_e32 v68, v88, v89
	v_add_f32_e32 v59, v65, v66
	v_add_f32_e32 v0, v0, v58
	v_add_f32_e32 v60, v67, v68
	v_add_f32_e32 v0, v0, v59
	v_add_f32_e32 v0, v0, v60
	s_andn2_b64 vcc, exec, s[26:27]
	s_waitcnt vmcnt(7)
	v_lshlrev_b32_e32 v82, 16, v72
	v_and_b32_e32 v83, 0xffff0000, v72
	v_lshlrev_b32_e32 v84, 16, v73
	v_and_b32_e32 v85, 0xffff0000, v73
	v_add_f32_e32 v61, v82, v83
	v_add_f32_e32 v62, v84, v85
	s_waitcnt vmcnt(6)
	v_lshlrev_b32_e32 v78, 16, v74
	v_and_b32_e32 v79, 0xffff0000, v74
	v_lshlrev_b32_e32 v80, 16, v75
	v_and_b32_e32 v81, 0xffff0000, v75
	v_add_f32_e32 v61, v61, v62
	v_add_f32_e32 v54, v78, v79
	v_add_f32_e32 v55, v80, v81
	v_add_f32_e32 v0, v0, v61
	v_add_f32_e32 v54, v54, v55
	s_waitcnt vmcnt(5)
	v_lshlrev_b32_e32 v74, 16, v76
	v_and_b32_e32 v75, 0xffff0000, v76
	v_lshlrev_b32_e32 v76, 16, v77
	v_and_b32_e32 v77, 0xffff0000, v77
	v_add_f32_e32 v0, v0, v54
	v_add_f32_e32 v54, v74, v75
	v_add_f32_e32 v55, v76, v77
	v_add_f32_e32 v54, v54, v55
	s_waitcnt vmcnt(4)
	v_lshlrev_b32_e32 v70, 16, v98
	v_and_b32_e32 v71, 0xffff0000, v98
	v_lshlrev_b32_e32 v72, 16, v99
	v_and_b32_e32 v73, 0xffff0000, v99
	v_add_f32_e32 v0, v0, v54
	v_add_f32_e32 v54, v70, v71
	v_add_f32_e32 v55, v72, v73
	v_add_f32_e32 v54, v54, v55
	s_waitcnt vmcnt(3)
	v_lshlrev_b32_e32 v66, 16, v120
	v_and_b32_e32 v67, 0xffff0000, v120
	v_lshlrev_b32_e32 v68, 16, v121
	v_and_b32_e32 v69, 0xffff0000, v121
	v_add_f32_e32 v0, v0, v54
	v_add_f32_e32 v54, v66, v67
	v_add_f32_e32 v55, v68, v69
	v_add_f32_e32 v54, v54, v55
	s_waitcnt vmcnt(2)
	v_lshlrev_b32_e32 v62, 16, v122
	v_and_b32_e32 v63, 0xffff0000, v122
	v_lshlrev_b32_e32 v64, 16, v123
	v_and_b32_e32 v65, 0xffff0000, v123
	v_add_f32_e32 v0, v0, v54
	v_add_f32_e32 v54, v62, v63
	v_add_f32_e32 v55, v64, v65
	v_add_f32_e32 v54, v54, v55
	s_waitcnt vmcnt(1)
	v_lshlrev_b32_e32 v58, 16, v124
	v_and_b32_e32 v59, 0xffff0000, v124
	v_lshlrev_b32_e32 v60, 16, v125
	v_and_b32_e32 v61, 0xffff0000, v125
	v_add_f32_e32 v0, v0, v54
	v_add_f32_e32 v54, v58, v59
	v_add_f32_e32 v55, v60, v61
	v_add_f32_e32 v54, v54, v55
	v_add_f32_e32 v0, v0, v54
	s_waitcnt vmcnt(0)
; template <bool IN_BF16>
; __device__ __forceinline__ void ln_row(int lane, const void* zrow, const float* g, const float* b, float* hrow, bf16* xrow) {
;     ...
;     const float mean = wave_sum(s) * (1.f / DM); float s2 = 0.f;
; #pragma unroll
;     for (int j = 0; j < 16; ++j) { v[j] = v[j] - mean; s2 += (v[j].x * v[j].x + v[j].y * v[j].y) + (v[j].z * v[j].z + v[j].w * v[j].w); }
;     const float rstd = 1.f / sqrtf(wave_sum(s2) * (1.f / DM) + LN_EPS);
	v_lshlrev_b32_e32 v54, 16, v126
	v_and_b32_e32 v55, 0xffff0000, v126
	v_lshlrev_b32_e32 v56, 16, v127
	v_and_b32_e32 v57, 0xffff0000, v127
	v_add_f32_e32 v98, v54, v55
	v_add_f32_e32 v99, v56, v57
	v_add_f32_e32 v98, v98, v99
	v_add_f32_e32 v0, v0, v98
	s_nop 1
	v_add_f32_dpp v0, v0, v0 quad_perm:[1,0,3,2] row_mask:0xf bank_mask:0xf bound_ctrl:1
	s_nop 1
	v_add_f32_dpp v0, v0, v0 quad_perm:[2,3,0,1] row_mask:0xf bank_mask:0xf bound_ctrl:1
	s_nop 1
	v_add_f32_dpp v0, v0, v0 row_half_mirror row_mask:0xf bank_mask:0xf bound_ctrl:1
	s_nop 1
	v_add_f32_dpp v0, v0, v0 row_mirror row_mask:0xf bank_mask:0xf bound_ctrl:1
	v_mov_b32_e32 v98, v0
	s_nop 1
	v_permlane16_swap_b32_e32 v0, v98
	v_add_f32_e32 v0, v0, v98
	v_mov_b32_e32 v98, v0
	s_nop 1
	v_permlane32_swap_b32_e32 v0, v98
	v_add_f32_e32 v0, v0, v98
	v_fmac_f32_e32 v117, 0xb9800000, v0
	v_fmac_f32_e32 v119, 0xb9800000, v0
	v_fmac_f32_e32 v116, 0xb9800000, v0
	v_fmac_f32_e32 v118, 0xb9800000, v0
	v_mul_f32_e32 v98, v119, v119
	v_mul_f32_e32 v99, v117, v117
	v_fmac_f32_e32 v98, v118, v118
	v_fmac_f32_e32 v99, v116, v116
	v_fmac_f32_e32 v115, 0xb9800000, v0
	v_fmac_f32_e32 v113, 0xb9800000, v0
	v_add_f32_e32 v98, v98, v99
	v_fmac_f32_e32 v114, 0xb9800000, v0
	v_fmac_f32_e32 v112, 0xb9800000, v0
	v_mul_f32_e32 v99, v113, v113
	v_mul_f32_e32 v120, v115, v115
	v_fmac_f32_e32 v99, v112, v112
	v_fmac_f32_e32 v120, v114, v114
	v_add_f32_e32 v99, v99, v120
	v_fmac_f32_e32 v111, 0xb9800000, v0
	v_fmac_f32_e32 v109, 0xb9800000, v0
	v_add_f32_e32 v98, v98, v99
	v_fmac_f32_e32 v110, 0xb9800000, v0
	v_fmac_f32_e32 v108, 0xb9800000, v0
	v_mul_f32_e32 v99, v109, v109
	v_mul_f32_e32 v120, v111, v111
	v_fmac_f32_e32 v99, v108, v108
	v_fmac_f32_e32 v120, v110, v110
	v_add_f32_e32 v99, v99, v120
	v_fmac_f32_e32 v107, 0xb9800000, v0
	v_fmac_f32_e32 v105, 0xb9800000, v0
	v_add_f32_e32 v98, v99, v98
	v_fmac_f32_e32 v106, 0xb9800000, v0
	v_fmac_f32_e32 v104, 0xb9800000, v0
	v_mul_f32_e32 v99, v105, v105
	v_mul_f32_e32 v120, v107, v107
	v_fmac_f32_e32 v99, v104, v104
	v_fmac_f32_e32 v120, v106, v106
	v_add_f32_e32 v99, v99, v120
	v_fmac_f32_e32 v103, 0xb9800000, v0
	v_fmac_f32_e32 v101, 0xb9800000, v0
	v_add_f32_e32 v98, v99, v98
	v_fmac_f32_e32 v102, 0xb9800000, v0
	v_fmac_f32_e32 v100, 0xb9800000, v0
	v_mul_f32_e32 v99, v101, v101
	v_mul_f32_e32 v120, v103, v103
	v_fmac_f32_e32 v99, v100, v100
	v_fmac_f32_e32 v120, v102, v102
	v_add_f32_e32 v99, v99, v120
	v_fmac_f32_e32 v97, 0xb9800000, v0
	v_fmac_f32_e32 v95, 0xb9800000, v0
	v_add_f32_e32 v98, v99, v98
	v_fmac_f32_e32 v96, 0xb9800000, v0
	v_fmac_f32_e32 v94, 0xb9800000, v0
	v_mul_f32_e32 v99, v95, v95
	v_mul_f32_e32 v120, v97, v97
	v_fmac_f32_e32 v99, v94, v94
	v_fmac_f32_e32 v120, v96, v96
	v_add_f32_e32 v99, v99, v120
	v_fmac_f32_e32 v93, 0xb9800000, v0
	v_fmac_f32_e32 v91, 0xb9800000, v0
	v_add_f32_e32 v98, v99, v98
	v_fmac_f32_e32 v92, 0xb9800000, v0
	v_fmac_f32_e32 v90, 0xb9800000, v0
	v_mul_f32_e32 v99, v91, v91
	v_mul_f32_e32 v120, v93, v93
	v_fmac_f32_e32 v99, v90, v90
	v_fmac_f32_e32 v120, v92, v92
	v_add_f32_e32 v99, v99, v120
	v_fmac_f32_e32 v89, 0xb9800000, v0
	v_fmac_f32_e32 v87, 0xb9800000, v0
	v_add_f32_e32 v98, v99, v98
	v_fmac_f32_e32 v88, 0xb9800000, v0
	v_fmac_f32_e32 v86, 0xb9800000, v0
	v_mul_f32_e32 v99, v87, v87
	v_mul_f32_e32 v120, v89, v89
	v_fmac_f32_e32 v99, v86, v86
	v_fmac_f32_e32 v120, v88, v88
	v_add_f32_e32 v99, v99, v120
	v_fmac_f32_e32 v85, 0xb9800000, v0
	v_fmac_f32_e32 v83, 0xb9800000, v0
	v_add_f32_e32 v98, v99, v98
	v_fmac_f32_e32 v84, 0xb9800000, v0
	v_fmac_f32_e32 v82, 0xb9800000, v0
	v_mul_f32_e32 v99, v83, v83
	v_mul_f32_e32 v120, v85, v85
	v_fmac_f32_e32 v99, v82, v82
	v_fmac_f32_e32 v120, v84, v84
	v_add_f32_e32 v99, v99, v120
	v_fmac_f32_e32 v81, 0xb9800000, v0
	v_fmac_f32_e32 v79, 0xb9800000, v0
	v_add_f32_e32 v98, v99, v98
	v_fmac_f32_e32 v80, 0xb9800000, v0
	v_fmac_f32_e32 v78, 0xb9800000, v0
	v_mul_f32_e32 v99, v79, v79
	v_mul_f32_e32 v120, v81, v81
	v_fmac_f32_e32 v99, v78, v78
	v_fmac_f32_e32 v120, v80, v80
	v_add_f32_e32 v99, v99, v120
	v_fmac_f32_e32 v77, 0xb9800000, v0
	v_fmac_f32_e32 v75, 0xb9800000, v0
	v_add_f32_e32 v98, v99, v98
	v_fmac_f32_e32 v76, 0xb9800000, v0
	v_fmac_f32_e32 v74, 0xb9800000, v0
	v_mul_f32_e32 v99, v75, v75
	v_mul_f32_e32 v120, v77, v77
	v_fmac_f32_e32 v99, v74, v74
	v_fmac_f32_e32 v120, v76, v76
	v_add_f32_e32 v99, v99, v120
	v_fmac_f32_e32 v73, 0xb9800000, v0
	v_fmac_f32_e32 v71, 0xb9800000, v0
	v_add_f32_e32 v98, v99, v98
	v_fmac_f32_e32 v72, 0xb9800000, v0
	v_fmac_f32_e32 v70, 0xb9800000, v0
	v_mul_f32_e32 v99, v71, v71
	v_mul_f32_e32 v120, v73, v73
	v_fmac_f32_e32 v99, v70, v70
	v_fmac_f32_e32 v120, v72, v72
	v_add_f32_e32 v99, v99, v120
	v_fmac_f32_e32 v69, 0xb9800000, v0
	v_fmac_f32_e32 v67, 0xb9800000, v0
	v_add_f32_e32 v98, v99, v98
	v_fmac_f32_e32 v68, 0xb9800000, v0
	v_fmac_f32_e32 v66, 0xb9800000, v0
	v_mul_f32_e32 v99, v67, v67
	v_mul_f32_e32 v120, v69, v69
	v_fmac_f32_e32 v99, v66, v66
	v_fmac_f32_e32 v120, v68, v68
	v_add_f32_e32 v99, v99, v120
	v_fmac_f32_e32 v65, 0xb9800000, v0
	v_fmac_f32_e32 v63, 0xb9800000, v0
	v_add_f32_e32 v98, v99, v98
	v_fmac_f32_e32 v64, 0xb9800000, v0
	v_fmac_f32_e32 v62, 0xb9800000, v0
	v_mul_f32_e32 v99, v63, v63
	v_mul_f32_e32 v120, v65, v65
	v_fmac_f32_e32 v99, v62, v62
	v_fmac_f32_e32 v120, v64, v64
	v_add_f32_e32 v99, v99, v120
	v_fmac_f32_e32 v61, 0xb9800000, v0
	v_fmac_f32_e32 v59, 0xb9800000, v0
	v_add_f32_e32 v98, v99, v98
	v_fmac_f32_e32 v60, 0xb9800000, v0
	v_fmac_f32_e32 v58, 0xb9800000, v0
	v_mul_f32_e32 v99, v59, v59
	v_mul_f32_e32 v120, v61, v61
	v_fmac_f32_e32 v99, v58, v58
	v_fmac_f32_e32 v120, v60, v60
	v_add_f32_e32 v99, v99, v120
	v_fmac_f32_e32 v57, 0xb9800000, v0
	v_fmac_f32_e32 v55, 0xb9800000, v0
	v_add_f32_e32 v98, v99, v98
	v_fmac_f32_e32 v56, 0xb9800000, v0
	v_fmac_f32_e32 v54, 0xb9800000, v0
	v_mul_f32_e32 v0, v55, v55
	v_mul_f32_e32 v99, v57, v57
	v_fmac_f32_e32 v0, v54, v54
	v_fmac_f32_e32 v99, v56, v56
	v_add_f32_e32 v0, v0, v99
	v_add_f32_e32 v0, v0, v98
	s_nop 1
	v_add_f32_dpp v0, v0, v0 quad_perm:[1,0,3,2] row_mask:0xf bank_mask:0xf bound_ctrl:1
	s_nop 1
	v_add_f32_dpp v0, v0, v0 quad_perm:[2,3,0,1] row_mask:0xf bank_mask:0xf bound_ctrl:1
	s_nop 1
	v_add_f32_dpp v0, v0, v0 row_half_mirror row_mask:0xf bank_mask:0xf bound_ctrl:1
	s_nop 1
	v_add_f32_dpp v0, v0, v0 row_mirror row_mask:0xf bank_mask:0xf bound_ctrl:1
	v_mov_b32_e32 v98, v0
	s_nop 1
	v_permlane16_swap_b32_e32 v0, v98
	v_add_f32_e32 v0, v0, v98
	v_mov_b32_e32 v120, v0
	s_nop 1
	v_permlane32_swap_b32_e32 v0, v120
	s_cbranch_vccnz .LBB0_1016
; #define GAS __attribute__((address_space(1)))
; __device__ __forceinline__ unsigned pk2(float lo, float hi) { return f2bf(lo) | (f2bf(hi) << 16); }
; template <bool IN_BF16>
; __device__ __forceinline__ void ln_row(int lane, const void* zrow, const float* g, const float* b, float* hrow, bf16* xrow) {
;     ...
;     const float rstd = 1.f / sqrtf(wave_sum(s2) * (1.f / DM) + LN_EPS);
;     const GAS f32x4* gr = (const GAS f32x4*)g + lane; const GAS f32x4* br = (const GAS f32x4*)b + lane;
; #pragma unroll
;     for (int j = 0; j < 16; ++j) { const f32x4 o = v[j] * rstd * gr[64 * j] + br[64 * j];
;         if (hrow) ((GAS f32x4*)hrow + lane)[64 * j] = o;
;         if (xrow) ((GAS unsigned long long*)xrow + lane)[64 * j] = (unsigned long long)pk2(o.x, o.y) | ((unsigned long long)pk2(o.z, o.w) << 32); }
	v_add_f32_e32 v0, v0, v120
	v_fmamk_f32 v0, v0, 0x39800000, v233
	v_cmp_gt_f32_e32 vcc, s19, v0
	v_mul_f32_e32 v120, 0x4f800000, v0
	s_add_u32 s14, s46, s50
	v_cndmask_b32_e32 v0, v0, v120, vcc
	v_sqrt_f32_e32 v120, v0
	s_addc_u32 s15, s47, s51
	v_lshl_add_u64 v[98:99], v[146:147], 3, s[14:15]
	v_add_u32_e32 v121, -1, v120
	v_fma_f32 v122, -v121, v120, v0
	v_cmp_ge_f32_e64 s[42:43], 0, v122
	v_add_u32_e32 v122, 1, v120
	s_nop 0
	v_cndmask_b32_e64 v121, v120, v121, s[42:43]
	v_fma_f32 v120, -v122, v120, v0
	v_cmp_lt_f32_e64 s[42:43], 0, v120
	s_nop 1
	v_cndmask_b32_e64 v120, v121, v122, s[42:43]
	v_mul_f32_e32 v121, 0x37800000, v120
	v_cndmask_b32_e32 v120, v120, v121, vcc
	v_cmp_class_f32_e32 vcc, v0, v238
	s_nop 1
	v_cndmask_b32_e32 v0, v120, v0, vcc
	v_div_scale_f32 v120, s[14:15], v0, v0, 1.0
	v_rcp_f32_e32 v121, v120
	s_nop 0
	v_fma_f32 v122, -v120, v121, 1.0
	v_fmac_f32_e32 v121, v122, v121
	v_div_scale_f32 v122, vcc, 1.0, v0, 1.0
	v_mul_f32_e32 v123, v122, v121
	v_fma_f32 v124, -v120, v123, v122
	v_fmac_f32_e32 v123, v124, v121
	v_fma_f32 v120, -v120, v123, v122
	v_div_fmas_f32 v120, v120, v121, v123
	v_div_fixup_f32 v0, v120, v0, 1.0
	global_load_dwordx4 v[120:123], v[4:5], off
	global_load_dwordx4 v[124:127], v[2:3], off
	v_pk_mul_f32 v[118:119], v[118:119], v[0:1] op_sel_hi:[1,0]
	v_pk_mul_f32 v[116:117], v[116:117], v[0:1] op_sel_hi:[1,0]
	s_waitcnt vmcnt(0)
	v_pk_fma_f32 v[118:119], v[118:119], v[124:125], v[120:121]
	s_nop 0
	v_pk_fma_f32 v[116:117], v[116:117], v[126:127], v[122:123]
	v_cvt_pk_bf16_f32 v118, v118, v119
	v_cvt_pk_bf16_f32 v119, v116, v117
	global_store_dwordx2 v[98:99], v[118:119], off
	v_pk_mul_f32 v[120:121], v[112:113], v[0:1] op_sel_hi:[1,0]
	v_pk_mul_f32 v[122:123], v[114:115], v[0:1] op_sel_hi:[1,0]
	global_load_dwordx4 v[112:115], v[2:3], off offset:1024
	global_load_dwordx4 v[116:119], v[4:5], off offset:1024
	s_waitcnt vmcnt(0)
	v_pk_fma_f32 v[112:113], v[120:121], v[112:113], v[116:117]
	s_nop 0
	v_pk_fma_f32 v[114:115], v[122:123], v[114:115], v[118:119]
	v_cvt_pk_bf16_f32 v112, v112, v113
	v_cvt_pk_bf16_f32 v113, v114, v115
	global_store_dwordx2 v[98:99], v[112:113], off offset:512
	v_pk_mul_f32 v[116:117], v[108:109], v[0:1] op_sel_hi:[1,0]
	v_pk_mul_f32 v[118:119], v[110:111], v[0:1] op_sel_hi:[1,0]
	global_load_dwordx4 v[108:111], v[2:3], off offset:2048
	global_load_dwordx4 v[112:115], v[4:5], off offset:2048
	s_waitcnt vmcnt(0)
	v_pk_fma_f32 v[108:109], v[116:117], v[108:109], v[112:113]
	s_nop 0
	v_pk_fma_f32 v[110:111], v[118:119], v[110:111], v[114:115]
	v_cvt_pk_bf16_f32 v108, v108, v109
	v_cvt_pk_bf16_f32 v109, v110, v111
	global_store_dwordx2 v[98:99], v[108:109], off offset:1024
	v_pk_mul_f32 v[112:113], v[104:105], v[0:1] op_sel_hi:[1,0]
	v_pk_mul_f32 v[114:115], v[106:107], v[0:1] op_sel_hi:[1,0]
	global_load_dwordx4 v[104:107], v[2:3], off offset:3072
	global_load_dwordx4 v[108:111], v[4:5], off offset:3072
	s_waitcnt vmcnt(0)
	v_pk_fma_f32 v[104:105], v[112:113], v[104:105], v[108:109]
	s_nop 0
	v_pk_fma_f32 v[106:107], v[114:115], v[106:107], v[110:111]
	v_cvt_pk_bf16_f32 v104, v104, v105
	v_cvt_pk_bf16_f32 v105, v106, v107
	global_store_dwordx2 v[98:99], v[104:105], off offset:1536
	v_pk_mul_f32 v[108:109], v[100:101], v[0:1] op_sel_hi:[1,0]
	v_pk_mul_f32 v[110:111], v[102:103], v[0:1] op_sel_hi:[1,0]
	global_load_dwordx4 v[100:103], v[6:7], off
	global_load_dwordx4 v[104:107], v[8:9], off
	s_waitcnt vmcnt(0)
	v_pk_fma_f32 v[100:101], v[108:109], v[100:101], v[104:105]
	s_nop 0
	v_pk_fma_f32 v[102:103], v[110:111], v[102:103], v[106:107]
	v_cvt_pk_bf16_f32 v100, v100, v101
	v_cvt_pk_bf16_f32 v101, v102, v103
	global_store_dwordx2 v[98:99], v[100:101], off offset:2048
	v_pk_mul_f32 v[104:105], v[94:95], v[0:1] op_sel_hi:[1,0]
	v_pk_mul_f32 v[106:107], v[96:97], v[0:1] op_sel_hi:[1,0]
	global_load_dwordx4 v[94:97], v[10:11], off
	global_load_dwordx4 v[100:103], v[12:13], off
	s_waitcnt vmcnt(0)
	v_pk_fma_f32 v[94:95], v[104:105], v[94:95], v[100:101]
	s_nop 0
	v_pk_fma_f32 v[96:97], v[106:107], v[96:97], v[102:103]
	v_cvt_pk_bf16_f32 v94, v94, v95
	v_cvt_pk_bf16_f32 v95, v96, v97
	global_store_dwordx2 v[98:99], v[94:95], off offset:2560
	v_pk_mul_f32 v[100:101], v[90:91], v[0:1] op_sel_hi:[1,0]
	v_pk_mul_f32 v[102:103], v[92:93], v[0:1] op_sel_hi:[1,0]
	global_load_dwordx4 v[90:93], v[14:15], off
	global_load_dwordx4 v[94:97], v[16:17], off
	s_waitcnt vmcnt(0)
; #define GAS __attribute__((address_space(1)))
; __device__ __forceinline__ unsigned pk2(float lo, float hi) { return f2bf(lo) | (f2bf(hi) << 16); }
; template <bool IN_BF16>
; __device__ __forceinline__ void ln_row(int lane, const void* zrow, const float* g, const float* b, float* hrow, bf16* xrow) {
;     ...
;     for (int j = 0; j < 16; ++j) { const f32x4 o = v[j] * rstd * gr[64 * j] + br[64 * j];
;         if (hrow) ((GAS f32x4*)hrow + lane)[64 * j] = o;
;         if (xrow) ((GAS unsigned long long*)xrow + lane)[64 * j] = (unsigned long long)pk2(o.x, o.y) | ((unsigned long long)pk2(o.z, o.w) << 32); }
	v_pk_fma_f32 v[90:91], v[100:101], v[90:91], v[94:95]
	s_nop 0
	v_pk_fma_f32 v[92:93], v[102:103], v[92:93], v[96:97]
	v_cvt_pk_bf16_f32 v90, v90, v91
	v_cvt_pk_bf16_f32 v91, v92, v93
	global_store_dwordx2 v[98:99], v[90:91], off offset:3072
	v_pk_mul_f32 v[94:95], v[86:87], v[0:1] op_sel_hi:[1,0]
	v_pk_mul_f32 v[96:97], v[88:89], v[0:1] op_sel_hi:[1,0]
	global_load_dwordx4 v[86:89], v[18:19], off
	global_load_dwordx4 v[90:93], v[20:21], off
	s_waitcnt vmcnt(0)
	v_pk_fma_f32 v[86:87], v[94:95], v[86:87], v[90:91]
	s_nop 0
	v_pk_fma_f32 v[88:89], v[96:97], v[88:89], v[92:93]
	v_cvt_pk_bf16_f32 v86, v86, v87
	v_cvt_pk_bf16_f32 v87, v88, v89
	global_store_dwordx2 v[98:99], v[86:87], off offset:3584
	v_pk_mul_f32 v[90:91], v[82:83], v[0:1] op_sel_hi:[1,0]
	v_pk_mul_f32 v[92:93], v[84:85], v[0:1] op_sel_hi:[1,0]
	global_load_dwordx4 v[82:85], v[22:23], off
	global_load_dwordx4 v[86:89], v[24:25], off
	s_waitcnt vmcnt(0)
	v_pk_fma_f32 v[82:83], v[90:91], v[82:83], v[86:87]
	s_nop 0
	v_pk_fma_f32 v[84:85], v[92:93], v[84:85], v[88:89]
	v_cvt_pk_bf16_f32 v86, v82, v83
	v_cvt_pk_bf16_f32 v87, v84, v85
	v_add_co_u32_e32 v82, vcc, s20, v98
	v_pk_mul_f32 v[88:89], v[78:79], v[0:1] op_sel_hi:[1,0]
	s_nop 0
	v_addc_co_u32_e32 v83, vcc, 0, v99, vcc
	global_store_dwordx2 v[82:83], v[86:87], off
	v_pk_mul_f32 v[90:91], v[80:81], v[0:1] op_sel_hi:[1,0]
	global_load_dwordx4 v[78:81], v[26:27], off
	global_load_dwordx4 v[84:87], v[28:29], off
	s_waitcnt vmcnt(0)
	v_pk_fma_f32 v[78:79], v[88:89], v[78:79], v[84:85]
	s_nop 0
	v_pk_fma_f32 v[80:81], v[90:91], v[80:81], v[86:87]
	v_cvt_pk_bf16_f32 v78, v78, v79
	v_cvt_pk_bf16_f32 v79, v80, v81
	global_store_dwordx2 v[82:83], v[78:79], off offset:512
	v_pk_mul_f32 v[84:85], v[74:75], v[0:1] op_sel_hi:[1,0]
	v_pk_mul_f32 v[86:87], v[76:77], v[0:1] op_sel_hi:[1,0]
	global_load_dwordx4 v[74:77], v[30:31], off
	global_load_dwordx4 v[78:81], v[32:33], off
	s_waitcnt vmcnt(0)
	v_pk_fma_f32 v[74:75], v[84:85], v[74:75], v[78:79]
	s_nop 0
	v_pk_fma_f32 v[76:77], v[86:87], v[76:77], v[80:81]
	v_cvt_pk_bf16_f32 v74, v74, v75
	v_cvt_pk_bf16_f32 v75, v76, v77
	global_store_dwordx2 v[82:83], v[74:75], off offset:1024
	v_pk_mul_f32 v[78:79], v[70:71], v[0:1] op_sel_hi:[1,0]
	v_pk_mul_f32 v[80:81], v[72:73], v[0:1] op_sel_hi:[1,0]
	global_load_dwordx4 v[70:73], v[34:35], off
	global_load_dwordx4 v[74:77], v[36:37], off
	s_waitcnt vmcnt(0)
	v_pk_fma_f32 v[70:71], v[78:79], v[70:71], v[74:75]
	s_nop 0
	v_pk_fma_f32 v[72:73], v[80:81], v[72:73], v[76:77]
	v_cvt_pk_bf16_f32 v70, v70, v71
	v_cvt_pk_bf16_f32 v71, v72, v73
	global_store_dwordx2 v[82:83], v[70:71], off offset:1536
	v_pk_mul_f32 v[74:75], v[66:67], v[0:1] op_sel_hi:[1,0]
	v_pk_mul_f32 v[76:77], v[68:69], v[0:1] op_sel_hi:[1,0]
	global_load_dwordx4 v[66:69], v[38:39], off
	global_load_dwordx4 v[70:73], v[40:41], off
	s_waitcnt vmcnt(0)
	v_pk_fma_f32 v[66:67], v[74:75], v[66:67], v[70:71]
	s_nop 0
	v_pk_fma_f32 v[68:69], v[76:77], v[68:69], v[72:73]
	v_cvt_pk_bf16_f32 v66, v66, v67
	v_cvt_pk_bf16_f32 v67, v68, v69
	global_store_dwordx2 v[82:83], v[66:67], off offset:2048
	v_pk_mul_f32 v[70:71], v[62:63], v[0:1] op_sel_hi:[1,0]
	v_pk_mul_f32 v[72:73], v[64:65], v[0:1] op_sel_hi:[1,0]
	global_load_dwordx4 v[62:65], v[42:43], off
	global_load_dwordx4 v[66:69], v[44:45], off
	s_waitcnt vmcnt(0)
	v_pk_fma_f32 v[62:63], v[70:71], v[62:63], v[66:67]
	s_nop 0
	v_pk_fma_f32 v[64:65], v[72:73], v[64:65], v[68:69]
	v_cvt_pk_bf16_f32 v62, v62, v63
	v_cvt_pk_bf16_f32 v63, v64, v65
	global_store_dwordx2 v[82:83], v[62:63], off offset:2560
	v_pk_mul_f32 v[66:67], v[58:59], v[0:1] op_sel_hi:[1,0]
	v_pk_mul_f32 v[68:69], v[60:61], v[0:1] op_sel_hi:[1,0]
	global_load_dwordx4 v[58:61], v[46:47], off
	global_load_dwordx4 v[62:65], v[48:49], off
	s_waitcnt vmcnt(0)
	v_pk_fma_f32 v[58:59], v[66:67], v[58:59], v[62:63]
	s_nop 0
	v_pk_fma_f32 v[60:61], v[68:69], v[60:61], v[64:65]
	v_cvt_pk_bf16_f32 v58, v58, v59
	v_cvt_pk_bf16_f32 v59, v60, v61
	global_store_dwordx2 v[82:83], v[58:59], off offset:3072
	v_pk_mul_f32 v[62:63], v[54:55], v[0:1] op_sel_hi:[1,0]
	v_pk_mul_f32 v[64:65], v[56:57], v[0:1] op_sel_hi:[1,0]
	global_load_dwordx4 v[54:57], v[50:51], off
	global_load_dwordx4 v[58:61], v[52:53], off
	s_waitcnt vmcnt(0)
	v_pk_fma_f32 v[54:55], v[62:63], v[54:55], v[58:59]
	s_nop 0
	v_pk_fma_f32 v[56:57], v[64:65], v[56:57], v[60:61]
	v_cvt_pk_bf16_f32 v54, v54, v55
	v_cvt_pk_bf16_f32 v55, v56, v57
	global_store_dwordx2 v[82:83], v[54:55], off offset:3584
	s_branch .LBB0_1016

; #define GAS __attribute__((address_space(1)))
; __device__ __forceinline__ unsigned pk2(float lo, float hi) { return f2bf(lo) | (f2bf(hi) << 16); }
; #define LN_X8(W, x) const float x##0 = bflo(W.x), x##1 = bfhi(W.x), x##2 = bflo(W.y), x##3 = bfhi(W.y), x##4 = bflo(W.z), x##5 = bfhi(W.z), x##6 = bflo(W.w), x##7 = bfhi(W.w)
; template <int NR>
; __device__ __forceinline__ void ln_rows(int lane, const bf16* Z, size_t rstride, const float* g, const float* b, float* Fout, bf16* Xout) {
;     ...
;         for (int r = 0; r < NR; ++r) { const float mu = mean[r], rs = rstd[r]; LN_X8(w[r][j], x);
;             const f32x4 o0 = (f32x4){(x0 - mu) * rs, (x1 - mu) * rs, (x2 - mu) * rs, (x3 - mu) * rs} * g0 + b0, o1 = (f32x4){(x4 - mu) * rs, (x5 - mu) * rs, (x6 - mu) * rs, (x7 - mu) * rs} * g1 + b1;
;             if (Fout) { GAS f32x4* fo = (GAS f32x4*)(Fout + r * rstride) + 2 * lane + 128 * j; fo[0] = o0; fo[1] = o1; }
;             if (Xout) { v4u ow; ow.x = pk2(o0.x, o0.y); ow.y = pk2(o0.z, o0.w); ow.z = pk2(o1.x, o1.y); ow.w = pk2(o1.z, o1.w); ((GAS v4u*)(Xout + r * rstride) + lane)[64 * j] = ow; } } }
.LBB0_1239:
	s_add_u32 s24, s64, s60
	s_addc_u32 s26, s65, s61
	s_and_b64 s[14:15], s[58:59], exec
	s_cselect_b32 s27, 0, s26
	s_cselect_b32 s26, 0, s24
	s_cmp_lg_u64 s[26:27], 0
	s_cselect_b64 s[14:15], -1, 0
	s_cmp_eq_u64 s[26:27], 0
	v_lshl_add_u64 v[184:185], v[150:151], 4, s[26:27]
	s_cbranch_scc1 .LBB0_1241
	v_cvt_pk_bf16_f32 v126, v126, v127
	v_cvt_pk_bf16_f32 v127, v128, v129
	v_cvt_pk_bf16_f32 v128, v146, v147
	v_cvt_pk_bf16_f32 v129, v148, v149
	global_store_dwordx4 v[184:185], v[126:129], off

; #define GAS __attribute__((address_space(1)))
; __device__ __forceinline__ unsigned pk2(float lo, float hi) { return f2bf(lo) | (f2bf(hi) << 16); }
; #define LN_X8(W, x) const float x##0 = bflo(W.x), x##1 = bfhi(W.x), x##2 = bflo(W.y), x##3 = bfhi(W.y), x##4 = bflo(W.z), x##5 = bfhi(W.z), x##6 = bflo(W.w), x##7 = bfhi(W.w)
; template <int NR>
; __device__ __forceinline__ void ln_rows(int lane, const bf16* Z, size_t rstride, const float* g, const float* b, float* Fout, bf16* Xout) {
;     ...
;         for (int r = 0; r < NR; ++r) { const float mu = mean[r], rs = rstd[r]; LN_X8(w[r][j], x);
;             const f32x4 o0 = (f32x4){(x0 - mu) * rs, (x1 - mu) * rs, (x2 - mu) * rs, (x3 - mu) * rs} * g0 + b0, o1 = (f32x4){(x4 - mu) * rs, (x5 - mu) * rs, (x6 - mu) * rs, (x7 - mu) * rs} * g1 + b1;
;             if (Fout) { GAS f32x4* fo = (GAS f32x4*)(Fout + r * rstride) + 2 * lane + 128 * j; fo[0] = o0; fo[1] = o1; }
;             if (Xout) { v4u ow; ow.x = pk2(o0.x, o0.y); ow.y = pk2(o0.z, o0.w); ow.z = pk2(o1.x, o1.y); ow.w = pk2(o1.z, o1.w); ((GAS v4u*)(Xout + r * rstride) + lane)[64 * j] = ow; } } }
.LBB0_1243:
	v_cndmask_b32_e64 v82, 0, 1, s[14:15]
	v_cmp_ne_u32_e64 s[40:41], 1, v82
	s_andn2_b64 vcc, exec, s[14:15]
	s_cbranch_vccnz .LBB0_1245
	v_cvt_pk_bf16_f32 v122, v122, v123
	v_cvt_pk_bf16_f32 v123, v124, v125
	v_cvt_pk_bf16_f32 v124, v126, v127
	s_lshl_b64 s[14:15], s[12:13], 1
	s_add_u32 s14, s26, s14
	s_addc_u32 s15, s27, s15
	v_cvt_pk_bf16_f32 v125, v128, v129
	v_lshl_add_u64 v[126:127], v[150:151], 4, s[14:15]
	global_store_dwordx4 v[126:127], v[122:125], off

; #define GAS __attribute__((address_space(1)))
; __device__ __forceinline__ unsigned pk2(float lo, float hi) { return f2bf(lo) | (f2bf(hi) << 16); }
; #define LN_X8(W, x) const float x##0 = bflo(W.x), x##1 = bfhi(W.x), x##2 = bflo(W.y), x##3 = bfhi(W.y), x##4 = bflo(W.z), x##5 = bfhi(W.z), x##6 = bflo(W.w), x##7 = bfhi(W.w)
; template <int NR>
; __device__ __forceinline__ void ln_rows(int lane, const bf16* Z, size_t rstride, const float* g, const float* b, float* Fout, bf16* Xout) {
;     ...
;         for (int r = 0; r < NR; ++r) { const float mu = mean[r], rs = rstd[r]; LN_X8(w[r][j], x);
;             const f32x4 o0 = (f32x4){(x0 - mu) * rs, (x1 - mu) * rs, (x2 - mu) * rs, (x3 - mu) * rs} * g0 + b0, o1 = (f32x4){(x4 - mu) * rs, (x5 - mu) * rs, (x6 - mu) * rs, (x7 - mu) * rs} * g1 + b1;
;             if (Fout) { GAS f32x4* fo = (GAS f32x4*)(Fout + r * rstride) + 2 * lane + 128 * j; fo[0] = o0; fo[1] = o1; }
;             if (Xout) { v4u ow; ow.x = pk2(o0.x, o0.y); ow.y = pk2(o0.z, o0.w); ow.z = pk2(o1.x, o1.y); ow.w = pk2(o1.z, o1.w); ((GAS v4u*)(Xout + r * rstride) + lane)[64 * j] = ow; } } }
.LBB0_1247:
	s_and_b64 vcc, exec, s[40:41]
	s_cbranch_vccnz .LBB0_1249
	v_cvt_pk_bf16_f32 v118, v118, v119
	v_cvt_pk_bf16_f32 v119, v120, v121
	v_cvt_pk_bf16_f32 v120, v122, v123
	s_lshl_b64 s[14:15], s[10:11], 1
	s_add_u32 s14, s26, s14
	s_addc_u32 s15, s27, s15
	v_cvt_pk_bf16_f32 v121, v124, v125
	v_lshl_add_u64 v[122:123], v[150:151], 4, s[14:15]
	global_store_dwordx4 v[122:123], v[118:121], off

; #define GAS __attribute__((address_space(1)))
; __device__ __forceinline__ unsigned pk2(float lo, float hi) { return f2bf(lo) | (f2bf(hi) << 16); }
; #define LN_X8(W, x) const float x##0 = bflo(W.x), x##1 = bfhi(W.x), x##2 = bflo(W.y), x##3 = bfhi(W.y), x##4 = bflo(W.z), x##5 = bfhi(W.z), x##6 = bflo(W.w), x##7 = bfhi(W.w)
; template <int NR>
; __device__ __forceinline__ void ln_rows(int lane, const bf16* Z, size_t rstride, const float* g, const float* b, float* Fout, bf16* Xout) {
;     ...
;         for (int r = 0; r < NR; ++r) { const float mu = mean[r], rs = rstd[r]; LN_X8(w[r][j], x);
;             const f32x4 o0 = (f32x4){(x0 - mu) * rs, (x1 - mu) * rs, (x2 - mu) * rs, (x3 - mu) * rs} * g0 + b0, o1 = (f32x4){(x4 - mu) * rs, (x5 - mu) * rs, (x6 - mu) * rs, (x7 - mu) * rs} * g1 + b1;
;             if (Fout) { GAS f32x4* fo = (GAS f32x4*)(Fout + r * rstride) + 2 * lane + 128 * j; fo[0] = o0; fo[1] = o1; }
;             if (Xout) { v4u ow; ow.x = pk2(o0.x, o0.y); ow.y = pk2(o0.z, o0.w); ow.z = pk2(o1.x, o1.y); ow.w = pk2(o1.z, o1.w); ((GAS v4u*)(Xout + r * rstride) + lane)[64 * j] = ow; } } }
.LBB0_1251:
	s_and_b64 vcc, exec, s[40:41]
	s_cbranch_vccnz .LBB0_1253
	v_cvt_pk_bf16_f32 v114, v114, v115
	v_cvt_pk_bf16_f32 v115, v116, v117
	v_cvt_pk_bf16_f32 v116, v118, v119
	s_lshl_b64 s[14:15], s[22:23], 1
	s_add_u32 s14, s26, s14
	s_addc_u32 s15, s27, s15
	v_cvt_pk_bf16_f32 v117, v120, v121
	v_lshl_add_u64 v[118:119], v[150:151], 4, s[14:15]
	global_store_dwordx4 v[118:119], v[114:117], off

; #define GAS __attribute__((address_space(1)))
; __device__ __forceinline__ unsigned pk2(float lo, float hi) { return f2bf(lo) | (f2bf(hi) << 16); }
; #define LN_X8(W, x) const float x##0 = bflo(W.x), x##1 = bfhi(W.x), x##2 = bflo(W.y), x##3 = bfhi(W.y), x##4 = bflo(W.z), x##5 = bfhi(W.z), x##6 = bflo(W.w), x##7 = bfhi(W.w)
; template <int NR>
; __device__ __forceinline__ void ln_rows(int lane, const bf16* Z, size_t rstride, const float* g, const float* b, float* Fout, bf16* Xout) {
;     ...
;         for (int r = 0; r < NR; ++r) { const float mu = mean[r], rs = rstd[r]; LN_X8(w[r][j], x);
;             const f32x4 o0 = (f32x4){(x0 - mu) * rs, (x1 - mu) * rs, (x2 - mu) * rs, (x3 - mu) * rs} * g0 + b0, o1 = (f32x4){(x4 - mu) * rs, (x5 - mu) * rs, (x6 - mu) * rs, (x7 - mu) * rs} * g1 + b1;
;             if (Fout) { GAS f32x4* fo = (GAS f32x4*)(Fout + r * rstride) + 2 * lane + 128 * j; fo[0] = o0; fo[1] = o1; }
;             if (Xout) { v4u ow; ow.x = pk2(o0.x, o0.y); ow.y = pk2(o0.z, o0.w); ow.z = pk2(o1.x, o1.y); ow.w = pk2(o1.z, o1.w); ((GAS v4u*)(Xout + r * rstride) + lane)[64 * j] = ow; } } }
.LBB0_1255:
	s_and_b64 vcc, exec, s[40:41]
	s_cbranch_vccnz .LBB0_1257
	v_cvt_pk_bf16_f32 v130, v130, v131
	v_cvt_pk_bf16_f32 v131, v132, v133
	v_cvt_pk_bf16_f32 v132, v110, v111
	v_cvt_pk_bf16_f32 v133, v112, v113
	global_store_dwordx4 v[184:185], v[130:133], off offset:1024

; #define GAS __attribute__((address_space(1)))
; __device__ __forceinline__ unsigned pk2(float lo, float hi) { return f2bf(lo) | (f2bf(hi) << 16); }
; #define LN_X8(W, x) const float x##0 = bflo(W.x), x##1 = bfhi(W.x), x##2 = bflo(W.y), x##3 = bfhi(W.y), x##4 = bflo(W.z), x##5 = bfhi(W.z), x##6 = bflo(W.w), x##7 = bfhi(W.w)
; template <int NR>
; __device__ __forceinline__ void ln_rows(int lane, const bf16* Z, size_t rstride, const float* g, const float* b, float* Fout, bf16* Xout) {
;     ...
;         for (int r = 0; r < NR; ++r) { const float mu = mean[r], rs = rstd[r]; LN_X8(w[r][j], x);
;             const f32x4 o0 = (f32x4){(x0 - mu) * rs, (x1 - mu) * rs, (x2 - mu) * rs, (x3 - mu) * rs} * g0 + b0, o1 = (f32x4){(x4 - mu) * rs, (x5 - mu) * rs, (x6 - mu) * rs, (x7 - mu) * rs} * g1 + b1;
;             if (Fout) { GAS f32x4* fo = (GAS f32x4*)(Fout + r * rstride) + 2 * lane + 128 * j; fo[0] = o0; fo[1] = o1; }
;             if (Xout) { v4u ow; ow.x = pk2(o0.x, o0.y); ow.y = pk2(o0.z, o0.w); ow.z = pk2(o1.x, o1.y); ow.w = pk2(o1.z, o1.w); ((GAS v4u*)(Xout + r * rstride) + lane)[64 * j] = ow; } } }
.LBB0_1259:
	s_and_b64 vcc, exec, s[40:41]
	s_cbranch_vccnz .LBB0_1261
	v_cvt_pk_bf16_f32 v106, v106, v107
	v_cvt_pk_bf16_f32 v107, v108, v109
	v_cvt_pk_bf16_f32 v108, v110, v111
	s_lshl_b64 s[14:15], s[12:13], 1
	s_add_u32 s14, s26, s14
	s_addc_u32 s15, s27, s15
	v_cvt_pk_bf16_f32 v109, v112, v113
	v_lshl_add_u64 v[110:111], v[150:151], 4, s[14:15]
	global_store_dwordx4 v[110:111], v[106:109], off offset:1024

; #define GAS __attribute__((address_space(1)))
; __device__ __forceinline__ unsigned pk2(float lo, float hi) { return f2bf(lo) | (f2bf(hi) << 16); }
; #define LN_X8(W, x) const float x##0 = bflo(W.x), x##1 = bfhi(W.x), x##2 = bflo(W.y), x##3 = bfhi(W.y), x##4 = bflo(W.z), x##5 = bfhi(W.z), x##6 = bflo(W.w), x##7 = bfhi(W.w)
; template <int NR>
; __device__ __forceinline__ void ln_rows(int lane, const bf16* Z, size_t rstride, const float* g, const float* b, float* Fout, bf16* Xout) {
;     ...
;         for (int r = 0; r < NR; ++r) { const float mu = mean[r], rs = rstd[r]; LN_X8(w[r][j], x);
;             const f32x4 o0 = (f32x4){(x0 - mu) * rs, (x1 - mu) * rs, (x2 - mu) * rs, (x3 - mu) * rs} * g0 + b0, o1 = (f32x4){(x4 - mu) * rs, (x5 - mu) * rs, (x6 - mu) * rs, (x7 - mu) * rs} * g1 + b1;
;             if (Fout) { GAS f32x4* fo = (GAS f32x4*)(Fout + r * rstride) + 2 * lane + 128 * j; fo[0] = o0; fo[1] = o1; }
;             if (Xout) { v4u ow; ow.x = pk2(o0.x, o0.y); ow.y = pk2(o0.z, o0.w); ow.z = pk2(o1.x, o1.y); ow.w = pk2(o1.z, o1.w); ((GAS v4u*)(Xout + r * rstride) + lane)[64 * j] = ow; } } }
.LBB0_1263:
	s_and_b64 vcc, exec, s[40:41]
	s_cbranch_vccnz .LBB0_1265
	v_cvt_pk_bf16_f32 v102, v102, v103
	v_cvt_pk_bf16_f32 v103, v104, v105
	v_cvt_pk_bf16_f32 v104, v106, v107
	s_lshl_b64 s[14:15], s[10:11], 1
	s_add_u32 s14, s26, s14
	s_addc_u32 s15, s27, s15
	v_cvt_pk_bf16_f32 v105, v108, v109
	v_lshl_add_u64 v[106:107], v[150:151], 4, s[14:15]
	global_store_dwordx4 v[106:107], v[102:105], off offset:1024

; #define GAS __attribute__((address_space(1)))
; __device__ __forceinline__ unsigned pk2(float lo, float hi) { return f2bf(lo) | (f2bf(hi) << 16); }
; #define LN_X8(W, x) const float x##0 = bflo(W.x), x##1 = bfhi(W.x), x##2 = bflo(W.y), x##3 = bfhi(W.y), x##4 = bflo(W.z), x##5 = bfhi(W.z), x##6 = bflo(W.w), x##7 = bfhi(W.w)
; template <int NR>
; __device__ __forceinline__ void ln_rows(int lane, const bf16* Z, size_t rstride, const float* g, const float* b, float* Fout, bf16* Xout) {
;     ...
;         for (int r = 0; r < NR; ++r) { const float mu = mean[r], rs = rstd[r]; LN_X8(w[r][j], x);
;             const f32x4 o0 = (f32x4){(x0 - mu) * rs, (x1 - mu) * rs, (x2 - mu) * rs, (x3 - mu) * rs} * g0 + b0, o1 = (f32x4){(x4 - mu) * rs, (x5 - mu) * rs, (x6 - mu) * rs, (x7 - mu) * rs} * g1 + b1;
;             if (Fout) { GAS f32x4* fo = (GAS f32x4*)(Fout + r * rstride) + 2 * lane + 128 * j; fo[0] = o0; fo[1] = o1; }
;             if (Xout) { v4u ow; ow.x = pk2(o0.x, o0.y); ow.y = pk2(o0.z, o0.w); ow.z = pk2(o1.x, o1.y); ow.w = pk2(o1.z, o1.w); ((GAS v4u*)(Xout + r * rstride) + lane)[64 * j] = ow; } } }
.LBB0_1267:
	s_and_b64 vcc, exec, s[40:41]
	s_cbranch_vccnz .LBB0_1269
	v_cvt_pk_bf16_f32 v98, v98, v99
	v_cvt_pk_bf16_f32 v99, v100, v101
	v_cvt_pk_bf16_f32 v100, v102, v103
	s_lshl_b64 s[14:15], s[22:23], 1
	s_add_u32 s14, s26, s14
	s_addc_u32 s15, s27, s15
	v_cvt_pk_bf16_f32 v101, v104, v105
	v_lshl_add_u64 v[102:103], v[150:151], 4, s[14:15]
	global_store_dwordx4 v[102:103], v[98:101], off offset:1024

; #define GAS __attribute__((address_space(1)))
; __device__ __forceinline__ unsigned pk2(float lo, float hi) { return f2bf(lo) | (f2bf(hi) << 16); }
; #define LN_X8(W, x) const float x##0 = bflo(W.x), x##1 = bfhi(W.x), x##2 = bflo(W.y), x##3 = bfhi(W.y), x##4 = bflo(W.z), x##5 = bfhi(W.z), x##6 = bflo(W.w), x##7 = bfhi(W.w)
; template <int NR>
; __device__ __forceinline__ void ln_rows(int lane, const bf16* Z, size_t rstride, const float* g, const float* b, float* Fout, bf16* Xout) {
;     ...
;         for (int r = 0; r < NR; ++r) { const float mu = mean[r], rs = rstd[r]; LN_X8(w[r][j], x);
;             const f32x4 o0 = (f32x4){(x0 - mu) * rs, (x1 - mu) * rs, (x2 - mu) * rs, (x3 - mu) * rs} * g0 + b0, o1 = (f32x4){(x4 - mu) * rs, (x5 - mu) * rs, (x6 - mu) * rs, (x7 - mu) * rs} * g1 + b1;
;             if (Fout) { GAS f32x4* fo = (GAS f32x4*)(Fout + r * rstride) + 2 * lane + 128 * j; fo[0] = o0; fo[1] = o1; }
;             if (Xout) { v4u ow; ow.x = pk2(o0.x, o0.y); ow.y = pk2(o0.z, o0.w); ow.z = pk2(o1.x, o1.y); ow.w = pk2(o1.z, o1.w); ((GAS v4u*)(Xout + r * rstride) + lane)[64 * j] = ow; } } }
.LBB0_1271:
	s_and_b64 vcc, exec, s[40:41]
	s_cbranch_vccnz .LBB0_1273
	v_cvt_pk_bf16_f32 v114, v114, v115
	v_cvt_pk_bf16_f32 v115, v116, v117
	v_cvt_pk_bf16_f32 v116, v94, v95
	v_cvt_pk_bf16_f32 v117, v96, v97
	global_store_dwordx4 v[184:185], v[114:117], off offset:2048

; #define GAS __attribute__((address_space(1)))
; __device__ __forceinline__ unsigned pk2(float lo, float hi) { return f2bf(lo) | (f2bf(hi) << 16); }
; #define LN_X8(W, x) const float x##0 = bflo(W.x), x##1 = bfhi(W.x), x##2 = bflo(W.y), x##3 = bfhi(W.y), x##4 = bflo(W.z), x##5 = bfhi(W.z), x##6 = bflo(W.w), x##7 = bfhi(W.w)
; template <int NR>
; __device__ __forceinline__ void ln_rows(int lane, const bf16* Z, size_t rstride, const float* g, const float* b, float* Fout, bf16* Xout) {
;     ...
;         for (int r = 0; r < NR; ++r) { const float mu = mean[r], rs = rstd[r]; LN_X8(w[r][j], x);
;             const f32x4 o0 = (f32x4){(x0 - mu) * rs, (x1 - mu) * rs, (x2 - mu) * rs, (x3 - mu) * rs} * g0 + b0, o1 = (f32x4){(x4 - mu) * rs, (x5 - mu) * rs, (x6 - mu) * rs, (x7 - mu) * rs} * g1 + b1;
;             if (Fout) { GAS f32x4* fo = (GAS f32x4*)(Fout + r * rstride) + 2 * lane + 128 * j; fo[0] = o0; fo[1] = o1; }
;             if (Xout) { v4u ow; ow.x = pk2(o0.x, o0.y); ow.y = pk2(o0.z, o0.w); ow.z = pk2(o1.x, o1.y); ow.w = pk2(o1.z, o1.w); ((GAS v4u*)(Xout + r * rstride) + lane)[64 * j] = ow; } } }
.LBB0_1275:
	s_and_b64 vcc, exec, s[40:41]
	s_cbranch_vccnz .LBB0_1277
	v_cvt_pk_bf16_f32 v90, v90, v91
	v_cvt_pk_bf16_f32 v91, v92, v93
	v_cvt_pk_bf16_f32 v92, v94, v95
	s_lshl_b64 s[14:15], s[12:13], 1
	s_add_u32 s14, s26, s14
	s_addc_u32 s15, s27, s15
	v_cvt_pk_bf16_f32 v93, v96, v97
	v_lshl_add_u64 v[94:95], v[150:151], 4, s[14:15]
	global_store_dwordx4 v[94:95], v[90:93], off offset:2048

; #define GAS __attribute__((address_space(1)))
; __device__ __forceinline__ unsigned pk2(float lo, float hi) { return f2bf(lo) | (f2bf(hi) << 16); }
; #define LN_X8(W, x) const float x##0 = bflo(W.x), x##1 = bfhi(W.x), x##2 = bflo(W.y), x##3 = bfhi(W.y), x##4 = bflo(W.z), x##5 = bfhi(W.z), x##6 = bflo(W.w), x##7 = bfhi(W.w)
; template <int NR>
; __device__ __forceinline__ void ln_rows(int lane, const bf16* Z, size_t rstride, const float* g, const float* b, float* Fout, bf16* Xout) {
;     ...
;         for (int r = 0; r < NR; ++r) { const float mu = mean[r], rs = rstd[r]; LN_X8(w[r][j], x);
;             const f32x4 o0 = (f32x4){(x0 - mu) * rs, (x1 - mu) * rs, (x2 - mu) * rs, (x3 - mu) * rs} * g0 + b0, o1 = (f32x4){(x4 - mu) * rs, (x5 - mu) * rs, (x6 - mu) * rs, (x7 - mu) * rs} * g1 + b1;
;             if (Fout) { GAS f32x4* fo = (GAS f32x4*)(Fout + r * rstride) + 2 * lane + 128 * j; fo[0] = o0; fo[1] = o1; }
;             if (Xout) { v4u ow; ow.x = pk2(o0.x, o0.y); ow.y = pk2(o0.z, o0.w); ow.z = pk2(o1.x, o1.y); ow.w = pk2(o1.z, o1.w); ((GAS v4u*)(Xout + r * rstride) + lane)[64 * j] = ow; } } }
.LBB0_1279:
	s_and_b64 vcc, exec, s[40:41]
	s_cbranch_vccnz .LBB0_1281
	v_cvt_pk_bf16_f32 v86, v86, v87
	v_cvt_pk_bf16_f32 v87, v88, v89
	v_cvt_pk_bf16_f32 v88, v90, v91
	s_lshl_b64 s[14:15], s[10:11], 1
	s_add_u32 s14, s26, s14
	s_addc_u32 s15, s27, s15
	v_cvt_pk_bf16_f32 v89, v92, v93
	v_lshl_add_u64 v[90:91], v[150:151], 4, s[14:15]
	global_store_dwordx4 v[90:91], v[86:89], off offset:2048

; #define GAS __attribute__((address_space(1)))
; __device__ __forceinline__ unsigned pk2(float lo, float hi) { return f2bf(lo) | (f2bf(hi) << 16); }
; #define LN_X8(W, x) const float x##0 = bflo(W.x), x##1 = bfhi(W.x), x##2 = bflo(W.y), x##3 = bfhi(W.y), x##4 = bflo(W.z), x##5 = bfhi(W.z), x##6 = bflo(W.w), x##7 = bfhi(W.w)
; template <int NR>
; __device__ __forceinline__ void ln_rows(int lane, const bf16* Z, size_t rstride, const float* g, const float* b, float* Fout, bf16* Xout) {
;     ...
;         for (int r = 0; r < NR; ++r) { const float mu = mean[r], rs = rstd[r]; LN_X8(w[r][j], x);
;             const f32x4 o0 = (f32x4){(x0 - mu) * rs, (x1 - mu) * rs, (x2 - mu) * rs, (x3 - mu) * rs} * g0 + b0, o1 = (f32x4){(x4 - mu) * rs, (x5 - mu) * rs, (x6 - mu) * rs, (x7 - mu) * rs} * g1 + b1;
;             if (Fout) { GAS f32x4* fo = (GAS f32x4*)(Fout + r * rstride) + 2 * lane + 128 * j; fo[0] = o0; fo[1] = o1; }
;             if (Xout) { v4u ow; ow.x = pk2(o0.x, o0.y); ow.y = pk2(o0.z, o0.w); ow.z = pk2(o1.x, o1.y); ow.w = pk2(o1.z, o1.w); ((GAS v4u*)(Xout + r * rstride) + lane)[64 * j] = ow; } } }
.LBB0_1283:
	s_and_b64 vcc, exec, s[40:41]
	s_cbranch_vccnz .LBB0_1285
	v_cvt_pk_bf16_f32 v82, v82, v83
	v_cvt_pk_bf16_f32 v83, v84, v85
	v_cvt_pk_bf16_f32 v84, v86, v87
	s_lshl_b64 s[14:15], s[22:23], 1
	s_add_u32 s14, s26, s14
	s_addc_u32 s15, s27, s15
	v_cvt_pk_bf16_f32 v85, v88, v89
	v_lshl_add_u64 v[86:87], v[150:151], 4, s[14:15]
	global_store_dwordx4 v[86:87], v[82:85], off offset:2048

; #define GAS __attribute__((address_space(1)))
; __device__ __forceinline__ unsigned pk2(float lo, float hi) { return f2bf(lo) | (f2bf(hi) << 16); }
; #define LN_X8(W, x) const float x##0 = bflo(W.x), x##1 = bfhi(W.x), x##2 = bflo(W.y), x##3 = bfhi(W.y), x##4 = bflo(W.z), x##5 = bfhi(W.z), x##6 = bflo(W.w), x##7 = bfhi(W.w)
; template <int NR>
; __device__ __forceinline__ void ln_rows(int lane, const bf16* Z, size_t rstride, const float* g, const float* b, float* Fout, bf16* Xout) {
;     ...
;         for (int r = 0; r < NR; ++r) { const float mu = mean[r], rs = rstd[r]; LN_X8(w[r][j], x);
;             const f32x4 o0 = (f32x4){(x0 - mu) * rs, (x1 - mu) * rs, (x2 - mu) * rs, (x3 - mu) * rs} * g0 + b0, o1 = (f32x4){(x4 - mu) * rs, (x5 - mu) * rs, (x6 - mu) * rs, (x7 - mu) * rs} * g1 + b1;
;             if (Fout) { GAS f32x4* fo = (GAS f32x4*)(Fout + r * rstride) + 2 * lane + 128 * j; fo[0] = o0; fo[1] = o1; }
;             if (Xout) { v4u ow; ow.x = pk2(o0.x, o0.y); ow.y = pk2(o0.z, o0.w); ow.z = pk2(o1.x, o1.y); ow.w = pk2(o1.z, o1.w); ((GAS v4u*)(Xout + r * rstride) + lane)[64 * j] = ow; } } }
.LBB0_1287:
	s_and_b64 vcc, exec, s[40:41]
	s_cbranch_vccnz .LBB0_1289
	v_cvt_pk_bf16_f32 v98, v98, v99
	v_cvt_pk_bf16_f32 v99, v100, v101
	v_cvt_pk_bf16_f32 v100, v78, v79
	v_cvt_pk_bf16_f32 v101, v80, v81
	global_store_dwordx4 v[184:185], v[98:101], off offset:3072

; #define GAS __attribute__((address_space(1)))
; __device__ __forceinline__ unsigned pk2(float lo, float hi) { return f2bf(lo) | (f2bf(hi) << 16); }
; #define LN_X8(W, x) const float x##0 = bflo(W.x), x##1 = bfhi(W.x), x##2 = bflo(W.y), x##3 = bfhi(W.y), x##4 = bflo(W.z), x##5 = bfhi(W.z), x##6 = bflo(W.w), x##7 = bfhi(W.w)
; template <int NR>
; __device__ __forceinline__ void ln_rows(int lane, const bf16* Z, size_t rstride, const float* g, const float* b, float* Fout, bf16* Xout) {
;     ...
;         for (int r = 0; r < NR; ++r) { const float mu = mean[r], rs = rstd[r]; LN_X8(w[r][j], x);
;             const f32x4 o0 = (f32x4){(x0 - mu) * rs, (x1 - mu) * rs, (x2 - mu) * rs, (x3 - mu) * rs} * g0 + b0, o1 = (f32x4){(x4 - mu) * rs, (x5 - mu) * rs, (x6 - mu) * rs, (x7 - mu) * rs} * g1 + b1;
;             if (Fout) { GAS f32x4* fo = (GAS f32x4*)(Fout + r * rstride) + 2 * lane + 128 * j; fo[0] = o0; fo[1] = o1; }
;             if (Xout) { v4u ow; ow.x = pk2(o0.x, o0.y); ow.y = pk2(o0.z, o0.w); ow.z = pk2(o1.x, o1.y); ow.w = pk2(o1.z, o1.w); ((GAS v4u*)(Xout + r * rstride) + lane)[64 * j] = ow; } } }
.LBB0_1291:
	s_and_b64 vcc, exec, s[40:41]
	s_cbranch_vccnz .LBB0_1293
	v_cvt_pk_bf16_f32 v74, v74, v75
	v_cvt_pk_bf16_f32 v75, v76, v77
	v_cvt_pk_bf16_f32 v76, v78, v79
	s_lshl_b64 s[14:15], s[12:13], 1
	s_add_u32 s14, s26, s14
	s_addc_u32 s15, s27, s15
	v_cvt_pk_bf16_f32 v77, v80, v81
	v_lshl_add_u64 v[78:79], v[150:151], 4, s[14:15]
	global_store_dwordx4 v[78:79], v[74:77], off offset:3072

; #define GAS __attribute__((address_space(1)))
; __device__ __forceinline__ unsigned pk2(float lo, float hi) { return f2bf(lo) | (f2bf(hi) << 16); }
; #define LN_X8(W, x) const float x##0 = bflo(W.x), x##1 = bfhi(W.x), x##2 = bflo(W.y), x##3 = bfhi(W.y), x##4 = bflo(W.z), x##5 = bfhi(W.z), x##6 = bflo(W.w), x##7 = bfhi(W.w)
; template <int NR>
; __device__ __forceinline__ void ln_rows(int lane, const bf16* Z, size_t rstride, const float* g, const float* b, float* Fout, bf16* Xout) {
;     ...
;         for (int r = 0; r < NR; ++r) { const float mu = mean[r], rs = rstd[r]; LN_X8(w[r][j], x);
;             const f32x4 o0 = (f32x4){(x0 - mu) * rs, (x1 - mu) * rs, (x2 - mu) * rs, (x3 - mu) * rs} * g0 + b0, o1 = (f32x4){(x4 - mu) * rs, (x5 - mu) * rs, (x6 - mu) * rs, (x7 - mu) * rs} * g1 + b1;
;             if (Fout) { GAS f32x4* fo = (GAS f32x4*)(Fout + r * rstride) + 2 * lane + 128 * j; fo[0] = o0; fo[1] = o1; }
;             if (Xout) { v4u ow; ow.x = pk2(o0.x, o0.y); ow.y = pk2(o0.z, o0.w); ow.z = pk2(o1.x, o1.y); ow.w = pk2(o1.z, o1.w); ((GAS v4u*)(Xout + r * rstride) + lane)[64 * j] = ow; } } }
.LBB0_1295:
	s_and_b64 vcc, exec, s[40:41]
	s_cbranch_vccnz .LBB0_1297
	v_cvt_pk_bf16_f32 v70, v70, v71
	v_cvt_pk_bf16_f32 v71, v72, v73
	v_cvt_pk_bf16_f32 v72, v74, v75
	s_lshl_b64 s[14:15], s[10:11], 1
	s_add_u32 s14, s26, s14
	s_addc_u32 s15, s27, s15
	v_cvt_pk_bf16_f32 v73, v76, v77
	v_lshl_add_u64 v[74:75], v[150:151], 4, s[14:15]
	global_store_dwordx4 v[74:75], v[70:73], off offset:3072

; #define GAS __attribute__((address_space(1)))
; __device__ __forceinline__ unsigned pk2(float lo, float hi) { return f2bf(lo) | (f2bf(hi) << 16); }
; #define LN_X8(W, x) const float x##0 = bflo(W.x), x##1 = bfhi(W.x), x##2 = bflo(W.y), x##3 = bfhi(W.y), x##4 = bflo(W.z), x##5 = bfhi(W.z), x##6 = bflo(W.w), x##7 = bfhi(W.w)
; template <int NR>
; __device__ __forceinline__ void ln_rows(int lane, const bf16* Z, size_t rstride, const float* g, const float* b, float* Fout, bf16* Xout) {
;     ...
;         for (int r = 0; r < NR; ++r) { const float mu = mean[r], rs = rstd[r]; LN_X8(w[r][j], x);
;             const f32x4 o0 = (f32x4){(x0 - mu) * rs, (x1 - mu) * rs, (x2 - mu) * rs, (x3 - mu) * rs} * g0 + b0, o1 = (f32x4){(x4 - mu) * rs, (x5 - mu) * rs, (x6 - mu) * rs, (x7 - mu) * rs} * g1 + b1;
;             if (Fout) { GAS f32x4* fo = (GAS f32x4*)(Fout + r * rstride) + 2 * lane + 128 * j; fo[0] = o0; fo[1] = o1; }
;             if (Xout) { v4u ow; ow.x = pk2(o0.x, o0.y); ow.y = pk2(o0.z, o0.w); ow.z = pk2(o1.x, o1.y); ow.w = pk2(o1.z, o1.w); ((GAS v4u*)(Xout + r * rstride) + lane)[64 * j] = ow; } } }
.LBB0_1299:
	s_and_b64 vcc, exec, s[40:41]
	s_cbranch_vccnz .LBB0_1301
	v_cvt_pk_bf16_f32 v66, v66, v67
	v_cvt_pk_bf16_f32 v67, v68, v69
	v_cvt_pk_bf16_f32 v68, v70, v71
	s_lshl_b64 s[14:15], s[22:23], 1
	s_add_u32 s14, s26, s14
	s_addc_u32 s15, s27, s15
	v_cvt_pk_bf16_f32 v69, v72, v73
	v_lshl_add_u64 v[70:71], v[150:151], 4, s[14:15]
	global_store_dwordx4 v[70:71], v[66:69], off offset:3072

; #define GAS __attribute__((address_space(1)))
; __device__ __forceinline__ unsigned pk2(float lo, float hi) { return f2bf(lo) | (f2bf(hi) << 16); }
; #define LN_X8(W, x) const float x##0 = bflo(W.x), x##1 = bfhi(W.x), x##2 = bflo(W.y), x##3 = bfhi(W.y), x##4 = bflo(W.z), x##5 = bfhi(W.z), x##6 = bflo(W.w), x##7 = bfhi(W.w)
; template <int NR>
; __device__ __forceinline__ void ln_rows(int lane, const bf16* Z, size_t rstride, const float* g, const float* b, float* Fout, bf16* Xout) {
;     ...
;         for (int r = 0; r < NR; ++r) { const float mu = mean[r], rs = rstd[r]; LN_X8(w[r][j], x);
;             const f32x4 o0 = (f32x4){(x0 - mu) * rs, (x1 - mu) * rs, (x2 - mu) * rs, (x3 - mu) * rs} * g0 + b0, o1 = (f32x4){(x4 - mu) * rs, (x5 - mu) * rs, (x6 - mu) * rs, (x7 - mu) * rs} * g1 + b1;
;             if (Fout) { GAS f32x4* fo = (GAS f32x4*)(Fout + r * rstride) + 2 * lane + 128 * j; fo[0] = o0; fo[1] = o1; }
;             if (Xout) { v4u ow; ow.x = pk2(o0.x, o0.y); ow.y = pk2(o0.z, o0.w); ow.z = pk2(o1.x, o1.y); ow.w = pk2(o1.z, o1.w); ((GAS v4u*)(Xout + r * rstride) + lane)[64 * j] = ow; } } }
.LBB0_1303:
	s_and_b64 vcc, exec, s[40:41]
	s_cbranch_vccnz .LBB0_1305
	v_cvt_pk_bf16_f32 v82, v82, v83
	v_cvt_pk_bf16_f32 v83, v84, v85
	v_cvt_pk_bf16_f32 v84, v62, v63
	v_add_co_u32_e32 v62, vcc, 0x1000, v184
	v_cvt_pk_bf16_f32 v85, v64, v65
	s_nop 0
	v_addc_co_u32_e32 v63, vcc, 0, v185, vcc
	global_store_dwordx4 v[62:63], v[82:85], off

; #define GAS __attribute__((address_space(1)))
; __device__ __forceinline__ unsigned pk2(float lo, float hi) { return f2bf(lo) | (f2bf(hi) << 16); }
; #define LN_X8(W, x) const float x##0 = bflo(W.x), x##1 = bfhi(W.x), x##2 = bflo(W.y), x##3 = bfhi(W.y), x##4 = bflo(W.z), x##5 = bfhi(W.z), x##6 = bflo(W.w), x##7 = bfhi(W.w)
; template <int NR>
; __device__ __forceinline__ void ln_rows(int lane, const bf16* Z, size_t rstride, const float* g, const float* b, float* Fout, bf16* Xout) {
;     ...
;         for (int r = 0; r < NR; ++r) { const float mu = mean[r], rs = rstd[r]; LN_X8(w[r][j], x);
;             const f32x4 o0 = (f32x4){(x0 - mu) * rs, (x1 - mu) * rs, (x2 - mu) * rs, (x3 - mu) * rs} * g0 + b0, o1 = (f32x4){(x4 - mu) * rs, (x5 - mu) * rs, (x6 - mu) * rs, (x7 - mu) * rs} * g1 + b1;
;             if (Fout) { GAS f32x4* fo = (GAS f32x4*)(Fout + r * rstride) + 2 * lane + 128 * j; fo[0] = o0; fo[1] = o1; }
;             if (Xout) { v4u ow; ow.x = pk2(o0.x, o0.y); ow.y = pk2(o0.z, o0.w); ow.z = pk2(o1.x, o1.y); ow.w = pk2(o1.z, o1.w); ((GAS v4u*)(Xout + r * rstride) + lane)[64 * j] = ow; } } }
.LBB0_1307:
	s_and_b64 vcc, exec, s[40:41]
	s_cbranch_vccnz .LBB0_1309
	v_cvt_pk_bf16_f32 v58, v58, v59
	v_cvt_pk_bf16_f32 v59, v60, v61
	s_lshl_b64 s[14:15], s[12:13], 1
	s_add_u32 s14, s26, s14
	v_cvt_pk_bf16_f32 v60, v62, v63
	s_addc_u32 s15, s27, s15
	v_lshl_add_u64 v[62:63], v[150:151], 4, s[14:15]
	v_add_co_u32_e32 v62, vcc, 0x1000, v62
	v_cvt_pk_bf16_f32 v61, v64, v65
	s_nop 0
	v_addc_co_u32_e32 v63, vcc, 0, v63, vcc
	global_store_dwordx4 v[62:63], v[58:61], off

; #define GAS __attribute__((address_space(1)))
; __device__ __forceinline__ unsigned pk2(float lo, float hi) { return f2bf(lo) | (f2bf(hi) << 16); }
; #define LN_X8(W, x) const float x##0 = bflo(W.x), x##1 = bfhi(W.x), x##2 = bflo(W.y), x##3 = bfhi(W.y), x##4 = bflo(W.z), x##5 = bfhi(W.z), x##6 = bflo(W.w), x##7 = bfhi(W.w)
; template <int NR>
; __device__ __forceinline__ void ln_rows(int lane, const bf16* Z, size_t rstride, const float* g, const float* b, float* Fout, bf16* Xout) {
;     ...
;         for (int r = 0; r < NR; ++r) { const float mu = mean[r], rs = rstd[r]; LN_X8(w[r][j], x);
;             const f32x4 o0 = (f32x4){(x0 - mu) * rs, (x1 - mu) * rs, (x2 - mu) * rs, (x3 - mu) * rs} * g0 + b0, o1 = (f32x4){(x4 - mu) * rs, (x5 - mu) * rs, (x6 - mu) * rs, (x7 - mu) * rs} * g1 + b1;
;             if (Fout) { GAS f32x4* fo = (GAS f32x4*)(Fout + r * rstride) + 2 * lane + 128 * j; fo[0] = o0; fo[1] = o1; }
;             if (Xout) { v4u ow; ow.x = pk2(o0.x, o0.y); ow.y = pk2(o0.z, o0.w); ow.z = pk2(o1.x, o1.y); ow.w = pk2(o1.z, o1.w); ((GAS v4u*)(Xout + r * rstride) + lane)[64 * j] = ow; } } }
.LBB0_1311:
	s_and_b64 vcc, exec, s[40:41]
	s_cbranch_vccnz .LBB0_1313
	v_cvt_pk_bf16_f32 v54, v54, v55
	v_cvt_pk_bf16_f32 v55, v56, v57
	s_lshl_b64 s[14:15], s[10:11], 1
	s_add_u32 s14, s26, s14
	v_cvt_pk_bf16_f32 v56, v58, v59
	s_addc_u32 s15, s27, s15
	v_lshl_add_u64 v[58:59], v[150:151], 4, s[14:15]
	v_add_co_u32_e32 v58, vcc, 0x1000, v58
	v_cvt_pk_bf16_f32 v57, v60, v61
	s_nop 0
	v_addc_co_u32_e32 v59, vcc, 0, v59, vcc
	global_store_dwordx4 v[58:59], v[54:57], off

; #define GAS __attribute__((address_space(1)))
; __device__ __forceinline__ unsigned pk2(float lo, float hi) { return f2bf(lo) | (f2bf(hi) << 16); }
; #define LN_X8(W, x) const float x##0 = bflo(W.x), x##1 = bfhi(W.x), x##2 = bflo(W.y), x##3 = bfhi(W.y), x##4 = bflo(W.z), x##5 = bfhi(W.z), x##6 = bflo(W.w), x##7 = bfhi(W.w)
; template <int NR>
; __device__ __forceinline__ void ln_rows(int lane, const bf16* Z, size_t rstride, const float* g, const float* b, float* Fout, bf16* Xout) {
;     ...
;         for (int r = 0; r < NR; ++r) { const float mu = mean[r], rs = rstd[r]; LN_X8(w[r][j], x);
;             const f32x4 o0 = (f32x4){(x0 - mu) * rs, (x1 - mu) * rs, (x2 - mu) * rs, (x3 - mu) * rs} * g0 + b0, o1 = (f32x4){(x4 - mu) * rs, (x5 - mu) * rs, (x6 - mu) * rs, (x7 - mu) * rs} * g1 + b1;
;             if (Fout) { GAS f32x4* fo = (GAS f32x4*)(Fout + r * rstride) + 2 * lane + 128 * j; fo[0] = o0; fo[1] = o1; }
;             if (Xout) { v4u ow; ow.x = pk2(o0.x, o0.y); ow.y = pk2(o0.z, o0.w); ow.z = pk2(o1.x, o1.y); ow.w = pk2(o1.z, o1.w); ((GAS v4u*)(Xout + r * rstride) + lane)[64 * j] = ow; } } }
.LBB0_1315:
	s_and_b64 vcc, exec, s[40:41]
	s_cbranch_vccnz .LBB0_1317
	v_cvt_pk_bf16_f32 v50, v50, v51
	v_cvt_pk_bf16_f32 v51, v52, v53
	s_lshl_b64 s[14:15], s[22:23], 1
	s_add_u32 s14, s26, s14
	v_cvt_pk_bf16_f32 v52, v54, v55
	s_addc_u32 s15, s27, s15
	v_lshl_add_u64 v[54:55], v[150:151], 4, s[14:15]
	v_add_co_u32_e32 v54, vcc, 0x1000, v54
	v_cvt_pk_bf16_f32 v53, v56, v57
	s_nop 0
	v_addc_co_u32_e32 v55, vcc, 0, v55, vcc
	global_store_dwordx4 v[54:55], v[50:53], off

; #define GAS __attribute__((address_space(1)))
; __device__ __forceinline__ unsigned pk2(float lo, float hi) { return f2bf(lo) | (f2bf(hi) << 16); }
; #define LN_X8(W, x) const float x##0 = bflo(W.x), x##1 = bfhi(W.x), x##2 = bflo(W.y), x##3 = bfhi(W.y), x##4 = bflo(W.z), x##5 = bfhi(W.z), x##6 = bflo(W.w), x##7 = bfhi(W.w)
; template <int NR>
; __device__ __forceinline__ void ln_rows(int lane, const bf16* Z, size_t rstride, const float* g, const float* b, float* Fout, bf16* Xout) {
;     ...
;         for (int r = 0; r < NR; ++r) { const float mu = mean[r], rs = rstd[r]; LN_X8(w[r][j], x);
;             const f32x4 o0 = (f32x4){(x0 - mu) * rs, (x1 - mu) * rs, (x2 - mu) * rs, (x3 - mu) * rs} * g0 + b0, o1 = (f32x4){(x4 - mu) * rs, (x5 - mu) * rs, (x6 - mu) * rs, (x7 - mu) * rs} * g1 + b1;
;             if (Fout) { GAS f32x4* fo = (GAS f32x4*)(Fout + r * rstride) + 2 * lane + 128 * j; fo[0] = o0; fo[1] = o1; }
;             if (Xout) { v4u ow; ow.x = pk2(o0.x, o0.y); ow.y = pk2(o0.z, o0.w); ow.z = pk2(o1.x, o1.y); ow.w = pk2(o1.z, o1.w); ((GAS v4u*)(Xout + r * rstride) + lane)[64 * j] = ow; } } }
.LBB0_1319:
	s_and_b64 vcc, exec, s[40:41]
	s_cbranch_vccnz .LBB0_1321
	v_cvt_pk_bf16_f32 v66, v66, v67
	v_cvt_pk_bf16_f32 v67, v68, v69
	v_cvt_pk_bf16_f32 v68, v46, v47
	v_add_co_u32_e32 v46, vcc, 0x1000, v184
	v_cvt_pk_bf16_f32 v69, v48, v49
	s_nop 0
	v_addc_co_u32_e32 v47, vcc, 0, v185, vcc
	global_store_dwordx4 v[46:47], v[66:69], off offset:1024

; #define GAS __attribute__((address_space(1)))
; __device__ __forceinline__ unsigned pk2(float lo, float hi) { return f2bf(lo) | (f2bf(hi) << 16); }
; #define LN_X8(W, x) const float x##0 = bflo(W.x), x##1 = bfhi(W.x), x##2 = bflo(W.y), x##3 = bfhi(W.y), x##4 = bflo(W.z), x##5 = bfhi(W.z), x##6 = bflo(W.w), x##7 = bfhi(W.w)
; template <int NR>
; __device__ __forceinline__ void ln_rows(int lane, const bf16* Z, size_t rstride, const float* g, const float* b, float* Fout, bf16* Xout) {
;     ...
;         for (int r = 0; r < NR; ++r) { const float mu = mean[r], rs = rstd[r]; LN_X8(w[r][j], x);
;             const f32x4 o0 = (f32x4){(x0 - mu) * rs, (x1 - mu) * rs, (x2 - mu) * rs, (x3 - mu) * rs} * g0 + b0, o1 = (f32x4){(x4 - mu) * rs, (x5 - mu) * rs, (x6 - mu) * rs, (x7 - mu) * rs} * g1 + b1;
;             if (Fout) { GAS f32x4* fo = (GAS f32x4*)(Fout + r * rstride) + 2 * lane + 128 * j; fo[0] = o0; fo[1] = o1; }
;             if (Xout) { v4u ow; ow.x = pk2(o0.x, o0.y); ow.y = pk2(o0.z, o0.w); ow.z = pk2(o1.x, o1.y); ow.w = pk2(o1.z, o1.w); ((GAS v4u*)(Xout + r * rstride) + lane)[64 * j] = ow; } } }
.LBB0_1323:
	s_and_b64 vcc, exec, s[40:41]
	s_cbranch_vccnz .LBB0_1325
	v_cvt_pk_bf16_f32 v42, v42, v43
	v_cvt_pk_bf16_f32 v43, v44, v45
	s_lshl_b64 s[14:15], s[12:13], 1
	s_add_u32 s14, s26, s14
	v_cvt_pk_bf16_f32 v44, v46, v47
	s_addc_u32 s15, s27, s15
	v_lshl_add_u64 v[46:47], v[150:151], 4, s[14:15]
	v_add_co_u32_e32 v46, vcc, 0x1000, v46
	v_cvt_pk_bf16_f32 v45, v48, v49
	s_nop 0
	v_addc_co_u32_e32 v47, vcc, 0, v47, vcc
	global_store_dwordx4 v[46:47], v[42:45], off offset:1024

; #define GAS __attribute__((address_space(1)))
; __device__ __forceinline__ unsigned pk2(float lo, float hi) { return f2bf(lo) | (f2bf(hi) << 16); }
; #define LN_X8(W, x) const float x##0 = bflo(W.x), x##1 = bfhi(W.x), x##2 = bflo(W.y), x##3 = bfhi(W.y), x##4 = bflo(W.z), x##5 = bfhi(W.z), x##6 = bflo(W.w), x##7 = bfhi(W.w)
; template <int NR>
; __device__ __forceinline__ void ln_rows(int lane, const bf16* Z, size_t rstride, const float* g, const float* b, float* Fout, bf16* Xout) {
;     ...
;         for (int r = 0; r < NR; ++r) { const float mu = mean[r], rs = rstd[r]; LN_X8(w[r][j], x);
;             const f32x4 o0 = (f32x4){(x0 - mu) * rs, (x1 - mu) * rs, (x2 - mu) * rs, (x3 - mu) * rs} * g0 + b0, o1 = (f32x4){(x4 - mu) * rs, (x5 - mu) * rs, (x6 - mu) * rs, (x7 - mu) * rs} * g1 + b1;
;             if (Fout) { GAS f32x4* fo = (GAS f32x4*)(Fout + r * rstride) + 2 * lane + 128 * j; fo[0] = o0; fo[1] = o1; }
;             if (Xout) { v4u ow; ow.x = pk2(o0.x, o0.y); ow.y = pk2(o0.z, o0.w); ow.z = pk2(o1.x, o1.y); ow.w = pk2(o1.z, o1.w); ((GAS v4u*)(Xout + r * rstride) + lane)[64 * j] = ow; } } }
.LBB0_1327:
	s_and_b64 vcc, exec, s[40:41]
	s_cbranch_vccnz .LBB0_1329
	v_cvt_pk_bf16_f32 v38, v38, v39
	v_cvt_pk_bf16_f32 v39, v40, v41
	s_lshl_b64 s[14:15], s[10:11], 1
	s_add_u32 s14, s26, s14
	v_cvt_pk_bf16_f32 v40, v42, v43
	s_addc_u32 s15, s27, s15
	v_lshl_add_u64 v[42:43], v[150:151], 4, s[14:15]
	v_add_co_u32_e32 v42, vcc, 0x1000, v42
	v_cvt_pk_bf16_f32 v41, v44, v45
	s_nop 0
	v_addc_co_u32_e32 v43, vcc, 0, v43, vcc
	global_store_dwordx4 v[42:43], v[38:41], off offset:1024

; #define GAS __attribute__((address_space(1)))
; __device__ __forceinline__ unsigned pk2(float lo, float hi) { return f2bf(lo) | (f2bf(hi) << 16); }
; #define LN_X8(W, x) const float x##0 = bflo(W.x), x##1 = bfhi(W.x), x##2 = bflo(W.y), x##3 = bfhi(W.y), x##4 = bflo(W.z), x##5 = bfhi(W.z), x##6 = bflo(W.w), x##7 = bfhi(W.w)
; template <int NR>
; __device__ __forceinline__ void ln_rows(int lane, const bf16* Z, size_t rstride, const float* g, const float* b, float* Fout, bf16* Xout) {
;     ...
;         for (int r = 0; r < NR; ++r) { const float mu = mean[r], rs = rstd[r]; LN_X8(w[r][j], x);
;             const f32x4 o0 = (f32x4){(x0 - mu) * rs, (x1 - mu) * rs, (x2 - mu) * rs, (x3 - mu) * rs} * g0 + b0, o1 = (f32x4){(x4 - mu) * rs, (x5 - mu) * rs, (x6 - mu) * rs, (x7 - mu) * rs} * g1 + b1;
;             if (Fout) { GAS f32x4* fo = (GAS f32x4*)(Fout + r * rstride) + 2 * lane + 128 * j; fo[0] = o0; fo[1] = o1; }
;             if (Xout) { v4u ow; ow.x = pk2(o0.x, o0.y); ow.y = pk2(o0.z, o0.w); ow.z = pk2(o1.x, o1.y); ow.w = pk2(o1.z, o1.w); ((GAS v4u*)(Xout + r * rstride) + lane)[64 * j] = ow; } } }
.LBB0_1331:
	s_and_b64 vcc, exec, s[40:41]
	s_cbranch_vccnz .LBB0_1333
	v_cvt_pk_bf16_f32 v34, v34, v35
	v_cvt_pk_bf16_f32 v35, v36, v37
	s_lshl_b64 s[14:15], s[22:23], 1
	s_add_u32 s14, s26, s14
	v_cvt_pk_bf16_f32 v36, v38, v39
	s_addc_u32 s15, s27, s15
	v_lshl_add_u64 v[38:39], v[150:151], 4, s[14:15]
	v_add_co_u32_e32 v38, vcc, 0x1000, v38
	v_cvt_pk_bf16_f32 v37, v40, v41
	s_nop 0
	v_addc_co_u32_e32 v39, vcc, 0, v39, vcc
	global_store_dwordx4 v[38:39], v[34:37], off offset:1024

; #define GAS __attribute__((address_space(1)))
; __device__ __forceinline__ unsigned pk2(float lo, float hi) { return f2bf(lo) | (f2bf(hi) << 16); }
; #define LN_X8(W, x) const float x##0 = bflo(W.x), x##1 = bfhi(W.x), x##2 = bflo(W.y), x##3 = bfhi(W.y), x##4 = bflo(W.z), x##5 = bfhi(W.z), x##6 = bflo(W.w), x##7 = bfhi(W.w)
; template <int NR>
; __device__ __forceinline__ void ln_rows(int lane, const bf16* Z, size_t rstride, const float* g, const float* b, float* Fout, bf16* Xout) {
;     ...
;         for (int r = 0; r < NR; ++r) { const float mu = mean[r], rs = rstd[r]; LN_X8(w[r][j], x);
;             const f32x4 o0 = (f32x4){(x0 - mu) * rs, (x1 - mu) * rs, (x2 - mu) * rs, (x3 - mu) * rs} * g0 + b0, o1 = (f32x4){(x4 - mu) * rs, (x5 - mu) * rs, (x6 - mu) * rs, (x7 - mu) * rs} * g1 + b1;
;             if (Fout) { GAS f32x4* fo = (GAS f32x4*)(Fout + r * rstride) + 2 * lane + 128 * j; fo[0] = o0; fo[1] = o1; }
;             if (Xout) { v4u ow; ow.x = pk2(o0.x, o0.y); ow.y = pk2(o0.z, o0.w); ow.z = pk2(o1.x, o1.y); ow.w = pk2(o1.z, o1.w); ((GAS v4u*)(Xout + r * rstride) + lane)[64 * j] = ow; } } }
.LBB0_1335:
	s_and_b64 vcc, exec, s[40:41]
	s_cbranch_vccnz .LBB0_1337
	v_cvt_pk_bf16_f32 v50, v50, v51
	v_cvt_pk_bf16_f32 v51, v52, v53
	v_cvt_pk_bf16_f32 v52, v30, v31
	v_add_co_u32_e32 v30, vcc, 0x1000, v184
	v_cvt_pk_bf16_f32 v53, v32, v33
	s_nop 0
	v_addc_co_u32_e32 v31, vcc, 0, v185, vcc
	global_store_dwordx4 v[30:31], v[50:53], off offset:2048

; #define GAS __attribute__((address_space(1)))
; __device__ __forceinline__ unsigned pk2(float lo, float hi) { return f2bf(lo) | (f2bf(hi) << 16); }
; #define LN_X8(W, x) const float x##0 = bflo(W.x), x##1 = bfhi(W.x), x##2 = bflo(W.y), x##3 = bfhi(W.y), x##4 = bflo(W.z), x##5 = bfhi(W.z), x##6 = bflo(W.w), x##7 = bfhi(W.w)
; template <int NR>
; __device__ __forceinline__ void ln_rows(int lane, const bf16* Z, size_t rstride, const float* g, const float* b, float* Fout, bf16* Xout) {
;     ...
;         for (int r = 0; r < NR; ++r) { const float mu = mean[r], rs = rstd[r]; LN_X8(w[r][j], x);
;             const f32x4 o0 = (f32x4){(x0 - mu) * rs, (x1 - mu) * rs, (x2 - mu) * rs, (x3 - mu) * rs} * g0 + b0, o1 = (f32x4){(x4 - mu) * rs, (x5 - mu) * rs, (x6 - mu) * rs, (x7 - mu) * rs} * g1 + b1;
;             if (Fout) { GAS f32x4* fo = (GAS f32x4*)(Fout + r * rstride) + 2 * lane + 128 * j; fo[0] = o0; fo[1] = o1; }
;             if (Xout) { v4u ow; ow.x = pk2(o0.x, o0.y); ow.y = pk2(o0.z, o0.w); ow.z = pk2(o1.x, o1.y); ow.w = pk2(o1.z, o1.w); ((GAS v4u*)(Xout + r * rstride) + lane)[64 * j] = ow; } } }
.LBB0_1339:
	s_and_b64 vcc, exec, s[40:41]
	s_cbranch_vccnz .LBB0_1341
	v_cvt_pk_bf16_f32 v26, v26, v27
	v_cvt_pk_bf16_f32 v27, v28, v29
	s_lshl_b64 s[14:15], s[12:13], 1
	s_add_u32 s14, s26, s14
	v_cvt_pk_bf16_f32 v28, v30, v31
	s_addc_u32 s15, s27, s15
	v_lshl_add_u64 v[30:31], v[150:151], 4, s[14:15]
	v_add_co_u32_e32 v30, vcc, 0x1000, v30
	v_cvt_pk_bf16_f32 v29, v32, v33
	s_nop 0
	v_addc_co_u32_e32 v31, vcc, 0, v31, vcc
	global_store_dwordx4 v[30:31], v[26:29], off offset:2048

; #define GAS __attribute__((address_space(1)))
; __device__ __forceinline__ unsigned pk2(float lo, float hi) { return f2bf(lo) | (f2bf(hi) << 16); }
; #define LN_X8(W, x) const float x##0 = bflo(W.x), x##1 = bfhi(W.x), x##2 = bflo(W.y), x##3 = bfhi(W.y), x##4 = bflo(W.z), x##5 = bfhi(W.z), x##6 = bflo(W.w), x##7 = bfhi(W.w)
; template <int NR>
; __device__ __forceinline__ void ln_rows(int lane, const bf16* Z, size_t rstride, const float* g, const float* b, float* Fout, bf16* Xout) {
;     ...
;         for (int r = 0; r < NR; ++r) { const float mu = mean[r], rs = rstd[r]; LN_X8(w[r][j], x);
;             const f32x4 o0 = (f32x4){(x0 - mu) * rs, (x1 - mu) * rs, (x2 - mu) * rs, (x3 - mu) * rs} * g0 + b0, o1 = (f32x4){(x4 - mu) * rs, (x5 - mu) * rs, (x6 - mu) * rs, (x7 - mu) * rs} * g1 + b1;
;             if (Fout) { GAS f32x4* fo = (GAS f32x4*)(Fout + r * rstride) + 2 * lane + 128 * j; fo[0] = o0; fo[1] = o1; }
;             if (Xout) { v4u ow; ow.x = pk2(o0.x, o0.y); ow.y = pk2(o0.z, o0.w); ow.z = pk2(o1.x, o1.y); ow.w = pk2(o1.z, o1.w); ((GAS v4u*)(Xout + r * rstride) + lane)[64 * j] = ow; } } }
.LBB0_1343:
	s_and_b64 vcc, exec, s[40:41]
	s_cbranch_vccnz .LBB0_1345
	v_cvt_pk_bf16_f32 v22, v22, v23
	v_cvt_pk_bf16_f32 v23, v24, v25
	s_lshl_b64 s[14:15], s[10:11], 1
	s_add_u32 s14, s26, s14
	v_cvt_pk_bf16_f32 v24, v26, v27
	s_addc_u32 s15, s27, s15
	v_lshl_add_u64 v[26:27], v[150:151], 4, s[14:15]
	v_add_co_u32_e32 v26, vcc, 0x1000, v26
	v_cvt_pk_bf16_f32 v25, v28, v29
	s_nop 0
	v_addc_co_u32_e32 v27, vcc, 0, v27, vcc
	global_store_dwordx4 v[26:27], v[22:25], off offset:2048

; #define GAS __attribute__((address_space(1)))
; __device__ __forceinline__ unsigned pk2(float lo, float hi) { return f2bf(lo) | (f2bf(hi) << 16); }
; #define LN_X8(W, x) const float x##0 = bflo(W.x), x##1 = bfhi(W.x), x##2 = bflo(W.y), x##3 = bfhi(W.y), x##4 = bflo(W.z), x##5 = bfhi(W.z), x##6 = bflo(W.w), x##7 = bfhi(W.w)
; template <int NR>
; __device__ __forceinline__ void ln_rows(int lane, const bf16* Z, size_t rstride, const float* g, const float* b, float* Fout, bf16* Xout) {
;     ...
;         for (int r = 0; r < NR; ++r) { const float mu = mean[r], rs = rstd[r]; LN_X8(w[r][j], x);
;             const f32x4 o0 = (f32x4){(x0 - mu) * rs, (x1 - mu) * rs, (x2 - mu) * rs, (x3 - mu) * rs} * g0 + b0, o1 = (f32x4){(x4 - mu) * rs, (x5 - mu) * rs, (x6 - mu) * rs, (x7 - mu) * rs} * g1 + b1;
;             if (Fout) { GAS f32x4* fo = (GAS f32x4*)(Fout + r * rstride) + 2 * lane + 128 * j; fo[0] = o0; fo[1] = o1; }
;             if (Xout) { v4u ow; ow.x = pk2(o0.x, o0.y); ow.y = pk2(o0.z, o0.w); ow.z = pk2(o1.x, o1.y); ow.w = pk2(o1.z, o1.w); ((GAS v4u*)(Xout + r * rstride) + lane)[64 * j] = ow; } } }
.LBB0_1347:
	s_and_b64 vcc, exec, s[40:41]
	s_cbranch_vccnz .LBB0_1349
	v_cvt_pk_bf16_f32 v18, v18, v19
	v_cvt_pk_bf16_f32 v19, v20, v21
	s_lshl_b64 s[14:15], s[22:23], 1
	s_add_u32 s14, s26, s14
	v_cvt_pk_bf16_f32 v20, v22, v23
	s_addc_u32 s15, s27, s15
	v_lshl_add_u64 v[22:23], v[150:151], 4, s[14:15]
	v_add_co_u32_e32 v22, vcc, 0x1000, v22
	v_cvt_pk_bf16_f32 v21, v24, v25
	s_nop 0
	v_addc_co_u32_e32 v23, vcc, 0, v23, vcc
	global_store_dwordx4 v[22:23], v[18:21], off offset:2048

; #define GAS __attribute__((address_space(1)))
; __device__ __forceinline__ unsigned pk2(float lo, float hi) { return f2bf(lo) | (f2bf(hi) << 16); }
; #define LN_X8(W, x) const float x##0 = bflo(W.x), x##1 = bfhi(W.x), x##2 = bflo(W.y), x##3 = bfhi(W.y), x##4 = bflo(W.z), x##5 = bfhi(W.z), x##6 = bflo(W.w), x##7 = bfhi(W.w)
; template <int NR>
; __device__ __forceinline__ void ln_rows(int lane, const bf16* Z, size_t rstride, const float* g, const float* b, float* Fout, bf16* Xout) {
;     ...
;         for (int r = 0; r < NR; ++r) { const float mu = mean[r], rs = rstd[r]; LN_X8(w[r][j], x);
;             const f32x4 o0 = (f32x4){(x0 - mu) * rs, (x1 - mu) * rs, (x2 - mu) * rs, (x3 - mu) * rs} * g0 + b0, o1 = (f32x4){(x4 - mu) * rs, (x5 - mu) * rs, (x6 - mu) * rs, (x7 - mu) * rs} * g1 + b1;
;             if (Fout) { GAS f32x4* fo = (GAS f32x4*)(Fout + r * rstride) + 2 * lane + 128 * j; fo[0] = o0; fo[1] = o1; }
;             if (Xout) { v4u ow; ow.x = pk2(o0.x, o0.y); ow.y = pk2(o0.z, o0.w); ow.z = pk2(o1.x, o1.y); ow.w = pk2(o1.z, o1.w); ((GAS v4u*)(Xout + r * rstride) + lane)[64 * j] = ow; } } }
.LBB0_1351:
	s_and_b64 vcc, exec, s[40:41]
	s_cbranch_vccnz .LBB0_1353
	v_cvt_pk_bf16_f32 v34, v34, v35
	v_cvt_pk_bf16_f32 v35, v36, v37
	v_cvt_pk_bf16_f32 v36, v14, v15
	v_add_co_u32_e32 v14, vcc, 0x1000, v184
	v_cvt_pk_bf16_f32 v37, v16, v17
	s_nop 0
	v_addc_co_u32_e32 v15, vcc, 0, v185, vcc
	global_store_dwordx4 v[14:15], v[34:37], off offset:3072

; #define GAS __attribute__((address_space(1)))
; __device__ __forceinline__ unsigned pk2(float lo, float hi) { return f2bf(lo) | (f2bf(hi) << 16); }
; #define LN_X8(W, x) const float x##0 = bflo(W.x), x##1 = bfhi(W.x), x##2 = bflo(W.y), x##3 = bfhi(W.y), x##4 = bflo(W.z), x##5 = bfhi(W.z), x##6 = bflo(W.w), x##7 = bfhi(W.w)
; template <int NR>
; __device__ __forceinline__ void ln_rows(int lane, const bf16* Z, size_t rstride, const float* g, const float* b, float* Fout, bf16* Xout) {
;     ...
;         for (int r = 0; r < NR; ++r) { const float mu = mean[r], rs = rstd[r]; LN_X8(w[r][j], x);
;             const f32x4 o0 = (f32x4){(x0 - mu) * rs, (x1 - mu) * rs, (x2 - mu) * rs, (x3 - mu) * rs} * g0 + b0, o1 = (f32x4){(x4 - mu) * rs, (x5 - mu) * rs, (x6 - mu) * rs, (x7 - mu) * rs} * g1 + b1;
;             if (Fout) { GAS f32x4* fo = (GAS f32x4*)(Fout + r * rstride) + 2 * lane + 128 * j; fo[0] = o0; fo[1] = o1; }
;             if (Xout) { v4u ow; ow.x = pk2(o0.x, o0.y); ow.y = pk2(o0.z, o0.w); ow.z = pk2(o1.x, o1.y); ow.w = pk2(o1.z, o1.w); ((GAS v4u*)(Xout + r * rstride) + lane)[64 * j] = ow; } } }
.LBB0_1355:
	s_and_b64 vcc, exec, s[40:41]
	s_cbranch_vccnz .LBB0_1357
	v_cvt_pk_bf16_f32 v10, v10, v11
	v_cvt_pk_bf16_f32 v11, v12, v13
	s_lshl_b64 s[14:15], s[12:13], 1
	s_add_u32 s14, s26, s14
	v_cvt_pk_bf16_f32 v12, v14, v15
	s_addc_u32 s15, s27, s15
	v_lshl_add_u64 v[14:15], v[150:151], 4, s[14:15]
	v_add_co_u32_e32 v14, vcc, 0x1000, v14
	v_cvt_pk_bf16_f32 v13, v16, v17
	s_nop 0
	v_addc_co_u32_e32 v15, vcc, 0, v15, vcc
	global_store_dwordx4 v[14:15], v[10:13], off offset:3072

; #define GAS __attribute__((address_space(1)))
; __device__ __forceinline__ unsigned pk2(float lo, float hi) { return f2bf(lo) | (f2bf(hi) << 16); }
; #define LN_X8(W, x) const float x##0 = bflo(W.x), x##1 = bfhi(W.x), x##2 = bflo(W.y), x##3 = bfhi(W.y), x##4 = bflo(W.z), x##5 = bfhi(W.z), x##6 = bflo(W.w), x##7 = bfhi(W.w)
; template <int NR>
; __device__ __forceinline__ void ln_rows(int lane, const bf16* Z, size_t rstride, const float* g, const float* b, float* Fout, bf16* Xout) {
;     ...
;         for (int r = 0; r < NR; ++r) { const float mu = mean[r], rs = rstd[r]; LN_X8(w[r][j], x);
;             const f32x4 o0 = (f32x4){(x0 - mu) * rs, (x1 - mu) * rs, (x2 - mu) * rs, (x3 - mu) * rs} * g0 + b0, o1 = (f32x4){(x4 - mu) * rs, (x5 - mu) * rs, (x6 - mu) * rs, (x7 - mu) * rs} * g1 + b1;
;             if (Fout) { GAS f32x4* fo = (GAS f32x4*)(Fout + r * rstride) + 2 * lane + 128 * j; fo[0] = o0; fo[1] = o1; }
;             if (Xout) { v4u ow; ow.x = pk2(o0.x, o0.y); ow.y = pk2(o0.z, o0.w); ow.z = pk2(o1.x, o1.y); ow.w = pk2(o1.z, o1.w); ((GAS v4u*)(Xout + r * rstride) + lane)[64 * j] = ow; } } }
.LBB0_1359:
	s_and_b64 vcc, exec, s[40:41]
	s_cbranch_vccnz .LBB0_1361
	v_cvt_pk_bf16_f32 v6, v6, v7
	v_cvt_pk_bf16_f32 v7, v8, v9
	s_lshl_b64 s[14:15], s[10:11], 1
	s_add_u32 s14, s26, s14
	v_cvt_pk_bf16_f32 v8, v10, v11
	s_addc_u32 s15, s27, s15
	v_lshl_add_u64 v[10:11], v[150:151], 4, s[14:15]
	v_add_co_u32_e32 v10, vcc, 0x1000, v10
	v_cvt_pk_bf16_f32 v9, v12, v13
	s_nop 0
	v_addc_co_u32_e32 v11, vcc, 0, v11, vcc
	global_store_dwordx4 v[10:11], v[6:9], off offset:3072

; #define GAS __attribute__((address_space(1)))
; __device__ __forceinline__ unsigned pk2(float lo, float hi) { return f2bf(lo) | (f2bf(hi) << 16); }
; #define LN_X8(W, x) const float x##0 = bflo(W.x), x##1 = bfhi(W.x), x##2 = bflo(W.y), x##3 = bfhi(W.y), x##4 = bflo(W.z), x##5 = bfhi(W.z), x##6 = bflo(W.w), x##7 = bfhi(W.w)
; template <int NR>
; __device__ __forceinline__ void ln_rows(int lane, const bf16* Z, size_t rstride, const float* g, const float* b, float* Fout, bf16* Xout) {
;     ...
;         for (int r = 0; r < NR; ++r) { const float mu = mean[r], rs = rstd[r]; LN_X8(w[r][j], x);
;             const f32x4 o0 = (f32x4){(x0 - mu) * rs, (x1 - mu) * rs, (x2 - mu) * rs, (x3 - mu) * rs} * g0 + b0, o1 = (f32x4){(x4 - mu) * rs, (x5 - mu) * rs, (x6 - mu) * rs, (x7 - mu) * rs} * g1 + b1;
;             if (Fout) { GAS f32x4* fo = (GAS f32x4*)(Fout + r * rstride) + 2 * lane + 128 * j; fo[0] = o0; fo[1] = o1; }
;             if (Xout) { v4u ow; ow.x = pk2(o0.x, o0.y); ow.y = pk2(o0.z, o0.w); ow.z = pk2(o1.x, o1.y); ow.w = pk2(o1.z, o1.w); ((GAS v4u*)(Xout + r * rstride) + lane)[64 * j] = ow; } } }
.LBB0_1363:
	s_and_b64 vcc, exec, s[40:41]
	s_cbranch_vccnz .LBB0_1236
	v_cvt_pk_bf16_f32 v2, v2, v3
	v_cvt_pk_bf16_f32 v3, v4, v5
	s_lshl_b64 s[14:15], s[22:23], 1
	s_add_u32 s14, s26, s14
	v_cvt_pk_bf16_f32 v4, v6, v7
	s_addc_u32 s15, s27, s15
	v_lshl_add_u64 v[6:7], v[150:151], 4, s[14:15]
	v_add_co_u32_e32 v6, vcc, 0x1000, v6
	v_cvt_pk_bf16_f32 v5, v8, v9
	s_nop 0
	v_addc_co_u32_e32 v7, vcc, 0, v7, vcc
	global_store_dwordx4 v[6:7], v[2:5], off offset:3072
	s_branch .LBB0_1236

; #define GAS __attribute__((address_space(1)))
; __device__ __forceinline__ unsigned pk2(float lo, float hi) { return f2bf(lo) | (f2bf(hi) << 16); }
; template <bool IN_BF16>
; __device__ __forceinline__ void ln_row(int lane, const void* zrow, const float* g, const float* b, float* hrow, bf16* xrow) {
;     ...
;     for (int j = 0; j < 16; ++j) { const f32x4 o = v[j] * rstd * gr[64 * j] + br[64 * j];
;         if (hrow) ((GAS f32x4*)hrow + lane)[64 * j] = o;
;         if (xrow) ((GAS unsigned long long*)xrow + lane)[64 * j] = (unsigned long long)pk2(o.x, o.y) | ((unsigned long long)pk2(o.z, o.w) << 32); }
.LBB0_1370:
	s_add_u32 s20, s46, s50
	s_addc_u32 s24, s47, s51
	s_and_b64 s[28:29], s[44:45], exec
	s_cselect_b32 s37, 0, s24
	s_cselect_b32 s36, 0, s20
	s_cmp_lg_u64 s[36:37], 0
	s_cselect_b64 s[28:29], -1, 0
	s_cmp_eq_u64 s[36:37], 0
	v_lshl_add_u64 v[74:75], v[150:151], 3, s[36:37]
	s_cbranch_scc1 .LBB0_1372
	v_cvt_pk_bf16_f32 v2, v2, v3
	v_cvt_pk_bf16_f32 v3, v4, v5
	global_store_dwordx2 v[74:75], v[2:3], off

; #define GAS __attribute__((address_space(1)))
; __device__ __forceinline__ unsigned pk2(float lo, float hi) { return f2bf(lo) | (f2bf(hi) << 16); }
; template <bool IN_BF16>
; __device__ __forceinline__ void ln_row(int lane, const void* zrow, const float* g, const float* b, float* hrow, bf16* xrow) {
;     ...
;     for (int j = 0; j < 16; ++j) { const f32x4 o = v[j] * rstd * gr[64 * j] + br[64 * j];
;         if (hrow) ((GAS f32x4*)hrow + lane)[64 * j] = o;
;         if (xrow) ((GAS unsigned long long*)xrow + lane)[64 * j] = (unsigned long long)pk2(o.x, o.y) | ((unsigned long long)pk2(o.z, o.w) << 32); }
.LBB0_1374:
	v_cndmask_b32_e64 v0, 0, 1, s[28:29]
	v_cmp_ne_u32_e64 s[40:41], 1, v0
	s_andn2_b64 vcc, exec, s[28:29]
	s_movk_i32 s20, 0x1000
	s_cbranch_vccnz .LBB0_1376
	v_cvt_pk_bf16_f32 v2, v2, v3
	v_cvt_pk_bf16_f32 v3, v4, v5
	global_store_dwordx2 v[74:75], v[2:3], off offset:512

; #define GAS __attribute__((address_space(1)))
; __device__ __forceinline__ unsigned pk2(float lo, float hi) { return f2bf(lo) | (f2bf(hi) << 16); }
; template <bool IN_BF16>
; __device__ __forceinline__ void ln_row(int lane, const void* zrow, const float* g, const float* b, float* hrow, bf16* xrow) {
;     ...
;     for (int j = 0; j < 16; ++j) { const f32x4 o = v[j] * rstd * gr[64 * j] + br[64 * j];
;         if (hrow) ((GAS f32x4*)hrow + lane)[64 * j] = o;
;         if (xrow) ((GAS unsigned long long*)xrow + lane)[64 * j] = (unsigned long long)pk2(o.x, o.y) | ((unsigned long long)pk2(o.z, o.w) << 32); }
.LBB0_1378:
	s_and_b64 vcc, exec, s[40:41]
	s_cbranch_vccnz .LBB0_1380
	v_cvt_pk_bf16_f32 v2, v2, v3
	v_cvt_pk_bf16_f32 v3, v4, v5
	global_store_dwordx2 v[74:75], v[2:3], off offset:1024

; #define GAS __attribute__((address_space(1)))
; __device__ __forceinline__ unsigned pk2(float lo, float hi) { return f2bf(lo) | (f2bf(hi) << 16); }
; template <bool IN_BF16>
; __device__ __forceinline__ void ln_row(int lane, const void* zrow, const float* g, const float* b, float* hrow, bf16* xrow) {
;     ...
;     for (int j = 0; j < 16; ++j) { const f32x4 o = v[j] * rstd * gr[64 * j] + br[64 * j];
;         if (hrow) ((GAS f32x4*)hrow + lane)[64 * j] = o;
;         if (xrow) ((GAS unsigned long long*)xrow + lane)[64 * j] = (unsigned long long)pk2(o.x, o.y) | ((unsigned long long)pk2(o.z, o.w) << 32); }
.LBB0_1382:
	s_and_b64 vcc, exec, s[40:41]
	s_cbranch_vccnz .LBB0_1384
	v_cvt_pk_bf16_f32 v2, v2, v3
	v_cvt_pk_bf16_f32 v3, v4, v5
	global_store_dwordx2 v[74:75], v[2:3], off offset:1536

; #define GAS __attribute__((address_space(1)))
; __device__ __forceinline__ unsigned pk2(float lo, float hi) { return f2bf(lo) | (f2bf(hi) << 16); }
; template <bool IN_BF16>
; __device__ __forceinline__ void ln_row(int lane, const void* zrow, const float* g, const float* b, float* hrow, bf16* xrow) {
;     ...
;     for (int j = 0; j < 16; ++j) { const f32x4 o = v[j] * rstd * gr[64 * j] + br[64 * j];
;         if (hrow) ((GAS f32x4*)hrow + lane)[64 * j] = o;
;         if (xrow) ((GAS unsigned long long*)xrow + lane)[64 * j] = (unsigned long long)pk2(o.x, o.y) | ((unsigned long long)pk2(o.z, o.w) << 32); }
.LBB0_1386:
	s_and_b64 vcc, exec, s[40:41]
	s_cbranch_vccnz .LBB0_1388
	v_cvt_pk_bf16_f32 v2, v2, v3
	v_cvt_pk_bf16_f32 v3, v4, v5
	global_store_dwordx2 v[74:75], v[2:3], off offset:2048

; #define GAS __attribute__((address_space(1)))
; __device__ __forceinline__ unsigned pk2(float lo, float hi) { return f2bf(lo) | (f2bf(hi) << 16); }
; template <bool IN_BF16>
; __device__ __forceinline__ void ln_row(int lane, const void* zrow, const float* g, const float* b, float* hrow, bf16* xrow) {
;     ...
;     for (int j = 0; j < 16; ++j) { const f32x4 o = v[j] * rstd * gr[64 * j] + br[64 * j];
;         if (hrow) ((GAS f32x4*)hrow + lane)[64 * j] = o;
;         if (xrow) ((GAS unsigned long long*)xrow + lane)[64 * j] = (unsigned long long)pk2(o.x, o.y) | ((unsigned long long)pk2(o.z, o.w) << 32); }
.LBB0_1390:
	s_and_b64 vcc, exec, s[40:41]
	s_cbranch_vccnz .LBB0_1392
	v_cvt_pk_bf16_f32 v2, v2, v3
	v_cvt_pk_bf16_f32 v3, v4, v5
	global_store_dwordx2 v[74:75], v[2:3], off offset:2560

; #define GAS __attribute__((address_space(1)))
; __device__ __forceinline__ unsigned pk2(float lo, float hi) { return f2bf(lo) | (f2bf(hi) << 16); }
; template <bool IN_BF16>
; __device__ __forceinline__ void ln_row(int lane, const void* zrow, const float* g, const float* b, float* hrow, bf16* xrow) {
;     ...
;     for (int j = 0; j < 16; ++j) { const f32x4 o = v[j] * rstd * gr[64 * j] + br[64 * j];
;         if (hrow) ((GAS f32x4*)hrow + lane)[64 * j] = o;
;         if (xrow) ((GAS unsigned long long*)xrow + lane)[64 * j] = (unsigned long long)pk2(o.x, o.y) | ((unsigned long long)pk2(o.z, o.w) << 32); }
.LBB0_1394:
	s_and_b64 vcc, exec, s[40:41]
	s_cbranch_vccnz .LBB0_1396
	v_cvt_pk_bf16_f32 v2, v2, v3
	v_cvt_pk_bf16_f32 v3, v4, v5
	global_store_dwordx2 v[74:75], v[2:3], off offset:3072

; #define GAS __attribute__((address_space(1)))
; __device__ __forceinline__ unsigned pk2(float lo, float hi) { return f2bf(lo) | (f2bf(hi) << 16); }
; template <bool IN_BF16>
; __device__ __forceinline__ void ln_row(int lane, const void* zrow, const float* g, const float* b, float* hrow, bf16* xrow) {
;     ...
;     for (int j = 0; j < 16; ++j) { const f32x4 o = v[j] * rstd * gr[64 * j] + br[64 * j];
;         if (hrow) ((GAS f32x4*)hrow + lane)[64 * j] = o;
;         if (xrow) ((GAS unsigned long long*)xrow + lane)[64 * j] = (unsigned long long)pk2(o.x, o.y) | ((unsigned long long)pk2(o.z, o.w) << 32); }
.LBB0_1398:
	s_and_b64 vcc, exec, s[40:41]
	s_cbranch_vccnz .LBB0_1400
	v_cvt_pk_bf16_f32 v2, v2, v3
	v_cvt_pk_bf16_f32 v3, v4, v5
	global_store_dwordx2 v[74:75], v[2:3], off offset:3584

; #define GAS __attribute__((address_space(1)))
; __device__ __forceinline__ unsigned pk2(float lo, float hi) { return f2bf(lo) | (f2bf(hi) << 16); }
; template <bool IN_BF16>
; __device__ __forceinline__ void ln_row(int lane, const void* zrow, const float* g, const float* b, float* hrow, bf16* xrow) {
;     ...
;     for (int j = 0; j < 16; ++j) { const f32x4 o = v[j] * rstd * gr[64 * j] + br[64 * j];
;         if (hrow) ((GAS f32x4*)hrow + lane)[64 * j] = o;
;         if (xrow) ((GAS unsigned long long*)xrow + lane)[64 * j] = (unsigned long long)pk2(o.x, o.y) | ((unsigned long long)pk2(o.z, o.w) << 32); }
.LBB0_1402:
	s_and_b64 vcc, exec, s[40:41]
	s_cbranch_vccnz .LBB0_1404
	v_cvt_pk_bf16_f32 v2, v2, v3
	v_bfe_u32 v0, v4, 16, 1
	v_add3_u32 v0, v4, v0, s25
	v_bfe_u32 v3, v5, 16, 1
	v_lshrrev_b32_e32 v0, 16, v0
	v_add3_u32 v3, v5, v3, s25
	v_add_co_u32_e32 v4, vcc, 0x1000, v74
	v_and_or_b32 v3, v3, s33, v0
	s_nop 0
	v_addc_co_u32_e32 v5, vcc, 0, v75, vcc
	global_store_dwordx2 v[4:5], v[2:3], off

; #define GAS __attribute__((address_space(1)))
; __device__ __forceinline__ unsigned pk2(float lo, float hi) { return f2bf(lo) | (f2bf(hi) << 16); }
; template <bool IN_BF16>
; __device__ __forceinline__ void ln_row(int lane, const void* zrow, const float* g, const float* b, float* hrow, bf16* xrow) {
;     ...
;     for (int j = 0; j < 16; ++j) { const f32x4 o = v[j] * rstd * gr[64 * j] + br[64 * j];
;         if (hrow) ((GAS f32x4*)hrow + lane)[64 * j] = o;
;         if (xrow) ((GAS unsigned long long*)xrow + lane)[64 * j] = (unsigned long long)pk2(o.x, o.y) | ((unsigned long long)pk2(o.z, o.w) << 32); }
.LBB0_1406:
	s_and_b64 vcc, exec, s[40:41]
	s_cbranch_vccnz .LBB0_1408
	v_cvt_pk_bf16_f32 v2, v2, v3
	v_bfe_u32 v0, v4, 16, 1
	v_add3_u32 v0, v4, v0, s25
	v_bfe_u32 v3, v5, 16, 1
	v_lshrrev_b32_e32 v0, 16, v0
	v_add3_u32 v3, v5, v3, s25
	v_add_co_u32_e32 v4, vcc, 0x1000, v74
	v_and_or_b32 v3, v3, s33, v0
	s_nop 0
	v_addc_co_u32_e32 v5, vcc, 0, v75, vcc
	global_store_dwordx2 v[4:5], v[2:3], off offset:512

; #define GAS __attribute__((address_space(1)))
; __device__ __forceinline__ unsigned pk2(float lo, float hi) { return f2bf(lo) | (f2bf(hi) << 16); }
; template <bool IN_BF16>
; __device__ __forceinline__ void ln_row(int lane, const void* zrow, const float* g, const float* b, float* hrow, bf16* xrow) {
;     ...
;     for (int j = 0; j < 16; ++j) { const f32x4 o = v[j] * rstd * gr[64 * j] + br[64 * j];
;         if (hrow) ((GAS f32x4*)hrow + lane)[64 * j] = o;
;         if (xrow) ((GAS unsigned long long*)xrow + lane)[64 * j] = (unsigned long long)pk2(o.x, o.y) | ((unsigned long long)pk2(o.z, o.w) << 32); }
.LBB0_1410:
	s_and_b64 vcc, exec, s[40:41]
	s_cbranch_vccnz .LBB0_1412
	v_cvt_pk_bf16_f32 v2, v2, v3
	v_bfe_u32 v0, v4, 16, 1
	v_add3_u32 v0, v4, v0, s25
	v_bfe_u32 v3, v5, 16, 1
	v_lshrrev_b32_e32 v0, 16, v0
	v_add3_u32 v3, v5, v3, s25
	v_add_co_u32_e32 v4, vcc, 0x1000, v74
	v_and_or_b32 v3, v3, s33, v0
	s_nop 0
	v_addc_co_u32_e32 v5, vcc, 0, v75, vcc
	global_store_dwordx2 v[4:5], v[2:3], off offset:1024

; #define GAS __attribute__((address_space(1)))
; __device__ __forceinline__ unsigned pk2(float lo, float hi) { return f2bf(lo) | (f2bf(hi) << 16); }
; template <bool IN_BF16>
; __device__ __forceinline__ void ln_row(int lane, const void* zrow, const float* g, const float* b, float* hrow, bf16* xrow) {
;     ...
;     for (int j = 0; j < 16; ++j) { const f32x4 o = v[j] * rstd * gr[64 * j] + br[64 * j];
;         if (hrow) ((GAS f32x4*)hrow + lane)[64 * j] = o;
;         if (xrow) ((GAS unsigned long long*)xrow + lane)[64 * j] = (unsigned long long)pk2(o.x, o.y) | ((unsigned long long)pk2(o.z, o.w) << 32); }
.LBB0_1414:
	s_and_b64 vcc, exec, s[40:41]
	s_cbranch_vccnz .LBB0_1416
	v_cvt_pk_bf16_f32 v2, v2, v3
	v_bfe_u32 v0, v4, 16, 1
	v_add3_u32 v0, v4, v0, s25
	v_bfe_u32 v3, v5, 16, 1
	v_lshrrev_b32_e32 v0, 16, v0
	v_add3_u32 v3, v5, v3, s25
	v_add_co_u32_e32 v4, vcc, 0x1000, v74
	v_and_or_b32 v3, v3, s33, v0
	s_nop 0
	v_addc_co_u32_e32 v5, vcc, 0, v75, vcc
	global_store_dwordx2 v[4:5], v[2:3], off offset:1536

; #define GAS __attribute__((address_space(1)))
; __device__ __forceinline__ unsigned pk2(float lo, float hi) { return f2bf(lo) | (f2bf(hi) << 16); }
; template <bool IN_BF16>
; __device__ __forceinline__ void ln_row(int lane, const void* zrow, const float* g, const float* b, float* hrow, bf16* xrow) {
;     ...
;     for (int j = 0; j < 16; ++j) { const f32x4 o = v[j] * rstd * gr[64 * j] + br[64 * j];
;         if (hrow) ((GAS f32x4*)hrow + lane)[64 * j] = o;
;         if (xrow) ((GAS unsigned long long*)xrow + lane)[64 * j] = (unsigned long long)pk2(o.x, o.y) | ((unsigned long long)pk2(o.z, o.w) << 32); }
.LBB0_1418:
	s_and_b64 vcc, exec, s[40:41]
	s_cbranch_vccnz .LBB0_1420
	v_cvt_pk_bf16_f32 v2, v2, v3
	v_bfe_u32 v0, v4, 16, 1
	v_add3_u32 v0, v4, v0, s25
	v_bfe_u32 v3, v5, 16, 1
	v_lshrrev_b32_e32 v0, 16, v0
	v_add3_u32 v3, v5, v3, s25
	v_add_co_u32_e32 v4, vcc, 0x1000, v74
	v_and_or_b32 v3, v3, s33, v0
	s_nop 0
	v_addc_co_u32_e32 v5, vcc, 0, v75, vcc
	global_store_dwordx2 v[4:5], v[2:3], off offset:2048

; #define GAS __attribute__((address_space(1)))
; __device__ __forceinline__ unsigned pk2(float lo, float hi) { return f2bf(lo) | (f2bf(hi) << 16); }
; template <bool IN_BF16>
; __device__ __forceinline__ void ln_row(int lane, const void* zrow, const float* g, const float* b, float* hrow, bf16* xrow) {
;     ...
;     for (int j = 0; j < 16; ++j) { const f32x4 o = v[j] * rstd * gr[64 * j] + br[64 * j];
;         if (hrow) ((GAS f32x4*)hrow + lane)[64 * j] = o;
;         if (xrow) ((GAS unsigned long long*)xrow + lane)[64 * j] = (unsigned long long)pk2(o.x, o.y) | ((unsigned long long)pk2(o.z, o.w) << 32); }
.LBB0_1422:
	s_and_b64 vcc, exec, s[40:41]
	s_cbranch_vccnz .LBB0_1424
	v_cvt_pk_bf16_f32 v2, v2, v3
	v_bfe_u32 v0, v4, 16, 1
	v_add3_u32 v0, v4, v0, s25
	v_bfe_u32 v3, v5, 16, 1
	v_lshrrev_b32_e32 v0, 16, v0
	v_add3_u32 v3, v5, v3, s25
	v_add_co_u32_e32 v4, vcc, 0x1000, v74
	v_and_or_b32 v3, v3, s33, v0
	s_nop 0
	v_addc_co_u32_e32 v5, vcc, 0, v75, vcc
	global_store_dwordx2 v[4:5], v[2:3], off offset:2560

; #define GAS __attribute__((address_space(1)))
; __device__ __forceinline__ unsigned pk2(float lo, float hi) { return f2bf(lo) | (f2bf(hi) << 16); }
; template <bool IN_BF16>
; __device__ __forceinline__ void ln_row(int lane, const void* zrow, const float* g, const float* b, float* hrow, bf16* xrow) {
;     ...
;     for (int j = 0; j < 16; ++j) { const f32x4 o = v[j] * rstd * gr[64 * j] + br[64 * j];
;         if (hrow) ((GAS f32x4*)hrow + lane)[64 * j] = o;
;         if (xrow) ((GAS unsigned long long*)xrow + lane)[64 * j] = (unsigned long long)pk2(o.x, o.y) | ((unsigned long long)pk2(o.z, o.w) << 32); }
.LBB0_1426:
	s_and_b64 vcc, exec, s[40:41]
	s_cbranch_vccnz .LBB0_1428
	v_cvt_pk_bf16_f32 v2, v2, v3
	v_bfe_u32 v0, v4, 16, 1
	v_add3_u32 v0, v4, v0, s25
	v_bfe_u32 v3, v5, 16, 1
	v_lshrrev_b32_e32 v0, 16, v0
	v_add3_u32 v3, v5, v3, s25
	v_add_co_u32_e32 v4, vcc, 0x1000, v74
	v_and_or_b32 v3, v3, s33, v0
	s_nop 0
	v_addc_co_u32_e32 v5, vcc, 0, v75, vcc
	global_store_dwordx2 v[4:5], v[2:3], off offset:3072

; #define GAS __attribute__((address_space(1)))
; __device__ __forceinline__ unsigned pk2(float lo, float hi) { return f2bf(lo) | (f2bf(hi) << 16); }
; template <bool IN_BF16>
; __device__ __forceinline__ void ln_row(int lane, const void* zrow, const float* g, const float* b, float* hrow, bf16* xrow) {
;     ...
;     for (int j = 0; j < 16; ++j) { const f32x4 o = v[j] * rstd * gr[64 * j] + br[64 * j];
;         if (hrow) ((GAS f32x4*)hrow + lane)[64 * j] = o;
;         if (xrow) ((GAS unsigned long long*)xrow + lane)[64 * j] = (unsigned long long)pk2(o.x, o.y) | ((unsigned long long)pk2(o.z, o.w) << 32); }
.LBB0_1430:
	s_and_b64 vcc, exec, s[40:41]
	s_cbranch_vccnz .LBB0_1367
	v_cvt_pk_bf16_f32 v2, v2, v3
	v_bfe_u32 v0, v4, 16, 1
	v_add3_u32 v0, v4, v0, s25
	v_bfe_u32 v3, v5, 16, 1
	v_lshrrev_b32_e32 v0, 16, v0
	v_add3_u32 v3, v5, v3, s25
	v_add_co_u32_e32 v4, vcc, 0x1000, v74
	v_and_or_b32 v3, v3, s33, v0
	s_nop 0
	v_addc_co_u32_e32 v5, vcc, 0, v75, vcc
	global_store_dwordx2 v[4:5], v[2:3], off offset:3584
	s_branch .LBB0_1367
